# ladder + B0 ds_reads of phases 1/5 hoisted one phase earlier (into load segments 8/4) with vmcnt(10) cover in L3/L7
# speedup vs baseline: 1.0059x; 1.0059x over previous
.LBB0_30:
	s_add_u32 s10, s52, 0x100
	v_mov_b32_e32 v0, 0
	s_addc_u32 s11, s53, 0
	s_mov_b32 s12, -2
	s_waitcnt lgkmcnt(0)
	v_mov_b32_e32 v1, v0
	v_mov_b32_e32 v2, v0
	v_mov_b32_e32 v3, v0
	v_mov_b32_e32 v4, v0
	v_mov_b32_e32 v5, v0
	v_mov_b32_e32 v6, v0
	v_mov_b32_e32 v7, v0
	v_mov_b32_e32 v12, v0
	v_mov_b32_e32 v13, v0
	v_mov_b32_e32 v14, v0
	v_mov_b32_e32 v15, v0
	v_mov_b32_e32 v20, v0
	v_mov_b32_e32 v21, v0
	v_mov_b32_e32 v22, v0
	v_mov_b32_e32 v23, v0
	v_mov_b32_e32 v28, v0
	v_mov_b32_e32 v29, v0
	v_mov_b32_e32 v30, v0
	v_mov_b32_e32 v31, v0
	v_mov_b32_e32 v36, v0
	v_mov_b32_e32 v37, v0
	v_mov_b32_e32 v38, v0
	v_mov_b32_e32 v39, v0
	v_mov_b32_e32 v44, v0
	v_mov_b32_e32 v45, v0
	v_mov_b32_e32 v46, v0
	v_mov_b32_e32 v47, v0
	v_mov_b32_e32 v52, v0
	v_mov_b32_e32 v53, v0
	v_mov_b32_e32 v54, v0
	v_mov_b32_e32 v55, v0
	v_mov_b32_e32 v8, v0
	v_mov_b32_e32 v9, v0
	v_mov_b32_e32 v10, v0
	v_mov_b32_e32 v11, v0
	v_mov_b32_e32 v16, v0
	v_mov_b32_e32 v17, v0
	v_mov_b32_e32 v18, v0
	v_mov_b32_e32 v19, v0
	v_mov_b32_e32 v24, v0
	v_mov_b32_e32 v25, v0
	v_mov_b32_e32 v26, v0
	v_mov_b32_e32 v27, v0
	v_mov_b32_e32 v32, v0
	v_mov_b32_e32 v33, v0
	v_mov_b32_e32 v34, v0
	v_mov_b32_e32 v35, v0
	v_mov_b32_e32 v40, v0
	v_mov_b32_e32 v41, v0
	v_mov_b32_e32 v42, v0
	v_mov_b32_e32 v43, v0
	v_mov_b32_e32 v48, v0
	v_mov_b32_e32 v49, v0
	v_mov_b32_e32 v50, v0
	v_mov_b32_e32 v51, v0
	v_mov_b32_e32 v56, v0
	v_mov_b32_e32 v57, v0
	v_mov_b32_e32 v58, v0
	v_mov_b32_e32 v59, v0
	v_mov_b32_e32 v60, v0
	v_mov_b32_e32 v61, v0
	v_mov_b32_e32 v62, v0
	v_mov_b32_e32 v63, v0
	v_mov_b32_e32 v64, v0
	v_mov_b32_e32 v65, v0
	v_mov_b32_e32 v66, v0
	v_mov_b32_e32 v67, v0
	v_mov_b32_e32 v68, v0
	v_mov_b32_e32 v69, v0
	v_mov_b32_e32 v70, v0
	v_mov_b32_e32 v71, v0
	v_mov_b32_e32 v72, v0
	v_mov_b32_e32 v73, v0
	v_mov_b32_e32 v74, v0
	v_mov_b32_e32 v75, v0
	v_mov_b32_e32 v76, v0
	v_mov_b32_e32 v77, v0
	v_mov_b32_e32 v78, v0
	v_mov_b32_e32 v79, v0
	v_mov_b32_e32 v92, v0
	v_mov_b32_e32 v93, v0
	v_mov_b32_e32 v94, v0
	v_mov_b32_e32 v95, v0
	v_mov_b32_e32 v100, v0
	v_mov_b32_e32 v101, v0
	v_mov_b32_e32 v102, v0
	v_mov_b32_e32 v103, v0
	v_mov_b32_e32 v112, v0
	v_mov_b32_e32 v113, v0
	v_mov_b32_e32 v114, v0
	v_mov_b32_e32 v115, v0
	v_mov_b32_e32 v116, v0
	v_mov_b32_e32 v117, v0
	v_mov_b32_e32 v118, v0
	v_mov_b32_e32 v119, v0
	v_mov_b32_e32 v80, v0
	v_mov_b32_e32 v81, v0
	v_mov_b32_e32 v82, v0
	v_mov_b32_e32 v83, v0
	v_mov_b32_e32 v84, v0
	v_mov_b32_e32 v85, v0
	v_mov_b32_e32 v86, v0
	v_mov_b32_e32 v87, v0
	v_mov_b32_e32 v88, v0
	v_mov_b32_e32 v89, v0
	v_mov_b32_e32 v90, v0
	v_mov_b32_e32 v91, v0
	v_mov_b32_e32 v96, v0
	v_mov_b32_e32 v97, v0
	v_mov_b32_e32 v98, v0
	v_mov_b32_e32 v99, v0
	v_mov_b32_e32 v104, v0
	v_mov_b32_e32 v105, v0
	v_mov_b32_e32 v106, v0
	v_mov_b32_e32 v107, v0
	v_mov_b32_e32 v108, v0
	v_mov_b32_e32 v109, v0
	v_mov_b32_e32 v110, v0
	v_mov_b32_e32 v111, v0
	v_mov_b32_e32 v120, v0
	v_mov_b32_e32 v121, v0
	v_mov_b32_e32 v122, v0
	v_mov_b32_e32 v123, v0
	v_mov_b32_e32 v124, v0
	v_mov_b32_e32 v125, v0
	v_mov_b32_e32 v126, v0
	v_mov_b32_e32 v127, v0
	v_add_u32_e32 v146, 0x10000, v206
	ds_read_b128 v[128:131], v146
	ds_read_b128 v[132:135], v146 offset:1024
	ds_read_b128 v[136:139], v146 offset:2048
	ds_read_b128 v[146:149], v146 offset:3072
.LBB0_31:
	s_add_u32 s46, s50, 0x100
	s_addc_u32 s47, s51, 0
	s_add_i32 s6, 0, 0x10000
	s_cmp_eq_u32 s12, 40
	s_cselect_b32 s53, s31, s47
	s_cselect_b32 s52, s30, s46
	s_cselect_b32 s49, s35, s11
	s_cselect_b32 s48, s34, s10
	v_lshl_add_u64 v[214:215], s[50:51], 0, v[158:159]
	s_add_i32 m0, s58, 0xc000
	ds_read_b128 v[162:165], v208
	ds_read_b128 v[166:169], v208 offset:1024
	ds_read_b128 v[170:173], v208 offset:2048
	ds_read_b128 v[174:177], v208 offset:3072
	ds_read_b128 v[178:181], v208 offset:4096
	ds_read_b128 v[182:185], v208 offset:5120
	ds_read_b128 v[194:197], v208 offset:6144
	ds_read_b128 v[210:213], v208 offset:7168
	global_load_lds_dwordx4 v[214:215], off
	v_lshl_add_u64 v[214:215], s[50:51], 0, v[160:161]
	s_add_i32 m0, s58, 0xe000
	s_nop 0
	global_load_lds_dwordx4 v[214:215], off
	s_waitcnt lgkmcnt(8)
	s_barrier
	s_setprio 1
	s_waitcnt lgkmcnt(7)
	v_mfma_f32_16x16x32_bf16 v[124:127], v[128:131], v[162:165], v[124:127]
	v_mfma_f32_16x16x32_bf16 v[120:123], v[136:139], v[162:165], v[120:123]
	s_waitcnt lgkmcnt(5)
	v_mfma_f32_16x16x32_bf16 v[108:111], v[128:131], v[170:173], v[108:111]
	v_mfma_f32_16x16x32_bf16 v[104:107], v[136:139], v[170:173], v[104:107]
	s_waitcnt lgkmcnt(3)
	v_mfma_f32_16x16x32_bf16 v[96:99], v[128:131], v[178:181], v[96:99]
	v_mfma_f32_16x16x32_bf16 v[88:91], v[136:139], v[178:181], v[88:91]
	s_waitcnt lgkmcnt(1)
	v_mfma_f32_16x16x32_bf16 v[84:87], v[128:131], v[194:197], v[84:87]
	v_mfma_f32_16x16x32_bf16 v[80:83], v[136:139], v[194:197], v[80:83]
	v_mfma_f32_16x16x32_bf16 v[124:127], v[132:135], v[166:169], v[124:127]
	v_mfma_f32_16x16x32_bf16 v[120:123], v[146:149], v[166:169], v[120:123]
	v_mfma_f32_16x16x32_bf16 v[108:111], v[132:135], v[174:177], v[108:111]
	v_mfma_f32_16x16x32_bf16 v[104:107], v[146:149], v[174:177], v[104:107]
	v_mfma_f32_16x16x32_bf16 v[96:99], v[132:135], v[182:185], v[96:99]
	v_mfma_f32_16x16x32_bf16 v[88:91], v[146:149], v[182:185], v[88:91]
	s_waitcnt lgkmcnt(0)
	v_mfma_f32_16x16x32_bf16 v[84:87], v[132:135], v[210:213], v[84:87]
	v_mfma_f32_16x16x32_bf16 v[80:83], v[146:149], v[210:213], v[80:83]
	s_setprio 0
	s_barrier
	s_add_i32 s19, 0, 0x14000
	s_add_i32 s6, s6, s57
	v_add_u32_e32 v192, s19, v206
	v_lshl_add_u64 v[230:231], s[48:49], 0, v[140:141]
	s_mov_b32 m0, s6
	ds_read_b128 v[214:217], v192
	ds_read_b128 v[218:221], v192 offset:1024
	ds_read_b128 v[222:225], v192 offset:2048
	ds_read_b128 v[226:229], v192 offset:3072
	global_load_lds_dwordx4 v[230:231], off
	v_lshl_add_u64 v[232:233], s[48:49], 0, v[150:151]
	s_add_i32 m0, s6, 0x2000
	s_nop 0
	global_load_lds_dwordx4 v[232:233], off
	s_barrier
	s_setprio 1
	s_waitcnt lgkmcnt(3)
	v_mfma_f32_16x16x32_bf16 v[116:119], v[214:217], v[162:165], v[116:119]
	s_waitcnt lgkmcnt(1)
	v_mfma_f32_16x16x32_bf16 v[112:115], v[222:225], v[162:165], v[112:115]
	v_mfma_f32_16x16x32_bf16 v[100:103], v[214:217], v[170:173], v[100:103]
	v_mfma_f32_16x16x32_bf16 v[92:95], v[222:225], v[170:173], v[92:95]
	v_mfma_f32_16x16x32_bf16 v[76:79], v[214:217], v[178:181], v[76:79]
	v_mfma_f32_16x16x32_bf16 v[72:75], v[222:225], v[178:181], v[72:75]
	v_mfma_f32_16x16x32_bf16 v[68:71], v[214:217], v[194:197], v[68:71]
	v_mfma_f32_16x16x32_bf16 v[64:67], v[222:225], v[194:197], v[64:67]
	v_mfma_f32_16x16x32_bf16 v[116:119], v[218:221], v[166:169], v[116:119]
	s_waitcnt lgkmcnt(0)
	v_mfma_f32_16x16x32_bf16 v[112:115], v[226:229], v[166:169], v[112:115]
	v_mfma_f32_16x16x32_bf16 v[100:103], v[218:221], v[174:177], v[100:103]
	v_mfma_f32_16x16x32_bf16 v[92:95], v[226:229], v[174:177], v[92:95]
	v_mfma_f32_16x16x32_bf16 v[76:79], v[218:221], v[182:185], v[76:79]
	v_mfma_f32_16x16x32_bf16 v[72:75], v[226:229], v[182:185], v[72:75]
	v_mfma_f32_16x16x32_bf16 v[68:71], v[218:221], v[210:213], v[68:71]
	v_mfma_f32_16x16x32_bf16 v[64:67], v[226:229], v[210:213], v[64:67]
	s_setprio 0
	s_mov_b32 m0, s58
	v_lshl_add_u64 v[234:235], s[52:53], 0, v[154:155]
	s_barrier
	ds_read_b128 v[162:165], v208 offset:16384
	ds_read_b128 v[166:169], v208 offset:17408
	ds_read_b128 v[170:173], v208 offset:18432
	ds_read_b128 v[174:177], v208 offset:19456
	ds_read_b128 v[178:181], v208 offset:20480
	ds_read_b128 v[182:185], v208 offset:21504
	ds_read_b128 v[194:197], v208 offset:22528
	ds_read_b128 v[210:213], v208 offset:23552
	global_load_lds_dwordx4 v[234:235], off
	v_lshl_add_u64 v[236:237], s[52:53], 0, v[152:153]
	s_mov_b32 m0, s59
	s_nop 0
	global_load_lds_dwordx4 v[236:237], off
	s_waitcnt vmcnt(10)
	s_barrier
	s_setprio 1
	s_waitcnt lgkmcnt(7)
	v_mfma_f32_16x16x32_bf16 v[60:63], v[128:131], v[162:165], v[60:63]
	v_mfma_f32_16x16x32_bf16 v[56:59], v[136:139], v[162:165], v[56:59]
	s_waitcnt lgkmcnt(5)
	v_mfma_f32_16x16x32_bf16 v[48:51], v[128:131], v[170:173], v[48:51]
	v_mfma_f32_16x16x32_bf16 v[40:43], v[136:139], v[170:173], v[40:43]
	s_waitcnt lgkmcnt(3)
	v_mfma_f32_16x16x32_bf16 v[32:35], v[128:131], v[178:181], v[32:35]
	v_mfma_f32_16x16x32_bf16 v[24:27], v[136:139], v[178:181], v[24:27]
	s_waitcnt lgkmcnt(1)
	v_mfma_f32_16x16x32_bf16 v[16:19], v[128:131], v[194:197], v[16:19]
	v_mfma_f32_16x16x32_bf16 v[8:11], v[136:139], v[194:197], v[8:11]
	v_mfma_f32_16x16x32_bf16 v[60:63], v[132:135], v[166:169], v[60:63]
	v_mfma_f32_16x16x32_bf16 v[56:59], v[146:149], v[166:169], v[56:59]
	v_mfma_f32_16x16x32_bf16 v[48:51], v[132:135], v[174:177], v[48:51]
	v_mfma_f32_16x16x32_bf16 v[40:43], v[146:149], v[174:177], v[40:43]
	v_mfma_f32_16x16x32_bf16 v[32:35], v[132:135], v[182:185], v[32:35]
	v_mfma_f32_16x16x32_bf16 v[24:27], v[146:149], v[182:185], v[24:27]
	s_waitcnt lgkmcnt(0)
	v_mfma_f32_16x16x32_bf16 v[16:19], v[132:135], v[210:213], v[16:19]
	v_mfma_f32_16x16x32_bf16 v[8:11], v[146:149], v[210:213], v[8:11]
	s_setprio 0
	s_barrier
	s_add_u32 s50, s48, 0xb0000
	s_addc_u32 s51, s49, 0
	s_add_i32 s6, s19, s57
	v_lshl_add_u64 v[128:129], s[50:51], 0, v[140:141]
	s_mov_b32 m0, s6
	s_nop 0
	global_load_lds_dwordx4 v[128:129], off
	v_lshl_add_u64 v[128:129], s[50:51], 0, v[150:151]
	s_add_i32 m0, s6, 0x2000
	s_nop 0
	global_load_lds_dwordx4 v[128:129], off
	v_add_u32_e32 v146, 0x18000, v206
	ds_read_b128 v[128:131], v146
	ds_read_b128 v[132:135], v146 offset:1024
	ds_read_b128 v[136:139], v146 offset:2048
	ds_read_b128 v[146:149], v146 offset:3072
	s_waitcnt vmcnt(6)
	s_barrier
	s_setprio 1
	v_mfma_f32_16x16x32_bf16 v[52:55], v[214:217], v[162:165], v[52:55]
	v_mfma_f32_16x16x32_bf16 v[44:47], v[222:225], v[162:165], v[44:47]
	v_mfma_f32_16x16x32_bf16 v[36:39], v[214:217], v[170:173], v[36:39]
	v_mfma_f32_16x16x32_bf16 v[28:31], v[222:225], v[170:173], v[28:31]
	v_mfma_f32_16x16x32_bf16 v[20:23], v[214:217], v[178:181], v[20:23]
	v_mfma_f32_16x16x32_bf16 v[12:15], v[222:225], v[178:181], v[12:15]
	v_mfma_f32_16x16x32_bf16 v[4:7], v[214:217], v[194:197], v[4:7]
	v_mfma_f32_16x16x32_bf16 v[0:3], v[222:225], v[194:197], v[0:3]
	v_mfma_f32_16x16x32_bf16 v[52:55], v[218:221], v[166:169], v[52:55]
	v_mfma_f32_16x16x32_bf16 v[44:47], v[226:229], v[166:169], v[44:47]
	v_mfma_f32_16x16x32_bf16 v[36:39], v[218:221], v[174:177], v[36:39]
	v_mfma_f32_16x16x32_bf16 v[28:31], v[226:229], v[174:177], v[28:31]
	v_mfma_f32_16x16x32_bf16 v[20:23], v[218:221], v[182:185], v[20:23]
	v_mfma_f32_16x16x32_bf16 v[12:15], v[226:229], v[182:185], v[12:15]
	v_mfma_f32_16x16x32_bf16 v[4:7], v[218:221], v[210:213], v[4:7]
	v_mfma_f32_16x16x32_bf16 v[0:3], v[226:229], v[210:213], v[0:3]
	s_setprio 0
	s_add_i32 s6, 0, 0x18000
	s_barrier
	s_add_u32 s50, s52, 0xb0000
	s_addc_u32 s51, s53, 0
	s_mov_b32 m0, s68
	v_lshl_add_u64 v[214:215], s[50:51], 0, v[154:155]
	ds_read_b128 v[162:165], v208 offset:32768
	ds_read_b128 v[166:169], v208 offset:33792
	ds_read_b128 v[170:173], v208 offset:34816
	ds_read_b128 v[174:177], v208 offset:35840
	ds_read_b128 v[178:181], v208 offset:36864
	ds_read_b128 v[182:185], v208 offset:37888
	ds_read_b128 v[194:197], v208 offset:38912
	ds_read_b128 v[210:213], v208 offset:39936
	global_load_lds_dwordx4 v[214:215], off
	v_lshl_add_u64 v[214:215], s[50:51], 0, v[152:153]
	s_mov_b32 m0, s69
	s_nop 0
	global_load_lds_dwordx4 v[214:215], off
	s_waitcnt lgkmcnt(8)
	s_barrier
	s_setprio 1
	s_waitcnt lgkmcnt(7)
	v_mfma_f32_16x16x32_bf16 v[124:127], v[128:131], v[162:165], v[124:127]
	v_mfma_f32_16x16x32_bf16 v[120:123], v[136:139], v[162:165], v[120:123]
	s_waitcnt lgkmcnt(5)
	v_mfma_f32_16x16x32_bf16 v[108:111], v[128:131], v[170:173], v[108:111]
	v_mfma_f32_16x16x32_bf16 v[104:107], v[136:139], v[170:173], v[104:107]
	s_waitcnt lgkmcnt(3)
	v_mfma_f32_16x16x32_bf16 v[96:99], v[128:131], v[178:181], v[96:99]
	v_mfma_f32_16x16x32_bf16 v[88:91], v[136:139], v[178:181], v[88:91]
	s_waitcnt lgkmcnt(1)
	v_mfma_f32_16x16x32_bf16 v[84:87], v[128:131], v[194:197], v[84:87]
	v_mfma_f32_16x16x32_bf16 v[80:83], v[136:139], v[194:197], v[80:83]
	v_mfma_f32_16x16x32_bf16 v[124:127], v[132:135], v[166:169], v[124:127]
	v_mfma_f32_16x16x32_bf16 v[120:123], v[146:149], v[166:169], v[120:123]
	v_mfma_f32_16x16x32_bf16 v[108:111], v[132:135], v[174:177], v[108:111]
	v_mfma_f32_16x16x32_bf16 v[104:107], v[146:149], v[174:177], v[104:107]
	v_mfma_f32_16x16x32_bf16 v[96:99], v[132:135], v[182:185], v[96:99]
	v_mfma_f32_16x16x32_bf16 v[88:91], v[146:149], v[182:185], v[88:91]
	s_waitcnt lgkmcnt(0)
	v_mfma_f32_16x16x32_bf16 v[84:87], v[132:135], v[210:213], v[84:87]
	v_mfma_f32_16x16x32_bf16 v[80:83], v[146:149], v[210:213], v[80:83]
	s_setprio 0
	s_barrier
	s_add_i32 s19, 0, 0x1c000
	s_add_i32 s6, s6, s57
	v_add_u32_e32 v192, s19, v206
	v_lshl_add_u64 v[230:231], v[230:231], 0, s[36:37]
	s_mov_b32 m0, s6
	ds_read_b128 v[214:217], v192
	ds_read_b128 v[218:221], v192 offset:1024
	ds_read_b128 v[222:225], v192 offset:2048
	ds_read_b128 v[226:229], v192 offset:3072
	global_load_lds_dwordx4 v[230:231], off
	v_lshl_add_u64 v[230:231], v[232:233], 0, s[36:37]
	s_add_i32 m0, s6, 0x2000
	s_nop 0
	global_load_lds_dwordx4 v[230:231], off
	s_barrier
	s_setprio 1
	s_waitcnt lgkmcnt(3)
	v_mfma_f32_16x16x32_bf16 v[116:119], v[214:217], v[162:165], v[116:119]
	s_waitcnt lgkmcnt(1)
	v_mfma_f32_16x16x32_bf16 v[112:115], v[222:225], v[162:165], v[112:115]
	v_mfma_f32_16x16x32_bf16 v[100:103], v[214:217], v[170:173], v[100:103]
	v_mfma_f32_16x16x32_bf16 v[92:95], v[222:225], v[170:173], v[92:95]
	v_mfma_f32_16x16x32_bf16 v[76:79], v[214:217], v[178:181], v[76:79]
	v_mfma_f32_16x16x32_bf16 v[72:75], v[222:225], v[178:181], v[72:75]
	v_mfma_f32_16x16x32_bf16 v[68:71], v[214:217], v[194:197], v[68:71]
	v_mfma_f32_16x16x32_bf16 v[64:67], v[222:225], v[194:197], v[64:67]
	v_mfma_f32_16x16x32_bf16 v[116:119], v[218:221], v[166:169], v[116:119]
	s_waitcnt lgkmcnt(0)
	v_mfma_f32_16x16x32_bf16 v[112:115], v[226:229], v[166:169], v[112:115]
	v_mfma_f32_16x16x32_bf16 v[100:103], v[218:221], v[174:177], v[100:103]
	v_mfma_f32_16x16x32_bf16 v[92:95], v[226:229], v[174:177], v[92:95]
	v_mfma_f32_16x16x32_bf16 v[76:79], v[218:221], v[182:185], v[76:79]
	v_mfma_f32_16x16x32_bf16 v[72:75], v[226:229], v[182:185], v[72:75]
	v_mfma_f32_16x16x32_bf16 v[68:71], v[218:221], v[210:213], v[68:71]
	v_mfma_f32_16x16x32_bf16 v[64:67], v[226:229], v[210:213], v[64:67]
	s_setprio 0
	s_mov_b32 m0, s70
	v_lshl_add_u64 v[230:231], v[234:235], 0, s[36:37]
	s_barrier
	ds_read_b128 v[162:165], v208 offset:49152
	ds_read_b128 v[166:169], v208 offset:50176
	ds_read_b128 v[170:173], v208 offset:51200
	ds_read_b128 v[174:177], v208 offset:52224
	ds_read_b128 v[178:181], v208 offset:53248
	ds_read_b128 v[182:185], v208 offset:54272
	ds_read_b128 v[194:197], v208 offset:55296
	ds_read_b128 v[210:213], v208 offset:56320
	global_load_lds_dwordx4 v[230:231], off
	v_lshl_add_u64 v[230:231], v[236:237], 0, s[36:37]
	s_mov_b32 m0, s71
	s_nop 0
	global_load_lds_dwordx4 v[230:231], off
	s_waitcnt vmcnt(10)
	s_barrier
	s_setprio 1
	s_waitcnt lgkmcnt(7)
	v_mfma_f32_16x16x32_bf16 v[60:63], v[128:131], v[162:165], v[60:63]
	v_mfma_f32_16x16x32_bf16 v[56:59], v[136:139], v[162:165], v[56:59]
	s_waitcnt lgkmcnt(5)
	v_mfma_f32_16x16x32_bf16 v[48:51], v[128:131], v[170:173], v[48:51]
	v_mfma_f32_16x16x32_bf16 v[40:43], v[136:139], v[170:173], v[40:43]
	s_waitcnt lgkmcnt(3)
	v_mfma_f32_16x16x32_bf16 v[32:35], v[128:131], v[178:181], v[32:35]
	v_mfma_f32_16x16x32_bf16 v[24:27], v[136:139], v[178:181], v[24:27]
	s_waitcnt lgkmcnt(1)
	v_mfma_f32_16x16x32_bf16 v[16:19], v[128:131], v[194:197], v[16:19]
	v_mfma_f32_16x16x32_bf16 v[8:11], v[136:139], v[194:197], v[8:11]
	v_mfma_f32_16x16x32_bf16 v[60:63], v[132:135], v[166:169], v[60:63]
	v_mfma_f32_16x16x32_bf16 v[56:59], v[146:149], v[166:169], v[56:59]
	v_mfma_f32_16x16x32_bf16 v[48:51], v[132:135], v[174:177], v[48:51]
	v_mfma_f32_16x16x32_bf16 v[40:43], v[146:149], v[174:177], v[40:43]
	v_mfma_f32_16x16x32_bf16 v[32:35], v[132:135], v[182:185], v[32:35]
	v_mfma_f32_16x16x32_bf16 v[24:27], v[146:149], v[182:185], v[24:27]
	s_waitcnt lgkmcnt(0)
	v_mfma_f32_16x16x32_bf16 v[16:19], v[132:135], v[210:213], v[16:19]
	v_mfma_f32_16x16x32_bf16 v[8:11], v[146:149], v[210:213], v[8:11]
	s_setprio 0
	s_barrier
	s_add_u32 s48, s48, 0xb0080
	s_addc_u32 s49, s49, 0
	s_add_i32 s6, s19, s57
	v_lshl_add_u64 v[128:129], s[48:49], 0, v[140:141]
	s_mov_b32 m0, s6
	s_nop 0
	global_load_lds_dwordx4 v[128:129], off
	v_lshl_add_u64 v[128:129], s[48:49], 0, v[150:151]
	s_add_i32 m0, s6, 0x2000
	s_nop 0
	global_load_lds_dwordx4 v[128:129], off
	v_add_u32_e32 v146, 0x10000, v206
	ds_read_b128 v[128:131], v146
	ds_read_b128 v[132:135], v146 offset:1024
	ds_read_b128 v[136:139], v146 offset:2048
	ds_read_b128 v[146:149], v146 offset:3072
	s_waitcnt vmcnt(6)
	s_barrier
	s_setprio 1
	v_mfma_f32_16x16x32_bf16 v[52:55], v[214:217], v[162:165], v[52:55]
	v_mfma_f32_16x16x32_bf16 v[44:47], v[222:225], v[162:165], v[44:47]
	v_mfma_f32_16x16x32_bf16 v[36:39], v[214:217], v[170:173], v[36:39]
	v_mfma_f32_16x16x32_bf16 v[28:31], v[222:225], v[170:173], v[28:31]
	v_mfma_f32_16x16x32_bf16 v[20:23], v[214:217], v[178:181], v[20:23]
	v_mfma_f32_16x16x32_bf16 v[12:15], v[222:225], v[178:181], v[12:15]
	v_mfma_f32_16x16x32_bf16 v[4:7], v[214:217], v[194:197], v[4:7]
	v_mfma_f32_16x16x32_bf16 v[0:3], v[222:225], v[194:197], v[0:3]
	v_mfma_f32_16x16x32_bf16 v[52:55], v[218:221], v[166:169], v[52:55]
	v_mfma_f32_16x16x32_bf16 v[44:47], v[226:229], v[166:169], v[44:47]
	v_mfma_f32_16x16x32_bf16 v[36:39], v[218:221], v[174:177], v[36:39]
	v_mfma_f32_16x16x32_bf16 v[28:31], v[226:229], v[174:177], v[28:31]
	v_mfma_f32_16x16x32_bf16 v[20:23], v[218:221], v[182:185], v[20:23]
	v_mfma_f32_16x16x32_bf16 v[12:15], v[226:229], v[182:185], v[12:15]
	v_mfma_f32_16x16x32_bf16 v[4:7], v[218:221], v[210:213], v[4:7]
	v_mfma_f32_16x16x32_bf16 v[0:3], v[226:229], v[210:213], v[0:3]
	s_setprio 0
	s_add_i32 s12, s12, 2
	s_add_u32 s10, s10, 0x100
	s_addc_u32 s11, s11, 0
	s_cmp_gt_u32 s12, 41
	s_mov_b64 s[50:51], s[46:47]
	s_barrier
	s_cbranch_scc0 .LBB0_31
	s_waitcnt lgkmcnt(0)
	s_ashr_i32 s39, s38, 31
	v_lshl_or_b32 v128, s81, 8, v207
	s_lshl_b64 s[10:11], s[38:39], 8
	v_ashrrev_i32_e32 v129, 31, v128
	v_lshl_add_u64 v[168:169], s[10:11], 0, v[156:157]
	v_lshlrev_b64 v[170:171], 1, v[128:129]
	v_lshl_add_u64 v[174:175], s[4:5], 0, v[170:171]
	v_lshlrev_b64 v[172:173], 11, v[168:169]
	v_lshl_add_u64 v[128:129], v[174:175], 0, v[172:173]
	global_load_dwordx4 v[146:149], v[128:129], off
	global_load_dwordx4 v[182:185], v[128:129], off offset:256
	v_or_b32_e32 v166, 16, v168
	v_mov_b32_e32 v167, v169
	v_lshlrev_b64 v[176:177], 11, v[166:167]
	v_lshl_add_u64 v[128:129], v[174:175], 0, v[176:177]
	global_load_dwordx4 v[194:197], v[128:129], off
	global_load_dwordx4 v[210:213], v[128:129], off offset:256
	v_or_b32_e32 v164, 32, v168
	v_mov_b32_e32 v165, v169
	v_or_b32_e32 v162, 48, v168
	v_mov_b32_e32 v163, v169
	v_lshlrev_b64 v[180:181], 11, v[164:165]
	v_lshlrev_b64 v[178:179], 11, v[162:163]
	v_lshl_add_u64 v[128:129], v[174:175], 0, v[180:181]
	v_lshl_add_u64 v[130:131], v[174:175], 0, v[178:179]
	global_load_dwordx4 v[214:217], v[128:129], off
	global_load_dwordx4 v[136:139], v[128:129], off offset:256
	global_load_dwordx4 v[132:135], v[130:131], off
	s_nop 0
	global_load_dwordx4 v[128:131], v[130:131], off offset:256
	s_mov_b64 s[10:11], 0x90
	v_lshl_add_u64 v[172:173], s[28:29], 0, v[172:173]
	v_lshl_add_u64 v[172:173], v[172:173], 0, v[170:171]
	s_waitcnt vmcnt(0)
	v_lshlrev_b32_e32 v218, 16, v146
	v_and_b32_e32 v219, 0xffff0000, v146
	v_lshlrev_b32_e32 v220, 16, v148
	v_and_b32_e32 v221, 0xffff0000, v148
	v_lshlrev_b32_e32 v146, 16, v147
	v_and_b32_e32 v147, 0xffff0000, v147
	v_lshlrev_b32_e32 v222, 16, v182
	v_and_b32_e32 v223, 0xffff0000, v182
	v_lshlrev_b32_e32 v224, 16, v184
	v_and_b32_e32 v225, 0xffff0000, v184
	v_lshlrev_b32_e32 v182, 16, v183
	v_and_b32_e32 v183, 0xffff0000, v183
	v_pk_fma_f32 v[124:125], v[124:125], 0.5, v[218:219] op_sel_hi:[1,0,1]
	v_pk_fma_f32 v[120:121], v[120:121], 0.5, v[220:221] op_sel_hi:[1,0,1]
	v_pk_fma_f32 v[126:127], v[126:127], 0.5, v[146:147] op_sel_hi:[1,0,1]
	v_pk_fma_f32 v[116:117], v[116:117], 0.5, v[222:223] op_sel_hi:[1,0,1]
	v_pk_fma_f32 v[146:147], v[112:113], 0.5, v[224:225] op_sel_hi:[1,0,1]
	v_pk_fma_f32 v[118:119], v[118:119], 0.5, v[182:183] op_sel_hi:[1,0,1]
	v_pk_mul_f32 v[220:221], v[124:125], v[124:125]
	v_pk_mul_f32 v[222:223], v[126:127], v[126:127]
	v_cvt_pk_bf16_f32 v112, v124, v125
	v_cvt_pk_bf16_f32 v113, v126, v127
	v_pk_mul_f32 v[124:125], v[116:117], v[116:117]
	v_pk_mul_f32 v[126:127], v[118:119], v[118:119]
	v_pk_mul_f32 v[228:229], v[146:147], v[146:147]
	v_cvt_pk_bf16_f32 v116, v116, v117
	v_cvt_pk_bf16_f32 v117, v118, v119
	v_cvt_pk_bf16_f32 v118, v146, v147
	v_add_f32_e32 v146, v220, v221
	v_add_f32_e32 v146, v222, v146
	v_lshlrev_b32_e32 v148, 16, v149
	v_and_b32_e32 v149, 0xffff0000, v149
	v_pk_mul_f32 v[224:225], v[120:121], v[120:121]
	v_add_f32_e32 v146, v223, v146
	v_pk_fma_f32 v[122:123], v[122:123], 0.5, v[148:149] op_sel_hi:[1,0,1]
	v_add_f32_e32 v146, v224, v146
	v_pk_mul_f32 v[226:227], v[122:123], v[122:123]
	v_add_f32_e32 v146, v225, v146
	v_add_f32_e32 v146, v226, v146
	v_add_f32_e32 v146, v227, v146
	v_add_f32_e32 v124, v124, v146
	v_add_f32_e32 v124, v125, v124
	v_add_f32_e32 v124, v126, v124
	v_lshlrev_b32_e32 v184, 16, v185
	v_and_b32_e32 v185, 0xffff0000, v185
	v_add_f32_e32 v124, v127, v124
	v_pk_fma_f32 v[148:149], v[114:115], 0.5, v[184:185] op_sel_hi:[1,0,1]
	v_add_f32_e32 v124, v228, v124
	v_pk_mul_f32 v[230:231], v[148:149], v[148:149]
	v_add_f32_e32 v124, v229, v124
	v_add_f32_e32 v124, v230, v124
	v_add_f32_e32 v209, v231, v124
	v_lshlrev_b32_e32 v124, 16, v212
	v_and_b32_e32 v125, 0xffff0000, v212
	v_pk_fma_f32 v[124:125], v[92:93], 0.5, v[124:125] op_sel_hi:[1,0,1]
	v_lshlrev_b32_e32 v92, 16, v211
	v_and_b32_e32 v93, 0xffff0000, v211
	v_pk_fma_f32 v[102:103], v[102:103], 0.5, v[92:93] op_sel_hi:[1,0,1]
	v_lshlrev_b32_e32 v92, 16, v213
	v_and_b32_e32 v93, 0xffff0000, v213
	v_pk_fma_f32 v[126:127], v[94:95], 0.5, v[92:93] op_sel_hi:[1,0,1]
	v_lshlrev_b32_e32 v92, 16, v214
	v_and_b32_e32 v93, 0xffff0000, v214
	v_pk_fma_f32 v[92:93], v[96:97], 0.5, v[92:93] op_sel_hi:[1,0,1]
	v_lshlrev_b32_e32 v96, 16, v217
	v_and_b32_e32 v97, 0xffff0000, v217
	v_lshlrev_b32_e32 v94, 16, v216
	v_and_b32_e32 v95, 0xffff0000, v216
	v_pk_fma_f32 v[90:91], v[90:91], 0.5, v[96:97] op_sel_hi:[1,0,1]
	v_lshlrev_b32_e32 v96, 16, v136
	v_and_b32_e32 v97, 0xffff0000, v136
	v_lshlrev_b32_e32 v182, 16, v194
	v_and_b32_e32 v183, 0xffff0000, v194
	v_pk_fma_f32 v[88:89], v[88:89], 0.5, v[94:95] op_sel_hi:[1,0,1]
	v_lshlrev_b32_e32 v94, 16, v215
	v_and_b32_e32 v95, 0xffff0000, v215
	v_pk_fma_f32 v[96:97], v[76:77], 0.5, v[96:97] op_sel_hi:[1,0,1]
	v_lshl_add_u64 v[76:77], v[168:169], 0, s[36:37]
	v_lshlrev_b32_e32 v184, 16, v196
	v_and_b32_e32 v185, 0xffff0000, v196
	v_cvt_pk_bf16_f32 v114, v120, v121
	v_pk_fma_f32 v[120:121], v[108:109], 0.5, v[182:183] op_sel_hi:[1,0,1]
	v_pk_fma_f32 v[94:95], v[98:99], 0.5, v[94:95] op_sel_hi:[1,0,1]
	v_lshlrev_b64 v[182:183], 11, v[76:77]
	v_lshlrev_b32_e32 v98, 16, v138
	v_and_b32_e32 v99, 0xffff0000, v138
	v_pk_fma_f32 v[108:109], v[104:105], 0.5, v[184:185] op_sel_hi:[1,0,1]
	v_lshl_add_u64 v[184:185], v[174:175], 0, v[182:183]
	v_pk_fma_f32 v[98:99], v[72:73], 0.5, v[98:99] op_sel_hi:[1,0,1]
	v_lshlrev_b32_e32 v72, 16, v137
	v_and_b32_e32 v73, 0xffff0000, v137
	v_lshlrev_b32_e32 v218, 16, v210
	v_and_b32_e32 v219, 0xffff0000, v210
	global_load_dwordx4 v[210:213], v[184:185], off
	v_pk_fma_f32 v[136:137], v[78:79], 0.5, v[72:73] op_sel_hi:[1,0,1]
	v_lshlrev_b32_e32 v72, 16, v139
	v_and_b32_e32 v73, 0xffff0000, v139
	v_pk_fma_f32 v[138:139], v[74:75], 0.5, v[72:73] op_sel_hi:[1,0,1]
	v_lshlrev_b32_e32 v72, 16, v132
	v_and_b32_e32 v73, 0xffff0000, v132
	v_pk_fma_f32 v[74:75], v[84:85], 0.5, v[72:73] op_sel_hi:[1,0,1]
	v_lshlrev_b32_e32 v72, 16, v134
	v_and_b32_e32 v73, 0xffff0000, v134
	v_pk_fma_f32 v[78:79], v[80:81], 0.5, v[72:73] op_sel_hi:[1,0,1]
	v_lshlrev_b32_e32 v72, 16, v133
	v_and_b32_e32 v73, 0xffff0000, v133
	v_pk_fma_f32 v[100:101], v[100:101], 0.5, v[218:219] op_sel_hi:[1,0,1]
	global_load_dwordx4 v[218:221], v[184:185], off offset:256
	v_pk_fma_f32 v[80:81], v[86:87], 0.5, v[72:73] op_sel_hi:[1,0,1]
	v_lshlrev_b32_e32 v72, 16, v135
	v_and_b32_e32 v73, 0xffff0000, v135
	v_pk_fma_f32 v[82:83], v[82:83], 0.5, v[72:73] op_sel_hi:[1,0,1]
	v_lshl_add_u64 v[72:73], v[168:169], 0, s[10:11]
	v_lshlrev_b64 v[132:133], 11, v[72:73]
	v_lshl_add_u64 v[134:135], v[174:175], 0, v[132:133]
	v_lshlrev_b32_e32 v84, 16, v128
	v_and_b32_e32 v85, 0xffff0000, v128
	global_load_dwordx4 v[226:229], v[134:135], off
	global_load_dwordx4 v[234:237], v[134:135], off offset:256
	v_pk_fma_f32 v[84:85], v[68:69], 0.5, v[84:85] op_sel_hi:[1,0,1]
	v_lshlrev_b32_e32 v68, 16, v130
	v_and_b32_e32 v69, 0xffff0000, v130
	v_pk_fma_f32 v[86:87], v[64:65], 0.5, v[68:69] op_sel_hi:[1,0,1]
	v_lshlrev_b32_e32 v64, 16, v129
	v_and_b32_e32 v65, 0xffff0000, v129
	s_mov_b64 s[10:11], 0xa0
	v_pk_fma_f32 v[128:129], v[70:71], 0.5, v[64:65] op_sel_hi:[1,0,1]
	v_lshl_add_u64 v[70:71], v[168:169], 0, s[10:11]
	s_mov_b64 s[10:11], 0xb0
	v_lshlrev_b32_e32 v64, 16, v131
	v_and_b32_e32 v65, 0xffff0000, v131
	v_lshlrev_b64 v[134:135], 11, v[70:71]
	v_lshl_add_u64 v[68:69], v[168:169], 0, s[10:11]
	v_pk_fma_f32 v[130:131], v[66:67], 0.5, v[64:65] op_sel_hi:[1,0,1]
	v_lshl_add_u64 v[64:65], v[174:175], 0, v[134:135]
	v_lshlrev_b64 v[184:185], 11, v[68:69]
	global_load_dwordx4 v[238:241], v[64:65], off
	global_load_dwordx4 v[242:245], v[64:65], off offset:256
	v_lshl_add_u64 v[64:65], v[174:175], 0, v[184:185]
	global_load_dwordx4 v[246:249], v[64:65], off
	s_nop 0
	global_load_dwordx4 v[64:67], v[64:65], off offset:256
	v_lshlrev_b32_e32 v194, 16, v195
	v_and_b32_e32 v195, 0xffff0000, v195
	v_lshlrev_b32_e32 v196, 16, v197
	v_and_b32_e32 v197, 0xffff0000, v197
	v_cvt_pk_bf16_f32 v115, v122, v123
	v_cvt_pk_bf16_f32 v119, v148, v149
	v_pk_fma_f32 v[122:123], v[110:111], 0.5, v[194:195] op_sel_hi:[1,0,1]
	v_pk_fma_f32 v[110:111], v[106:107], 0.5, v[196:197] op_sel_hi:[1,0,1]
	global_store_dwordx4 v[172:173], v[112:115], off
	global_store_dwordx4 v[172:173], v[116:119], off offset:256
	v_cvt_pk_bf16_f32 v104, v120, v121
	v_lshl_add_u64 v[112:113], s[28:29], 0, v[176:177]
	v_cvt_pk_bf16_f32 v105, v122, v123
	v_cvt_pk_bf16_f32 v106, v108, v109
	v_cvt_pk_bf16_f32 v107, v110, v111
	v_lshl_add_u64 v[112:113], v[112:113], 0, v[170:171]
	v_cvt_pk_bf16_f32 v146, v100, v101
	v_cvt_pk_bf16_f32 v147, v102, v103
	v_cvt_pk_bf16_f32 v148, v124, v125
	v_cvt_pk_bf16_f32 v149, v126, v127
	global_store_dwordx4 v[112:113], v[104:107], off
	global_store_dwordx4 v[112:113], v[146:149], off offset:256
	v_cvt_pk_bf16_f32 v194, v92, v93
	v_lshl_add_u64 v[104:105], s[28:29], 0, v[180:181]
	v_cvt_pk_bf16_f32 v195, v94, v95
	v_cvt_pk_bf16_f32 v196, v88, v89
	v_cvt_pk_bf16_f32 v197, v90, v91
	v_lshl_add_u64 v[104:105], v[104:105], 0, v[170:171]
	v_cvt_pk_bf16_f32 v214, v96, v97
	v_cvt_pk_bf16_f32 v215, v136, v137
	v_cvt_pk_bf16_f32 v216, v98, v99
	v_cvt_pk_bf16_f32 v217, v138, v139
	global_store_dwordx4 v[104:105], v[194:197], off
	global_store_dwordx4 v[104:105], v[214:217], off offset:256
	v_lshl_add_u64 v[104:105], s[28:29], 0, v[178:179]
	v_cvt_pk_bf16_f32 v222, v74, v75
	v_cvt_pk_bf16_f32 v223, v80, v81
	v_cvt_pk_bf16_f32 v224, v78, v79
	v_cvt_pk_bf16_f32 v225, v82, v83
	v_lshl_add_u64 v[104:105], v[104:105], 0, v[170:171]
	v_cvt_pk_bf16_f32 v230, v84, v85
	v_cvt_pk_bf16_f32 v231, v128, v129
	v_cvt_pk_bf16_f32 v232, v86, v87
	v_cvt_pk_bf16_f32 v233, v130, v131
	global_store_dwordx4 v[104:105], v[222:225], off
	global_store_dwordx4 v[104:105], v[230:233], off offset:256
	s_waitcnt vmcnt(0)
	v_lshlrev_b32_e32 v104, 16, v210
	v_and_b32_e32 v105, 0xffff0000, v210
	v_pk_fma_f32 v[60:61], v[60:61], 0.5, v[104:105] op_sel_hi:[1,0,1]
	v_lshlrev_b32_e32 v104, 16, v212
	v_and_b32_e32 v105, 0xffff0000, v212
	v_pk_fma_f32 v[56:57], v[56:57], 0.5, v[104:105] op_sel_hi:[1,0,1]
	v_lshlrev_b32_e32 v104, 16, v211
	v_and_b32_e32 v105, 0xffff0000, v211
	v_pk_fma_f32 v[62:63], v[62:63], 0.5, v[104:105] op_sel_hi:[1,0,1]
	v_lshlrev_b32_e32 v104, 16, v213
	v_and_b32_e32 v105, 0xffff0000, v213
	v_pk_fma_f32 v[58:59], v[58:59], 0.5, v[104:105] op_sel_hi:[1,0,1]
	v_lshlrev_b32_e32 v104, 16, v218
	v_and_b32_e32 v105, 0xffff0000, v218
	v_pk_fma_f32 v[52:53], v[52:53], 0.5, v[104:105] op_sel_hi:[1,0,1]
	v_lshlrev_b32_e32 v104, 16, v220
	v_and_b32_e32 v105, 0xffff0000, v220
	v_pk_fma_f32 v[104:105], v[44:45], 0.5, v[104:105] op_sel_hi:[1,0,1]
	v_lshlrev_b32_e32 v44, 16, v219
	v_and_b32_e32 v45, 0xffff0000, v219
	v_pk_fma_f32 v[54:55], v[54:55], 0.5, v[44:45] op_sel_hi:[1,0,1]
	v_lshlrev_b32_e32 v44, 16, v221
	v_and_b32_e32 v45, 0xffff0000, v221
	v_pk_fma_f32 v[106:107], v[46:47], 0.5, v[44:45] op_sel_hi:[1,0,1]
	v_lshlrev_b32_e32 v44, 16, v226
	v_and_b32_e32 v45, 0xffff0000, v226
	v_pk_fma_f32 v[44:45], v[48:49], 0.5, v[44:45] op_sel_hi:[1,0,1]
	v_lshlrev_b32_e32 v48, 16, v229
	v_and_b32_e32 v49, 0xffff0000, v229
	v_pk_fma_f32 v[42:43], v[42:43], 0.5, v[48:49] op_sel_hi:[1,0,1]
	v_lshlrev_b32_e32 v48, 16, v234
	v_and_b32_e32 v49, 0xffff0000, v234
	v_pk_fma_f32 v[36:37], v[36:37], 0.5, v[48:49] op_sel_hi:[1,0,1]
	v_lshlrev_b32_e32 v48, 16, v236
	v_and_b32_e32 v49, 0xffff0000, v236
	v_lshlrev_b32_e32 v46, 16, v228
	v_and_b32_e32 v47, 0xffff0000, v228
	v_pk_fma_f32 v[48:49], v[28:29], 0.5, v[48:49] op_sel_hi:[1,0,1]
	v_lshlrev_b32_e32 v28, 16, v235
	v_and_b32_e32 v29, 0xffff0000, v235
	v_pk_fma_f32 v[40:41], v[40:41], 0.5, v[46:47] op_sel_hi:[1,0,1]
	v_lshlrev_b32_e32 v46, 16, v227
	v_and_b32_e32 v47, 0xffff0000, v227
	v_pk_fma_f32 v[38:39], v[38:39], 0.5, v[28:29] op_sel_hi:[1,0,1]
	v_lshlrev_b32_e32 v28, 16, v237
	v_and_b32_e32 v29, 0xffff0000, v237
	v_pk_fma_f32 v[46:47], v[50:51], 0.5, v[46:47] op_sel_hi:[1,0,1]
	v_pk_fma_f32 v[50:51], v[30:31], 0.5, v[28:29] op_sel_hi:[1,0,1]
	v_lshlrev_b32_e32 v28, 16, v238
	v_and_b32_e32 v29, 0xffff0000, v238
	v_lshlrev_b32_e32 v180, 16, v64
	v_and_b32_e32 v181, 0xffff0000, v64
	v_pk_fma_f32 v[28:29], v[32:33], 0.5, v[28:29] op_sel_hi:[1,0,1]
	v_lshlrev_b32_e32 v32, 16, v241
	v_and_b32_e32 v33, 0xffff0000, v241
	v_pk_fma_f32 v[4:5], v[4:5], 0.5, v[180:181] op_sel_hi:[1,0,1]
	v_lshlrev_b32_e32 v180, 16, v66
	v_and_b32_e32 v181, 0xffff0000, v66
	v_pk_fma_f32 v[26:27], v[26:27], 0.5, v[32:33] op_sel_hi:[1,0,1]
	v_lshlrev_b32_e32 v32, 16, v242
	v_and_b32_e32 v33, 0xffff0000, v242
	v_pk_fma_f32 v[0:1], v[0:1], 0.5, v[180:181] op_sel_hi:[1,0,1]
	v_lshl_add_u64 v[180:181], s[28:29], 0, v[182:183]
	v_cvt_pk_bf16_f32 v112, v60, v61
	v_cvt_pk_bf16_f32 v113, v62, v63
	v_cvt_pk_bf16_f32 v114, v56, v57
	v_cvt_pk_bf16_f32 v115, v58, v59
	v_pk_fma_f32 v[20:21], v[20:21], 0.5, v[32:33] op_sel_hi:[1,0,1]
	v_lshlrev_b32_e32 v32, 16, v244
	v_and_b32_e32 v33, 0xffff0000, v244
	v_lshl_add_u64 v[180:181], v[180:181], 0, v[170:171]
	v_cvt_pk_bf16_f32 v116, v52, v53
	v_cvt_pk_bf16_f32 v117, v54, v55
	v_cvt_pk_bf16_f32 v118, v104, v105
	v_cvt_pk_bf16_f32 v119, v106, v107
	v_lshlrev_b32_e32 v30, 16, v240
	v_and_b32_e32 v31, 0xffff0000, v240
	v_pk_fma_f32 v[32:33], v[12:13], 0.5, v[32:33] op_sel_hi:[1,0,1]
	v_lshlrev_b32_e32 v12, 16, v243
	v_and_b32_e32 v13, 0xffff0000, v243
	global_store_dwordx4 v[180:181], v[112:115], off
	global_store_dwordx4 v[180:181], v[116:119], off offset:256
	v_cvt_pk_bf16_f32 v146, v44, v45
	v_lshl_add_u64 v[112:113], s[28:29], 0, v[132:133]
	v_cvt_pk_bf16_f32 v147, v46, v47
	v_cvt_pk_bf16_f32 v148, v40, v41
	v_cvt_pk_bf16_f32 v149, v42, v43
	v_pk_fma_f32 v[24:25], v[24:25], 0.5, v[30:31] op_sel_hi:[1,0,1]
	v_lshlrev_b32_e32 v30, 16, v239
	v_and_b32_e32 v31, 0xffff0000, v239
	v_pk_fma_f32 v[22:23], v[22:23], 0.5, v[12:13] op_sel_hi:[1,0,1]
	v_lshlrev_b32_e32 v12, 16, v245
	v_and_b32_e32 v13, 0xffff0000, v245
	v_lshl_add_u64 v[112:113], v[112:113], 0, v[170:171]
	v_cvt_pk_bf16_f32 v172, v36, v37
	v_cvt_pk_bf16_f32 v173, v38, v39
	v_cvt_pk_bf16_f32 v174, v48, v49
	v_cvt_pk_bf16_f32 v175, v50, v51
	v_pk_fma_f32 v[30:31], v[34:35], 0.5, v[30:31] op_sel_hi:[1,0,1]
	v_pk_fma_f32 v[34:35], v[14:15], 0.5, v[12:13] op_sel_hi:[1,0,1]
	v_lshlrev_b32_e32 v12, 16, v246
	v_and_b32_e32 v13, 0xffff0000, v246
	v_lshlrev_b32_e32 v14, 16, v248
	v_and_b32_e32 v15, 0xffff0000, v248
	global_store_dwordx4 v[112:113], v[146:149], off
	global_store_dwordx4 v[112:113], v[172:175], off offset:256
	v_lshl_add_u64 v[112:113], s[28:29], 0, v[134:135]
	v_cvt_pk_bf16_f32 v176, v28, v29
	v_cvt_pk_bf16_f32 v177, v30, v31
	v_cvt_pk_bf16_f32 v178, v24, v25
	v_cvt_pk_bf16_f32 v179, v26, v27
	v_pk_fma_f32 v[12:13], v[16:17], 0.5, v[12:13] op_sel_hi:[1,0,1]
	v_pk_fma_f32 v[8:9], v[8:9], 0.5, v[14:15] op_sel_hi:[1,0,1]
	v_lshlrev_b32_e32 v14, 16, v247
	v_and_b32_e32 v15, 0xffff0000, v247
	v_lshlrev_b32_e32 v16, 16, v249
	v_and_b32_e32 v17, 0xffff0000, v249
	v_lshlrev_b32_e32 v64, 16, v65
	v_and_b32_e32 v65, 0xffff0000, v65
	v_lshl_add_u64 v[112:113], v[112:113], 0, v[170:171]
	v_cvt_pk_bf16_f32 v194, v20, v21
	v_cvt_pk_bf16_f32 v195, v22, v23
	v_cvt_pk_bf16_f32 v196, v32, v33
	v_cvt_pk_bf16_f32 v197, v34, v35
	v_pk_fma_f32 v[14:15], v[18:19], 0.5, v[14:15] op_sel_hi:[1,0,1]
	v_pk_fma_f32 v[10:11], v[10:11], 0.5, v[16:17] op_sel_hi:[1,0,1]
	v_pk_fma_f32 v[6:7], v[6:7], 0.5, v[64:65] op_sel_hi:[1,0,1]
	v_lshlrev_b32_e32 v64, 16, v67
	v_and_b32_e32 v65, 0xffff0000, v67
	global_store_dwordx4 v[112:113], v[176:179], off
	global_store_dwordx4 v[112:113], v[194:197], off offset:256
	v_lshl_add_u64 v[112:113], s[28:29], 0, v[184:185]
	v_cvt_pk_bf16_f32 v16, v12, v13
	v_cvt_pk_bf16_f32 v17, v14, v15
	v_cvt_pk_bf16_f32 v18, v8, v9
	v_cvt_pk_bf16_f32 v19, v10, v11
	v_pk_fma_f32 v[2:3], v[2:3], 0.5, v[64:65] op_sel_hi:[1,0,1]
	v_lshl_add_u64 v[112:113], v[112:113], 0, v[170:171]
	v_cvt_pk_bf16_f32 v64, v4, v5
	v_cvt_pk_bf16_f32 v65, v6, v7
	v_cvt_pk_bf16_f32 v66, v0, v1
	v_cvt_pk_bf16_f32 v67, v2, v3
	global_store_dwordx4 v[112:113], v[16:19], off
	global_store_dwordx4 v[112:113], v[64:67], off offset:256
	s_lshl_b32 s10, s81, 2
	v_and_b32_e32 v17, 64, v188
	v_xor_b32_e32 v16, 16, v188
	v_add_u32_e32 v17, 64, v17
	v_cmp_lt_i32_e32 vcc, v16, v17
	v_xor_b32_e32 v18, 32, v188
	s_ashr_i32 s11, s10, 31
	v_cndmask_b32_e32 v16, v188, v16, vcc
	v_lshlrev_b32_e32 v16, 2, v16
	ds_bpermute_b32 v19, v16, v209
	v_cmp_lt_i32_e32 vcc, v18, v17
	s_lshl_b64 s[10:11], s[10:11], 2
	s_add_u32 s38, s73, s10
	v_cndmask_b32_e32 v17, v188, v18, vcc
	v_lshlrev_b32_e32 v17, 2, v17
	s_waitcnt lgkmcnt(0)
	v_add_f32_e32 v18, v209, v19
	ds_bpermute_b32 v19, v17, v18
	s_addc_u32 s39, s74, s11
	s_and_saveexec_b64 s[46:47], s[42:43]
	s_cbranch_execz .LBB0_34
	s_waitcnt lgkmcnt(0)
	v_add_f32_e32 v64, v18, v19
	v_lshlrev_b64 v[18:19], 6, v[168:169]
	v_lshl_add_u64 v[18:19], s[38:39], 0, v[18:19]
	global_store_dword v[18:19], v64, off

.LBB0_76:
	s_add_u32 s10, s50, 0x100
	s_addc_u32 s11, s51, 0
	s_ashr_i32 s35, s34, 31
	s_lshl_b64 s[46:47], s[34:35], 19
	s_add_u32 s48, s33, s46
	s_addc_u32 s49, s41, s47
	s_and_b64 s[46:47], s[44:45], exec
	s_cselect_b32 s12, s49, s27
	s_cselect_b32 s31, s48, s26
	s_ashr_i32 s39, s38, 31
	s_lshl_b64 s[46:47], s[38:39], 19
	s_add_u32 s46, s57, s46
	s_addc_u32 s47, s58, s47
	s_and_b64 s[52:53], s[44:45], exec
	s_cselect_b32 s35, s47, s51
	s_cselect_b32 s39, s46, s50
	s_add_u32 s50, s26, 0x40080
	s_addc_u32 s51, s27, 0
	v_lshl_add_u64 v[150:151], s[50:51], 0, v[136:137]
	v_lshl_add_u64 v[152:153], s[50:51], 0, v[138:139]
	s_mov_b32 s81, -2
	s_mov_b64 s[50:51], 0
	v_add_u32_e32 v146, 0x10000, v154
	ds_read_b128 v[158:161], v146
	ds_read_b128 v[162:165], v146 offset:1024
	ds_read_b128 v[166:169], v146 offset:2048
	ds_read_b128 v[170:173], v146 offset:3072
.LBB0_77:
	s_add_u32 s6, s26, s50
	s_addc_u32 s19, s27, s51
	s_add_u32 s6, s6, 0x100
	s_addc_u32 s19, s19, 0
	s_add_u32 s23, s10, s50
	s_addc_u32 s52, s11, s51
	s_add_i32 s82, 0, 0x10000
	s_cmpk_eq_i32 s50, 0x700
	s_cselect_b32 s55, s12, s19
	s_cselect_b32 s54, s31, s6
	s_cselect_b32 s53, s35, s52
	s_cselect_b32 s52, s39, s23
	v_lshl_add_u64 v[146:147], v[150:151], 0, s[50:51]
	s_add_i32 m0, s68, 0xc000
	ds_read_b128 v[174:177], v157
	ds_read_b128 v[178:181], v157 offset:1024
	ds_read_b128 v[182:185], v157 offset:2048
	ds_read_b128 v[206:209], v157 offset:3072
	ds_read_b128 v[210:213], v157 offset:4096
	ds_read_b128 v[214:217], v157 offset:5120
	ds_read_b128 v[218:221], v157 offset:6144
	ds_read_b128 v[222:225], v157 offset:7168
	global_load_lds_dwordx4 v[146:147], off
	v_lshl_add_u64 v[146:147], v[152:153], 0, s[50:51]
	s_add_i32 m0, s68, 0xe000
	s_nop 0
	global_load_lds_dwordx4 v[146:147], off
	s_waitcnt lgkmcnt(8)
	s_barrier
	s_setprio 1
	s_waitcnt lgkmcnt(7)
	v_mfma_f32_16x16x32_bf16 v[124:127], v[158:161], v[174:177], v[124:127]
	v_mfma_f32_16x16x32_bf16 v[120:123], v[166:169], v[174:177], v[120:123]
	s_waitcnt lgkmcnt(5)
	v_mfma_f32_16x16x32_bf16 v[116:119], v[158:161], v[182:185], v[116:119]
	v_mfma_f32_16x16x32_bf16 v[112:115], v[166:169], v[182:185], v[112:115]
	s_waitcnt lgkmcnt(3)
	v_mfma_f32_16x16x32_bf16 v[108:111], v[158:161], v[210:213], v[108:111]
	v_mfma_f32_16x16x32_bf16 v[104:107], v[166:169], v[210:213], v[104:107]
	s_waitcnt lgkmcnt(1)
	v_mfma_f32_16x16x32_bf16 v[100:103], v[158:161], v[218:221], v[100:103]
	v_mfma_f32_16x16x32_bf16 v[96:99], v[166:169], v[218:221], v[96:99]
	v_mfma_f32_16x16x32_bf16 v[124:127], v[162:165], v[178:181], v[124:127]
	v_mfma_f32_16x16x32_bf16 v[120:123], v[170:173], v[178:181], v[120:123]
	v_mfma_f32_16x16x32_bf16 v[116:119], v[162:165], v[206:209], v[116:119]
	v_mfma_f32_16x16x32_bf16 v[112:115], v[170:173], v[206:209], v[112:115]
	v_mfma_f32_16x16x32_bf16 v[108:111], v[162:165], v[214:217], v[108:111]
	v_mfma_f32_16x16x32_bf16 v[104:107], v[170:173], v[214:217], v[104:107]
	s_waitcnt lgkmcnt(0)
	v_mfma_f32_16x16x32_bf16 v[100:103], v[162:165], v[222:225], v[100:103]
	v_mfma_f32_16x16x32_bf16 v[96:99], v[170:173], v[222:225], v[96:99]
	s_setprio 0
	s_barrier
	s_add_i32 s6, 0, 0x14000
	v_add_u32_e32 v146, s6, v154
	s_add_i32 s19, s82, s59
	ds_read_b128 v[226:229], v146
	ds_read_b128 v[230:233], v146 offset:1024
	ds_read_b128 v[234:237], v146 offset:2048
	ds_read_b128 v[238:241], v146 offset:3072
	v_lshl_add_u64 v[146:147], s[52:53], 0, v[140:141]
	s_mov_b32 m0, s19
	v_lshl_add_u64 v[148:149], s[52:53], 0, v[132:133]
	global_load_lds_dwordx4 v[146:147], off
	s_add_i32 m0, s19, 0x2000
	s_nop 0
	global_load_lds_dwordx4 v[148:149], off
	s_barrier
	s_setprio 1
	s_waitcnt lgkmcnt(3)
	v_mfma_f32_16x16x32_bf16 v[92:95], v[226:229], v[174:177], v[92:95]
	s_waitcnt lgkmcnt(1)
	v_mfma_f32_16x16x32_bf16 v[88:91], v[234:237], v[174:177], v[88:91]
	v_mfma_f32_16x16x32_bf16 v[84:87], v[226:229], v[182:185], v[84:87]
	v_mfma_f32_16x16x32_bf16 v[80:83], v[234:237], v[182:185], v[80:83]
	v_mfma_f32_16x16x32_bf16 v[76:79], v[226:229], v[210:213], v[76:79]
	v_mfma_f32_16x16x32_bf16 v[72:75], v[234:237], v[210:213], v[72:75]
	v_mfma_f32_16x16x32_bf16 v[68:71], v[226:229], v[218:221], v[68:71]
	v_mfma_f32_16x16x32_bf16 v[64:67], v[234:237], v[218:221], v[64:67]
	v_mfma_f32_16x16x32_bf16 v[92:95], v[230:233], v[178:181], v[92:95]
	s_waitcnt lgkmcnt(0)
	v_mfma_f32_16x16x32_bf16 v[88:91], v[238:241], v[178:181], v[88:91]
	v_mfma_f32_16x16x32_bf16 v[84:87], v[230:233], v[206:209], v[84:87]
	v_mfma_f32_16x16x32_bf16 v[80:83], v[238:241], v[206:209], v[80:83]
	v_mfma_f32_16x16x32_bf16 v[76:79], v[230:233], v[214:217], v[76:79]
	v_mfma_f32_16x16x32_bf16 v[72:75], v[238:241], v[214:217], v[72:75]
	v_mfma_f32_16x16x32_bf16 v[68:71], v[230:233], v[222:225], v[68:71]
	v_mfma_f32_16x16x32_bf16 v[64:67], v[238:241], v[222:225], v[64:67]
	s_setprio 0
	s_mov_b32 m0, s68
	v_lshl_add_u64 v[194:195], s[54:55], 0, v[128:129]
	s_barrier
	ds_read_b128 v[174:177], v157 offset:16384
	ds_read_b128 v[178:181], v157 offset:17408
	ds_read_b128 v[182:185], v157 offset:18432
	ds_read_b128 v[206:209], v157 offset:19456
	ds_read_b128 v[210:213], v157 offset:20480
	ds_read_b128 v[214:217], v157 offset:21504
	ds_read_b128 v[218:221], v157 offset:22528
	ds_read_b128 v[222:225], v157 offset:23552
	global_load_lds_dwordx4 v[194:195], off
	v_lshl_add_u64 v[196:197], s[54:55], 0, v[130:131]
	s_mov_b32 m0, s69
	s_nop 0
	global_load_lds_dwordx4 v[196:197], off
	s_waitcnt vmcnt(10)
	s_barrier
	s_setprio 1
	s_waitcnt lgkmcnt(7)
	v_mfma_f32_16x16x32_bf16 v[60:63], v[158:161], v[174:177], v[60:63]
	v_mfma_f32_16x16x32_bf16 v[56:59], v[166:169], v[174:177], v[56:59]
	s_waitcnt lgkmcnt(5)
	v_mfma_f32_16x16x32_bf16 v[52:55], v[158:161], v[182:185], v[52:55]
	v_mfma_f32_16x16x32_bf16 v[48:51], v[166:169], v[182:185], v[48:51]
	s_waitcnt lgkmcnt(3)
	v_mfma_f32_16x16x32_bf16 v[44:47], v[158:161], v[210:213], v[44:47]
	v_mfma_f32_16x16x32_bf16 v[40:43], v[166:169], v[210:213], v[40:43]
	s_waitcnt lgkmcnt(1)
	v_mfma_f32_16x16x32_bf16 v[36:39], v[158:161], v[218:221], v[36:39]
	v_mfma_f32_16x16x32_bf16 v[32:35], v[166:169], v[218:221], v[32:35]
	v_mfma_f32_16x16x32_bf16 v[60:63], v[162:165], v[178:181], v[60:63]
	v_mfma_f32_16x16x32_bf16 v[56:59], v[170:173], v[178:181], v[56:59]
	v_mfma_f32_16x16x32_bf16 v[52:55], v[162:165], v[206:209], v[52:55]
	v_mfma_f32_16x16x32_bf16 v[48:51], v[170:173], v[206:209], v[48:51]
	v_mfma_f32_16x16x32_bf16 v[44:47], v[162:165], v[214:217], v[44:47]
	v_mfma_f32_16x16x32_bf16 v[40:43], v[170:173], v[214:217], v[40:43]
	s_waitcnt lgkmcnt(0)
	v_mfma_f32_16x16x32_bf16 v[36:39], v[162:165], v[222:225], v[36:39]
	v_mfma_f32_16x16x32_bf16 v[32:35], v[170:173], v[222:225], v[32:35]
	s_setprio 0
	s_barrier
	s_add_u32 s82, s52, 0x40000
	s_addc_u32 s83, s53, 0
	s_add_i32 s6, s6, s59
	v_lshl_add_u64 v[158:159], s[82:83], 0, v[140:141]
	s_mov_b32 m0, s6
	s_nop 0
	global_load_lds_dwordx4 v[158:159], off
	v_lshl_add_u64 v[158:159], s[82:83], 0, v[132:133]
	s_add_i32 m0, s6, 0x2000
	s_nop 0
	global_load_lds_dwordx4 v[158:159], off
	v_add_u32_e32 v170, 0x18000, v154
	ds_read_b128 v[158:161], v170
	ds_read_b128 v[162:165], v170 offset:1024
	ds_read_b128 v[166:169], v170 offset:2048
	ds_read_b128 v[170:173], v170 offset:3072
	s_waitcnt vmcnt(6)
	s_barrier
	s_setprio 1
	v_mfma_f32_16x16x32_bf16 v[28:31], v[226:229], v[174:177], v[28:31]
	v_mfma_f32_16x16x32_bf16 v[24:27], v[234:237], v[174:177], v[24:27]
	v_mfma_f32_16x16x32_bf16 v[20:23], v[226:229], v[182:185], v[20:23]
	v_mfma_f32_16x16x32_bf16 v[16:19], v[234:237], v[182:185], v[16:19]
	v_mfma_f32_16x16x32_bf16 v[12:15], v[226:229], v[210:213], v[12:15]
	v_mfma_f32_16x16x32_bf16 v[8:11], v[234:237], v[210:213], v[8:11]
	v_mfma_f32_16x16x32_bf16 v[4:7], v[226:229], v[218:221], v[4:7]
	v_mfma_f32_16x16x32_bf16 v[0:3], v[234:237], v[218:221], v[0:3]
	v_mfma_f32_16x16x32_bf16 v[28:31], v[230:233], v[178:181], v[28:31]
	v_mfma_f32_16x16x32_bf16 v[24:27], v[238:241], v[178:181], v[24:27]
	v_mfma_f32_16x16x32_bf16 v[20:23], v[230:233], v[206:209], v[20:23]
	v_mfma_f32_16x16x32_bf16 v[16:19], v[238:241], v[206:209], v[16:19]
	v_mfma_f32_16x16x32_bf16 v[12:15], v[230:233], v[214:217], v[12:15]
	v_mfma_f32_16x16x32_bf16 v[8:11], v[238:241], v[214:217], v[8:11]
	v_mfma_f32_16x16x32_bf16 v[4:7], v[230:233], v[222:225], v[4:7]
	v_mfma_f32_16x16x32_bf16 v[0:3], v[238:241], v[222:225], v[0:3]
	s_setprio 0
	s_add_i32 s6, 0, 0x18000
	s_barrier
	s_add_u32 s54, s54, 0x40000
	s_addc_u32 s55, s55, 0
	s_mov_b32 m0, s70
	v_lshl_add_u64 v[226:227], s[54:55], 0, v[128:129]
	ds_read_b128 v[174:177], v157 offset:32768
	ds_read_b128 v[178:181], v157 offset:33792
	ds_read_b128 v[182:185], v157 offset:34816
	ds_read_b128 v[206:209], v157 offset:35840
	ds_read_b128 v[210:213], v157 offset:36864
	ds_read_b128 v[214:217], v157 offset:37888
	ds_read_b128 v[218:221], v157 offset:38912
	ds_read_b128 v[222:225], v157 offset:39936
	global_load_lds_dwordx4 v[226:227], off
	v_lshl_add_u64 v[226:227], s[54:55], 0, v[130:131]
	s_mov_b32 m0, s71
	s_nop 0
	global_load_lds_dwordx4 v[226:227], off
	s_waitcnt lgkmcnt(8)
	s_barrier
	s_setprio 1
	s_waitcnt lgkmcnt(7)
	v_mfma_f32_16x16x32_bf16 v[124:127], v[158:161], v[174:177], v[124:127]
	v_mfma_f32_16x16x32_bf16 v[120:123], v[166:169], v[174:177], v[120:123]
	s_waitcnt lgkmcnt(5)
	v_mfma_f32_16x16x32_bf16 v[116:119], v[158:161], v[182:185], v[116:119]
	v_mfma_f32_16x16x32_bf16 v[112:115], v[166:169], v[182:185], v[112:115]
	s_waitcnt lgkmcnt(3)
	v_mfma_f32_16x16x32_bf16 v[108:111], v[158:161], v[210:213], v[108:111]
	v_mfma_f32_16x16x32_bf16 v[104:107], v[166:169], v[210:213], v[104:107]
	s_waitcnt lgkmcnt(1)
	v_mfma_f32_16x16x32_bf16 v[100:103], v[158:161], v[218:221], v[100:103]
	v_mfma_f32_16x16x32_bf16 v[96:99], v[166:169], v[218:221], v[96:99]
	v_mfma_f32_16x16x32_bf16 v[124:127], v[162:165], v[178:181], v[124:127]
	v_mfma_f32_16x16x32_bf16 v[120:123], v[170:173], v[178:181], v[120:123]
	v_mfma_f32_16x16x32_bf16 v[116:119], v[162:165], v[206:209], v[116:119]
	v_mfma_f32_16x16x32_bf16 v[112:115], v[170:173], v[206:209], v[112:115]
	v_mfma_f32_16x16x32_bf16 v[108:111], v[162:165], v[214:217], v[108:111]
	v_mfma_f32_16x16x32_bf16 v[104:107], v[170:173], v[214:217], v[104:107]
	s_waitcnt lgkmcnt(0)
	v_mfma_f32_16x16x32_bf16 v[100:103], v[162:165], v[222:225], v[100:103]
	v_mfma_f32_16x16x32_bf16 v[96:99], v[170:173], v[222:225], v[96:99]
	s_setprio 0
	s_barrier
	s_add_i32 s19, 0, 0x1c000
	s_add_i32 s6, s6, s59
	v_add_u32_e32 v192, s19, v154
	v_lshl_add_u64 v[146:147], v[146:147], 0, s[36:37]
	s_mov_b32 m0, s6
	ds_read_b128 v[226:229], v192
	ds_read_b128 v[230:233], v192 offset:1024
	ds_read_b128 v[234:237], v192 offset:2048
	ds_read_b128 v[238:241], v192 offset:3072
	global_load_lds_dwordx4 v[146:147], off
	v_lshl_add_u64 v[146:147], v[148:149], 0, s[36:37]
	s_add_i32 m0, s6, 0x2000
	s_nop 0
	global_load_lds_dwordx4 v[146:147], off
	s_barrier
	s_setprio 1
	s_waitcnt lgkmcnt(3)
	v_mfma_f32_16x16x32_bf16 v[92:95], v[226:229], v[174:177], v[92:95]
	s_waitcnt lgkmcnt(1)
	v_mfma_f32_16x16x32_bf16 v[88:91], v[234:237], v[174:177], v[88:91]
	v_mfma_f32_16x16x32_bf16 v[84:87], v[226:229], v[182:185], v[84:87]
	v_mfma_f32_16x16x32_bf16 v[80:83], v[234:237], v[182:185], v[80:83]
	v_mfma_f32_16x16x32_bf16 v[76:79], v[226:229], v[210:213], v[76:79]
	v_mfma_f32_16x16x32_bf16 v[72:75], v[234:237], v[210:213], v[72:75]
	v_mfma_f32_16x16x32_bf16 v[68:71], v[226:229], v[218:221], v[68:71]
	v_mfma_f32_16x16x32_bf16 v[64:67], v[234:237], v[218:221], v[64:67]
	v_mfma_f32_16x16x32_bf16 v[92:95], v[230:233], v[178:181], v[92:95]
	s_waitcnt lgkmcnt(0)
	v_mfma_f32_16x16x32_bf16 v[88:91], v[238:241], v[178:181], v[88:91]
	v_mfma_f32_16x16x32_bf16 v[84:87], v[230:233], v[206:209], v[84:87]
	v_mfma_f32_16x16x32_bf16 v[80:83], v[238:241], v[206:209], v[80:83]
	v_mfma_f32_16x16x32_bf16 v[76:79], v[230:233], v[214:217], v[76:79]
	v_mfma_f32_16x16x32_bf16 v[72:75], v[238:241], v[214:217], v[72:75]
	v_mfma_f32_16x16x32_bf16 v[68:71], v[230:233], v[222:225], v[68:71]
	v_mfma_f32_16x16x32_bf16 v[64:67], v[238:241], v[222:225], v[64:67]
	s_setprio 0
	s_mov_b32 m0, s72
	v_lshl_add_u64 v[146:147], v[194:195], 0, s[36:37]
	s_barrier
	ds_read_b128 v[174:177], v157 offset:49152
	ds_read_b128 v[178:181], v157 offset:50176
	ds_read_b128 v[182:185], v157 offset:51200
	ds_read_b128 v[206:209], v157 offset:52224
	ds_read_b128 v[210:213], v157 offset:53248
	ds_read_b128 v[214:217], v157 offset:54272
	ds_read_b128 v[218:221], v157 offset:55296
	ds_read_b128 v[222:225], v157 offset:56320
	global_load_lds_dwordx4 v[146:147], off
	v_lshl_add_u64 v[146:147], v[196:197], 0, s[36:37]
	s_mov_b32 m0, s73
	s_nop 0
	global_load_lds_dwordx4 v[146:147], off
	s_waitcnt vmcnt(10)
	s_barrier
	s_setprio 1
	s_waitcnt lgkmcnt(7)
	v_mfma_f32_16x16x32_bf16 v[60:63], v[158:161], v[174:177], v[60:63]
	v_mfma_f32_16x16x32_bf16 v[56:59], v[166:169], v[174:177], v[56:59]
	s_waitcnt lgkmcnt(5)
	v_mfma_f32_16x16x32_bf16 v[52:55], v[158:161], v[182:185], v[52:55]
	v_mfma_f32_16x16x32_bf16 v[48:51], v[166:169], v[182:185], v[48:51]
	s_waitcnt lgkmcnt(3)
	v_mfma_f32_16x16x32_bf16 v[44:47], v[158:161], v[210:213], v[44:47]
	v_mfma_f32_16x16x32_bf16 v[40:43], v[166:169], v[210:213], v[40:43]
	s_waitcnt lgkmcnt(1)
	v_mfma_f32_16x16x32_bf16 v[36:39], v[158:161], v[218:221], v[36:39]
	v_mfma_f32_16x16x32_bf16 v[32:35], v[166:169], v[218:221], v[32:35]
	v_mfma_f32_16x16x32_bf16 v[60:63], v[162:165], v[178:181], v[60:63]
	v_mfma_f32_16x16x32_bf16 v[56:59], v[170:173], v[178:181], v[56:59]
	v_mfma_f32_16x16x32_bf16 v[52:55], v[162:165], v[206:209], v[52:55]
	v_mfma_f32_16x16x32_bf16 v[48:51], v[170:173], v[206:209], v[48:51]
	v_mfma_f32_16x16x32_bf16 v[44:47], v[162:165], v[214:217], v[44:47]
	v_mfma_f32_16x16x32_bf16 v[40:43], v[170:173], v[214:217], v[40:43]
	s_waitcnt lgkmcnt(0)
	v_mfma_f32_16x16x32_bf16 v[36:39], v[162:165], v[222:225], v[36:39]
	v_mfma_f32_16x16x32_bf16 v[32:35], v[170:173], v[222:225], v[32:35]
	s_setprio 0
	s_barrier
	s_add_u32 s52, s52, 0x40080
	s_addc_u32 s53, s53, 0
	s_add_i32 s6, s19, s59
	v_lshl_add_u64 v[146:147], s[52:53], 0, v[140:141]
	s_mov_b32 m0, s6
	s_nop 0
	global_load_lds_dwordx4 v[146:147], off
	v_lshl_add_u64 v[146:147], s[52:53], 0, v[132:133]
	s_add_i32 m0, s6, 0x2000
	s_nop 0
	global_load_lds_dwordx4 v[146:147], off
	v_add_u32_e32 v146, 0x10000, v154
	ds_read_b128 v[158:161], v146
	ds_read_b128 v[162:165], v146 offset:1024
	ds_read_b128 v[166:169], v146 offset:2048
	ds_read_b128 v[170:173], v146 offset:3072
	s_waitcnt vmcnt(6)
	s_barrier
	s_setprio 1
	v_mfma_f32_16x16x32_bf16 v[28:31], v[226:229], v[174:177], v[28:31]
	v_mfma_f32_16x16x32_bf16 v[24:27], v[234:237], v[174:177], v[24:27]
	v_mfma_f32_16x16x32_bf16 v[20:23], v[226:229], v[182:185], v[20:23]
	v_mfma_f32_16x16x32_bf16 v[16:19], v[234:237], v[182:185], v[16:19]
	v_mfma_f32_16x16x32_bf16 v[12:15], v[226:229], v[210:213], v[12:15]
	v_mfma_f32_16x16x32_bf16 v[8:11], v[234:237], v[210:213], v[8:11]
	v_mfma_f32_16x16x32_bf16 v[4:7], v[226:229], v[218:221], v[4:7]
	v_mfma_f32_16x16x32_bf16 v[0:3], v[234:237], v[218:221], v[0:3]
	v_mfma_f32_16x16x32_bf16 v[28:31], v[230:233], v[178:181], v[28:31]
	v_mfma_f32_16x16x32_bf16 v[24:27], v[238:241], v[178:181], v[24:27]
	v_mfma_f32_16x16x32_bf16 v[20:23], v[230:233], v[206:209], v[20:23]
	v_mfma_f32_16x16x32_bf16 v[16:19], v[238:241], v[206:209], v[16:19]
	v_mfma_f32_16x16x32_bf16 v[12:15], v[230:233], v[214:217], v[12:15]
	v_mfma_f32_16x16x32_bf16 v[8:11], v[238:241], v[214:217], v[8:11]
	v_mfma_f32_16x16x32_bf16 v[4:7], v[230:233], v[222:225], v[4:7]
	v_mfma_f32_16x16x32_bf16 v[0:3], v[238:241], v[222:225], v[0:3]
	s_setprio 0
	s_add_i32 s81, s81, 2
	s_add_u32 s50, s50, 0x100
	s_addc_u32 s51, s51, 0
	s_cmp_gt_u32 s81, 13
	s_barrier
	s_cbranch_scc0 .LBB0_77
	s_waitcnt lgkmcnt(0)
	v_lshl_add_u32 v158, s75, 10, v155
	ds_read2_b32 v[146:147], v158 offset1:16
	s_add_u32 s50, s10, 0xffffff00
	s_addc_u32 s51, s11, -1
	s_ashr_i32 s31, s30, 31
	s_lshl_b64 s[10:11], s[30:31], 8
	s_waitcnt lgkmcnt(0)
	v_pk_mul_f32 v[148:149], v[124:125], v[146:147] op_sel_hi:[1,0]
	v_lshl_add_u64 v[152:153], v[134:135], 0, s[10:11]
	v_mul_f32_e32 v159, 0xbfb8aa3b, v148
	v_exp_f32_e32 v159, v159
	s_movk_i32 s6, 0x1600
	v_lshl_or_b32 v150, s74, 7, v156
	v_ashrrev_i32_e32 v151, 31, v150
	v_add_f32_e32 v159, 1.0, v159
	v_rcp_f32_e32 v160, v159
	v_mul_f32_e32 v159, 0xbfb8aa3b, v149
	v_exp_f32_e32 v159, v159
	s_nop 0
	v_add_f32_e32 v159, 1.0, v159
	v_rcp_f32_e32 v161, v159
	s_nop 0
	v_pk_mul_f32 v[148:149], v[148:149], v[160:161]
	v_pk_mul_f32 v[160:161], v[92:93], v[146:147] op_sel_hi:[1,0]
	s_nop 0
	v_pk_mul_f32 v[148:149], v[160:161], v[148:149]
	v_pk_mul_f32 v[160:161], v[126:127], v[146:147] op_sel_hi:[1,0]
	s_nop 0
	v_mul_f32_e32 v159, 0xbfb8aa3b, v160
	v_exp_f32_e32 v159, v159
	s_nop 0
	v_add_f32_e32 v159, 1.0, v159
	v_rcp_f32_e32 v162, v159
	v_mul_f32_e32 v159, 0xbfb8aa3b, v161
	v_exp_f32_e32 v159, v159
	s_nop 0
	v_add_f32_e32 v159, 1.0, v159
	v_rcp_f32_e32 v163, v159
	s_nop 0
	v_pk_mul_f32 v[160:161], v[160:161], v[162:163]
	v_pk_mul_f32 v[162:163], v[94:95], v[146:147] op_sel_hi:[1,0]
	s_nop 0
	v_pk_mul_f32 v[162:163], v[162:163], v[160:161]
	v_pk_mul_f32 v[160:161], v[120:121], v[146:147] op_sel_hi:[1,0]
	s_nop 0
	v_mul_f32_e32 v159, 0xbfb8aa3b, v160
	v_exp_f32_e32 v159, v159
	s_nop 0
	v_add_f32_e32 v159, 1.0, v159
	v_rcp_f32_e32 v164, v159
	v_mul_f32_e32 v159, 0xbfb8aa3b, v161
	v_exp_f32_e32 v159, v159
	s_nop 0
	v_add_f32_e32 v159, 1.0, v159
	v_rcp_f32_e32 v165, v159
	s_nop 0
	v_pk_mul_f32 v[160:161], v[160:161], v[164:165]
	v_pk_mul_f32 v[164:165], v[88:89], v[146:147] op_sel_hi:[1,0]
	s_nop 0
	v_pk_mul_f32 v[164:165], v[164:165], v[160:161]
	v_pk_mul_f32 v[160:161], v[122:123], v[146:147] op_sel_hi:[1,0]
	s_nop 0
	v_mul_f32_e32 v159, 0xbfb8aa3b, v160
	v_exp_f32_e32 v159, v159
	s_nop 0
	v_add_f32_e32 v159, 1.0, v159
	v_rcp_f32_e32 v166, v159
	v_mul_f32_e32 v159, 0xbfb8aa3b, v161
	v_exp_f32_e32 v159, v159
	s_nop 0
	v_add_f32_e32 v159, 1.0, v159
	v_rcp_f32_e32 v167, v159
	s_nop 0
	v_pk_mul_f32 v[160:161], v[160:161], v[166:167]
	v_pk_mul_f32 v[166:167], v[90:91], v[146:147] op_sel_hi:[1,0]
	s_nop 0
	v_pk_mul_f32 v[166:167], v[166:167], v[160:161]
	v_cvt_pk_bf16_f32 v160, v148, v149
	v_mov_b64_e32 v[148:149], s[28:29]
	v_mad_u64_u32 v[148:149], s[10:11], v152, s6, v[148:149]
	v_mov_b32_e32 v146, v149
	v_mad_u64_u32 v[152:153], s[10:11], v153, s6, v[146:147]
	v_mov_b32_e32 v149, v152
	v_mov_b32_e32 v146, v147
	v_lshl_add_u64 v[150:151], v[150:151], 1, v[148:149]
	v_pk_mul_f32 v[148:149], v[116:117], v[146:147] op_sel_hi:[1,0]
	v_cvt_pk_bf16_f32 v161, v162, v163
	v_mul_f32_e32 v147, 0xbfb8aa3b, v148
	v_exp_f32_e32 v147, v147
	v_cvt_pk_bf16_f32 v162, v164, v165
	v_cvt_pk_bf16_f32 v163, v166, v167
	global_store_dwordx4 v[150:151], v[160:163], off
	v_add_f32_e32 v147, 1.0, v147
	v_rcp_f32_e32 v152, v147
	v_mul_f32_e32 v147, 0xbfb8aa3b, v149
	v_exp_f32_e32 v147, v147
	s_mov_b32 s6, 0x16000
	v_add_f32_e32 v147, 1.0, v147
	v_rcp_f32_e32 v153, v147
	s_nop 0
	v_pk_mul_f32 v[148:149], v[148:149], v[152:153]
	v_pk_mul_f32 v[152:153], v[84:85], v[146:147] op_sel_hi:[1,0]
	s_nop 0
	v_pk_mul_f32 v[148:149], v[152:153], v[148:149]
	v_pk_mul_f32 v[152:153], v[118:119], v[146:147] op_sel_hi:[1,0]
	s_nop 0
	v_mul_f32_e32 v147, 0xbfb8aa3b, v152
	v_exp_f32_e32 v147, v147
	s_nop 0
	v_add_f32_e32 v147, 1.0, v147
	v_rcp_f32_e32 v160, v147
	v_mul_f32_e32 v147, 0xbfb8aa3b, v153
	v_exp_f32_e32 v147, v147
	s_nop 0
	v_add_f32_e32 v147, 1.0, v147
	v_rcp_f32_e32 v161, v147
	s_nop 0
	v_pk_mul_f32 v[152:153], v[152:153], v[160:161]
	v_pk_mul_f32 v[160:161], v[86:87], v[146:147] op_sel_hi:[1,0]
	s_nop 0
	v_pk_mul_f32 v[152:153], v[160:161], v[152:153]
	v_pk_mul_f32 v[160:161], v[112:113], v[146:147] op_sel_hi:[1,0]
	s_nop 0
	v_mul_f32_e32 v147, 0xbfb8aa3b, v160
	v_exp_f32_e32 v147, v147
	s_nop 0
	v_add_f32_e32 v147, 1.0, v147
	v_rcp_f32_e32 v162, v147
	v_mul_f32_e32 v147, 0xbfb8aa3b, v161
	v_exp_f32_e32 v147, v147
	s_nop 0
	v_add_f32_e32 v147, 1.0, v147
	v_rcp_f32_e32 v163, v147
	s_nop 0
	v_pk_mul_f32 v[160:161], v[160:161], v[162:163]
	v_pk_mul_f32 v[162:163], v[80:81], v[146:147] op_sel_hi:[1,0]
	s_nop 0
	v_pk_mul_f32 v[162:163], v[162:163], v[160:161]
	v_pk_mul_f32 v[160:161], v[114:115], v[146:147] op_sel_hi:[1,0]
	v_cvt_pk_bf16_f32 v162, v162, v163
	v_mul_f32_e32 v147, 0xbfb8aa3b, v160
	v_exp_f32_e32 v147, v147
	s_nop 0
	v_add_f32_e32 v147, 1.0, v147
	v_rcp_f32_e32 v164, v147
	v_mul_f32_e32 v147, 0xbfb8aa3b, v161
	v_exp_f32_e32 v147, v147
	s_nop 0
	v_add_f32_e32 v147, 1.0, v147
	v_rcp_f32_e32 v165, v147
	v_pk_mul_f32 v[146:147], v[82:83], v[146:147] op_sel_hi:[1,0]
	v_pk_mul_f32 v[160:161], v[160:161], v[164:165]
	s_nop 0
	v_pk_mul_f32 v[146:147], v[146:147], v[160:161]
	v_cvt_pk_bf16_f32 v160, v148, v149
	v_cvt_pk_bf16_f32 v163, v146, v147
	v_add_co_u32_e32 v146, vcc, s6, v150
	v_cvt_pk_bf16_f32 v161, v152, v153
	s_nop 0
	v_addc_co_u32_e32 v147, vcc, 0, v151, vcc
	global_store_dwordx4 v[146:147], v[160:163], off
	ds_read2_b32 v[146:147], v158 offset0:32 offset1:48
	s_mov_b32 s6, 0x2c000
	s_waitcnt lgkmcnt(0)
	v_pk_mul_f32 v[148:149], v[108:109], v[146:147] op_sel_hi:[1,0]
	s_nop 0
	v_mul_f32_e32 v152, 0xbfb8aa3b, v148
	v_mul_f32_e32 v153, 0xbfb8aa3b, v149
	v_exp_f32_e32 v152, v152
	v_exp_f32_e32 v153, v153
	v_add_f32_e32 v152, 1.0, v152
	v_add_f32_e32 v153, 1.0, v153
	v_rcp_f32_e32 v152, v152
	v_rcp_f32_e32 v153, v153
	s_nop 0
	v_pk_mul_f32 v[148:149], v[148:149], v[152:153]
	v_pk_mul_f32 v[152:153], v[76:77], v[146:147] op_sel_hi:[1,0]
	s_nop 0
	v_pk_mul_f32 v[148:149], v[152:153], v[148:149]
	v_pk_mul_f32 v[152:153], v[110:111], v[146:147] op_sel_hi:[1,0]
	s_nop 0
	v_mul_f32_e32 v159, 0xbfb8aa3b, v152
	v_exp_f32_e32 v159, v159
	s_nop 0
	v_add_f32_e32 v159, 1.0, v159
	v_rcp_f32_e32 v160, v159
	v_mul_f32_e32 v159, 0xbfb8aa3b, v153
	v_exp_f32_e32 v159, v159
	s_nop 0
	v_add_f32_e32 v159, 1.0, v159
	v_rcp_f32_e32 v161, v159
	s_nop 0
	v_pk_mul_f32 v[152:153], v[152:153], v[160:161]
	v_pk_mul_f32 v[160:161], v[78:79], v[146:147] op_sel_hi:[1,0]
	s_nop 0
	v_pk_mul_f32 v[152:153], v[160:161], v[152:153]
	v_pk_mul_f32 v[160:161], v[104:105], v[146:147] op_sel_hi:[1,0]
	s_nop 0
	v_mul_f32_e32 v159, 0xbfb8aa3b, v160
	v_exp_f32_e32 v159, v159
	s_nop 0
	v_add_f32_e32 v159, 1.0, v159
	v_rcp_f32_e32 v162, v159
	v_mul_f32_e32 v159, 0xbfb8aa3b, v161
	v_exp_f32_e32 v159, v159
	s_nop 0
	v_add_f32_e32 v159, 1.0, v159
	v_rcp_f32_e32 v163, v159
	s_nop 0
	v_pk_mul_f32 v[160:161], v[160:161], v[162:163]
	v_pk_mul_f32 v[162:163], v[72:73], v[146:147] op_sel_hi:[1,0]
	s_nop 0
	v_pk_mul_f32 v[162:163], v[162:163], v[160:161]
	v_pk_mul_f32 v[160:161], v[106:107], v[146:147] op_sel_hi:[1,0]
	v_cvt_pk_bf16_f32 v162, v162, v163
	v_mul_f32_e32 v159, 0xbfb8aa3b, v160
	v_exp_f32_e32 v159, v159
	s_nop 0
	v_add_f32_e32 v159, 1.0, v159
	v_rcp_f32_e32 v164, v159
	v_mul_f32_e32 v159, 0xbfb8aa3b, v161
	v_exp_f32_e32 v159, v159
	s_nop 0
	v_add_f32_e32 v159, 1.0, v159
	v_rcp_f32_e32 v165, v159
	s_nop 0
	v_pk_mul_f32 v[160:161], v[160:161], v[164:165]
	v_pk_mul_f32 v[164:165], v[74:75], v[146:147] op_sel_hi:[1,0]
	v_mov_b32_e32 v146, v147
	v_pk_mul_f32 v[164:165], v[164:165], v[160:161]
	v_cvt_pk_bf16_f32 v160, v148, v149
	v_add_co_u32_e32 v148, vcc, s6, v150
	v_cvt_pk_bf16_f32 v161, v152, v153
	v_cvt_pk_bf16_f32 v163, v164, v165
	v_addc_co_u32_e32 v149, vcc, 0, v151, vcc
	global_store_dwordx4 v[148:149], v[160:163], off
	v_pk_mul_f32 v[148:149], v[100:101], v[146:147] op_sel_hi:[1,0]
	s_mov_b32 s6, 0x42000
	v_mul_f32_e32 v147, 0xbfb8aa3b, v148
	v_exp_f32_e32 v147, v147
	s_nop 0
	v_add_f32_e32 v147, 1.0, v147
	v_rcp_f32_e32 v152, v147
	v_mul_f32_e32 v147, 0xbfb8aa3b, v149
	v_exp_f32_e32 v147, v147
	s_nop 0
	v_add_f32_e32 v147, 1.0, v147
	v_rcp_f32_e32 v153, v147
	s_nop 0
	v_pk_mul_f32 v[148:149], v[148:149], v[152:153]
	v_pk_mul_f32 v[152:153], v[68:69], v[146:147] op_sel_hi:[1,0]
	s_nop 0
	v_pk_mul_f32 v[148:149], v[152:153], v[148:149]
	v_pk_mul_f32 v[152:153], v[102:103], v[146:147] op_sel_hi:[1,0]
	s_nop 0
	v_mul_f32_e32 v147, 0xbfb8aa3b, v152
	v_exp_f32_e32 v147, v147
	s_nop 0
	v_add_f32_e32 v147, 1.0, v147
	v_rcp_f32_e32 v160, v147
	v_mul_f32_e32 v147, 0xbfb8aa3b, v153
	v_exp_f32_e32 v147, v147
	s_nop 0
	v_add_f32_e32 v147, 1.0, v147
	v_rcp_f32_e32 v161, v147
	s_nop 0
	v_pk_mul_f32 v[152:153], v[152:153], v[160:161]
	v_pk_mul_f32 v[160:161], v[70:71], v[146:147] op_sel_hi:[1,0]
	s_nop 0
	v_pk_mul_f32 v[152:153], v[160:161], v[152:153]
	v_pk_mul_f32 v[160:161], v[96:97], v[146:147] op_sel_hi:[1,0]
	s_nop 0
	v_mul_f32_e32 v147, 0xbfb8aa3b, v160
	v_exp_f32_e32 v147, v147
	s_nop 0
	v_add_f32_e32 v147, 1.0, v147
	v_rcp_f32_e32 v162, v147
	v_mul_f32_e32 v147, 0xbfb8aa3b, v161
	v_exp_f32_e32 v147, v147
	s_nop 0
	v_add_f32_e32 v147, 1.0, v147
	v_rcp_f32_e32 v163, v147
	s_nop 0
	v_pk_mul_f32 v[160:161], v[160:161], v[162:163]
	v_pk_mul_f32 v[162:163], v[64:65], v[146:147] op_sel_hi:[1,0]
	s_nop 0
	v_pk_mul_f32 v[162:163], v[162:163], v[160:161]
	v_pk_mul_f32 v[160:161], v[98:99], v[146:147] op_sel_hi:[1,0]
	v_cvt_pk_bf16_f32 v162, v162, v163
	v_mul_f32_e32 v147, 0xbfb8aa3b, v160
	v_exp_f32_e32 v147, v147
	s_nop 0
	v_add_f32_e32 v147, 1.0, v147
	v_rcp_f32_e32 v164, v147
	v_mul_f32_e32 v147, 0xbfb8aa3b, v161
	v_exp_f32_e32 v147, v147
	s_nop 0
	v_add_f32_e32 v147, 1.0, v147
	v_rcp_f32_e32 v165, v147
	v_pk_mul_f32 v[146:147], v[66:67], v[146:147] op_sel_hi:[1,0]
	v_pk_mul_f32 v[160:161], v[160:161], v[164:165]
	s_nop 0
	v_pk_mul_f32 v[146:147], v[146:147], v[160:161]
	v_cvt_pk_bf16_f32 v160, v148, v149
	v_cvt_pk_bf16_f32 v163, v146, v147
	v_add_co_u32_e32 v146, vcc, s6, v150
	v_cvt_pk_bf16_f32 v161, v152, v153
	s_nop 0
	v_addc_co_u32_e32 v147, vcc, 0, v151, vcc
	global_store_dwordx4 v[146:147], v[160:163], off
	ds_read2_b32 v[146:147], v158 offset0:128 offset1:144
	s_mov_b32 s6, 0xb0000
	s_waitcnt lgkmcnt(0)
	v_pk_mul_f32 v[148:149], v[60:61], v[146:147] op_sel_hi:[1,0]
	s_nop 0
	v_mul_f32_e32 v152, 0xbfb8aa3b, v148
	v_mul_f32_e32 v153, 0xbfb8aa3b, v149
	v_exp_f32_e32 v152, v152
	v_exp_f32_e32 v153, v153
	v_add_f32_e32 v152, 1.0, v152
	v_add_f32_e32 v153, 1.0, v153
	v_rcp_f32_e32 v152, v152
	v_rcp_f32_e32 v153, v153
	s_nop 0
	v_pk_mul_f32 v[148:149], v[148:149], v[152:153]
	v_pk_mul_f32 v[152:153], v[28:29], v[146:147] op_sel_hi:[1,0]
	s_nop 0
	v_pk_mul_f32 v[148:149], v[152:153], v[148:149]
	v_pk_mul_f32 v[152:153], v[62:63], v[146:147] op_sel_hi:[1,0]
	s_nop 0
	v_mul_f32_e32 v159, 0xbfb8aa3b, v152
	v_exp_f32_e32 v159, v159
	s_nop 0
	v_add_f32_e32 v159, 1.0, v159
	v_rcp_f32_e32 v160, v159
	v_mul_f32_e32 v159, 0xbfb8aa3b, v153
	v_exp_f32_e32 v159, v159
	s_nop 0
	v_add_f32_e32 v159, 1.0, v159
	v_rcp_f32_e32 v161, v159
	s_nop 0
	v_pk_mul_f32 v[152:153], v[152:153], v[160:161]
	v_pk_mul_f32 v[160:161], v[30:31], v[146:147] op_sel_hi:[1,0]
	s_nop 0
	v_pk_mul_f32 v[152:153], v[160:161], v[152:153]
	v_pk_mul_f32 v[160:161], v[56:57], v[146:147] op_sel_hi:[1,0]
	s_nop 0
	v_mul_f32_e32 v159, 0xbfb8aa3b, v160
	v_exp_f32_e32 v159, v159
	s_nop 0
	v_add_f32_e32 v159, 1.0, v159
	v_rcp_f32_e32 v162, v159
	v_mul_f32_e32 v159, 0xbfb8aa3b, v161
	v_exp_f32_e32 v159, v159
	s_nop 0
	v_add_f32_e32 v159, 1.0, v159
	v_rcp_f32_e32 v163, v159
	s_nop 0
	v_pk_mul_f32 v[160:161], v[160:161], v[162:163]
	v_pk_mul_f32 v[162:163], v[24:25], v[146:147] op_sel_hi:[1,0]
	s_nop 0
	v_pk_mul_f32 v[162:163], v[162:163], v[160:161]
	v_pk_mul_f32 v[160:161], v[58:59], v[146:147] op_sel_hi:[1,0]
	v_cvt_pk_bf16_f32 v162, v162, v163
	v_mul_f32_e32 v159, 0xbfb8aa3b, v160
	v_exp_f32_e32 v159, v159
	s_nop 0
	v_add_f32_e32 v159, 1.0, v159
	v_rcp_f32_e32 v164, v159
	v_mul_f32_e32 v159, 0xbfb8aa3b, v161
	v_exp_f32_e32 v159, v159
	s_nop 0
	v_add_f32_e32 v159, 1.0, v159
	v_rcp_f32_e32 v165, v159
	s_nop 0
	v_pk_mul_f32 v[160:161], v[160:161], v[164:165]
	v_pk_mul_f32 v[164:165], v[26:27], v[146:147] op_sel_hi:[1,0]
	v_mov_b32_e32 v146, v147
	v_pk_mul_f32 v[164:165], v[164:165], v[160:161]
	v_cvt_pk_bf16_f32 v160, v148, v149
	v_add_co_u32_e32 v148, vcc, s6, v150
	v_cvt_pk_bf16_f32 v161, v152, v153
	v_cvt_pk_bf16_f32 v163, v164, v165
	v_addc_co_u32_e32 v149, vcc, 0, v151, vcc
	global_store_dwordx4 v[148:149], v[160:163], off
	v_pk_mul_f32 v[148:149], v[52:53], v[146:147] op_sel_hi:[1,0]
	s_mov_b32 s6, 0xc6000
	v_mul_f32_e32 v147, 0xbfb8aa3b, v148
	v_exp_f32_e32 v147, v147
	s_nop 0
	v_add_f32_e32 v147, 1.0, v147
	v_rcp_f32_e32 v152, v147
	v_mul_f32_e32 v147, 0xbfb8aa3b, v149
	v_exp_f32_e32 v147, v147
	s_nop 0
	v_add_f32_e32 v147, 1.0, v147
	v_rcp_f32_e32 v153, v147
	s_nop 0
	v_pk_mul_f32 v[148:149], v[148:149], v[152:153]
	v_pk_mul_f32 v[152:153], v[20:21], v[146:147] op_sel_hi:[1,0]
	s_nop 0
	v_pk_mul_f32 v[148:149], v[152:153], v[148:149]
	v_pk_mul_f32 v[152:153], v[54:55], v[146:147] op_sel_hi:[1,0]
	s_nop 0
	v_mul_f32_e32 v147, 0xbfb8aa3b, v152
	v_exp_f32_e32 v147, v147
	s_nop 0
	v_add_f32_e32 v147, 1.0, v147
	v_rcp_f32_e32 v160, v147
	v_mul_f32_e32 v147, 0xbfb8aa3b, v153
	v_exp_f32_e32 v147, v147
	s_nop 0
	v_add_f32_e32 v147, 1.0, v147
	v_rcp_f32_e32 v161, v147
	s_nop 0
	v_pk_mul_f32 v[152:153], v[152:153], v[160:161]
	v_pk_mul_f32 v[160:161], v[22:23], v[146:147] op_sel_hi:[1,0]
	s_nop 0
	v_pk_mul_f32 v[152:153], v[160:161], v[152:153]
	v_pk_mul_f32 v[160:161], v[48:49], v[146:147] op_sel_hi:[1,0]
	s_nop 0
	v_mul_f32_e32 v147, 0xbfb8aa3b, v160
	v_exp_f32_e32 v147, v147
	s_nop 0
	v_add_f32_e32 v147, 1.0, v147
	v_rcp_f32_e32 v162, v147
	v_mul_f32_e32 v147, 0xbfb8aa3b, v161
	v_exp_f32_e32 v147, v147
	s_nop 0
	v_add_f32_e32 v147, 1.0, v147
	v_rcp_f32_e32 v163, v147
	s_nop 0
	v_pk_mul_f32 v[160:161], v[160:161], v[162:163]
	v_pk_mul_f32 v[162:163], v[16:17], v[146:147] op_sel_hi:[1,0]
	s_nop 0
	v_pk_mul_f32 v[162:163], v[162:163], v[160:161]
	v_pk_mul_f32 v[160:161], v[50:51], v[146:147] op_sel_hi:[1,0]
	v_cvt_pk_bf16_f32 v162, v162, v163
	v_mul_f32_e32 v147, 0xbfb8aa3b, v160
	v_exp_f32_e32 v147, v147
	s_nop 0
	v_add_f32_e32 v147, 1.0, v147
	v_rcp_f32_e32 v164, v147
	v_mul_f32_e32 v147, 0xbfb8aa3b, v161
	v_exp_f32_e32 v147, v147
	s_nop 0
	v_add_f32_e32 v147, 1.0, v147
	v_rcp_f32_e32 v165, v147
	v_pk_mul_f32 v[146:147], v[18:19], v[146:147] op_sel_hi:[1,0]
	v_pk_mul_f32 v[160:161], v[160:161], v[164:165]
	s_nop 0
	v_pk_mul_f32 v[146:147], v[146:147], v[160:161]
	v_cvt_pk_bf16_f32 v160, v148, v149
	v_cvt_pk_bf16_f32 v163, v146, v147
	v_add_co_u32_e32 v146, vcc, s6, v150
	v_cvt_pk_bf16_f32 v161, v152, v153
	s_nop 0
	v_addc_co_u32_e32 v147, vcc, 0, v151, vcc
	global_store_dwordx4 v[146:147], v[160:163], off
	ds_read2_b32 v[146:147], v158 offset0:160 offset1:176
	s_mov_b32 s6, 0xdc000
	s_waitcnt lgkmcnt(0)
	v_pk_mul_f32 v[148:149], v[44:45], v[146:147] op_sel_hi:[1,0]
	s_nop 0
	v_mul_f32_e32 v152, 0xbfb8aa3b, v148
	v_mul_f32_e32 v153, 0xbfb8aa3b, v149
	v_exp_f32_e32 v152, v152
	v_exp_f32_e32 v153, v153
	v_add_f32_e32 v152, 1.0, v152
	v_add_f32_e32 v153, 1.0, v153
	v_rcp_f32_e32 v152, v152
	v_rcp_f32_e32 v153, v153
	s_nop 0
	v_pk_mul_f32 v[148:149], v[148:149], v[152:153]
	v_pk_mul_f32 v[152:153], v[12:13], v[146:147] op_sel_hi:[1,0]
	s_nop 0
	v_pk_mul_f32 v[148:149], v[152:153], v[148:149]
	v_pk_mul_f32 v[152:153], v[46:47], v[146:147] op_sel_hi:[1,0]
	s_nop 0
	v_mul_f32_e32 v158, 0xbfb8aa3b, v152
	v_mul_f32_e32 v159, 0xbfb8aa3b, v153
	v_exp_f32_e32 v158, v158
	v_exp_f32_e32 v159, v159
	v_add_f32_e32 v158, 1.0, v158
	v_add_f32_e32 v159, 1.0, v159
	v_rcp_f32_e32 v158, v158
	v_rcp_f32_e32 v159, v159
	s_nop 0
	v_pk_mul_f32 v[152:153], v[152:153], v[158:159]
	v_pk_mul_f32 v[158:159], v[14:15], v[146:147] op_sel_hi:[1,0]
	s_nop 0
	v_pk_mul_f32 v[152:153], v[158:159], v[152:153]
	v_pk_mul_f32 v[158:159], v[40:41], v[146:147] op_sel_hi:[1,0]
	s_nop 0
	v_mul_f32_e32 v160, 0xbfb8aa3b, v158
	v_mul_f32_e32 v161, 0xbfb8aa3b, v159
	v_exp_f32_e32 v160, v160
	v_exp_f32_e32 v161, v161
	v_add_f32_e32 v160, 1.0, v160
	v_add_f32_e32 v161, 1.0, v161
	v_rcp_f32_e32 v160, v160
	v_rcp_f32_e32 v161, v161
	s_nop 0
	v_pk_mul_f32 v[158:159], v[158:159], v[160:161]
	v_pk_mul_f32 v[160:161], v[8:9], v[146:147] op_sel_hi:[1,0]
	s_nop 0
	v_pk_mul_f32 v[160:161], v[160:161], v[158:159]
	v_pk_mul_f32 v[158:159], v[42:43], v[146:147] op_sel_hi:[1,0]
	v_cvt_pk_bf16_f32 v160, v160, v161
	v_mul_f32_e32 v162, 0xbfb8aa3b, v158
	v_mul_f32_e32 v163, 0xbfb8aa3b, v159
	v_exp_f32_e32 v162, v162
	v_exp_f32_e32 v163, v163
	v_add_f32_e32 v162, 1.0, v162
	v_add_f32_e32 v163, 1.0, v163
	v_rcp_f32_e32 v162, v162
	v_rcp_f32_e32 v163, v163
	s_nop 0
	v_pk_mul_f32 v[158:159], v[158:159], v[162:163]
	v_pk_mul_f32 v[162:163], v[10:11], v[146:147] op_sel_hi:[1,0]
	v_mov_b32_e32 v146, v147
	v_pk_mul_f32 v[162:163], v[162:163], v[158:159]
	v_cvt_pk_bf16_f32 v158, v148, v149
	v_add_co_u32_e32 v148, vcc, s6, v150
	v_cvt_pk_bf16_f32 v159, v152, v153
	v_cvt_pk_bf16_f32 v161, v162, v163
	v_addc_co_u32_e32 v149, vcc, 0, v151, vcc
	global_store_dwordx4 v[148:149], v[158:161], off
	v_pk_mul_f32 v[148:149], v[36:37], v[146:147] op_sel_hi:[1,0]
	s_nop 0
	v_mul_f32_e32 v147, 0xbfb8aa3b, v148
	v_exp_f32_e32 v147, v147
	s_nop 0
	v_add_f32_e32 v147, 1.0, v147
	v_rcp_f32_e32 v152, v147
	v_mul_f32_e32 v147, 0xbfb8aa3b, v149
	v_exp_f32_e32 v147, v147
	s_nop 0
	v_add_f32_e32 v147, 1.0, v147
	v_rcp_f32_e32 v153, v147
	s_nop 0
	v_pk_mul_f32 v[148:149], v[148:149], v[152:153]
	v_pk_mul_f32 v[152:153], v[4:5], v[146:147] op_sel_hi:[1,0]
	s_nop 0
	v_pk_mul_f32 v[148:149], v[152:153], v[148:149]
	v_pk_mul_f32 v[152:153], v[38:39], v[146:147] op_sel_hi:[1,0]
	s_nop 0
	v_mul_f32_e32 v147, 0xbfb8aa3b, v152
	v_exp_f32_e32 v147, v147
	s_nop 0
	v_add_f32_e32 v147, 1.0, v147
	v_rcp_f32_e32 v158, v147
	v_mul_f32_e32 v147, 0xbfb8aa3b, v153
	v_exp_f32_e32 v147, v147
	s_nop 0
	v_add_f32_e32 v147, 1.0, v147
	v_rcp_f32_e32 v159, v147
	s_nop 0
	v_pk_mul_f32 v[152:153], v[152:153], v[158:159]
	v_pk_mul_f32 v[158:159], v[6:7], v[146:147] op_sel_hi:[1,0]
	s_nop 0
	v_pk_mul_f32 v[152:153], v[158:159], v[152:153]
	v_pk_mul_f32 v[158:159], v[32:33], v[146:147] op_sel_hi:[1,0]
	s_nop 0
	v_mul_f32_e32 v147, 0xbfb8aa3b, v158
	v_exp_f32_e32 v147, v147
	s_nop 0
	v_add_f32_e32 v147, 1.0, v147
	v_rcp_f32_e32 v160, v147
	v_mul_f32_e32 v147, 0xbfb8aa3b, v159
	v_exp_f32_e32 v147, v147
	s_nop 0
	v_add_f32_e32 v147, 1.0, v147
	v_rcp_f32_e32 v161, v147
	s_nop 0
	v_pk_mul_f32 v[158:159], v[158:159], v[160:161]
	v_pk_mul_f32 v[160:161], v[0:1], v[146:147] op_sel_hi:[1,0]
	s_nop 0
	v_pk_mul_f32 v[160:161], v[160:161], v[158:159]
	v_pk_mul_f32 v[158:159], v[34:35], v[146:147] op_sel_hi:[1,0]
	v_cvt_pk_bf16_f32 v160, v160, v161
	v_mul_f32_e32 v147, 0xbfb8aa3b, v158
	v_exp_f32_e32 v147, v147
	s_nop 0
	v_add_f32_e32 v147, 1.0, v147
	v_rcp_f32_e32 v162, v147
	v_mul_f32_e32 v147, 0xbfb8aa3b, v159
	v_exp_f32_e32 v147, v147
	s_nop 0
	v_add_f32_e32 v147, 1.0, v147
	v_rcp_f32_e32 v163, v147
	v_pk_mul_f32 v[146:147], v[2:3], v[146:147] op_sel_hi:[1,0]
	v_pk_mul_f32 v[158:159], v[158:159], v[162:163]
	s_nop 0
	v_pk_mul_f32 v[146:147], v[146:147], v[158:159]
	v_cvt_pk_bf16_f32 v158, v148, v149
	v_cvt_pk_bf16_f32 v161, v146, v147
	v_add_co_u32_e32 v146, vcc, 0xf2000, v150
	v_cvt_pk_bf16_f32 v159, v152, v153
	s_nop 0
	v_addc_co_u32_e32 v147, vcc, 0, v151, vcc
	s_andn2_b64 vcc, exec, s[44:45]
	global_store_dwordx4 v[146:147], v[158:161], off
	s_cbranch_vccz .LBB0_73
	s_mov_b64 s[46:47], s[50:51]
	s_andn2_b64 vcc, exec, s[42:43]
	s_mov_b64 s[50:51], s[46:47]
	s_cbranch_vccnz .LBB0_74

.LBB0_102:
	s_add_u32 s54, s54, 0x40080
	s_addc_u32 s55, s55, 0
	s_add_u32 s10, s58, 0x100
	v_mov_b32_e32 v0, 0
	s_addc_u32 s11, s59, 0
	s_mov_b32 s12, -2
	s_waitcnt lgkmcnt(0)
	v_mov_b32_e32 v1, v0
	v_mov_b32_e32 v2, v0
	v_mov_b32_e32 v3, v0
	v_mov_b32_e32 v4, v0
	v_mov_b32_e32 v5, v0
	v_mov_b32_e32 v6, v0
	v_mov_b32_e32 v7, v0
	v_mov_b32_e32 v12, v0
	v_mov_b32_e32 v13, v0
	v_mov_b32_e32 v14, v0
	v_mov_b32_e32 v15, v0
	v_mov_b32_e32 v20, v0
	v_mov_b32_e32 v21, v0
	v_mov_b32_e32 v22, v0
	v_mov_b32_e32 v23, v0
	v_mov_b32_e32 v28, v0
	v_mov_b32_e32 v29, v0
	v_mov_b32_e32 v30, v0
	v_mov_b32_e32 v31, v0
	v_mov_b32_e32 v36, v0
	v_mov_b32_e32 v37, v0
	v_mov_b32_e32 v38, v0
	v_mov_b32_e32 v39, v0
	v_mov_b32_e32 v44, v0
	v_mov_b32_e32 v45, v0
	v_mov_b32_e32 v46, v0
	v_mov_b32_e32 v47, v0
	v_mov_b32_e32 v52, v0
	v_mov_b32_e32 v53, v0
	v_mov_b32_e32 v54, v0
	v_mov_b32_e32 v55, v0
	v_mov_b32_e32 v8, v0
	v_mov_b32_e32 v9, v0
	v_mov_b32_e32 v10, v0
	v_mov_b32_e32 v11, v0
	v_mov_b32_e32 v16, v0
	v_mov_b32_e32 v17, v0
	v_mov_b32_e32 v18, v0
	v_mov_b32_e32 v19, v0
	v_mov_b32_e32 v24, v0
	v_mov_b32_e32 v25, v0
	v_mov_b32_e32 v26, v0
	v_mov_b32_e32 v27, v0
	v_mov_b32_e32 v32, v0
	v_mov_b32_e32 v33, v0
	v_mov_b32_e32 v34, v0
	v_mov_b32_e32 v35, v0
	v_mov_b32_e32 v40, v0
	v_mov_b32_e32 v41, v0
	v_mov_b32_e32 v42, v0
	v_mov_b32_e32 v43, v0
	v_mov_b32_e32 v48, v0
	v_mov_b32_e32 v49, v0
	v_mov_b32_e32 v50, v0
	v_mov_b32_e32 v51, v0
	v_mov_b32_e32 v56, v0
	v_mov_b32_e32 v57, v0
	v_mov_b32_e32 v58, v0
	v_mov_b32_e32 v59, v0
	v_mov_b32_e32 v60, v0
	v_mov_b32_e32 v61, v0
	v_mov_b32_e32 v62, v0
	v_mov_b32_e32 v63, v0
	v_mov_b32_e32 v64, v0
	v_mov_b32_e32 v65, v0
	v_mov_b32_e32 v66, v0
	v_mov_b32_e32 v67, v0
	v_mov_b32_e32 v68, v0
	v_mov_b32_e32 v69, v0
	v_mov_b32_e32 v70, v0
	v_mov_b32_e32 v71, v0
	v_mov_b32_e32 v72, v0
	v_mov_b32_e32 v73, v0
	v_mov_b32_e32 v74, v0
	v_mov_b32_e32 v75, v0
	v_mov_b32_e32 v76, v0
	v_mov_b32_e32 v77, v0
	v_mov_b32_e32 v78, v0
	v_mov_b32_e32 v79, v0
	v_mov_b32_e32 v92, v0
	v_mov_b32_e32 v93, v0
	v_mov_b32_e32 v94, v0
	v_mov_b32_e32 v95, v0
	v_mov_b32_e32 v100, v0
	v_mov_b32_e32 v101, v0
	v_mov_b32_e32 v102, v0
	v_mov_b32_e32 v103, v0
	v_mov_b32_e32 v112, v0
	v_mov_b32_e32 v113, v0
	v_mov_b32_e32 v114, v0
	v_mov_b32_e32 v115, v0
	v_mov_b32_e32 v116, v0
	v_mov_b32_e32 v117, v0
	v_mov_b32_e32 v118, v0
	v_mov_b32_e32 v119, v0
	v_mov_b32_e32 v80, v0
	v_mov_b32_e32 v81, v0
	v_mov_b32_e32 v82, v0
	v_mov_b32_e32 v83, v0
	v_mov_b32_e32 v84, v0
	v_mov_b32_e32 v85, v0
	v_mov_b32_e32 v86, v0
	v_mov_b32_e32 v87, v0
	v_mov_b32_e32 v88, v0
	v_mov_b32_e32 v89, v0
	v_mov_b32_e32 v90, v0
	v_mov_b32_e32 v91, v0
	v_mov_b32_e32 v96, v0
	v_mov_b32_e32 v97, v0
	v_mov_b32_e32 v98, v0
	v_mov_b32_e32 v99, v0
	v_mov_b32_e32 v104, v0
	v_mov_b32_e32 v105, v0
	v_mov_b32_e32 v106, v0
	v_mov_b32_e32 v107, v0
	v_mov_b32_e32 v108, v0
	v_mov_b32_e32 v109, v0
	v_mov_b32_e32 v110, v0
	v_mov_b32_e32 v111, v0
	v_mov_b32_e32 v120, v0
	v_mov_b32_e32 v121, v0
	v_mov_b32_e32 v122, v0
	v_mov_b32_e32 v123, v0
	v_mov_b32_e32 v124, v0
	v_mov_b32_e32 v125, v0
	v_mov_b32_e32 v126, v0
	v_mov_b32_e32 v127, v0
	v_add_u32_e32 v146, 0x10000, v206
	ds_read_b128 v[128:131], v146
	ds_read_b128 v[132:135], v146 offset:1024
	ds_read_b128 v[136:139], v146 offset:2048
	ds_read_b128 v[146:149], v146 offset:3072
.LBB0_103:
	s_add_u32 s6, s54, 0xfffc0080
	s_addc_u32 s19, s55, -1
	s_add_i32 s23, 0, 0x10000
	s_cmp_eq_u32 s12, 12
	s_cselect_b32 s69, s47, s19
	s_cselect_b32 s68, s46, s6
	s_cselect_b32 s59, s49, s11
	s_cselect_b32 s58, s48, s10
	v_lshl_add_u64 v[192:193], s[54:55], 0, v[158:159]
	s_add_i32 m0, s72, 0xc000
	ds_read_b128 v[162:165], v208
	ds_read_b128 v[166:169], v208 offset:1024
	ds_read_b128 v[170:173], v208 offset:2048
	ds_read_b128 v[174:177], v208 offset:3072
	ds_read_b128 v[178:181], v208 offset:4096
	ds_read_b128 v[182:185], v208 offset:5120
	ds_read_b128 v[194:197], v208 offset:6144
	ds_read_b128 v[210:213], v208 offset:7168
	global_load_lds_dwordx4 v[192:193], off
	v_lshl_add_u64 v[192:193], s[54:55], 0, v[160:161]
	s_add_i32 m0, s72, 0xe000
	s_nop 0
	global_load_lds_dwordx4 v[192:193], off
	s_waitcnt lgkmcnt(8)
	s_barrier
	s_setprio 1
	s_waitcnt lgkmcnt(7)
	v_mfma_f32_16x16x32_bf16 v[124:127], v[128:131], v[162:165], v[124:127]
	v_mfma_f32_16x16x32_bf16 v[120:123], v[136:139], v[162:165], v[120:123]
	s_waitcnt lgkmcnt(5)
	v_mfma_f32_16x16x32_bf16 v[108:111], v[128:131], v[170:173], v[108:111]
	v_mfma_f32_16x16x32_bf16 v[104:107], v[136:139], v[170:173], v[104:107]
	s_waitcnt lgkmcnt(3)
	v_mfma_f32_16x16x32_bf16 v[96:99], v[128:131], v[178:181], v[96:99]
	v_mfma_f32_16x16x32_bf16 v[88:91], v[136:139], v[178:181], v[88:91]
	s_waitcnt lgkmcnt(1)
	v_mfma_f32_16x16x32_bf16 v[84:87], v[128:131], v[194:197], v[84:87]
	v_mfma_f32_16x16x32_bf16 v[80:83], v[136:139], v[194:197], v[80:83]
	v_mfma_f32_16x16x32_bf16 v[124:127], v[132:135], v[166:169], v[124:127]
	v_mfma_f32_16x16x32_bf16 v[120:123], v[146:149], v[166:169], v[120:123]
	v_mfma_f32_16x16x32_bf16 v[108:111], v[132:135], v[174:177], v[108:111]
	v_mfma_f32_16x16x32_bf16 v[104:107], v[146:149], v[174:177], v[104:107]
	v_mfma_f32_16x16x32_bf16 v[96:99], v[132:135], v[182:185], v[96:99]
	v_mfma_f32_16x16x32_bf16 v[88:91], v[146:149], v[182:185], v[88:91]
	s_waitcnt lgkmcnt(0)
	v_mfma_f32_16x16x32_bf16 v[84:87], v[132:135], v[210:213], v[84:87]
	v_mfma_f32_16x16x32_bf16 v[80:83], v[146:149], v[210:213], v[80:83]
	s_setprio 0
	s_barrier
	s_add_i32 s6, 0, 0x14000
	v_add_u32_e32 v192, s6, v206
	s_add_i32 s19, s23, s71
	ds_read_b128 v[214:217], v192
	ds_read_b128 v[218:221], v192 offset:1024
	ds_read_b128 v[222:225], v192 offset:2048
	ds_read_b128 v[226:229], v192 offset:3072
	v_lshl_add_u64 v[192:193], s[58:59], 0, v[140:141]
	s_mov_b32 m0, s19
	v_lshl_add_u64 v[230:231], s[58:59], 0, v[150:151]
	global_load_lds_dwordx4 v[192:193], off
	s_add_i32 m0, s19, 0x2000
	s_nop 0
	global_load_lds_dwordx4 v[230:231], off
	s_barrier
	s_setprio 1
	s_waitcnt lgkmcnt(3)
	v_mfma_f32_16x16x32_bf16 v[116:119], v[214:217], v[162:165], v[116:119]
	s_waitcnt lgkmcnt(1)
	v_mfma_f32_16x16x32_bf16 v[112:115], v[222:225], v[162:165], v[112:115]
	v_mfma_f32_16x16x32_bf16 v[100:103], v[214:217], v[170:173], v[100:103]
	v_mfma_f32_16x16x32_bf16 v[92:95], v[222:225], v[170:173], v[92:95]
	v_mfma_f32_16x16x32_bf16 v[76:79], v[214:217], v[178:181], v[76:79]
	v_mfma_f32_16x16x32_bf16 v[72:75], v[222:225], v[178:181], v[72:75]
	v_mfma_f32_16x16x32_bf16 v[68:71], v[214:217], v[194:197], v[68:71]
	v_mfma_f32_16x16x32_bf16 v[64:67], v[222:225], v[194:197], v[64:67]
	v_mfma_f32_16x16x32_bf16 v[116:119], v[218:221], v[166:169], v[116:119]
	s_waitcnt lgkmcnt(0)
	v_mfma_f32_16x16x32_bf16 v[112:115], v[226:229], v[166:169], v[112:115]
	v_mfma_f32_16x16x32_bf16 v[100:103], v[218:221], v[174:177], v[100:103]
	v_mfma_f32_16x16x32_bf16 v[92:95], v[226:229], v[174:177], v[92:95]
	v_mfma_f32_16x16x32_bf16 v[76:79], v[218:221], v[182:185], v[76:79]
	v_mfma_f32_16x16x32_bf16 v[72:75], v[226:229], v[182:185], v[72:75]
	v_mfma_f32_16x16x32_bf16 v[68:71], v[218:221], v[210:213], v[68:71]
	v_mfma_f32_16x16x32_bf16 v[64:67], v[226:229], v[210:213], v[64:67]
	s_setprio 0
	s_mov_b32 m0, s72
	v_lshl_add_u64 v[232:233], s[68:69], 0, v[154:155]
	s_barrier
	ds_read_b128 v[162:165], v208 offset:16384
	ds_read_b128 v[166:169], v208 offset:17408
	ds_read_b128 v[170:173], v208 offset:18432
	ds_read_b128 v[174:177], v208 offset:19456
	ds_read_b128 v[178:181], v208 offset:20480
	ds_read_b128 v[182:185], v208 offset:21504
	ds_read_b128 v[194:197], v208 offset:22528
	ds_read_b128 v[210:213], v208 offset:23552
	global_load_lds_dwordx4 v[232:233], off
	v_lshl_add_u64 v[234:235], s[68:69], 0, v[152:153]
	s_mov_b32 m0, s73
	s_nop 0
	global_load_lds_dwordx4 v[234:235], off
	s_waitcnt vmcnt(10)
	s_barrier
	s_setprio 1
	s_waitcnt lgkmcnt(7)
	v_mfma_f32_16x16x32_bf16 v[60:63], v[128:131], v[162:165], v[60:63]
	v_mfma_f32_16x16x32_bf16 v[56:59], v[136:139], v[162:165], v[56:59]
	s_waitcnt lgkmcnt(5)
	v_mfma_f32_16x16x32_bf16 v[48:51], v[128:131], v[170:173], v[48:51]
	v_mfma_f32_16x16x32_bf16 v[40:43], v[136:139], v[170:173], v[40:43]
	s_waitcnt lgkmcnt(3)
	v_mfma_f32_16x16x32_bf16 v[32:35], v[128:131], v[178:181], v[32:35]
	v_mfma_f32_16x16x32_bf16 v[24:27], v[136:139], v[178:181], v[24:27]
	s_waitcnt lgkmcnt(1)
	v_mfma_f32_16x16x32_bf16 v[16:19], v[128:131], v[194:197], v[16:19]
	v_mfma_f32_16x16x32_bf16 v[8:11], v[136:139], v[194:197], v[8:11]
	v_mfma_f32_16x16x32_bf16 v[60:63], v[132:135], v[166:169], v[60:63]
	v_mfma_f32_16x16x32_bf16 v[56:59], v[146:149], v[166:169], v[56:59]
	v_mfma_f32_16x16x32_bf16 v[48:51], v[132:135], v[174:177], v[48:51]
	v_mfma_f32_16x16x32_bf16 v[40:43], v[146:149], v[174:177], v[40:43]
	v_mfma_f32_16x16x32_bf16 v[32:35], v[132:135], v[182:185], v[32:35]
	v_mfma_f32_16x16x32_bf16 v[24:27], v[146:149], v[182:185], v[24:27]
	s_waitcnt lgkmcnt(0)
	v_mfma_f32_16x16x32_bf16 v[16:19], v[132:135], v[210:213], v[16:19]
	v_mfma_f32_16x16x32_bf16 v[8:11], v[146:149], v[210:213], v[8:11]
	s_setprio 0
	s_barrier
	s_add_u32 s86, s58, 0x40000
	s_addc_u32 s87, s59, 0
	s_add_i32 s6, s6, s71
	v_lshl_add_u64 v[128:129], s[86:87], 0, v[140:141]
	s_mov_b32 m0, s6
	s_nop 0
	global_load_lds_dwordx4 v[128:129], off
	v_lshl_add_u64 v[128:129], s[86:87], 0, v[150:151]
	s_add_i32 m0, s6, 0x2000
	s_nop 0
	global_load_lds_dwordx4 v[128:129], off
	v_add_u32_e32 v146, 0x18000, v206
	ds_read_b128 v[128:131], v146
	ds_read_b128 v[132:135], v146 offset:1024
	ds_read_b128 v[136:139], v146 offset:2048
	ds_read_b128 v[146:149], v146 offset:3072
	s_waitcnt vmcnt(6)
	s_barrier
	s_setprio 1
	v_mfma_f32_16x16x32_bf16 v[52:55], v[214:217], v[162:165], v[52:55]
	v_mfma_f32_16x16x32_bf16 v[44:47], v[222:225], v[162:165], v[44:47]
	v_mfma_f32_16x16x32_bf16 v[36:39], v[214:217], v[170:173], v[36:39]
	v_mfma_f32_16x16x32_bf16 v[28:31], v[222:225], v[170:173], v[28:31]
	v_mfma_f32_16x16x32_bf16 v[20:23], v[214:217], v[178:181], v[20:23]
	v_mfma_f32_16x16x32_bf16 v[12:15], v[222:225], v[178:181], v[12:15]
	v_mfma_f32_16x16x32_bf16 v[4:7], v[214:217], v[194:197], v[4:7]
	v_mfma_f32_16x16x32_bf16 v[0:3], v[222:225], v[194:197], v[0:3]
	v_mfma_f32_16x16x32_bf16 v[52:55], v[218:221], v[166:169], v[52:55]
	v_mfma_f32_16x16x32_bf16 v[44:47], v[226:229], v[166:169], v[44:47]
	v_mfma_f32_16x16x32_bf16 v[36:39], v[218:221], v[174:177], v[36:39]
	v_mfma_f32_16x16x32_bf16 v[28:31], v[226:229], v[174:177], v[28:31]
	v_mfma_f32_16x16x32_bf16 v[20:23], v[218:221], v[182:185], v[20:23]
	v_mfma_f32_16x16x32_bf16 v[12:15], v[226:229], v[182:185], v[12:15]
	v_mfma_f32_16x16x32_bf16 v[4:7], v[218:221], v[210:213], v[4:7]
	v_mfma_f32_16x16x32_bf16 v[0:3], v[226:229], v[210:213], v[0:3]
	s_setprio 0
	s_add_i32 s6, 0, 0x18000
	s_barrier
	s_add_u32 s68, s68, 0x40000
	s_addc_u32 s69, s69, 0
	s_mov_b32 m0, s74
	v_lshl_add_u64 v[214:215], s[68:69], 0, v[154:155]
	ds_read_b128 v[162:165], v208 offset:32768
	ds_read_b128 v[166:169], v208 offset:33792
	ds_read_b128 v[170:173], v208 offset:34816
	ds_read_b128 v[174:177], v208 offset:35840
	ds_read_b128 v[178:181], v208 offset:36864
	ds_read_b128 v[182:185], v208 offset:37888
	ds_read_b128 v[194:197], v208 offset:38912
	ds_read_b128 v[210:213], v208 offset:39936
	global_load_lds_dwordx4 v[214:215], off
	v_lshl_add_u64 v[214:215], s[68:69], 0, v[152:153]
	s_mov_b32 m0, s75
	s_nop 0
	global_load_lds_dwordx4 v[214:215], off
	s_waitcnt lgkmcnt(8)
	s_barrier
	s_setprio 1
	s_waitcnt lgkmcnt(7)
	v_mfma_f32_16x16x32_bf16 v[124:127], v[128:131], v[162:165], v[124:127]
	v_mfma_f32_16x16x32_bf16 v[120:123], v[136:139], v[162:165], v[120:123]
	s_waitcnt lgkmcnt(5)
	v_mfma_f32_16x16x32_bf16 v[108:111], v[128:131], v[170:173], v[108:111]
	v_mfma_f32_16x16x32_bf16 v[104:107], v[136:139], v[170:173], v[104:107]
	s_waitcnt lgkmcnt(3)
	v_mfma_f32_16x16x32_bf16 v[96:99], v[128:131], v[178:181], v[96:99]
	v_mfma_f32_16x16x32_bf16 v[88:91], v[136:139], v[178:181], v[88:91]
	s_waitcnt lgkmcnt(1)
	v_mfma_f32_16x16x32_bf16 v[84:87], v[128:131], v[194:197], v[84:87]
	v_mfma_f32_16x16x32_bf16 v[80:83], v[136:139], v[194:197], v[80:83]
	v_mfma_f32_16x16x32_bf16 v[124:127], v[132:135], v[166:169], v[124:127]
	v_mfma_f32_16x16x32_bf16 v[120:123], v[146:149], v[166:169], v[120:123]
	v_mfma_f32_16x16x32_bf16 v[108:111], v[132:135], v[174:177], v[108:111]
	v_mfma_f32_16x16x32_bf16 v[104:107], v[146:149], v[174:177], v[104:107]
	v_mfma_f32_16x16x32_bf16 v[96:99], v[132:135], v[182:185], v[96:99]
	v_mfma_f32_16x16x32_bf16 v[88:91], v[146:149], v[182:185], v[88:91]
	s_waitcnt lgkmcnt(0)
	v_mfma_f32_16x16x32_bf16 v[84:87], v[132:135], v[210:213], v[84:87]
	v_mfma_f32_16x16x32_bf16 v[80:83], v[146:149], v[210:213], v[80:83]
	s_setprio 0
	s_barrier
	s_add_i32 s19, 0, 0x1c000
	s_add_i32 s6, s6, s71
	v_add_u32_e32 v209, s19, v206
	v_lshl_add_u64 v[192:193], v[192:193], 0, s[36:37]
	s_mov_b32 m0, s6
	ds_read_b128 v[214:217], v209
	ds_read_b128 v[218:221], v209 offset:1024
	ds_read_b128 v[222:225], v209 offset:2048
	ds_read_b128 v[226:229], v209 offset:3072
	global_load_lds_dwordx4 v[192:193], off
	v_lshl_add_u64 v[192:193], v[230:231], 0, s[36:37]
	s_add_i32 m0, s6, 0x2000
	s_nop 0
	global_load_lds_dwordx4 v[192:193], off
	s_barrier
	s_setprio 1
	s_waitcnt lgkmcnt(3)
	v_mfma_f32_16x16x32_bf16 v[116:119], v[214:217], v[162:165], v[116:119]
	s_waitcnt lgkmcnt(1)
	v_mfma_f32_16x16x32_bf16 v[112:115], v[222:225], v[162:165], v[112:115]
	v_mfma_f32_16x16x32_bf16 v[100:103], v[214:217], v[170:173], v[100:103]
	v_mfma_f32_16x16x32_bf16 v[92:95], v[222:225], v[170:173], v[92:95]
	v_mfma_f32_16x16x32_bf16 v[76:79], v[214:217], v[178:181], v[76:79]
	v_mfma_f32_16x16x32_bf16 v[72:75], v[222:225], v[178:181], v[72:75]
	v_mfma_f32_16x16x32_bf16 v[68:71], v[214:217], v[194:197], v[68:71]
	v_mfma_f32_16x16x32_bf16 v[64:67], v[222:225], v[194:197], v[64:67]
	v_mfma_f32_16x16x32_bf16 v[116:119], v[218:221], v[166:169], v[116:119]
	s_waitcnt lgkmcnt(0)
	v_mfma_f32_16x16x32_bf16 v[112:115], v[226:229], v[166:169], v[112:115]
	v_mfma_f32_16x16x32_bf16 v[100:103], v[218:221], v[174:177], v[100:103]
	v_mfma_f32_16x16x32_bf16 v[92:95], v[226:229], v[174:177], v[92:95]
	v_mfma_f32_16x16x32_bf16 v[76:79], v[218:221], v[182:185], v[76:79]
	v_mfma_f32_16x16x32_bf16 v[72:75], v[226:229], v[182:185], v[72:75]
	v_mfma_f32_16x16x32_bf16 v[68:71], v[218:221], v[210:213], v[68:71]
	v_mfma_f32_16x16x32_bf16 v[64:67], v[226:229], v[210:213], v[64:67]
	s_setprio 0
	s_mov_b32 m0, s80
	v_lshl_add_u64 v[192:193], v[232:233], 0, s[36:37]
	s_barrier
	ds_read_b128 v[162:165], v208 offset:49152
	ds_read_b128 v[166:169], v208 offset:50176
	ds_read_b128 v[170:173], v208 offset:51200
	ds_read_b128 v[174:177], v208 offset:52224
	ds_read_b128 v[178:181], v208 offset:53248
	ds_read_b128 v[182:185], v208 offset:54272
	ds_read_b128 v[194:197], v208 offset:55296
	ds_read_b128 v[210:213], v208 offset:56320
	global_load_lds_dwordx4 v[192:193], off
	v_lshl_add_u64 v[192:193], v[234:235], 0, s[36:37]
	s_mov_b32 m0, s81
	s_nop 0
	global_load_lds_dwordx4 v[192:193], off
	s_waitcnt vmcnt(10)
	s_barrier
	s_setprio 1
	s_waitcnt lgkmcnt(7)
	v_mfma_f32_16x16x32_bf16 v[60:63], v[128:131], v[162:165], v[60:63]
	v_mfma_f32_16x16x32_bf16 v[56:59], v[136:139], v[162:165], v[56:59]
	s_waitcnt lgkmcnt(5)
	v_mfma_f32_16x16x32_bf16 v[48:51], v[128:131], v[170:173], v[48:51]
	v_mfma_f32_16x16x32_bf16 v[40:43], v[136:139], v[170:173], v[40:43]
	s_waitcnt lgkmcnt(3)
	v_mfma_f32_16x16x32_bf16 v[32:35], v[128:131], v[178:181], v[32:35]
	v_mfma_f32_16x16x32_bf16 v[24:27], v[136:139], v[178:181], v[24:27]
	s_waitcnt lgkmcnt(1)
	v_mfma_f32_16x16x32_bf16 v[16:19], v[128:131], v[194:197], v[16:19]
	v_mfma_f32_16x16x32_bf16 v[8:11], v[136:139], v[194:197], v[8:11]
	v_mfma_f32_16x16x32_bf16 v[60:63], v[132:135], v[166:169], v[60:63]
	v_mfma_f32_16x16x32_bf16 v[56:59], v[146:149], v[166:169], v[56:59]
	v_mfma_f32_16x16x32_bf16 v[48:51], v[132:135], v[174:177], v[48:51]
	v_mfma_f32_16x16x32_bf16 v[40:43], v[146:149], v[174:177], v[40:43]
	v_mfma_f32_16x16x32_bf16 v[32:35], v[132:135], v[182:185], v[32:35]
	v_mfma_f32_16x16x32_bf16 v[24:27], v[146:149], v[182:185], v[24:27]
	s_waitcnt lgkmcnt(0)
	v_mfma_f32_16x16x32_bf16 v[16:19], v[132:135], v[210:213], v[16:19]
	v_mfma_f32_16x16x32_bf16 v[8:11], v[146:149], v[210:213], v[8:11]
	s_setprio 0
	s_barrier
	s_add_u32 s58, s58, 0x40080
	s_addc_u32 s59, s59, 0
	s_add_i32 s6, s19, s71
	v_lshl_add_u64 v[128:129], s[58:59], 0, v[140:141]
	s_mov_b32 m0, s6
	s_nop 0
	global_load_lds_dwordx4 v[128:129], off
	v_lshl_add_u64 v[128:129], s[58:59], 0, v[150:151]
	s_add_i32 m0, s6, 0x2000
	s_nop 0
	global_load_lds_dwordx4 v[128:129], off
	v_add_u32_e32 v146, 0x10000, v206
	ds_read_b128 v[128:131], v146
	ds_read_b128 v[132:135], v146 offset:1024
	ds_read_b128 v[136:139], v146 offset:2048
	ds_read_b128 v[146:149], v146 offset:3072
	s_waitcnt vmcnt(6)
	s_barrier
	s_setprio 1
	v_mfma_f32_16x16x32_bf16 v[52:55], v[214:217], v[162:165], v[52:55]
	v_mfma_f32_16x16x32_bf16 v[44:47], v[222:225], v[162:165], v[44:47]
	v_mfma_f32_16x16x32_bf16 v[36:39], v[214:217], v[170:173], v[36:39]
	v_mfma_f32_16x16x32_bf16 v[28:31], v[222:225], v[170:173], v[28:31]
	v_mfma_f32_16x16x32_bf16 v[20:23], v[214:217], v[178:181], v[20:23]
	v_mfma_f32_16x16x32_bf16 v[12:15], v[222:225], v[178:181], v[12:15]
	v_mfma_f32_16x16x32_bf16 v[4:7], v[214:217], v[194:197], v[4:7]
	v_mfma_f32_16x16x32_bf16 v[0:3], v[222:225], v[194:197], v[0:3]
	v_mfma_f32_16x16x32_bf16 v[52:55], v[218:221], v[166:169], v[52:55]
	v_mfma_f32_16x16x32_bf16 v[44:47], v[226:229], v[166:169], v[44:47]
	v_mfma_f32_16x16x32_bf16 v[36:39], v[218:221], v[174:177], v[36:39]
	v_mfma_f32_16x16x32_bf16 v[28:31], v[226:229], v[174:177], v[28:31]
	v_mfma_f32_16x16x32_bf16 v[20:23], v[218:221], v[182:185], v[20:23]
	v_mfma_f32_16x16x32_bf16 v[12:15], v[226:229], v[182:185], v[12:15]
	v_mfma_f32_16x16x32_bf16 v[4:7], v[218:221], v[210:213], v[4:7]
	v_mfma_f32_16x16x32_bf16 v[0:3], v[226:229], v[210:213], v[0:3]
	s_setprio 0
	s_add_i32 s12, s12, 2
	s_add_u32 s54, s54, 0x100
	s_addc_u32 s55, s55, 0
	s_add_u32 s10, s10, 0x100
	s_addc_u32 s11, s11, 0
	s_cmp_gt_u32 s12, 13
	s_barrier
	s_cbranch_scc0 .LBB0_103
	s_waitcnt lgkmcnt(0)
	s_ashr_i32 s51, s50, 31
	s_ashr_i32 s53, s52, 31
	s_lshl_b64 s[10:11], s[50:51], 13
	s_lshl_b64 s[50:51], s[52:53], 8
	s_add_u32 s10, s50, s10
	v_lshl_or_b32 v128, s85, 8, v207
	s_addc_u32 s11, s51, s11
	v_ashrrev_i32_e32 v129, 31, v128
	v_lshl_add_u64 v[168:169], s[10:11], 0, v[156:157]
	v_lshlrev_b64 v[170:171], 1, v[128:129]
	v_lshl_add_u64 v[174:175], s[26:27], 0, v[170:171]
	v_lshlrev_b64 v[172:173], 11, v[168:169]
	v_or_b32_e32 v166, 16, v168
	v_mov_b32_e32 v167, v169
	v_lshl_add_u64 v[128:129], v[174:175], 0, v[172:173]
	v_lshlrev_b64 v[176:177], 11, v[166:167]
	global_load_dwordx4 v[146:149], v[128:129], off
	global_load_dwordx4 v[182:185], v[128:129], off offset:256
	v_lshl_add_u64 v[128:129], v[174:175], 0, v[176:177]
	global_load_dwordx4 v[194:197], v[128:129], off
	global_load_dwordx4 v[210:213], v[128:129], off offset:256
	v_or_b32_e32 v164, 32, v168
	v_mov_b32_e32 v165, v169
	v_or_b32_e32 v162, 48, v168
	v_mov_b32_e32 v163, v169
	v_lshlrev_b64 v[180:181], 11, v[164:165]
	v_lshlrev_b64 v[178:179], 11, v[162:163]
	v_lshl_add_u64 v[128:129], v[174:175], 0, v[180:181]
	v_lshl_add_u64 v[130:131], v[174:175], 0, v[178:179]
	global_load_dwordx4 v[214:217], v[128:129], off
	global_load_dwordx4 v[136:139], v[128:129], off offset:256
	global_load_dwordx4 v[132:135], v[130:131], off
	s_nop 0
	global_load_dwordx4 v[128:131], v[130:131], off offset:256
	s_mov_b64 s[10:11], 0x90
	v_lshl_add_u64 v[172:173], s[28:29], 0, v[172:173]
	v_lshl_add_u64 v[172:173], v[172:173], 0, v[170:171]
	s_waitcnt vmcnt(0)
	v_lshlrev_b32_e32 v192, 16, v146
	v_and_b32_e32 v193, 0xffff0000, v146
	v_lshlrev_b32_e32 v218, 16, v148
	v_and_b32_e32 v219, 0xffff0000, v148
	v_lshlrev_b32_e32 v146, 16, v147
	v_and_b32_e32 v147, 0xffff0000, v147
	v_lshlrev_b32_e32 v148, 16, v149
	v_and_b32_e32 v149, 0xffff0000, v149
	v_lshlrev_b32_e32 v220, 16, v182
	v_and_b32_e32 v221, 0xffff0000, v182
	v_lshlrev_b32_e32 v222, 16, v184
	v_and_b32_e32 v223, 0xffff0000, v184
	v_lshlrev_b32_e32 v182, 16, v183
	v_and_b32_e32 v183, 0xffff0000, v183
	v_lshlrev_b32_e32 v184, 16, v185
	v_and_b32_e32 v185, 0xffff0000, v185
	v_pk_add_f32 v[124:125], v[124:125], v[192:193]
	v_pk_add_f32 v[126:127], v[126:127], v[146:147]
	v_pk_add_f32 v[122:123], v[122:123], v[148:149]
	v_pk_add_f32 v[116:117], v[116:117], v[220:221]
	v_pk_add_f32 v[146:147], v[112:113], v[222:223]
	v_pk_add_f32 v[118:119], v[118:119], v[182:183]
	v_pk_add_f32 v[148:149], v[114:115], v[184:185]
	v_lshlrev_b32_e32 v182, 16, v194
	v_and_b32_e32 v183, 0xffff0000, v194
	v_lshlrev_b32_e32 v184, 16, v196
	v_and_b32_e32 v185, 0xffff0000, v196
	v_lshlrev_b32_e32 v192, 16, v195
	v_and_b32_e32 v193, 0xffff0000, v195
	v_lshlrev_b32_e32 v194, 16, v197
	v_and_b32_e32 v195, 0xffff0000, v197
	v_pk_mul_f32 v[196:197], v[124:125], v[124:125]
	v_pk_add_f32 v[120:121], v[120:121], v[218:219]
	v_pk_mul_f32 v[218:219], v[126:127], v[126:127]
	v_cvt_pk_bf16_f32 v112, v124, v125
	v_cvt_pk_bf16_f32 v113, v126, v127
	v_pk_mul_f32 v[124:125], v[116:117], v[116:117]
	v_pk_mul_f32 v[126:127], v[118:119], v[118:119]
	v_pk_mul_f32 v[224:225], v[146:147], v[146:147]
	v_cvt_pk_bf16_f32 v116, v116, v117
	v_cvt_pk_bf16_f32 v117, v118, v119
	v_cvt_pk_bf16_f32 v118, v146, v147
	v_add_f32_e32 v146, v196, v197
	v_add_f32_e32 v146, v218, v146
	v_pk_mul_f32 v[220:221], v[120:121], v[120:121]
	v_add_f32_e32 v146, v219, v146
	v_add_f32_e32 v146, v220, v146
	v_pk_mul_f32 v[222:223], v[122:123], v[122:123]
	v_add_f32_e32 v146, v221, v146
	v_add_f32_e32 v146, v222, v146
	v_add_f32_e32 v146, v223, v146
	v_add_f32_e32 v124, v124, v146
	v_add_f32_e32 v124, v125, v124
	v_add_f32_e32 v124, v126, v124
	v_add_f32_e32 v124, v127, v124
	v_add_f32_e32 v124, v224, v124
	v_pk_mul_f32 v[226:227], v[148:149], v[148:149]
	v_add_f32_e32 v124, v225, v124
	v_add_f32_e32 v124, v226, v124
	v_add_f32_e32 v209, v227, v124
	v_lshlrev_b32_e32 v124, 16, v210
	v_and_b32_e32 v125, 0xffff0000, v210
	v_pk_add_f32 v[100:101], v[100:101], v[124:125]
	v_lshlrev_b32_e32 v124, 16, v212
	v_and_b32_e32 v125, 0xffff0000, v212
	v_pk_add_f32 v[124:125], v[92:93], v[124:125]
	v_lshlrev_b32_e32 v92, 16, v211
	v_and_b32_e32 v93, 0xffff0000, v211
	v_pk_add_f32 v[102:103], v[102:103], v[92:93]
	v_lshlrev_b32_e32 v92, 16, v213
	v_and_b32_e32 v93, 0xffff0000, v213
	v_pk_add_f32 v[126:127], v[94:95], v[92:93]
	v_lshlrev_b32_e32 v92, 16, v214
	v_and_b32_e32 v93, 0xffff0000, v214
	v_pk_add_f32 v[92:93], v[96:97], v[92:93]
	v_lshlrev_b32_e32 v96, 16, v217
	v_and_b32_e32 v97, 0xffff0000, v217
	v_lshlrev_b32_e32 v94, 16, v216
	v_and_b32_e32 v95, 0xffff0000, v216
	v_pk_add_f32 v[90:91], v[90:91], v[96:97]
	v_lshlrev_b32_e32 v96, 16, v136
	v_and_b32_e32 v97, 0xffff0000, v136
	v_pk_add_f32 v[88:89], v[88:89], v[94:95]
	v_lshlrev_b32_e32 v94, 16, v215
	v_and_b32_e32 v95, 0xffff0000, v215
	v_pk_add_f32 v[96:97], v[76:77], v[96:97]
	v_lshl_add_u64 v[76:77], v[168:169], 0, s[36:37]
	v_cvt_pk_bf16_f32 v114, v120, v121
	v_pk_add_f32 v[120:121], v[108:109], v[182:183]
	v_pk_add_f32 v[94:95], v[98:99], v[94:95]
	v_lshlrev_b64 v[182:183], 11, v[76:77]
	v_lshlrev_b32_e32 v98, 16, v138
	v_and_b32_e32 v99, 0xffff0000, v138
	v_pk_add_f32 v[108:109], v[104:105], v[184:185]
	v_lshl_add_u64 v[184:185], v[174:175], 0, v[182:183]
	v_pk_add_f32 v[98:99], v[72:73], v[98:99]
	v_lshlrev_b32_e32 v72, 16, v137
	v_and_b32_e32 v73, 0xffff0000, v137
	global_load_dwordx4 v[210:213], v[184:185], off
	global_load_dwordx4 v[218:221], v[184:185], off offset:256
	v_pk_add_f32 v[136:137], v[78:79], v[72:73]
	v_lshlrev_b32_e32 v72, 16, v139
	v_and_b32_e32 v73, 0xffff0000, v139
	v_pk_add_f32 v[138:139], v[74:75], v[72:73]
	v_lshlrev_b32_e32 v72, 16, v132
	v_and_b32_e32 v73, 0xffff0000, v132
	v_pk_add_f32 v[74:75], v[84:85], v[72:73]
	v_lshlrev_b32_e32 v72, 16, v134
	v_and_b32_e32 v73, 0xffff0000, v134
	v_pk_add_f32 v[78:79], v[80:81], v[72:73]
	v_lshlrev_b32_e32 v72, 16, v133
	v_and_b32_e32 v73, 0xffff0000, v133
	v_pk_add_f32 v[80:81], v[86:87], v[72:73]
	v_lshlrev_b32_e32 v72, 16, v135
	v_and_b32_e32 v73, 0xffff0000, v135
	v_pk_add_f32 v[82:83], v[82:83], v[72:73]
	v_lshl_add_u64 v[72:73], v[168:169], 0, s[10:11]
	v_lshlrev_b64 v[132:133], 11, v[72:73]
	v_lshl_add_u64 v[134:135], v[174:175], 0, v[132:133]
	v_lshlrev_b32_e32 v84, 16, v128
	v_and_b32_e32 v85, 0xffff0000, v128
	global_load_dwordx4 v[226:229], v[134:135], off
	global_load_dwordx4 v[234:237], v[134:135], off offset:256
	v_pk_add_f32 v[84:85], v[68:69], v[84:85]
	v_lshlrev_b32_e32 v68, 16, v130
	v_and_b32_e32 v69, 0xffff0000, v130
	v_pk_add_f32 v[86:87], v[64:65], v[68:69]
	v_lshlrev_b32_e32 v64, 16, v129
	v_and_b32_e32 v65, 0xffff0000, v129
	s_mov_b64 s[10:11], 0xa0
	v_pk_add_f32 v[128:129], v[70:71], v[64:65]
	v_lshl_add_u64 v[70:71], v[168:169], 0, s[10:11]
	s_mov_b64 s[10:11], 0xb0
	v_lshlrev_b32_e32 v64, 16, v131
	v_and_b32_e32 v65, 0xffff0000, v131
	v_lshlrev_b64 v[134:135], 11, v[70:71]
	v_lshl_add_u64 v[68:69], v[168:169], 0, s[10:11]
	v_pk_add_f32 v[130:131], v[66:67], v[64:65]
	v_lshl_add_u64 v[64:65], v[174:175], 0, v[134:135]
	v_lshlrev_b64 v[184:185], 11, v[68:69]
	global_load_dwordx4 v[238:241], v[64:65], off
	global_load_dwordx4 v[242:245], v[64:65], off offset:256
	v_lshl_add_u64 v[64:65], v[174:175], 0, v[184:185]
	global_load_dwordx4 v[246:249], v[64:65], off
	s_nop 0
	global_load_dwordx4 v[64:67], v[64:65], off offset:256
	v_cvt_pk_bf16_f32 v115, v122, v123
	v_cvt_pk_bf16_f32 v119, v148, v149
	v_pk_add_f32 v[110:111], v[110:111], v[192:193]
	v_pk_add_f32 v[122:123], v[106:107], v[194:195]
	global_store_dwordx4 v[172:173], v[112:115], off
	global_store_dwordx4 v[172:173], v[116:119], off offset:256
	v_cvt_pk_bf16_f32 v104, v120, v121
	v_lshl_add_u64 v[112:113], s[28:29], 0, v[176:177]
	v_cvt_pk_bf16_f32 v105, v110, v111
	v_cvt_pk_bf16_f32 v106, v108, v109
	v_cvt_pk_bf16_f32 v107, v122, v123
	v_lshl_add_u64 v[112:113], v[112:113], 0, v[170:171]
	v_cvt_pk_bf16_f32 v146, v100, v101
	v_cvt_pk_bf16_f32 v147, v102, v103
	v_cvt_pk_bf16_f32 v148, v124, v125
	v_cvt_pk_bf16_f32 v149, v126, v127
	global_store_dwordx4 v[112:113], v[104:107], off
	global_store_dwordx4 v[112:113], v[146:149], off offset:256
	v_cvt_pk_bf16_f32 v194, v92, v93
	v_lshl_add_u64 v[104:105], s[28:29], 0, v[180:181]
	v_cvt_pk_bf16_f32 v195, v94, v95
	v_cvt_pk_bf16_f32 v196, v88, v89
	v_cvt_pk_bf16_f32 v197, v90, v91
	v_lshl_add_u64 v[104:105], v[104:105], 0, v[170:171]
	v_cvt_pk_bf16_f32 v214, v96, v97
	v_cvt_pk_bf16_f32 v215, v136, v137
	v_cvt_pk_bf16_f32 v216, v98, v99
	v_cvt_pk_bf16_f32 v217, v138, v139
	global_store_dwordx4 v[104:105], v[194:197], off
	global_store_dwordx4 v[104:105], v[214:217], off offset:256
	v_lshl_add_u64 v[104:105], s[28:29], 0, v[178:179]
	v_cvt_pk_bf16_f32 v222, v74, v75
	v_cvt_pk_bf16_f32 v223, v80, v81
	v_cvt_pk_bf16_f32 v224, v78, v79
	v_cvt_pk_bf16_f32 v225, v82, v83
	v_lshl_add_u64 v[104:105], v[104:105], 0, v[170:171]
	v_cvt_pk_bf16_f32 v230, v84, v85
	v_cvt_pk_bf16_f32 v231, v128, v129
	v_cvt_pk_bf16_f32 v232, v86, v87
	v_cvt_pk_bf16_f32 v233, v130, v131
	global_store_dwordx4 v[104:105], v[222:225], off
	global_store_dwordx4 v[104:105], v[230:233], off offset:256
	s_waitcnt vmcnt(0)
	v_lshlrev_b32_e32 v104, 16, v210
	v_and_b32_e32 v105, 0xffff0000, v210
	v_pk_add_f32 v[60:61], v[60:61], v[104:105]
	v_lshlrev_b32_e32 v104, 16, v212
	v_and_b32_e32 v105, 0xffff0000, v212
	v_pk_add_f32 v[56:57], v[56:57], v[104:105]
	v_lshlrev_b32_e32 v104, 16, v211
	v_and_b32_e32 v105, 0xffff0000, v211
	v_pk_add_f32 v[62:63], v[62:63], v[104:105]
	v_lshlrev_b32_e32 v104, 16, v213
	v_and_b32_e32 v105, 0xffff0000, v213
	v_pk_add_f32 v[58:59], v[58:59], v[104:105]
	v_lshlrev_b32_e32 v104, 16, v218
	v_and_b32_e32 v105, 0xffff0000, v218
	v_pk_add_f32 v[52:53], v[52:53], v[104:105]
	v_lshlrev_b32_e32 v104, 16, v220
	v_and_b32_e32 v105, 0xffff0000, v220
	v_pk_add_f32 v[104:105], v[44:45], v[104:105]
	v_lshlrev_b32_e32 v44, 16, v219
	v_and_b32_e32 v45, 0xffff0000, v219
	v_pk_add_f32 v[54:55], v[54:55], v[44:45]
	v_lshlrev_b32_e32 v44, 16, v221
	v_and_b32_e32 v45, 0xffff0000, v221
	v_pk_add_f32 v[106:107], v[46:47], v[44:45]
	v_lshlrev_b32_e32 v44, 16, v226
	v_and_b32_e32 v45, 0xffff0000, v226
	v_pk_add_f32 v[44:45], v[48:49], v[44:45]
	v_lshlrev_b32_e32 v48, 16, v229
	v_and_b32_e32 v49, 0xffff0000, v229
	v_pk_add_f32 v[42:43], v[42:43], v[48:49]
	v_lshlrev_b32_e32 v48, 16, v234
	v_and_b32_e32 v49, 0xffff0000, v234
	v_pk_add_f32 v[36:37], v[36:37], v[48:49]
	v_lshlrev_b32_e32 v48, 16, v236
	v_and_b32_e32 v49, 0xffff0000, v236
	v_lshlrev_b32_e32 v46, 16, v228
	v_and_b32_e32 v47, 0xffff0000, v228
	v_pk_add_f32 v[48:49], v[28:29], v[48:49]
	v_lshlrev_b32_e32 v28, 16, v235
	v_and_b32_e32 v29, 0xffff0000, v235
	v_pk_add_f32 v[40:41], v[40:41], v[46:47]
	v_lshlrev_b32_e32 v46, 16, v227
	v_and_b32_e32 v47, 0xffff0000, v227
	v_pk_add_f32 v[38:39], v[38:39], v[28:29]
	v_lshlrev_b32_e32 v28, 16, v237
	v_and_b32_e32 v29, 0xffff0000, v237
	v_pk_add_f32 v[46:47], v[50:51], v[46:47]
	v_pk_add_f32 v[50:51], v[30:31], v[28:29]
	v_lshlrev_b32_e32 v28, 16, v238
	v_and_b32_e32 v29, 0xffff0000, v238
	v_lshlrev_b32_e32 v180, 16, v64
	v_and_b32_e32 v181, 0xffff0000, v64
	v_pk_add_f32 v[28:29], v[32:33], v[28:29]
	v_lshlrev_b32_e32 v32, 16, v241
	v_and_b32_e32 v33, 0xffff0000, v241
	v_pk_add_f32 v[4:5], v[4:5], v[180:181]
	v_lshlrev_b32_e32 v180, 16, v66
	v_and_b32_e32 v181, 0xffff0000, v66
	v_pk_add_f32 v[26:27], v[26:27], v[32:33]
	v_lshlrev_b32_e32 v32, 16, v242
	v_and_b32_e32 v33, 0xffff0000, v242
	v_pk_add_f32 v[0:1], v[0:1], v[180:181]
	v_lshl_add_u64 v[180:181], s[28:29], 0, v[182:183]
	v_cvt_pk_bf16_f32 v112, v60, v61
	v_cvt_pk_bf16_f32 v113, v62, v63
	v_cvt_pk_bf16_f32 v114, v56, v57
	v_cvt_pk_bf16_f32 v115, v58, v59
	v_pk_add_f32 v[20:21], v[20:21], v[32:33]
	v_lshlrev_b32_e32 v32, 16, v244
	v_and_b32_e32 v33, 0xffff0000, v244
	v_lshl_add_u64 v[180:181], v[180:181], 0, v[170:171]
	v_cvt_pk_bf16_f32 v116, v52, v53
	v_cvt_pk_bf16_f32 v117, v54, v55
	v_cvt_pk_bf16_f32 v118, v104, v105
	v_cvt_pk_bf16_f32 v119, v106, v107
	v_lshlrev_b32_e32 v30, 16, v240
	v_and_b32_e32 v31, 0xffff0000, v240
	v_pk_add_f32 v[32:33], v[12:13], v[32:33]
	v_lshlrev_b32_e32 v12, 16, v243
	v_and_b32_e32 v13, 0xffff0000, v243
	global_store_dwordx4 v[180:181], v[112:115], off
	global_store_dwordx4 v[180:181], v[116:119], off offset:256
	v_cvt_pk_bf16_f32 v146, v44, v45
	v_lshl_add_u64 v[112:113], s[28:29], 0, v[132:133]
	v_cvt_pk_bf16_f32 v147, v46, v47
	v_cvt_pk_bf16_f32 v148, v40, v41
	v_cvt_pk_bf16_f32 v149, v42, v43
	v_pk_add_f32 v[24:25], v[24:25], v[30:31]
	v_lshlrev_b32_e32 v30, 16, v239
	v_and_b32_e32 v31, 0xffff0000, v239
	v_pk_add_f32 v[22:23], v[22:23], v[12:13]
	v_lshlrev_b32_e32 v12, 16, v245
	v_and_b32_e32 v13, 0xffff0000, v245
	v_lshl_add_u64 v[112:113], v[112:113], 0, v[170:171]
	v_cvt_pk_bf16_f32 v172, v36, v37
	v_cvt_pk_bf16_f32 v173, v38, v39
	v_cvt_pk_bf16_f32 v174, v48, v49
	v_cvt_pk_bf16_f32 v175, v50, v51
	v_pk_add_f32 v[30:31], v[34:35], v[30:31]
	v_pk_add_f32 v[34:35], v[14:15], v[12:13]
	v_lshlrev_b32_e32 v12, 16, v246
	v_and_b32_e32 v13, 0xffff0000, v246
	v_lshlrev_b32_e32 v14, 16, v248
	v_and_b32_e32 v15, 0xffff0000, v248
	global_store_dwordx4 v[112:113], v[146:149], off
	global_store_dwordx4 v[112:113], v[172:175], off offset:256
	v_lshl_add_u64 v[112:113], s[28:29], 0, v[134:135]
	v_cvt_pk_bf16_f32 v176, v28, v29
	v_cvt_pk_bf16_f32 v177, v30, v31
	v_cvt_pk_bf16_f32 v178, v24, v25
	v_cvt_pk_bf16_f32 v179, v26, v27
	v_pk_add_f32 v[12:13], v[16:17], v[12:13]
	v_pk_add_f32 v[8:9], v[8:9], v[14:15]
	v_lshlrev_b32_e32 v14, 16, v247
	v_and_b32_e32 v15, 0xffff0000, v247
	v_lshlrev_b32_e32 v16, 16, v249
	v_and_b32_e32 v17, 0xffff0000, v249
	v_lshlrev_b32_e32 v64, 16, v65
	v_and_b32_e32 v65, 0xffff0000, v65
	v_lshl_add_u64 v[112:113], v[112:113], 0, v[170:171]
	v_cvt_pk_bf16_f32 v194, v20, v21
	v_cvt_pk_bf16_f32 v195, v22, v23
	v_cvt_pk_bf16_f32 v196, v32, v33
	v_cvt_pk_bf16_f32 v197, v34, v35
	v_pk_add_f32 v[14:15], v[18:19], v[14:15]
	v_pk_add_f32 v[10:11], v[10:11], v[16:17]
	v_pk_add_f32 v[6:7], v[6:7], v[64:65]
	v_lshlrev_b32_e32 v64, 16, v67
	v_and_b32_e32 v65, 0xffff0000, v67
	global_store_dwordx4 v[112:113], v[176:179], off
	global_store_dwordx4 v[112:113], v[194:197], off offset:256
	v_lshl_add_u64 v[112:113], s[28:29], 0, v[184:185]
	v_cvt_pk_bf16_f32 v16, v12, v13
	v_cvt_pk_bf16_f32 v17, v14, v15
	v_cvt_pk_bf16_f32 v18, v8, v9
	v_cvt_pk_bf16_f32 v19, v10, v11
	v_pk_add_f32 v[2:3], v[2:3], v[64:65]
	v_lshl_add_u64 v[112:113], v[112:113], 0, v[170:171]
	v_cvt_pk_bf16_f32 v64, v4, v5
	v_cvt_pk_bf16_f32 v65, v6, v7
	v_cvt_pk_bf16_f32 v66, v0, v1
	v_cvt_pk_bf16_f32 v67, v2, v3
	global_store_dwordx4 v[112:113], v[16:19], off
	global_store_dwordx4 v[112:113], v[64:67], off offset:256
	s_lshl_b32 s10, s85, 2
	v_and_b32_e32 v17, 64, v188
	v_xor_b32_e32 v16, 16, v188
	v_add_u32_e32 v17, 64, v17
	v_cmp_lt_i32_e32 vcc, v16, v17
	v_xor_b32_e32 v18, 32, v188
	s_ashr_i32 s11, s10, 31
	v_cndmask_b32_e32 v16, v188, v16, vcc
	v_lshlrev_b32_e32 v16, 2, v16
	ds_bpermute_b32 v19, v16, v209
	v_cmp_lt_i32_e32 vcc, v18, v17
	s_lshl_b64 s[10:11], s[10:11], 2
	s_add_u32 s50, s83, s10
	v_cndmask_b32_e32 v17, v188, v18, vcc
	v_lshlrev_b32_e32 v17, 2, v17
	s_waitcnt lgkmcnt(0)
	v_add_f32_e32 v18, v209, v19
	ds_bpermute_b32 v19, v17, v18
	s_addc_u32 s51, s84, s11
	s_and_saveexec_b64 s[52:53], s[42:43]
	s_cbranch_execz .LBB0_106
	s_waitcnt lgkmcnt(0)
	v_add_f32_e32 v64, v18, v19
	v_lshlrev_b64 v[18:19], 6, v[168:169]
	v_lshl_add_u64 v[18:19], s[50:51], 0, v[18:19]
	global_store_dword v[18:19], v64, off

.LBB0_191:
	s_add_u32 s29, s54, 0x100
	s_addc_u32 s31, s55, 0
	s_add_u32 s10, s26, 0x40080
	s_addc_u32 s11, s27, 0
	v_lshl_add_u64 v[152:153], s[10:11], 0, v[138:139]
	v_lshl_add_u64 v[154:155], s[10:11], 0, v[150:151]
	s_mov_b32 s10, -2
	s_mov_b64 s[54:55], 0
	v_add_u32_e32 v169, 0x10000, v156
	ds_read_b128 v[146:149], v169
	ds_read_b128 v[170:173], v169 offset:1024
	ds_read_b128 v[174:177], v169 offset:2048
	ds_read_b128 v[178:181], v169 offset:3072
.LBB0_192:
	s_add_u32 s6, s26, s54
	s_addc_u32 s11, s27, s55
	s_add_u32 s6, s6, 0x100
	s_addc_u32 s11, s11, 0
	s_add_u32 s12, s29, s54
	s_addc_u32 s19, s31, s55
	s_add_i32 s23, 0, 0x10000
	s_cmpk_eq_i32 s54, 0x700
	s_cselect_b32 s69, s53, s11
	s_cselect_b32 s68, s52, s6
	s_cselect_b32 s59, s49, s19
	s_cselect_b32 s58, s48, s12
	v_lshl_add_u64 v[230:231], v[152:153], 0, s[54:55]
	s_add_i32 m0, s72, 0xc000
	ds_read_b128 v[182:185], v168
	ds_read_b128 v[194:197], v168 offset:1024
	ds_read_b128 v[206:209], v168 offset:2048
	ds_read_b128 v[210:213], v168 offset:3072
	ds_read_b128 v[214:217], v168 offset:4096
	ds_read_b128 v[218:221], v168 offset:5120
	ds_read_b128 v[222:225], v168 offset:6144
	ds_read_b128 v[226:229], v168 offset:7168
	global_load_lds_dwordx4 v[230:231], off
	v_lshl_add_u64 v[230:231], v[154:155], 0, s[54:55]
	s_add_i32 m0, s72, 0xe000
	s_nop 0
	global_load_lds_dwordx4 v[230:231], off
	s_waitcnt lgkmcnt(8)
	s_barrier
	s_setprio 1
	s_waitcnt lgkmcnt(7)
	v_mfma_f32_16x16x32_bf16 v[16:19], v[146:149], v[182:185], v[16:19]
	v_mfma_f32_16x16x32_bf16 v[20:23], v[174:177], v[182:185], v[20:23]
	s_waitcnt lgkmcnt(5)
	v_mfma_f32_16x16x32_bf16 v[40:43], v[146:149], v[206:209], v[40:43]
	v_mfma_f32_16x16x32_bf16 v[32:35], v[174:177], v[206:209], v[32:35]
	s_waitcnt lgkmcnt(3)
	v_mfma_f32_16x16x32_bf16 v[64:67], v[146:149], v[214:217], v[64:67]
	v_mfma_f32_16x16x32_bf16 v[56:59], v[174:177], v[214:217], v[56:59]
	s_waitcnt lgkmcnt(1)
	v_mfma_f32_16x16x32_bf16 v[88:91], v[146:149], v[222:225], v[88:91]
	v_mfma_f32_16x16x32_bf16 v[80:83], v[174:177], v[222:225], v[80:83]
	v_mfma_f32_16x16x32_bf16 v[16:19], v[170:173], v[194:197], v[16:19]
	v_mfma_f32_16x16x32_bf16 v[20:23], v[178:181], v[194:197], v[20:23]
	v_mfma_f32_16x16x32_bf16 v[40:43], v[170:173], v[210:213], v[40:43]
	v_mfma_f32_16x16x32_bf16 v[32:35], v[178:181], v[210:213], v[32:35]
	v_mfma_f32_16x16x32_bf16 v[64:67], v[170:173], v[218:221], v[64:67]
	v_mfma_f32_16x16x32_bf16 v[56:59], v[178:181], v[218:221], v[56:59]
	s_waitcnt lgkmcnt(0)
	v_mfma_f32_16x16x32_bf16 v[88:91], v[170:173], v[226:229], v[88:91]
	v_mfma_f32_16x16x32_bf16 v[80:83], v[178:181], v[226:229], v[80:83]
	s_setprio 0
	s_barrier
	s_add_i32 s6, 0, 0x14000
	s_add_i32 s11, s23, s71
	v_add_u32_e32 v169, s6, v156
	v_lshl_add_u64 v[246:247], s[58:59], 0, v[130:131]
	s_mov_b32 m0, s11
	ds_read_b128 v[230:233], v169
	ds_read_b128 v[234:237], v169 offset:1024
	ds_read_b128 v[238:241], v169 offset:2048
	ds_read_b128 v[242:245], v169 offset:3072
	global_load_lds_dwordx4 v[246:247], off
	v_lshl_add_u64 v[248:249], s[58:59], 0, v[134:135]
	s_add_i32 m0, s11, 0x2000
	s_nop 0
	global_load_lds_dwordx4 v[248:249], off
	s_barrier
	s_setprio 1
	s_waitcnt lgkmcnt(3)
	v_mfma_f32_16x16x32_bf16 v[0:3], v[230:233], v[182:185], v[0:3]
	s_waitcnt lgkmcnt(1)
	v_mfma_f32_16x16x32_bf16 v[4:7], v[238:241], v[182:185], v[4:7]
	v_mfma_f32_16x16x32_bf16 v[8:11], v[230:233], v[206:209], v[8:11]
	v_mfma_f32_16x16x32_bf16 v[12:15], v[238:241], v[206:209], v[12:15]
	v_mfma_f32_16x16x32_bf16 v[24:27], v[230:233], v[214:217], v[24:27]
	v_mfma_f32_16x16x32_bf16 v[28:31], v[238:241], v[214:217], v[28:31]
	v_mfma_f32_16x16x32_bf16 v[48:51], v[230:233], v[222:225], v[48:51]
	v_mfma_f32_16x16x32_bf16 v[52:55], v[238:241], v[222:225], v[52:55]
	v_mfma_f32_16x16x32_bf16 v[0:3], v[234:237], v[194:197], v[0:3]
	s_waitcnt lgkmcnt(0)
	v_mfma_f32_16x16x32_bf16 v[4:7], v[242:245], v[194:197], v[4:7]
	v_mfma_f32_16x16x32_bf16 v[8:11], v[234:237], v[210:213], v[8:11]
	v_mfma_f32_16x16x32_bf16 v[12:15], v[242:245], v[210:213], v[12:15]
	v_mfma_f32_16x16x32_bf16 v[24:27], v[234:237], v[218:221], v[24:27]
	v_mfma_f32_16x16x32_bf16 v[28:31], v[242:245], v[218:221], v[28:31]
	v_mfma_f32_16x16x32_bf16 v[48:51], v[234:237], v[226:229], v[48:51]
	v_mfma_f32_16x16x32_bf16 v[52:55], v[242:245], v[226:229], v[52:55]
	s_setprio 0
	s_mov_b32 m0, s72
	v_lshl_add_u64 v[250:251], s[68:69], 0, v[128:129]
	s_barrier
	ds_read_b128 v[182:185], v168 offset:16384
	ds_read_b128 v[194:197], v168 offset:17408
	ds_read_b128 v[206:209], v168 offset:18432
	ds_read_b128 v[210:213], v168 offset:19456
	ds_read_b128 v[214:217], v168 offset:20480
	ds_read_b128 v[218:221], v168 offset:21504
	ds_read_b128 v[222:225], v168 offset:22528
	ds_read_b128 v[226:229], v168 offset:23552
	global_load_lds_dwordx4 v[250:251], off
	v_lshl_add_u64 v[192:193], s[68:69], 0, v[132:133]
	s_mov_b32 m0, s73
	s_nop 0
	global_load_lds_dwordx4 v[192:193], off
	s_waitcnt vmcnt(10)
	s_barrier
	s_setprio 1
	s_waitcnt lgkmcnt(7)
	v_mfma_f32_16x16x32_bf16 v[76:79], v[146:149], v[182:185], v[76:79]
	v_mfma_f32_16x16x32_bf16 v[72:75], v[174:177], v[182:185], v[72:75]
	s_waitcnt lgkmcnt(5)
	v_mfma_f32_16x16x32_bf16 v[100:103], v[146:149], v[206:209], v[100:103]
	v_mfma_f32_16x16x32_bf16 v[96:99], v[174:177], v[206:209], v[96:99]
	s_waitcnt lgkmcnt(3)
	v_mfma_f32_16x16x32_bf16 v[116:119], v[146:149], v[214:217], v[116:119]
	v_mfma_f32_16x16x32_bf16 v[112:115], v[174:177], v[214:217], v[112:115]
	s_waitcnt lgkmcnt(1)
	v_mfma_f32_16x16x32_bf16 v[124:127], v[146:149], v[222:225], v[124:127]
	v_mfma_f32_16x16x32_bf16 v[120:123], v[174:177], v[222:225], v[120:123]
	v_mfma_f32_16x16x32_bf16 v[76:79], v[170:173], v[194:197], v[76:79]
	v_mfma_f32_16x16x32_bf16 v[72:75], v[178:181], v[194:197], v[72:75]
	v_mfma_f32_16x16x32_bf16 v[100:103], v[170:173], v[210:213], v[100:103]
	v_mfma_f32_16x16x32_bf16 v[96:99], v[178:181], v[210:213], v[96:99]
	v_mfma_f32_16x16x32_bf16 v[116:119], v[170:173], v[218:221], v[116:119]
	v_mfma_f32_16x16x32_bf16 v[112:115], v[178:181], v[218:221], v[112:115]
	s_waitcnt lgkmcnt(0)
	v_mfma_f32_16x16x32_bf16 v[124:127], v[170:173], v[226:229], v[124:127]
	v_mfma_f32_16x16x32_bf16 v[120:123], v[178:181], v[226:229], v[120:123]
	s_setprio 0
	s_barrier
	s_add_u32 s88, s58, 0x40000
	s_addc_u32 s89, s59, 0
	s_add_i32 s6, s6, s71
	v_lshl_add_u64 v[146:147], s[88:89], 0, v[130:131]
	s_mov_b32 m0, s6
	s_nop 0
	global_load_lds_dwordx4 v[146:147], off
	v_lshl_add_u64 v[146:147], s[88:89], 0, v[134:135]
	s_add_i32 m0, s6, 0x2000
	s_nop 0
	global_load_lds_dwordx4 v[146:147], off
	v_add_u32_e32 v169, 0x18000, v156
	ds_read_b128 v[146:149], v169
	ds_read_b128 v[170:173], v169 offset:1024
	ds_read_b128 v[174:177], v169 offset:2048
	ds_read_b128 v[178:181], v169 offset:3072
	s_waitcnt vmcnt(6)
	s_barrier
	s_setprio 1
	v_mfma_f32_16x16x32_bf16 v[36:39], v[230:233], v[182:185], v[36:39]
	v_mfma_f32_16x16x32_bf16 v[44:47], v[238:241], v[182:185], v[44:47]
	v_mfma_f32_16x16x32_bf16 v[60:63], v[230:233], v[206:209], v[60:63]
	v_mfma_f32_16x16x32_bf16 v[68:71], v[238:241], v[206:209], v[68:71]
	v_mfma_f32_16x16x32_bf16 v[84:87], v[230:233], v[214:217], v[84:87]
	v_mfma_f32_16x16x32_bf16 v[92:95], v[238:241], v[214:217], v[92:95]
	v_mfma_f32_16x16x32_bf16 v[108:111], v[230:233], v[222:225], v[108:111]
	v_mfma_f32_16x16x32_bf16 v[104:107], v[238:241], v[222:225], v[104:107]
	v_mfma_f32_16x16x32_bf16 v[36:39], v[234:237], v[194:197], v[36:39]
	v_mfma_f32_16x16x32_bf16 v[44:47], v[242:245], v[194:197], v[44:47]
	v_mfma_f32_16x16x32_bf16 v[60:63], v[234:237], v[210:213], v[60:63]
	v_mfma_f32_16x16x32_bf16 v[68:71], v[242:245], v[210:213], v[68:71]
	v_mfma_f32_16x16x32_bf16 v[84:87], v[234:237], v[218:221], v[84:87]
	v_mfma_f32_16x16x32_bf16 v[92:95], v[242:245], v[218:221], v[92:95]
	v_mfma_f32_16x16x32_bf16 v[108:111], v[234:237], v[226:229], v[108:111]
	v_mfma_f32_16x16x32_bf16 v[104:107], v[242:245], v[226:229], v[104:107]
	s_setprio 0
	s_add_i32 s6, 0, 0x18000
	s_barrier
	s_add_u32 s68, s68, 0x40000
	s_addc_u32 s69, s69, 0
	s_mov_b32 m0, s74
	v_lshl_add_u64 v[230:231], s[68:69], 0, v[128:129]
	ds_read_b128 v[182:185], v168 offset:32768
	ds_read_b128 v[194:197], v168 offset:33792
	ds_read_b128 v[206:209], v168 offset:34816
	ds_read_b128 v[210:213], v168 offset:35840
	ds_read_b128 v[214:217], v168 offset:36864
	ds_read_b128 v[218:221], v168 offset:37888
	ds_read_b128 v[222:225], v168 offset:38912
	ds_read_b128 v[226:229], v168 offset:39936
	global_load_lds_dwordx4 v[230:231], off
	v_lshl_add_u64 v[230:231], s[68:69], 0, v[132:133]
	s_mov_b32 m0, s75
	s_nop 0
	global_load_lds_dwordx4 v[230:231], off
	s_waitcnt lgkmcnt(8)
	s_barrier
	s_setprio 1
	s_waitcnt lgkmcnt(7)
	v_mfma_f32_16x16x32_bf16 v[16:19], v[146:149], v[182:185], v[16:19]
	v_mfma_f32_16x16x32_bf16 v[20:23], v[174:177], v[182:185], v[20:23]
	s_waitcnt lgkmcnt(5)
	v_mfma_f32_16x16x32_bf16 v[40:43], v[146:149], v[206:209], v[40:43]
	v_mfma_f32_16x16x32_bf16 v[32:35], v[174:177], v[206:209], v[32:35]
	s_waitcnt lgkmcnt(3)
	v_mfma_f32_16x16x32_bf16 v[64:67], v[146:149], v[214:217], v[64:67]
	v_mfma_f32_16x16x32_bf16 v[56:59], v[174:177], v[214:217], v[56:59]
	s_waitcnt lgkmcnt(1)
	v_mfma_f32_16x16x32_bf16 v[88:91], v[146:149], v[222:225], v[88:91]
	v_mfma_f32_16x16x32_bf16 v[80:83], v[174:177], v[222:225], v[80:83]
	v_mfma_f32_16x16x32_bf16 v[16:19], v[170:173], v[194:197], v[16:19]
	v_mfma_f32_16x16x32_bf16 v[20:23], v[178:181], v[194:197], v[20:23]
	v_mfma_f32_16x16x32_bf16 v[40:43], v[170:173], v[210:213], v[40:43]
	v_mfma_f32_16x16x32_bf16 v[32:35], v[178:181], v[210:213], v[32:35]
	v_mfma_f32_16x16x32_bf16 v[64:67], v[170:173], v[218:221], v[64:67]
	v_mfma_f32_16x16x32_bf16 v[56:59], v[178:181], v[218:221], v[56:59]
	s_waitcnt lgkmcnt(0)
	v_mfma_f32_16x16x32_bf16 v[88:91], v[170:173], v[226:229], v[88:91]
	v_mfma_f32_16x16x32_bf16 v[80:83], v[178:181], v[226:229], v[80:83]
	s_setprio 0
	s_barrier
	s_add_i32 s11, 0, 0x1c000
	s_add_i32 s6, s6, s71
	v_add_u32_e32 v169, s11, v156
	v_lshl_add_u64 v[246:247], v[246:247], 0, s[36:37]
	s_mov_b32 m0, s6
	ds_read_b128 v[230:233], v169
	ds_read_b128 v[234:237], v169 offset:1024
	ds_read_b128 v[238:241], v169 offset:2048
	ds_read_b128 v[242:245], v169 offset:3072
	global_load_lds_dwordx4 v[246:247], off
	v_lshl_add_u64 v[246:247], v[248:249], 0, s[36:37]
	s_add_i32 m0, s6, 0x2000
	s_nop 0
	global_load_lds_dwordx4 v[246:247], off
	s_barrier
	s_setprio 1
	s_waitcnt lgkmcnt(3)
	v_mfma_f32_16x16x32_bf16 v[0:3], v[230:233], v[182:185], v[0:3]
	s_waitcnt lgkmcnt(1)
	v_mfma_f32_16x16x32_bf16 v[4:7], v[238:241], v[182:185], v[4:7]
	v_mfma_f32_16x16x32_bf16 v[8:11], v[230:233], v[206:209], v[8:11]
	v_mfma_f32_16x16x32_bf16 v[12:15], v[238:241], v[206:209], v[12:15]
	v_mfma_f32_16x16x32_bf16 v[24:27], v[230:233], v[214:217], v[24:27]
	v_mfma_f32_16x16x32_bf16 v[28:31], v[238:241], v[214:217], v[28:31]
	v_mfma_f32_16x16x32_bf16 v[48:51], v[230:233], v[222:225], v[48:51]
	v_mfma_f32_16x16x32_bf16 v[52:55], v[238:241], v[222:225], v[52:55]
	v_mfma_f32_16x16x32_bf16 v[0:3], v[234:237], v[194:197], v[0:3]
	s_waitcnt lgkmcnt(0)
	v_mfma_f32_16x16x32_bf16 v[4:7], v[242:245], v[194:197], v[4:7]
	v_mfma_f32_16x16x32_bf16 v[8:11], v[234:237], v[210:213], v[8:11]
	v_mfma_f32_16x16x32_bf16 v[12:15], v[242:245], v[210:213], v[12:15]
	v_mfma_f32_16x16x32_bf16 v[24:27], v[234:237], v[218:221], v[24:27]
	v_mfma_f32_16x16x32_bf16 v[28:31], v[242:245], v[218:221], v[28:31]
	v_mfma_f32_16x16x32_bf16 v[48:51], v[234:237], v[226:229], v[48:51]
	v_mfma_f32_16x16x32_bf16 v[52:55], v[242:245], v[226:229], v[52:55]
	s_setprio 0
	s_mov_b32 m0, s82
	v_lshl_add_u64 v[246:247], v[250:251], 0, s[36:37]
	s_barrier
	ds_read_b128 v[182:185], v168 offset:49152
	ds_read_b128 v[194:197], v168 offset:50176
	ds_read_b128 v[206:209], v168 offset:51200
	ds_read_b128 v[210:213], v168 offset:52224
	ds_read_b128 v[214:217], v168 offset:53248
	ds_read_b128 v[218:221], v168 offset:54272
	ds_read_b128 v[222:225], v168 offset:55296
	ds_read_b128 v[226:229], v168 offset:56320
	global_load_lds_dwordx4 v[246:247], off
	v_lshl_add_u64 v[192:193], v[192:193], 0, s[36:37]
	s_mov_b32 m0, s83
	s_nop 0
	global_load_lds_dwordx4 v[192:193], off
	s_waitcnt vmcnt(10)
	s_barrier
	s_setprio 1
	s_waitcnt lgkmcnt(7)
	v_mfma_f32_16x16x32_bf16 v[76:79], v[146:149], v[182:185], v[76:79]
	v_mfma_f32_16x16x32_bf16 v[72:75], v[174:177], v[182:185], v[72:75]
	s_waitcnt lgkmcnt(5)
	v_mfma_f32_16x16x32_bf16 v[100:103], v[146:149], v[206:209], v[100:103]
	v_mfma_f32_16x16x32_bf16 v[96:99], v[174:177], v[206:209], v[96:99]
	s_waitcnt lgkmcnt(3)
	v_mfma_f32_16x16x32_bf16 v[116:119], v[146:149], v[214:217], v[116:119]
	v_mfma_f32_16x16x32_bf16 v[112:115], v[174:177], v[214:217], v[112:115]
	s_waitcnt lgkmcnt(1)
	v_mfma_f32_16x16x32_bf16 v[124:127], v[146:149], v[222:225], v[124:127]
	v_mfma_f32_16x16x32_bf16 v[120:123], v[174:177], v[222:225], v[120:123]
	v_mfma_f32_16x16x32_bf16 v[76:79], v[170:173], v[194:197], v[76:79]
	v_mfma_f32_16x16x32_bf16 v[72:75], v[178:181], v[194:197], v[72:75]
	v_mfma_f32_16x16x32_bf16 v[100:103], v[170:173], v[210:213], v[100:103]
	v_mfma_f32_16x16x32_bf16 v[96:99], v[178:181], v[210:213], v[96:99]
	v_mfma_f32_16x16x32_bf16 v[116:119], v[170:173], v[218:221], v[116:119]
	v_mfma_f32_16x16x32_bf16 v[112:115], v[178:181], v[218:221], v[112:115]
	s_waitcnt lgkmcnt(0)
	v_mfma_f32_16x16x32_bf16 v[124:127], v[170:173], v[226:229], v[124:127]
	v_mfma_f32_16x16x32_bf16 v[120:123], v[178:181], v[226:229], v[120:123]
	s_setprio 0
	s_barrier
	s_add_u32 s58, s58, 0x40080
	s_addc_u32 s59, s59, 0
	s_add_i32 s6, s11, s71
	v_lshl_add_u64 v[146:147], s[58:59], 0, v[130:131]
	s_mov_b32 m0, s6
	s_nop 0
	global_load_lds_dwordx4 v[146:147], off
	v_lshl_add_u64 v[146:147], s[58:59], 0, v[134:135]
	s_add_i32 m0, s6, 0x2000
	s_nop 0
	global_load_lds_dwordx4 v[146:147], off
	v_add_u32_e32 v169, 0x10000, v156
	ds_read_b128 v[146:149], v169
	ds_read_b128 v[170:173], v169 offset:1024
	ds_read_b128 v[174:177], v169 offset:2048
	ds_read_b128 v[178:181], v169 offset:3072
	s_waitcnt vmcnt(6)
	s_barrier
	s_setprio 1
	v_mfma_f32_16x16x32_bf16 v[36:39], v[230:233], v[182:185], v[36:39]
	v_mfma_f32_16x16x32_bf16 v[44:47], v[238:241], v[182:185], v[44:47]
	v_mfma_f32_16x16x32_bf16 v[60:63], v[230:233], v[206:209], v[60:63]
	v_mfma_f32_16x16x32_bf16 v[68:71], v[238:241], v[206:209], v[68:71]
	v_mfma_f32_16x16x32_bf16 v[84:87], v[230:233], v[214:217], v[84:87]
	v_mfma_f32_16x16x32_bf16 v[92:95], v[238:241], v[214:217], v[92:95]
	v_mfma_f32_16x16x32_bf16 v[108:111], v[230:233], v[222:225], v[108:111]
	v_mfma_f32_16x16x32_bf16 v[104:107], v[238:241], v[222:225], v[104:107]
	v_mfma_f32_16x16x32_bf16 v[36:39], v[234:237], v[194:197], v[36:39]
	v_mfma_f32_16x16x32_bf16 v[44:47], v[242:245], v[194:197], v[44:47]
	v_mfma_f32_16x16x32_bf16 v[60:63], v[234:237], v[210:213], v[60:63]
	v_mfma_f32_16x16x32_bf16 v[68:71], v[242:245], v[210:213], v[68:71]
	v_mfma_f32_16x16x32_bf16 v[84:87], v[234:237], v[218:221], v[84:87]
	v_mfma_f32_16x16x32_bf16 v[92:95], v[242:245], v[218:221], v[92:95]
	v_mfma_f32_16x16x32_bf16 v[108:111], v[234:237], v[226:229], v[108:111]
	v_mfma_f32_16x16x32_bf16 v[104:107], v[242:245], v[226:229], v[104:107]
	s_setprio 0
	s_add_i32 s10, s10, 2
	s_add_u32 s54, s54, 0x100
	s_addc_u32 s55, s55, 0
	s_cmp_gt_u32 s10, 13
	s_barrier
	s_cbranch_scc0 .LBB0_192
	s_waitcnt lgkmcnt(0)
	s_lshl_b32 s6, s84, 10
	v_add_u32_e32 v154, s6, v167
	ds_read_b32 v148, v154
	s_mov_b32 s6, 0xff61b1e6
	v_and_b32_e32 v147, 64, v188
	v_xor_b32_e32 v146, 16, v188
	v_add_u32_e32 v147, 64, v147
	s_waitcnt lgkmcnt(0)
	v_mul_f32_e32 v174, v16, v148
	v_mul_f32_e32 v16, v17, v148
	v_max3_f32 v17, v174, s6, v16
	v_mul_f32_e32 v18, v18, v148
	v_mul_f32_e32 v19, v19, v148
	v_max3_f32 v17, v17, v18, v19
	v_mul_f32_e32 v20, v20, v148
	v_mul_f32_e32 v21, v21, v148
	v_max3_f32 v17, v17, v20, v21
	v_mul_f32_e32 v22, v22, v148
	v_mul_f32_e32 v23, v23, v148
	v_max3_f32 v17, v17, v22, v23
	v_mul_f32_e32 v0, v0, v148
	v_mul_f32_e32 v1, v1, v148
	v_max3_f32 v17, v17, v0, v1
	v_mul_f32_e32 v2, v2, v148
	v_mul_f32_e32 v3, v3, v148
	v_cmp_lt_i32_e32 vcc, v146, v147
	v_max3_f32 v17, v17, v2, v3
	v_mul_f32_e32 v4, v4, v148
	v_mul_f32_e32 v5, v5, v148
	v_cndmask_b32_e32 v146, v188, v146, vcc
	v_max3_f32 v17, v17, v4, v5
	v_mul_f32_e32 v6, v6, v148
	v_mul_f32_e32 v7, v7, v148
	v_lshlrev_b32_e32 v152, 2, v146
	v_max3_f32 v17, v17, v6, v7
	ds_bpermute_b32 v146, v152, v17
	v_xor_b32_e32 v148, 32, v188
	v_cmp_lt_i32_e32 vcc, v148, v147
	s_waitcnt lgkmcnt(0)
	v_max_f32_e32 v146, v146, v146
	v_cndmask_b32_e32 v147, v188, v148, vcc
	v_lshlrev_b32_e32 v153, 2, v147
	v_max_f32_e32 v17, v17, v146
	ds_bpermute_b32 v155, v153, v17
	s_and_saveexec_b64 s[54:55], s[42:43]
	s_cbranch_execz .LBB0_195
	s_waitcnt lgkmcnt(0)
	v_max_f32_e32 v146, v155, v155
	v_max_f32_e32 v17, v17, v17
	v_max_f32_e32 v17, v17, v146
	v_add_u32_e32 v146, s85, v157
	ds_write_b32 v146, v17

.LBB0_247:
	s_ashr_i32 s35, s34, 31
	s_lshl_b64 s[10:11], s[34:35], 19
	v_cmp_lt_i64_e32 vcc, s[46:47], v[142:143]
	s_add_u32 s46, s26, s10
	s_addc_u32 s47, s27, s11
	s_and_b64 s[10:11], vcc, exec
	s_cselect_b32 s10, s47, s53
	s_cselect_b32 s11, s46, s52
	s_ashr_i32 s39, s38, 31
	s_lshl_b64 s[48:49], s[38:39], 19
	s_add_u32 s48, s33, s48
	s_addc_u32 s49, s41, s49
	s_and_b64 s[58:59], vcc, exec
	s_cselect_b32 s12, s49, s55
	s_cselect_b32 s35, s48, s54
	s_add_u32 s52, s52, 0x40080
	s_addc_u32 s53, s53, 0
	s_add_u32 s39, s54, 0x100
	v_mov_b32_e32 v0, 0
	s_addc_u32 s51, s55, 0
	s_mov_b32 s82, -2
	s_waitcnt lgkmcnt(0)
	v_mov_b32_e32 v1, v0
	v_mov_b32_e32 v2, v0
	v_mov_b32_e32 v3, v0
	v_mov_b32_e32 v4, v0
	v_mov_b32_e32 v5, v0
	v_mov_b32_e32 v6, v0
	v_mov_b32_e32 v7, v0
	v_mov_b32_e32 v12, v0
	v_mov_b32_e32 v13, v0
	v_mov_b32_e32 v14, v0
	v_mov_b32_e32 v15, v0
	v_mov_b32_e32 v20, v0
	v_mov_b32_e32 v21, v0
	v_mov_b32_e32 v22, v0
	v_mov_b32_e32 v23, v0
	v_mov_b32_e32 v28, v0
	v_mov_b32_e32 v29, v0
	v_mov_b32_e32 v30, v0
	v_mov_b32_e32 v31, v0
	v_mov_b32_e32 v36, v0
	v_mov_b32_e32 v37, v0
	v_mov_b32_e32 v38, v0
	v_mov_b32_e32 v39, v0
	v_mov_b32_e32 v44, v0
	v_mov_b32_e32 v45, v0
	v_mov_b32_e32 v46, v0
	v_mov_b32_e32 v47, v0
	v_mov_b32_e32 v52, v0
	v_mov_b32_e32 v53, v0
	v_mov_b32_e32 v54, v0
	v_mov_b32_e32 v55, v0
	v_mov_b32_e32 v8, v0
	v_mov_b32_e32 v9, v0
	v_mov_b32_e32 v10, v0
	v_mov_b32_e32 v11, v0
	v_mov_b32_e32 v16, v0
	v_mov_b32_e32 v17, v0
	v_mov_b32_e32 v18, v0
	v_mov_b32_e32 v19, v0
	v_mov_b32_e32 v24, v0
	v_mov_b32_e32 v25, v0
	v_mov_b32_e32 v26, v0
	v_mov_b32_e32 v27, v0
	v_mov_b32_e32 v32, v0
	v_mov_b32_e32 v33, v0
	v_mov_b32_e32 v34, v0
	v_mov_b32_e32 v35, v0
	v_mov_b32_e32 v40, v0
	v_mov_b32_e32 v41, v0
	v_mov_b32_e32 v42, v0
	v_mov_b32_e32 v43, v0
	v_mov_b32_e32 v48, v0
	v_mov_b32_e32 v49, v0
	v_mov_b32_e32 v50, v0
	v_mov_b32_e32 v51, v0
	v_mov_b32_e32 v56, v0
	v_mov_b32_e32 v57, v0
	v_mov_b32_e32 v58, v0
	v_mov_b32_e32 v59, v0
	v_mov_b32_e32 v60, v0
	v_mov_b32_e32 v61, v0
	v_mov_b32_e32 v62, v0
	v_mov_b32_e32 v63, v0
	v_mov_b32_e32 v64, v0
	v_mov_b32_e32 v65, v0
	v_mov_b32_e32 v66, v0
	v_mov_b32_e32 v67, v0
	v_mov_b32_e32 v68, v0
	v_mov_b32_e32 v69, v0
	v_mov_b32_e32 v70, v0
	v_mov_b32_e32 v71, v0
	v_mov_b32_e32 v72, v0
	v_mov_b32_e32 v73, v0
	v_mov_b32_e32 v74, v0
	v_mov_b32_e32 v75, v0
	v_mov_b32_e32 v76, v0
	v_mov_b32_e32 v77, v0
	v_mov_b32_e32 v78, v0
	v_mov_b32_e32 v79, v0
	v_mov_b32_e32 v92, v0
	v_mov_b32_e32 v93, v0
	v_mov_b32_e32 v94, v0
	v_mov_b32_e32 v95, v0
	v_mov_b32_e32 v100, v0
	v_mov_b32_e32 v101, v0
	v_mov_b32_e32 v102, v0
	v_mov_b32_e32 v103, v0
	v_mov_b32_e32 v112, v0
	v_mov_b32_e32 v113, v0
	v_mov_b32_e32 v114, v0
	v_mov_b32_e32 v115, v0
	v_mov_b32_e32 v116, v0
	v_mov_b32_e32 v117, v0
	v_mov_b32_e32 v118, v0
	v_mov_b32_e32 v119, v0
	v_mov_b32_e32 v80, v0
	v_mov_b32_e32 v81, v0
	v_mov_b32_e32 v82, v0
	v_mov_b32_e32 v83, v0
	v_mov_b32_e32 v84, v0
	v_mov_b32_e32 v85, v0
	v_mov_b32_e32 v86, v0
	v_mov_b32_e32 v87, v0
	v_mov_b32_e32 v88, v0
	v_mov_b32_e32 v89, v0
	v_mov_b32_e32 v90, v0
	v_mov_b32_e32 v91, v0
	v_mov_b32_e32 v96, v0
	v_mov_b32_e32 v97, v0
	v_mov_b32_e32 v98, v0
	v_mov_b32_e32 v99, v0
	v_mov_b32_e32 v104, v0
	v_mov_b32_e32 v105, v0
	v_mov_b32_e32 v106, v0
	v_mov_b32_e32 v107, v0
	v_mov_b32_e32 v108, v0
	v_mov_b32_e32 v109, v0
	v_mov_b32_e32 v110, v0
	v_mov_b32_e32 v111, v0
	v_mov_b32_e32 v120, v0
	v_mov_b32_e32 v121, v0
	v_mov_b32_e32 v122, v0
	v_mov_b32_e32 v123, v0
	v_mov_b32_e32 v124, v0
	v_mov_b32_e32 v125, v0
	v_mov_b32_e32 v126, v0
	v_mov_b32_e32 v127, v0
	v_add_u32_e32 v146, 0x10000, v206
	ds_read_b128 v[128:131], v146
	ds_read_b128 v[132:135], v146 offset:1024
	ds_read_b128 v[136:139], v146 offset:2048
	ds_read_b128 v[146:149], v146 offset:3072
.LBB0_248:
	s_add_u32 s6, s52, 0xfffc0080
	s_addc_u32 s19, s53, -1
	s_add_i32 s23, 0, 0x10000
	s_cmp_eq_u32 s82, 12
	s_cselect_b32 s59, s10, s19
	s_cselect_b32 s58, s11, s6
	s_cselect_b32 s55, s12, s51
	s_cselect_b32 s54, s35, s39
	v_lshl_add_u64 v[214:215], s[52:53], 0, v[158:159]
	s_add_i32 m0, s68, 0xc000
	ds_read_b128 v[162:165], v208
	ds_read_b128 v[166:169], v208 offset:1024
	ds_read_b128 v[170:173], v208 offset:2048
	ds_read_b128 v[174:177], v208 offset:3072
	ds_read_b128 v[178:181], v208 offset:4096
	ds_read_b128 v[182:185], v208 offset:5120
	ds_read_b128 v[194:197], v208 offset:6144
	ds_read_b128 v[210:213], v208 offset:7168
	global_load_lds_dwordx4 v[214:215], off
	v_lshl_add_u64 v[214:215], s[52:53], 0, v[160:161]
	s_add_i32 m0, s68, 0xe000
	s_nop 0
	global_load_lds_dwordx4 v[214:215], off
	s_waitcnt lgkmcnt(8)
	s_barrier
	s_setprio 1
	s_waitcnt lgkmcnt(7)
	v_mfma_f32_16x16x32_bf16 v[124:127], v[128:131], v[162:165], v[124:127]
	v_mfma_f32_16x16x32_bf16 v[120:123], v[136:139], v[162:165], v[120:123]
	s_waitcnt lgkmcnt(5)
	v_mfma_f32_16x16x32_bf16 v[108:111], v[128:131], v[170:173], v[108:111]
	v_mfma_f32_16x16x32_bf16 v[104:107], v[136:139], v[170:173], v[104:107]
	s_waitcnt lgkmcnt(3)
	v_mfma_f32_16x16x32_bf16 v[96:99], v[128:131], v[178:181], v[96:99]
	v_mfma_f32_16x16x32_bf16 v[88:91], v[136:139], v[178:181], v[88:91]
	s_waitcnt lgkmcnt(1)
	v_mfma_f32_16x16x32_bf16 v[84:87], v[128:131], v[194:197], v[84:87]
	v_mfma_f32_16x16x32_bf16 v[80:83], v[136:139], v[194:197], v[80:83]
	v_mfma_f32_16x16x32_bf16 v[124:127], v[132:135], v[166:169], v[124:127]
	v_mfma_f32_16x16x32_bf16 v[120:123], v[146:149], v[166:169], v[120:123]
	v_mfma_f32_16x16x32_bf16 v[108:111], v[132:135], v[174:177], v[108:111]
	v_mfma_f32_16x16x32_bf16 v[104:107], v[146:149], v[174:177], v[104:107]
	v_mfma_f32_16x16x32_bf16 v[96:99], v[132:135], v[182:185], v[96:99]
	v_mfma_f32_16x16x32_bf16 v[88:91], v[146:149], v[182:185], v[88:91]
	s_waitcnt lgkmcnt(0)
	v_mfma_f32_16x16x32_bf16 v[84:87], v[132:135], v[210:213], v[84:87]
	v_mfma_f32_16x16x32_bf16 v[80:83], v[146:149], v[210:213], v[80:83]
	s_setprio 0
	s_barrier
	s_add_i32 s6, 0, 0x14000
	s_add_i32 s19, s23, s57
	v_add_u32_e32 v192, s6, v206
	v_lshl_add_u64 v[230:231], s[54:55], 0, v[140:141]
	s_mov_b32 m0, s19
	ds_read_b128 v[214:217], v192
	ds_read_b128 v[218:221], v192 offset:1024
	ds_read_b128 v[222:225], v192 offset:2048
	ds_read_b128 v[226:229], v192 offset:3072
	global_load_lds_dwordx4 v[230:231], off
	v_lshl_add_u64 v[232:233], s[54:55], 0, v[150:151]
	s_add_i32 m0, s19, 0x2000
	s_nop 0
	global_load_lds_dwordx4 v[232:233], off
	s_barrier
	s_setprio 1
	s_waitcnt lgkmcnt(3)
	v_mfma_f32_16x16x32_bf16 v[116:119], v[214:217], v[162:165], v[116:119]
	s_waitcnt lgkmcnt(1)
	v_mfma_f32_16x16x32_bf16 v[112:115], v[222:225], v[162:165], v[112:115]
	v_mfma_f32_16x16x32_bf16 v[100:103], v[214:217], v[170:173], v[100:103]
	v_mfma_f32_16x16x32_bf16 v[92:95], v[222:225], v[170:173], v[92:95]
	v_mfma_f32_16x16x32_bf16 v[76:79], v[214:217], v[178:181], v[76:79]
	v_mfma_f32_16x16x32_bf16 v[72:75], v[222:225], v[178:181], v[72:75]
	v_mfma_f32_16x16x32_bf16 v[68:71], v[214:217], v[194:197], v[68:71]
	v_mfma_f32_16x16x32_bf16 v[64:67], v[222:225], v[194:197], v[64:67]
	v_mfma_f32_16x16x32_bf16 v[116:119], v[218:221], v[166:169], v[116:119]
	s_waitcnt lgkmcnt(0)
	v_mfma_f32_16x16x32_bf16 v[112:115], v[226:229], v[166:169], v[112:115]
	v_mfma_f32_16x16x32_bf16 v[100:103], v[218:221], v[174:177], v[100:103]
	v_mfma_f32_16x16x32_bf16 v[92:95], v[226:229], v[174:177], v[92:95]
	v_mfma_f32_16x16x32_bf16 v[76:79], v[218:221], v[182:185], v[76:79]
	v_mfma_f32_16x16x32_bf16 v[72:75], v[226:229], v[182:185], v[72:75]
	v_mfma_f32_16x16x32_bf16 v[68:71], v[218:221], v[210:213], v[68:71]
	v_mfma_f32_16x16x32_bf16 v[64:67], v[226:229], v[210:213], v[64:67]
	s_setprio 0
	s_mov_b32 m0, s68
	v_lshl_add_u64 v[234:235], s[58:59], 0, v[154:155]
	s_barrier
	ds_read_b128 v[162:165], v208 offset:16384
	ds_read_b128 v[166:169], v208 offset:17408
	ds_read_b128 v[170:173], v208 offset:18432
	ds_read_b128 v[174:177], v208 offset:19456
	ds_read_b128 v[178:181], v208 offset:20480
	ds_read_b128 v[182:185], v208 offset:21504
	ds_read_b128 v[194:197], v208 offset:22528
	ds_read_b128 v[210:213], v208 offset:23552
	global_load_lds_dwordx4 v[234:235], off
	v_lshl_add_u64 v[236:237], s[58:59], 0, v[152:153]
	s_mov_b32 m0, s69
	s_nop 0
	global_load_lds_dwordx4 v[236:237], off
	s_waitcnt vmcnt(10)
	s_barrier
	s_setprio 1
	s_waitcnt lgkmcnt(7)
	v_mfma_f32_16x16x32_bf16 v[60:63], v[128:131], v[162:165], v[60:63]
	v_mfma_f32_16x16x32_bf16 v[56:59], v[136:139], v[162:165], v[56:59]
	s_waitcnt lgkmcnt(5)
	v_mfma_f32_16x16x32_bf16 v[48:51], v[128:131], v[170:173], v[48:51]
	v_mfma_f32_16x16x32_bf16 v[40:43], v[136:139], v[170:173], v[40:43]
	s_waitcnt lgkmcnt(3)
	v_mfma_f32_16x16x32_bf16 v[32:35], v[128:131], v[178:181], v[32:35]
	v_mfma_f32_16x16x32_bf16 v[24:27], v[136:139], v[178:181], v[24:27]
	s_waitcnt lgkmcnt(1)
	v_mfma_f32_16x16x32_bf16 v[16:19], v[128:131], v[194:197], v[16:19]
	v_mfma_f32_16x16x32_bf16 v[8:11], v[136:139], v[194:197], v[8:11]
	v_mfma_f32_16x16x32_bf16 v[60:63], v[132:135], v[166:169], v[60:63]
	v_mfma_f32_16x16x32_bf16 v[56:59], v[146:149], v[166:169], v[56:59]
	v_mfma_f32_16x16x32_bf16 v[48:51], v[132:135], v[174:177], v[48:51]
	v_mfma_f32_16x16x32_bf16 v[40:43], v[146:149], v[174:177], v[40:43]
	v_mfma_f32_16x16x32_bf16 v[32:35], v[132:135], v[182:185], v[32:35]
	v_mfma_f32_16x16x32_bf16 v[24:27], v[146:149], v[182:185], v[24:27]
	s_waitcnt lgkmcnt(0)
	v_mfma_f32_16x16x32_bf16 v[16:19], v[132:135], v[210:213], v[16:19]
	v_mfma_f32_16x16x32_bf16 v[8:11], v[146:149], v[210:213], v[8:11]
	s_setprio 0
	s_barrier
	s_add_u32 s84, s54, 0x40000
	s_addc_u32 s85, s55, 0
	s_add_i32 s6, s6, s57
	v_lshl_add_u64 v[128:129], s[84:85], 0, v[140:141]
	s_mov_b32 m0, s6
	s_nop 0
	global_load_lds_dwordx4 v[128:129], off
	v_lshl_add_u64 v[128:129], s[84:85], 0, v[150:151]
	s_add_i32 m0, s6, 0x2000
	s_nop 0
	global_load_lds_dwordx4 v[128:129], off
	v_add_u32_e32 v146, 0x18000, v206
	ds_read_b128 v[128:131], v146
	ds_read_b128 v[132:135], v146 offset:1024
	ds_read_b128 v[136:139], v146 offset:2048
	ds_read_b128 v[146:149], v146 offset:3072
	s_waitcnt vmcnt(6)
	s_barrier
	s_setprio 1
	v_mfma_f32_16x16x32_bf16 v[52:55], v[214:217], v[162:165], v[52:55]
	v_mfma_f32_16x16x32_bf16 v[44:47], v[222:225], v[162:165], v[44:47]
	v_mfma_f32_16x16x32_bf16 v[36:39], v[214:217], v[170:173], v[36:39]
	v_mfma_f32_16x16x32_bf16 v[28:31], v[222:225], v[170:173], v[28:31]
	v_mfma_f32_16x16x32_bf16 v[20:23], v[214:217], v[178:181], v[20:23]
	v_mfma_f32_16x16x32_bf16 v[12:15], v[222:225], v[178:181], v[12:15]
	v_mfma_f32_16x16x32_bf16 v[4:7], v[214:217], v[194:197], v[4:7]
	v_mfma_f32_16x16x32_bf16 v[0:3], v[222:225], v[194:197], v[0:3]
	v_mfma_f32_16x16x32_bf16 v[52:55], v[218:221], v[166:169], v[52:55]
	v_mfma_f32_16x16x32_bf16 v[44:47], v[226:229], v[166:169], v[44:47]
	v_mfma_f32_16x16x32_bf16 v[36:39], v[218:221], v[174:177], v[36:39]
	v_mfma_f32_16x16x32_bf16 v[28:31], v[226:229], v[174:177], v[28:31]
	v_mfma_f32_16x16x32_bf16 v[20:23], v[218:221], v[182:185], v[20:23]
	v_mfma_f32_16x16x32_bf16 v[12:15], v[226:229], v[182:185], v[12:15]
	v_mfma_f32_16x16x32_bf16 v[4:7], v[218:221], v[210:213], v[4:7]
	v_mfma_f32_16x16x32_bf16 v[0:3], v[226:229], v[210:213], v[0:3]
	s_setprio 0
	s_add_i32 s6, 0, 0x18000
	s_barrier
	s_add_u32 s58, s58, 0x40000
	s_addc_u32 s59, s59, 0
	s_mov_b32 m0, s70
	v_lshl_add_u64 v[214:215], s[58:59], 0, v[154:155]
	ds_read_b128 v[162:165], v208 offset:32768
	ds_read_b128 v[166:169], v208 offset:33792
	ds_read_b128 v[170:173], v208 offset:34816
	ds_read_b128 v[174:177], v208 offset:35840
	ds_read_b128 v[178:181], v208 offset:36864
	ds_read_b128 v[182:185], v208 offset:37888
	ds_read_b128 v[194:197], v208 offset:38912
	ds_read_b128 v[210:213], v208 offset:39936
	global_load_lds_dwordx4 v[214:215], off
	v_lshl_add_u64 v[214:215], s[58:59], 0, v[152:153]
	s_mov_b32 m0, s71
	s_nop 0
	global_load_lds_dwordx4 v[214:215], off
	s_waitcnt lgkmcnt(8)
	s_barrier
	s_setprio 1
	s_waitcnt lgkmcnt(7)
	v_mfma_f32_16x16x32_bf16 v[124:127], v[128:131], v[162:165], v[124:127]
	v_mfma_f32_16x16x32_bf16 v[120:123], v[136:139], v[162:165], v[120:123]
	s_waitcnt lgkmcnt(5)
	v_mfma_f32_16x16x32_bf16 v[108:111], v[128:131], v[170:173], v[108:111]
	v_mfma_f32_16x16x32_bf16 v[104:107], v[136:139], v[170:173], v[104:107]
	s_waitcnt lgkmcnt(3)
	v_mfma_f32_16x16x32_bf16 v[96:99], v[128:131], v[178:181], v[96:99]
	v_mfma_f32_16x16x32_bf16 v[88:91], v[136:139], v[178:181], v[88:91]
	s_waitcnt lgkmcnt(1)
	v_mfma_f32_16x16x32_bf16 v[84:87], v[128:131], v[194:197], v[84:87]
	v_mfma_f32_16x16x32_bf16 v[80:83], v[136:139], v[194:197], v[80:83]
	v_mfma_f32_16x16x32_bf16 v[124:127], v[132:135], v[166:169], v[124:127]
	v_mfma_f32_16x16x32_bf16 v[120:123], v[146:149], v[166:169], v[120:123]
	v_mfma_f32_16x16x32_bf16 v[108:111], v[132:135], v[174:177], v[108:111]
	v_mfma_f32_16x16x32_bf16 v[104:107], v[146:149], v[174:177], v[104:107]
	v_mfma_f32_16x16x32_bf16 v[96:99], v[132:135], v[182:185], v[96:99]
	v_mfma_f32_16x16x32_bf16 v[88:91], v[146:149], v[182:185], v[88:91]
	s_waitcnt lgkmcnt(0)
	v_mfma_f32_16x16x32_bf16 v[84:87], v[132:135], v[210:213], v[84:87]
	v_mfma_f32_16x16x32_bf16 v[80:83], v[146:149], v[210:213], v[80:83]
	s_setprio 0
	s_barrier
	s_add_i32 s19, 0, 0x1c000
	s_add_i32 s6, s6, s57
	v_add_u32_e32 v192, s19, v206
	v_lshl_add_u64 v[230:231], v[230:231], 0, s[36:37]
	s_mov_b32 m0, s6
	ds_read_b128 v[214:217], v192
	ds_read_b128 v[218:221], v192 offset:1024
	ds_read_b128 v[222:225], v192 offset:2048
	ds_read_b128 v[226:229], v192 offset:3072
	global_load_lds_dwordx4 v[230:231], off
	v_lshl_add_u64 v[230:231], v[232:233], 0, s[36:37]
	s_add_i32 m0, s6, 0x2000
	s_nop 0
	global_load_lds_dwordx4 v[230:231], off
	s_barrier
	s_setprio 1
	s_waitcnt lgkmcnt(3)
	v_mfma_f32_16x16x32_bf16 v[116:119], v[214:217], v[162:165], v[116:119]
	s_waitcnt lgkmcnt(1)
	v_mfma_f32_16x16x32_bf16 v[112:115], v[222:225], v[162:165], v[112:115]
	v_mfma_f32_16x16x32_bf16 v[100:103], v[214:217], v[170:173], v[100:103]
	v_mfma_f32_16x16x32_bf16 v[92:95], v[222:225], v[170:173], v[92:95]
	v_mfma_f32_16x16x32_bf16 v[76:79], v[214:217], v[178:181], v[76:79]
	v_mfma_f32_16x16x32_bf16 v[72:75], v[222:225], v[178:181], v[72:75]
	v_mfma_f32_16x16x32_bf16 v[68:71], v[214:217], v[194:197], v[68:71]
	v_mfma_f32_16x16x32_bf16 v[64:67], v[222:225], v[194:197], v[64:67]
	v_mfma_f32_16x16x32_bf16 v[116:119], v[218:221], v[166:169], v[116:119]
	s_waitcnt lgkmcnt(0)
	v_mfma_f32_16x16x32_bf16 v[112:115], v[226:229], v[166:169], v[112:115]
	v_mfma_f32_16x16x32_bf16 v[100:103], v[218:221], v[174:177], v[100:103]
	v_mfma_f32_16x16x32_bf16 v[92:95], v[226:229], v[174:177], v[92:95]
	v_mfma_f32_16x16x32_bf16 v[76:79], v[218:221], v[182:185], v[76:79]
	v_mfma_f32_16x16x32_bf16 v[72:75], v[226:229], v[182:185], v[72:75]
	v_mfma_f32_16x16x32_bf16 v[68:71], v[218:221], v[210:213], v[68:71]
	v_mfma_f32_16x16x32_bf16 v[64:67], v[226:229], v[210:213], v[64:67]
	s_setprio 0
	s_mov_b32 m0, s72
	v_lshl_add_u64 v[230:231], v[234:235], 0, s[36:37]
	s_barrier
	ds_read_b128 v[162:165], v208 offset:49152
	ds_read_b128 v[166:169], v208 offset:50176
	ds_read_b128 v[170:173], v208 offset:51200
	ds_read_b128 v[174:177], v208 offset:52224
	ds_read_b128 v[178:181], v208 offset:53248
	ds_read_b128 v[182:185], v208 offset:54272
	ds_read_b128 v[194:197], v208 offset:55296
	ds_read_b128 v[210:213], v208 offset:56320
	global_load_lds_dwordx4 v[230:231], off
	v_lshl_add_u64 v[230:231], v[236:237], 0, s[36:37]
	s_mov_b32 m0, s73
	s_nop 0
	global_load_lds_dwordx4 v[230:231], off
	s_waitcnt vmcnt(10)
	s_barrier
	s_setprio 1
	s_waitcnt lgkmcnt(7)
	v_mfma_f32_16x16x32_bf16 v[60:63], v[128:131], v[162:165], v[60:63]
	v_mfma_f32_16x16x32_bf16 v[56:59], v[136:139], v[162:165], v[56:59]
	s_waitcnt lgkmcnt(5)
	v_mfma_f32_16x16x32_bf16 v[48:51], v[128:131], v[170:173], v[48:51]
	v_mfma_f32_16x16x32_bf16 v[40:43], v[136:139], v[170:173], v[40:43]
	s_waitcnt lgkmcnt(3)
	v_mfma_f32_16x16x32_bf16 v[32:35], v[128:131], v[178:181], v[32:35]
	v_mfma_f32_16x16x32_bf16 v[24:27], v[136:139], v[178:181], v[24:27]
	s_waitcnt lgkmcnt(1)
	v_mfma_f32_16x16x32_bf16 v[16:19], v[128:131], v[194:197], v[16:19]
	v_mfma_f32_16x16x32_bf16 v[8:11], v[136:139], v[194:197], v[8:11]
	v_mfma_f32_16x16x32_bf16 v[60:63], v[132:135], v[166:169], v[60:63]
	v_mfma_f32_16x16x32_bf16 v[56:59], v[146:149], v[166:169], v[56:59]
	v_mfma_f32_16x16x32_bf16 v[48:51], v[132:135], v[174:177], v[48:51]
	v_mfma_f32_16x16x32_bf16 v[40:43], v[146:149], v[174:177], v[40:43]
	v_mfma_f32_16x16x32_bf16 v[32:35], v[132:135], v[182:185], v[32:35]
	v_mfma_f32_16x16x32_bf16 v[24:27], v[146:149], v[182:185], v[24:27]
	s_waitcnt lgkmcnt(0)
	v_mfma_f32_16x16x32_bf16 v[16:19], v[132:135], v[210:213], v[16:19]
	v_mfma_f32_16x16x32_bf16 v[8:11], v[146:149], v[210:213], v[8:11]
	s_setprio 0
	s_barrier
	s_add_u32 s54, s54, 0x40080
	s_addc_u32 s55, s55, 0
	s_add_i32 s6, s19, s57
	v_lshl_add_u64 v[128:129], s[54:55], 0, v[140:141]
	s_mov_b32 m0, s6
	s_nop 0
	global_load_lds_dwordx4 v[128:129], off
	v_lshl_add_u64 v[128:129], s[54:55], 0, v[150:151]
	s_add_i32 m0, s6, 0x2000
	s_nop 0
	global_load_lds_dwordx4 v[128:129], off
	v_add_u32_e32 v146, 0x10000, v206
	ds_read_b128 v[128:131], v146
	ds_read_b128 v[132:135], v146 offset:1024
	ds_read_b128 v[136:139], v146 offset:2048
	ds_read_b128 v[146:149], v146 offset:3072
	s_waitcnt vmcnt(6)
	s_barrier
	s_setprio 1
	v_mfma_f32_16x16x32_bf16 v[52:55], v[214:217], v[162:165], v[52:55]
	v_mfma_f32_16x16x32_bf16 v[44:47], v[222:225], v[162:165], v[44:47]
	v_mfma_f32_16x16x32_bf16 v[36:39], v[214:217], v[170:173], v[36:39]
	v_mfma_f32_16x16x32_bf16 v[28:31], v[222:225], v[170:173], v[28:31]
	v_mfma_f32_16x16x32_bf16 v[20:23], v[214:217], v[178:181], v[20:23]
	v_mfma_f32_16x16x32_bf16 v[12:15], v[222:225], v[178:181], v[12:15]
	v_mfma_f32_16x16x32_bf16 v[4:7], v[214:217], v[194:197], v[4:7]
	v_mfma_f32_16x16x32_bf16 v[0:3], v[222:225], v[194:197], v[0:3]
	v_mfma_f32_16x16x32_bf16 v[52:55], v[218:221], v[166:169], v[52:55]
	v_mfma_f32_16x16x32_bf16 v[44:47], v[226:229], v[166:169], v[44:47]
	v_mfma_f32_16x16x32_bf16 v[36:39], v[218:221], v[174:177], v[36:39]
	v_mfma_f32_16x16x32_bf16 v[28:31], v[226:229], v[174:177], v[28:31]
	v_mfma_f32_16x16x32_bf16 v[20:23], v[218:221], v[182:185], v[20:23]
	v_mfma_f32_16x16x32_bf16 v[12:15], v[226:229], v[182:185], v[12:15]
	v_mfma_f32_16x16x32_bf16 v[4:7], v[218:221], v[210:213], v[4:7]
	v_mfma_f32_16x16x32_bf16 v[0:3], v[226:229], v[210:213], v[0:3]
	s_setprio 0
	s_add_i32 s82, s82, 2
	s_add_u32 s52, s52, 0x100
	s_addc_u32 s53, s53, 0
	s_add_u32 s39, s39, 0x100
	s_addc_u32 s51, s51, 0
	s_cmp_gt_u32 s82, 13
	s_barrier
	s_cbranch_scc0 .LBB0_248
	s_waitcnt lgkmcnt(0)
	s_ashr_i32 s51, s50, 31
	v_lshl_or_b32 v128, s81, 8, v207
	s_lshl_b64 s[10:11], s[50:51], 8
	v_ashrrev_i32_e32 v129, 31, v128
	v_lshl_add_u64 v[168:169], s[10:11], 0, v[156:157]
	v_lshlrev_b64 v[170:171], 1, v[128:129]
	v_lshl_add_u64 v[174:175], s[28:29], 0, v[170:171]
	v_lshlrev_b64 v[172:173], 11, v[168:169]
	v_lshl_add_u64 v[128:129], v[174:175], 0, v[172:173]
	global_load_dwordx4 v[146:149], v[128:129], off
	global_load_dwordx4 v[182:185], v[128:129], off offset:256
	v_or_b32_e32 v166, 16, v168
	v_mov_b32_e32 v167, v169
	v_lshlrev_b64 v[176:177], 11, v[166:167]
	v_lshl_add_u64 v[128:129], v[174:175], 0, v[176:177]
	global_load_dwordx4 v[194:197], v[128:129], off
	global_load_dwordx4 v[210:213], v[128:129], off offset:256
	v_or_b32_e32 v164, 32, v168
	v_mov_b32_e32 v165, v169
	v_or_b32_e32 v162, 48, v168
	v_mov_b32_e32 v163, v169
	v_lshlrev_b64 v[180:181], 11, v[164:165]
	v_lshlrev_b64 v[178:179], 11, v[162:163]
	v_lshl_add_u64 v[128:129], v[174:175], 0, v[180:181]
	v_lshl_add_u64 v[130:131], v[174:175], 0, v[178:179]
	global_load_dwordx4 v[214:217], v[128:129], off
	global_load_dwordx4 v[136:139], v[128:129], off offset:256
	global_load_dwordx4 v[132:135], v[130:131], off
	s_nop 0
	global_load_dwordx4 v[128:131], v[130:131], off offset:256
	s_mov_b64 s[10:11], 0x90
	v_lshl_add_u64 v[172:173], s[30:31], 0, v[172:173]
	v_lshl_add_u64 v[172:173], v[172:173], 0, v[170:171]
	s_waitcnt vmcnt(0)
	v_lshlrev_b32_e32 v218, 16, v146
	v_and_b32_e32 v219, 0xffff0000, v146
	v_lshlrev_b32_e32 v220, 16, v148
	v_and_b32_e32 v221, 0xffff0000, v148
	v_lshlrev_b32_e32 v146, 16, v147
	v_and_b32_e32 v147, 0xffff0000, v147
	v_lshlrev_b32_e32 v222, 16, v182
	v_and_b32_e32 v223, 0xffff0000, v182
	v_lshlrev_b32_e32 v224, 16, v184
	v_and_b32_e32 v225, 0xffff0000, v184
	v_lshlrev_b32_e32 v182, 16, v183
	v_and_b32_e32 v183, 0xffff0000, v183
	v_pk_add_f32 v[124:125], v[124:125], v[218:219]
	v_pk_add_f32 v[120:121], v[120:121], v[220:221]
	v_pk_add_f32 v[126:127], v[126:127], v[146:147]
	v_pk_add_f32 v[116:117], v[116:117], v[222:223]
	v_pk_add_f32 v[146:147], v[112:113], v[224:225]
	v_pk_add_f32 v[118:119], v[118:119], v[182:183]
	v_pk_mul_f32 v[220:221], v[124:125], v[124:125]
	v_pk_mul_f32 v[222:223], v[126:127], v[126:127]
	v_cvt_pk_bf16_f32 v112, v124, v125
	v_cvt_pk_bf16_f32 v113, v126, v127
	v_pk_mul_f32 v[124:125], v[116:117], v[116:117]
	v_pk_mul_f32 v[126:127], v[118:119], v[118:119]
	v_pk_mul_f32 v[228:229], v[146:147], v[146:147]
	v_cvt_pk_bf16_f32 v116, v116, v117
	v_cvt_pk_bf16_f32 v117, v118, v119
	v_cvt_pk_bf16_f32 v118, v146, v147
	v_add_f32_e32 v146, v220, v221
	v_add_f32_e32 v146, v222, v146
	v_lshlrev_b32_e32 v148, 16, v149
	v_and_b32_e32 v149, 0xffff0000, v149
	v_pk_mul_f32 v[224:225], v[120:121], v[120:121]
	v_add_f32_e32 v146, v223, v146
	v_pk_add_f32 v[122:123], v[122:123], v[148:149]
	v_add_f32_e32 v146, v224, v146
	v_pk_mul_f32 v[226:227], v[122:123], v[122:123]
	v_add_f32_e32 v146, v225, v146
	v_add_f32_e32 v146, v226, v146
	v_add_f32_e32 v146, v227, v146
	v_add_f32_e32 v124, v124, v146
	v_add_f32_e32 v124, v125, v124
	v_add_f32_e32 v124, v126, v124
	v_lshlrev_b32_e32 v184, 16, v185
	v_and_b32_e32 v185, 0xffff0000, v185
	v_add_f32_e32 v124, v127, v124
	v_pk_add_f32 v[148:149], v[114:115], v[184:185]
	v_add_f32_e32 v124, v228, v124
	v_pk_mul_f32 v[230:231], v[148:149], v[148:149]
	v_add_f32_e32 v124, v229, v124
	v_add_f32_e32 v124, v230, v124
	v_add_f32_e32 v209, v231, v124
	v_lshlrev_b32_e32 v124, 16, v212
	v_and_b32_e32 v125, 0xffff0000, v212
	v_pk_add_f32 v[124:125], v[92:93], v[124:125]
	v_lshlrev_b32_e32 v92, 16, v211
	v_and_b32_e32 v93, 0xffff0000, v211
	v_pk_add_f32 v[102:103], v[102:103], v[92:93]
	v_lshlrev_b32_e32 v92, 16, v213
	v_and_b32_e32 v93, 0xffff0000, v213
	v_pk_add_f32 v[126:127], v[94:95], v[92:93]
	v_lshlrev_b32_e32 v92, 16, v214
	v_and_b32_e32 v93, 0xffff0000, v214
	v_pk_add_f32 v[92:93], v[96:97], v[92:93]
	v_lshlrev_b32_e32 v96, 16, v217
	v_and_b32_e32 v97, 0xffff0000, v217
	v_lshlrev_b32_e32 v94, 16, v216
	v_and_b32_e32 v95, 0xffff0000, v216
	v_pk_add_f32 v[90:91], v[90:91], v[96:97]
	v_lshlrev_b32_e32 v96, 16, v136
	v_and_b32_e32 v97, 0xffff0000, v136
	v_lshlrev_b32_e32 v182, 16, v194
	v_and_b32_e32 v183, 0xffff0000, v194
	v_pk_add_f32 v[88:89], v[88:89], v[94:95]
	v_lshlrev_b32_e32 v94, 16, v215
	v_and_b32_e32 v95, 0xffff0000, v215
	v_pk_add_f32 v[96:97], v[76:77], v[96:97]
	v_lshl_add_u64 v[76:77], v[168:169], 0, s[36:37]
	v_lshlrev_b32_e32 v184, 16, v196
	v_and_b32_e32 v185, 0xffff0000, v196
	v_cvt_pk_bf16_f32 v114, v120, v121
	v_pk_add_f32 v[120:121], v[108:109], v[182:183]
	v_pk_add_f32 v[94:95], v[98:99], v[94:95]
	v_lshlrev_b64 v[182:183], 11, v[76:77]
	v_lshlrev_b32_e32 v98, 16, v138
	v_and_b32_e32 v99, 0xffff0000, v138
	v_pk_add_f32 v[108:109], v[104:105], v[184:185]
	v_lshl_add_u64 v[184:185], v[174:175], 0, v[182:183]
	v_pk_add_f32 v[98:99], v[72:73], v[98:99]
	v_lshlrev_b32_e32 v72, 16, v137
	v_and_b32_e32 v73, 0xffff0000, v137
	v_lshlrev_b32_e32 v218, 16, v210
	v_and_b32_e32 v219, 0xffff0000, v210
	global_load_dwordx4 v[210:213], v[184:185], off
	v_pk_add_f32 v[136:137], v[78:79], v[72:73]
	v_lshlrev_b32_e32 v72, 16, v139
	v_and_b32_e32 v73, 0xffff0000, v139
	v_pk_add_f32 v[138:139], v[74:75], v[72:73]
	v_lshlrev_b32_e32 v72, 16, v132
	v_and_b32_e32 v73, 0xffff0000, v132
	v_pk_add_f32 v[74:75], v[84:85], v[72:73]
	v_lshlrev_b32_e32 v72, 16, v134
	v_and_b32_e32 v73, 0xffff0000, v134
	v_pk_add_f32 v[78:79], v[80:81], v[72:73]
	v_lshlrev_b32_e32 v72, 16, v133
	v_and_b32_e32 v73, 0xffff0000, v133
	v_pk_add_f32 v[100:101], v[100:101], v[218:219]
	global_load_dwordx4 v[218:221], v[184:185], off offset:256
	v_pk_add_f32 v[80:81], v[86:87], v[72:73]
	v_lshlrev_b32_e32 v72, 16, v135
	v_and_b32_e32 v73, 0xffff0000, v135
	v_pk_add_f32 v[82:83], v[82:83], v[72:73]
	v_lshl_add_u64 v[72:73], v[168:169], 0, s[10:11]
	v_lshlrev_b64 v[132:133], 11, v[72:73]
	v_lshl_add_u64 v[134:135], v[174:175], 0, v[132:133]
	v_lshlrev_b32_e32 v84, 16, v128
	v_and_b32_e32 v85, 0xffff0000, v128
	global_load_dwordx4 v[226:229], v[134:135], off
	global_load_dwordx4 v[234:237], v[134:135], off offset:256
	v_pk_add_f32 v[84:85], v[68:69], v[84:85]
	v_lshlrev_b32_e32 v68, 16, v130
	v_and_b32_e32 v69, 0xffff0000, v130
	v_pk_add_f32 v[86:87], v[64:65], v[68:69]
	v_lshlrev_b32_e32 v64, 16, v129
	v_and_b32_e32 v65, 0xffff0000, v129
	s_mov_b64 s[10:11], 0xa0
	v_pk_add_f32 v[128:129], v[70:71], v[64:65]
	v_lshl_add_u64 v[70:71], v[168:169], 0, s[10:11]
	s_mov_b64 s[10:11], 0xb0
	v_lshlrev_b32_e32 v64, 16, v131
	v_and_b32_e32 v65, 0xffff0000, v131
	v_lshlrev_b64 v[134:135], 11, v[70:71]
	v_lshl_add_u64 v[68:69], v[168:169], 0, s[10:11]
	v_pk_add_f32 v[130:131], v[66:67], v[64:65]
	v_lshl_add_u64 v[64:65], v[174:175], 0, v[134:135]
	v_lshlrev_b64 v[184:185], 11, v[68:69]
	global_load_dwordx4 v[238:241], v[64:65], off
	global_load_dwordx4 v[242:245], v[64:65], off offset:256
	v_lshl_add_u64 v[64:65], v[174:175], 0, v[184:185]
	global_load_dwordx4 v[246:249], v[64:65], off
	s_nop 0
	global_load_dwordx4 v[64:67], v[64:65], off offset:256
	v_lshlrev_b32_e32 v194, 16, v195
	v_and_b32_e32 v195, 0xffff0000, v195
	v_lshlrev_b32_e32 v196, 16, v197
	v_and_b32_e32 v197, 0xffff0000, v197
	v_cvt_pk_bf16_f32 v115, v122, v123
	v_cvt_pk_bf16_f32 v119, v148, v149
	v_pk_add_f32 v[122:123], v[110:111], v[194:195]
	v_pk_add_f32 v[110:111], v[106:107], v[196:197]
	global_store_dwordx4 v[172:173], v[112:115], off
	global_store_dwordx4 v[172:173], v[116:119], off offset:256
	v_cvt_pk_bf16_f32 v104, v120, v121
	v_lshl_add_u64 v[112:113], s[30:31], 0, v[176:177]
	v_cvt_pk_bf16_f32 v105, v122, v123
	v_cvt_pk_bf16_f32 v106, v108, v109
	v_cvt_pk_bf16_f32 v107, v110, v111
	v_lshl_add_u64 v[112:113], v[112:113], 0, v[170:171]
	v_cvt_pk_bf16_f32 v146, v100, v101
	v_cvt_pk_bf16_f32 v147, v102, v103
	v_cvt_pk_bf16_f32 v148, v124, v125
	v_cvt_pk_bf16_f32 v149, v126, v127
	global_store_dwordx4 v[112:113], v[104:107], off
	global_store_dwordx4 v[112:113], v[146:149], off offset:256
	v_cvt_pk_bf16_f32 v194, v92, v93
	v_lshl_add_u64 v[104:105], s[30:31], 0, v[180:181]
	v_cvt_pk_bf16_f32 v195, v94, v95
	v_cvt_pk_bf16_f32 v196, v88, v89
	v_cvt_pk_bf16_f32 v197, v90, v91
	v_lshl_add_u64 v[104:105], v[104:105], 0, v[170:171]
	v_cvt_pk_bf16_f32 v214, v96, v97
	v_cvt_pk_bf16_f32 v215, v136, v137
	v_cvt_pk_bf16_f32 v216, v98, v99
	v_cvt_pk_bf16_f32 v217, v138, v139
	global_store_dwordx4 v[104:105], v[194:197], off
	global_store_dwordx4 v[104:105], v[214:217], off offset:256
	v_lshl_add_u64 v[104:105], s[30:31], 0, v[178:179]
	v_cvt_pk_bf16_f32 v222, v74, v75
	v_cvt_pk_bf16_f32 v223, v80, v81
	v_cvt_pk_bf16_f32 v224, v78, v79
	v_cvt_pk_bf16_f32 v225, v82, v83
	v_lshl_add_u64 v[104:105], v[104:105], 0, v[170:171]
	v_cvt_pk_bf16_f32 v230, v84, v85
	v_cvt_pk_bf16_f32 v231, v128, v129
	v_cvt_pk_bf16_f32 v232, v86, v87
	v_cvt_pk_bf16_f32 v233, v130, v131
	global_store_dwordx4 v[104:105], v[222:225], off
	global_store_dwordx4 v[104:105], v[230:233], off offset:256
	s_waitcnt vmcnt(0)
	v_lshlrev_b32_e32 v104, 16, v210
	v_and_b32_e32 v105, 0xffff0000, v210
	v_pk_add_f32 v[60:61], v[60:61], v[104:105]
	v_lshlrev_b32_e32 v104, 16, v212
	v_and_b32_e32 v105, 0xffff0000, v212
	v_pk_add_f32 v[56:57], v[56:57], v[104:105]
	v_lshlrev_b32_e32 v104, 16, v211
	v_and_b32_e32 v105, 0xffff0000, v211
	v_pk_add_f32 v[62:63], v[62:63], v[104:105]
	v_lshlrev_b32_e32 v104, 16, v213
	v_and_b32_e32 v105, 0xffff0000, v213
	v_pk_add_f32 v[58:59], v[58:59], v[104:105]
	v_lshlrev_b32_e32 v104, 16, v218
	v_and_b32_e32 v105, 0xffff0000, v218
	v_pk_add_f32 v[52:53], v[52:53], v[104:105]
	v_lshlrev_b32_e32 v104, 16, v220
	v_and_b32_e32 v105, 0xffff0000, v220
	v_pk_add_f32 v[104:105], v[44:45], v[104:105]
	v_lshlrev_b32_e32 v44, 16, v219
	v_and_b32_e32 v45, 0xffff0000, v219
	v_pk_add_f32 v[54:55], v[54:55], v[44:45]
	v_lshlrev_b32_e32 v44, 16, v221
	v_and_b32_e32 v45, 0xffff0000, v221
	v_pk_add_f32 v[106:107], v[46:47], v[44:45]
	v_lshlrev_b32_e32 v44, 16, v226
	v_and_b32_e32 v45, 0xffff0000, v226
	v_pk_add_f32 v[44:45], v[48:49], v[44:45]
	v_lshlrev_b32_e32 v48, 16, v229
	v_and_b32_e32 v49, 0xffff0000, v229
	v_pk_add_f32 v[42:43], v[42:43], v[48:49]
	v_lshlrev_b32_e32 v48, 16, v234
	v_and_b32_e32 v49, 0xffff0000, v234
	v_pk_add_f32 v[36:37], v[36:37], v[48:49]
	v_lshlrev_b32_e32 v48, 16, v236
	v_and_b32_e32 v49, 0xffff0000, v236
	v_lshlrev_b32_e32 v46, 16, v228
	v_and_b32_e32 v47, 0xffff0000, v228
	v_pk_add_f32 v[48:49], v[28:29], v[48:49]
	v_lshlrev_b32_e32 v28, 16, v235
	v_and_b32_e32 v29, 0xffff0000, v235
	v_pk_add_f32 v[40:41], v[40:41], v[46:47]
	v_lshlrev_b32_e32 v46, 16, v227
	v_and_b32_e32 v47, 0xffff0000, v227
	v_pk_add_f32 v[38:39], v[38:39], v[28:29]
	v_lshlrev_b32_e32 v28, 16, v237
	v_and_b32_e32 v29, 0xffff0000, v237
	v_pk_add_f32 v[46:47], v[50:51], v[46:47]
	v_pk_add_f32 v[50:51], v[30:31], v[28:29]
	v_lshlrev_b32_e32 v28, 16, v238
	v_and_b32_e32 v29, 0xffff0000, v238
	v_lshlrev_b32_e32 v180, 16, v64
	v_and_b32_e32 v181, 0xffff0000, v64
	v_pk_add_f32 v[28:29], v[32:33], v[28:29]
	v_lshlrev_b32_e32 v32, 16, v241
	v_and_b32_e32 v33, 0xffff0000, v241
	v_pk_add_f32 v[4:5], v[4:5], v[180:181]
	v_lshlrev_b32_e32 v180, 16, v66
	v_and_b32_e32 v181, 0xffff0000, v66
	v_pk_add_f32 v[26:27], v[26:27], v[32:33]
	v_lshlrev_b32_e32 v32, 16, v242
	v_and_b32_e32 v33, 0xffff0000, v242
	v_pk_add_f32 v[0:1], v[0:1], v[180:181]
	v_lshl_add_u64 v[180:181], s[30:31], 0, v[182:183]
	v_cvt_pk_bf16_f32 v112, v60, v61
	v_cvt_pk_bf16_f32 v113, v62, v63
	v_cvt_pk_bf16_f32 v114, v56, v57
	v_cvt_pk_bf16_f32 v115, v58, v59
	v_pk_add_f32 v[20:21], v[20:21], v[32:33]
	v_lshlrev_b32_e32 v32, 16, v244
	v_and_b32_e32 v33, 0xffff0000, v244
	v_lshl_add_u64 v[180:181], v[180:181], 0, v[170:171]
	v_cvt_pk_bf16_f32 v116, v52, v53
	v_cvt_pk_bf16_f32 v117, v54, v55
	v_cvt_pk_bf16_f32 v118, v104, v105
	v_cvt_pk_bf16_f32 v119, v106, v107
	v_lshlrev_b32_e32 v30, 16, v240
	v_and_b32_e32 v31, 0xffff0000, v240
	v_pk_add_f32 v[32:33], v[12:13], v[32:33]
	v_lshlrev_b32_e32 v12, 16, v243
	v_and_b32_e32 v13, 0xffff0000, v243
	global_store_dwordx4 v[180:181], v[112:115], off
	global_store_dwordx4 v[180:181], v[116:119], off offset:256
	v_cvt_pk_bf16_f32 v146, v44, v45
	v_lshl_add_u64 v[112:113], s[30:31], 0, v[132:133]
	v_cvt_pk_bf16_f32 v147, v46, v47
	v_cvt_pk_bf16_f32 v148, v40, v41
	v_cvt_pk_bf16_f32 v149, v42, v43
	v_pk_add_f32 v[24:25], v[24:25], v[30:31]
	v_lshlrev_b32_e32 v30, 16, v239
	v_and_b32_e32 v31, 0xffff0000, v239
	v_pk_add_f32 v[22:23], v[22:23], v[12:13]
	v_lshlrev_b32_e32 v12, 16, v245
	v_and_b32_e32 v13, 0xffff0000, v245
	v_lshl_add_u64 v[112:113], v[112:113], 0, v[170:171]
	v_cvt_pk_bf16_f32 v172, v36, v37
	v_cvt_pk_bf16_f32 v173, v38, v39
	v_cvt_pk_bf16_f32 v174, v48, v49
	v_cvt_pk_bf16_f32 v175, v50, v51
	v_pk_add_f32 v[30:31], v[34:35], v[30:31]
	v_pk_add_f32 v[34:35], v[14:15], v[12:13]
	v_lshlrev_b32_e32 v12, 16, v246
	v_and_b32_e32 v13, 0xffff0000, v246
	v_lshlrev_b32_e32 v14, 16, v248
	v_and_b32_e32 v15, 0xffff0000, v248
	global_store_dwordx4 v[112:113], v[146:149], off
	global_store_dwordx4 v[112:113], v[172:175], off offset:256
	v_lshl_add_u64 v[112:113], s[30:31], 0, v[134:135]
	v_cvt_pk_bf16_f32 v176, v28, v29
	v_cvt_pk_bf16_f32 v177, v30, v31
	v_cvt_pk_bf16_f32 v178, v24, v25
	v_cvt_pk_bf16_f32 v179, v26, v27
	v_pk_add_f32 v[12:13], v[16:17], v[12:13]
	v_pk_add_f32 v[8:9], v[8:9], v[14:15]
	v_lshlrev_b32_e32 v14, 16, v247
	v_and_b32_e32 v15, 0xffff0000, v247
	v_lshlrev_b32_e32 v16, 16, v249
	v_and_b32_e32 v17, 0xffff0000, v249
	v_lshlrev_b32_e32 v64, 16, v65
	v_and_b32_e32 v65, 0xffff0000, v65
	v_lshl_add_u64 v[112:113], v[112:113], 0, v[170:171]
	v_cvt_pk_bf16_f32 v194, v20, v21
	v_cvt_pk_bf16_f32 v195, v22, v23
	v_cvt_pk_bf16_f32 v196, v32, v33
	v_cvt_pk_bf16_f32 v197, v34, v35
	v_pk_add_f32 v[14:15], v[18:19], v[14:15]
	v_pk_add_f32 v[10:11], v[10:11], v[16:17]
	v_pk_add_f32 v[6:7], v[6:7], v[64:65]
	v_lshlrev_b32_e32 v64, 16, v67
	v_and_b32_e32 v65, 0xffff0000, v67
	global_store_dwordx4 v[112:113], v[176:179], off
	global_store_dwordx4 v[112:113], v[194:197], off offset:256
	v_lshl_add_u64 v[112:113], s[30:31], 0, v[184:185]
	v_cvt_pk_bf16_f32 v16, v12, v13
	v_cvt_pk_bf16_f32 v17, v14, v15
	v_cvt_pk_bf16_f32 v18, v8, v9
	v_cvt_pk_bf16_f32 v19, v10, v11
	v_pk_add_f32 v[2:3], v[2:3], v[64:65]
	v_lshl_add_u64 v[112:113], v[112:113], 0, v[170:171]
	v_cvt_pk_bf16_f32 v64, v4, v5
	v_cvt_pk_bf16_f32 v65, v6, v7
	v_cvt_pk_bf16_f32 v66, v0, v1
	v_cvt_pk_bf16_f32 v67, v2, v3
	global_store_dwordx4 v[112:113], v[16:19], off
	global_store_dwordx4 v[112:113], v[64:67], off offset:256
	s_lshl_b32 s10, s81, 2
	v_and_b32_e32 v17, 64, v188
	v_xor_b32_e32 v16, 16, v188
	v_add_u32_e32 v17, 64, v17
	v_cmp_lt_i32_e32 vcc, v16, v17
	v_xor_b32_e32 v18, 32, v188
	s_ashr_i32 s11, s10, 31
	v_cndmask_b32_e32 v16, v188, v16, vcc
	v_lshlrev_b32_e32 v16, 2, v16
	ds_bpermute_b32 v19, v16, v209
	v_cmp_lt_i32_e32 vcc, v18, v17
	s_lshl_b64 s[10:11], s[10:11], 2
	s_add_u32 s50, s75, s10
	v_cndmask_b32_e32 v17, v188, v18, vcc
	v_lshlrev_b32_e32 v17, 2, v17
	s_waitcnt lgkmcnt(0)
	v_add_f32_e32 v18, v209, v19
	ds_bpermute_b32 v19, v17, v18
	s_addc_u32 s51, s80, s11
	s_and_saveexec_b64 s[52:53], s[42:43]
	s_cbranch_execz .LBB0_251
	s_waitcnt lgkmcnt(0)
	v_add_f32_e32 v64, v18, v19
	v_lshlrev_b64 v[18:19], 6, v[168:169]
	v_lshl_add_u64 v[18:19], s[50:51], 0, v[18:19]
	global_store_dword v[18:19], v64, off

.LBB0_294:
	s_add_u32 s10, s48, 0x100
	s_addc_u32 s11, s49, 0
	s_ashr_i32 s31, s30, 31
	s_lshl_b64 s[38:39], s[30:31], 19
	s_add_u32 s46, s33, s38
	s_addc_u32 s47, s41, s39
	s_and_b64 s[38:39], s[44:45], exec
	s_cselect_b32 s12, s47, s5
	s_cselect_b32 s29, s46, s4
	s_ashr_i32 s35, s34, 31
	s_lshl_b64 s[38:39], s[34:35], 19
	s_add_u32 s38, s54, s38
	s_addc_u32 s39, s55, s39
	s_and_b64 s[50:51], s[44:45], exec
	s_cselect_b32 s31, s39, s49
	s_cselect_b32 s35, s38, s48
	s_add_u32 s48, s4, 0x40080
	s_addc_u32 s49, s5, 0
	v_lshl_add_u64 v[150:151], s[48:49], 0, v[136:137]
	v_lshl_add_u64 v[152:153], s[48:49], 0, v[138:139]
	s_mov_b32 s75, -2
	s_mov_b64 s[48:49], 0
	v_add_u32_e32 v166, 0x10000, v154
	ds_read_b128 v[146:149], v166
	ds_read_b128 v[158:161], v166 offset:1024
	ds_read_b128 v[162:165], v166 offset:2048
	ds_read_b128 v[166:169], v166 offset:3072
.LBB0_295:
	s_add_u32 s6, s4, s48
	s_addc_u32 s19, s5, s49
	s_add_u32 s6, s6, 0x100
	s_addc_u32 s19, s19, 0
	s_add_u32 s23, s10, s48
	s_addc_u32 s50, s11, s49
	s_add_i32 s80, 0, 0x10000
	s_cmpk_eq_i32 s48, 0x700
	s_cselect_b32 s53, s12, s19
	s_cselect_b32 s52, s29, s6
	s_cselect_b32 s51, s31, s50
	s_cselect_b32 s50, s35, s23
	v_lshl_add_u64 v[218:219], v[150:151], 0, s[48:49]
	s_add_i32 m0, s58, 0xc000
	ds_read_b128 v[170:173], v157
	ds_read_b128 v[174:177], v157 offset:1024
	ds_read_b128 v[178:181], v157 offset:2048
	ds_read_b128 v[182:185], v157 offset:3072
	ds_read_b128 v[194:197], v157 offset:4096
	ds_read_b128 v[206:209], v157 offset:5120
	ds_read_b128 v[210:213], v157 offset:6144
	ds_read_b128 v[214:217], v157 offset:7168
	global_load_lds_dwordx4 v[218:219], off
	v_lshl_add_u64 v[218:219], v[152:153], 0, s[48:49]
	s_add_i32 m0, s58, 0xe000
	s_nop 0
	global_load_lds_dwordx4 v[218:219], off
	s_waitcnt lgkmcnt(8)
	s_barrier
	s_setprio 1
	s_waitcnt lgkmcnt(7)
	v_mfma_f32_16x16x32_bf16 v[124:127], v[146:149], v[170:173], v[124:127]
	v_mfma_f32_16x16x32_bf16 v[120:123], v[162:165], v[170:173], v[120:123]
	s_waitcnt lgkmcnt(5)
	v_mfma_f32_16x16x32_bf16 v[116:119], v[146:149], v[178:181], v[116:119]
	v_mfma_f32_16x16x32_bf16 v[112:115], v[162:165], v[178:181], v[112:115]
	s_waitcnt lgkmcnt(3)
	v_mfma_f32_16x16x32_bf16 v[108:111], v[146:149], v[194:197], v[108:111]
	v_mfma_f32_16x16x32_bf16 v[104:107], v[162:165], v[194:197], v[104:107]
	s_waitcnt lgkmcnt(1)
	v_mfma_f32_16x16x32_bf16 v[100:103], v[146:149], v[210:213], v[100:103]
	v_mfma_f32_16x16x32_bf16 v[96:99], v[162:165], v[210:213], v[96:99]
	v_mfma_f32_16x16x32_bf16 v[124:127], v[158:161], v[174:177], v[124:127]
	v_mfma_f32_16x16x32_bf16 v[120:123], v[166:169], v[174:177], v[120:123]
	v_mfma_f32_16x16x32_bf16 v[116:119], v[158:161], v[182:185], v[116:119]
	v_mfma_f32_16x16x32_bf16 v[112:115], v[166:169], v[182:185], v[112:115]
	v_mfma_f32_16x16x32_bf16 v[108:111], v[158:161], v[206:209], v[108:111]
	v_mfma_f32_16x16x32_bf16 v[104:107], v[166:169], v[206:209], v[104:107]
	s_waitcnt lgkmcnt(0)
	v_mfma_f32_16x16x32_bf16 v[100:103], v[158:161], v[214:217], v[100:103]
	v_mfma_f32_16x16x32_bf16 v[96:99], v[166:169], v[214:217], v[96:99]
	s_setprio 0
	s_barrier
	s_add_i32 s6, 0, 0x14000
	s_add_i32 s19, s80, s57
	v_add_u32_e32 v192, s6, v154
	v_lshl_add_u64 v[234:235], s[50:51], 0, v[140:141]
	s_mov_b32 m0, s19
	ds_read_b128 v[218:221], v192
	ds_read_b128 v[222:225], v192 offset:1024
	ds_read_b128 v[226:229], v192 offset:2048
	ds_read_b128 v[230:233], v192 offset:3072
	global_load_lds_dwordx4 v[234:235], off
	v_lshl_add_u64 v[236:237], s[50:51], 0, v[132:133]
	s_add_i32 m0, s19, 0x2000
	s_nop 0
	global_load_lds_dwordx4 v[236:237], off
	s_barrier
	s_setprio 1
	s_waitcnt lgkmcnt(3)
	v_mfma_f32_16x16x32_bf16 v[92:95], v[218:221], v[170:173], v[92:95]
	s_waitcnt lgkmcnt(1)
	v_mfma_f32_16x16x32_bf16 v[88:91], v[226:229], v[170:173], v[88:91]
	v_mfma_f32_16x16x32_bf16 v[84:87], v[218:221], v[178:181], v[84:87]
	v_mfma_f32_16x16x32_bf16 v[80:83], v[226:229], v[178:181], v[80:83]
	v_mfma_f32_16x16x32_bf16 v[76:79], v[218:221], v[194:197], v[76:79]
	v_mfma_f32_16x16x32_bf16 v[72:75], v[226:229], v[194:197], v[72:75]
	v_mfma_f32_16x16x32_bf16 v[68:71], v[218:221], v[210:213], v[68:71]
	v_mfma_f32_16x16x32_bf16 v[64:67], v[226:229], v[210:213], v[64:67]
	v_mfma_f32_16x16x32_bf16 v[92:95], v[222:225], v[174:177], v[92:95]
	s_waitcnt lgkmcnt(0)
	v_mfma_f32_16x16x32_bf16 v[88:91], v[230:233], v[174:177], v[88:91]
	v_mfma_f32_16x16x32_bf16 v[84:87], v[222:225], v[182:185], v[84:87]
	v_mfma_f32_16x16x32_bf16 v[80:83], v[230:233], v[182:185], v[80:83]
	v_mfma_f32_16x16x32_bf16 v[76:79], v[222:225], v[206:209], v[76:79]
	v_mfma_f32_16x16x32_bf16 v[72:75], v[230:233], v[206:209], v[72:75]
	v_mfma_f32_16x16x32_bf16 v[68:71], v[222:225], v[214:217], v[68:71]
	v_mfma_f32_16x16x32_bf16 v[64:67], v[230:233], v[214:217], v[64:67]
	s_setprio 0
	s_mov_b32 m0, s58
	v_lshl_add_u64 v[238:239], s[52:53], 0, v[128:129]
	s_barrier
	ds_read_b128 v[170:173], v157 offset:16384
	ds_read_b128 v[174:177], v157 offset:17408
	ds_read_b128 v[178:181], v157 offset:18432
	ds_read_b128 v[182:185], v157 offset:19456
	ds_read_b128 v[194:197], v157 offset:20480
	ds_read_b128 v[206:209], v157 offset:21504
	ds_read_b128 v[210:213], v157 offset:22528
	ds_read_b128 v[214:217], v157 offset:23552
	global_load_lds_dwordx4 v[238:239], off
	v_lshl_add_u64 v[240:241], s[52:53], 0, v[130:131]
	s_mov_b32 m0, s59
	s_nop 0
	global_load_lds_dwordx4 v[240:241], off
	s_waitcnt vmcnt(10)
	s_barrier
	s_setprio 1
	s_waitcnt lgkmcnt(7)
	v_mfma_f32_16x16x32_bf16 v[60:63], v[146:149], v[170:173], v[60:63]
	v_mfma_f32_16x16x32_bf16 v[56:59], v[162:165], v[170:173], v[56:59]
	s_waitcnt lgkmcnt(5)
	v_mfma_f32_16x16x32_bf16 v[52:55], v[146:149], v[178:181], v[52:55]
	v_mfma_f32_16x16x32_bf16 v[48:51], v[162:165], v[178:181], v[48:51]
	s_waitcnt lgkmcnt(3)
	v_mfma_f32_16x16x32_bf16 v[44:47], v[146:149], v[194:197], v[44:47]
	v_mfma_f32_16x16x32_bf16 v[40:43], v[162:165], v[194:197], v[40:43]
	s_waitcnt lgkmcnt(1)
	v_mfma_f32_16x16x32_bf16 v[36:39], v[146:149], v[210:213], v[36:39]
	v_mfma_f32_16x16x32_bf16 v[32:35], v[162:165], v[210:213], v[32:35]
	v_mfma_f32_16x16x32_bf16 v[60:63], v[158:161], v[174:177], v[60:63]
	v_mfma_f32_16x16x32_bf16 v[56:59], v[166:169], v[174:177], v[56:59]
	v_mfma_f32_16x16x32_bf16 v[52:55], v[158:161], v[182:185], v[52:55]
	v_mfma_f32_16x16x32_bf16 v[48:51], v[166:169], v[182:185], v[48:51]
	v_mfma_f32_16x16x32_bf16 v[44:47], v[158:161], v[206:209], v[44:47]
	v_mfma_f32_16x16x32_bf16 v[40:43], v[166:169], v[206:209], v[40:43]
	s_waitcnt lgkmcnt(0)
	v_mfma_f32_16x16x32_bf16 v[36:39], v[158:161], v[214:217], v[36:39]
	v_mfma_f32_16x16x32_bf16 v[32:35], v[166:169], v[214:217], v[32:35]
	s_setprio 0
	s_barrier
	s_add_u32 s80, s50, 0x40000
	s_addc_u32 s81, s51, 0
	s_add_i32 s6, s6, s57
	v_lshl_add_u64 v[146:147], s[80:81], 0, v[140:141]
	s_mov_b32 m0, s6
	s_nop 0
	global_load_lds_dwordx4 v[146:147], off
	v_lshl_add_u64 v[146:147], s[80:81], 0, v[132:133]
	s_add_i32 m0, s6, 0x2000
	s_nop 0
	global_load_lds_dwordx4 v[146:147], off
	v_add_u32_e32 v166, 0x18000, v154
	ds_read_b128 v[146:149], v166
	ds_read_b128 v[158:161], v166 offset:1024
	ds_read_b128 v[162:165], v166 offset:2048
	ds_read_b128 v[166:169], v166 offset:3072
	s_waitcnt vmcnt(6)
	s_barrier
	s_setprio 1
	v_mfma_f32_16x16x32_bf16 v[28:31], v[218:221], v[170:173], v[28:31]
	v_mfma_f32_16x16x32_bf16 v[24:27], v[226:229], v[170:173], v[24:27]
	v_mfma_f32_16x16x32_bf16 v[20:23], v[218:221], v[178:181], v[20:23]
	v_mfma_f32_16x16x32_bf16 v[16:19], v[226:229], v[178:181], v[16:19]
	v_mfma_f32_16x16x32_bf16 v[12:15], v[218:221], v[194:197], v[12:15]
	v_mfma_f32_16x16x32_bf16 v[8:11], v[226:229], v[194:197], v[8:11]
	v_mfma_f32_16x16x32_bf16 v[4:7], v[218:221], v[210:213], v[4:7]
	v_mfma_f32_16x16x32_bf16 v[0:3], v[226:229], v[210:213], v[0:3]
	v_mfma_f32_16x16x32_bf16 v[28:31], v[222:225], v[174:177], v[28:31]
	v_mfma_f32_16x16x32_bf16 v[24:27], v[230:233], v[174:177], v[24:27]
	v_mfma_f32_16x16x32_bf16 v[20:23], v[222:225], v[182:185], v[20:23]
	v_mfma_f32_16x16x32_bf16 v[16:19], v[230:233], v[182:185], v[16:19]
	v_mfma_f32_16x16x32_bf16 v[12:15], v[222:225], v[206:209], v[12:15]
	v_mfma_f32_16x16x32_bf16 v[8:11], v[230:233], v[206:209], v[8:11]
	v_mfma_f32_16x16x32_bf16 v[4:7], v[222:225], v[214:217], v[4:7]
	v_mfma_f32_16x16x32_bf16 v[0:3], v[230:233], v[214:217], v[0:3]
	s_setprio 0
	s_add_i32 s6, 0, 0x18000
	s_barrier
	s_add_u32 s52, s52, 0x40000
	s_addc_u32 s53, s53, 0
	s_mov_b32 m0, s68
	v_lshl_add_u64 v[218:219], s[52:53], 0, v[128:129]
	ds_read_b128 v[170:173], v157 offset:32768
	ds_read_b128 v[174:177], v157 offset:33792
	ds_read_b128 v[178:181], v157 offset:34816
	ds_read_b128 v[182:185], v157 offset:35840
	ds_read_b128 v[194:197], v157 offset:36864
	ds_read_b128 v[206:209], v157 offset:37888
	ds_read_b128 v[210:213], v157 offset:38912
	ds_read_b128 v[214:217], v157 offset:39936
	global_load_lds_dwordx4 v[218:219], off
	v_lshl_add_u64 v[218:219], s[52:53], 0, v[130:131]
	s_mov_b32 m0, s69
	s_nop 0
	global_load_lds_dwordx4 v[218:219], off
	s_waitcnt lgkmcnt(8)
	s_barrier
	s_setprio 1
	s_waitcnt lgkmcnt(7)
	v_mfma_f32_16x16x32_bf16 v[124:127], v[146:149], v[170:173], v[124:127]
	v_mfma_f32_16x16x32_bf16 v[120:123], v[162:165], v[170:173], v[120:123]
	s_waitcnt lgkmcnt(5)
	v_mfma_f32_16x16x32_bf16 v[116:119], v[146:149], v[178:181], v[116:119]
	v_mfma_f32_16x16x32_bf16 v[112:115], v[162:165], v[178:181], v[112:115]
	s_waitcnt lgkmcnt(3)
	v_mfma_f32_16x16x32_bf16 v[108:111], v[146:149], v[194:197], v[108:111]
	v_mfma_f32_16x16x32_bf16 v[104:107], v[162:165], v[194:197], v[104:107]
	s_waitcnt lgkmcnt(1)
	v_mfma_f32_16x16x32_bf16 v[100:103], v[146:149], v[210:213], v[100:103]
	v_mfma_f32_16x16x32_bf16 v[96:99], v[162:165], v[210:213], v[96:99]
	v_mfma_f32_16x16x32_bf16 v[124:127], v[158:161], v[174:177], v[124:127]
	v_mfma_f32_16x16x32_bf16 v[120:123], v[166:169], v[174:177], v[120:123]
	v_mfma_f32_16x16x32_bf16 v[116:119], v[158:161], v[182:185], v[116:119]
	v_mfma_f32_16x16x32_bf16 v[112:115], v[166:169], v[182:185], v[112:115]
	v_mfma_f32_16x16x32_bf16 v[108:111], v[158:161], v[206:209], v[108:111]
	v_mfma_f32_16x16x32_bf16 v[104:107], v[166:169], v[206:209], v[104:107]
	s_waitcnt lgkmcnt(0)
	v_mfma_f32_16x16x32_bf16 v[100:103], v[158:161], v[214:217], v[100:103]
	v_mfma_f32_16x16x32_bf16 v[96:99], v[166:169], v[214:217], v[96:99]
	s_setprio 0
	s_barrier
	s_add_i32 s19, 0, 0x1c000
	s_add_i32 s6, s6, s57
	v_add_u32_e32 v192, s19, v154
	v_lshl_add_u64 v[234:235], v[234:235], 0, s[36:37]
	s_mov_b32 m0, s6
	ds_read_b128 v[218:221], v192
	ds_read_b128 v[222:225], v192 offset:1024
	ds_read_b128 v[226:229], v192 offset:2048
	ds_read_b128 v[230:233], v192 offset:3072
	global_load_lds_dwordx4 v[234:235], off
	v_lshl_add_u64 v[234:235], v[236:237], 0, s[36:37]
	s_add_i32 m0, s6, 0x2000
	s_nop 0
	global_load_lds_dwordx4 v[234:235], off
	s_barrier
	s_setprio 1
	s_waitcnt lgkmcnt(3)
	v_mfma_f32_16x16x32_bf16 v[92:95], v[218:221], v[170:173], v[92:95]
	s_waitcnt lgkmcnt(1)
	v_mfma_f32_16x16x32_bf16 v[88:91], v[226:229], v[170:173], v[88:91]
	v_mfma_f32_16x16x32_bf16 v[84:87], v[218:221], v[178:181], v[84:87]
	v_mfma_f32_16x16x32_bf16 v[80:83], v[226:229], v[178:181], v[80:83]
	v_mfma_f32_16x16x32_bf16 v[76:79], v[218:221], v[194:197], v[76:79]
	v_mfma_f32_16x16x32_bf16 v[72:75], v[226:229], v[194:197], v[72:75]
	v_mfma_f32_16x16x32_bf16 v[68:71], v[218:221], v[210:213], v[68:71]
	v_mfma_f32_16x16x32_bf16 v[64:67], v[226:229], v[210:213], v[64:67]
	v_mfma_f32_16x16x32_bf16 v[92:95], v[222:225], v[174:177], v[92:95]
	s_waitcnt lgkmcnt(0)
	v_mfma_f32_16x16x32_bf16 v[88:91], v[230:233], v[174:177], v[88:91]
	v_mfma_f32_16x16x32_bf16 v[84:87], v[222:225], v[182:185], v[84:87]
	v_mfma_f32_16x16x32_bf16 v[80:83], v[230:233], v[182:185], v[80:83]
	v_mfma_f32_16x16x32_bf16 v[76:79], v[222:225], v[206:209], v[76:79]
	v_mfma_f32_16x16x32_bf16 v[72:75], v[230:233], v[206:209], v[72:75]
	v_mfma_f32_16x16x32_bf16 v[68:71], v[222:225], v[214:217], v[68:71]
	v_mfma_f32_16x16x32_bf16 v[64:67], v[230:233], v[214:217], v[64:67]
	s_setprio 0
	s_mov_b32 m0, s70
	v_lshl_add_u64 v[234:235], v[238:239], 0, s[36:37]
	s_barrier
	ds_read_b128 v[170:173], v157 offset:49152
	ds_read_b128 v[174:177], v157 offset:50176
	ds_read_b128 v[178:181], v157 offset:51200
	ds_read_b128 v[182:185], v157 offset:52224
	ds_read_b128 v[194:197], v157 offset:53248
	ds_read_b128 v[206:209], v157 offset:54272
	ds_read_b128 v[210:213], v157 offset:55296
	ds_read_b128 v[214:217], v157 offset:56320
	global_load_lds_dwordx4 v[234:235], off
	v_lshl_add_u64 v[234:235], v[240:241], 0, s[36:37]
	s_mov_b32 m0, s71
	s_nop 0
	global_load_lds_dwordx4 v[234:235], off
	s_waitcnt vmcnt(10)
	s_barrier
	s_setprio 1
	s_waitcnt lgkmcnt(7)
	v_mfma_f32_16x16x32_bf16 v[60:63], v[146:149], v[170:173], v[60:63]
	v_mfma_f32_16x16x32_bf16 v[56:59], v[162:165], v[170:173], v[56:59]
	s_waitcnt lgkmcnt(5)
	v_mfma_f32_16x16x32_bf16 v[52:55], v[146:149], v[178:181], v[52:55]
	v_mfma_f32_16x16x32_bf16 v[48:51], v[162:165], v[178:181], v[48:51]
	s_waitcnt lgkmcnt(3)
	v_mfma_f32_16x16x32_bf16 v[44:47], v[146:149], v[194:197], v[44:47]
	v_mfma_f32_16x16x32_bf16 v[40:43], v[162:165], v[194:197], v[40:43]
	s_waitcnt lgkmcnt(1)
	v_mfma_f32_16x16x32_bf16 v[36:39], v[146:149], v[210:213], v[36:39]
	v_mfma_f32_16x16x32_bf16 v[32:35], v[162:165], v[210:213], v[32:35]
	v_mfma_f32_16x16x32_bf16 v[60:63], v[158:161], v[174:177], v[60:63]
	v_mfma_f32_16x16x32_bf16 v[56:59], v[166:169], v[174:177], v[56:59]
	v_mfma_f32_16x16x32_bf16 v[52:55], v[158:161], v[182:185], v[52:55]
	v_mfma_f32_16x16x32_bf16 v[48:51], v[166:169], v[182:185], v[48:51]
	v_mfma_f32_16x16x32_bf16 v[44:47], v[158:161], v[206:209], v[44:47]
	v_mfma_f32_16x16x32_bf16 v[40:43], v[166:169], v[206:209], v[40:43]
	s_waitcnt lgkmcnt(0)
	v_mfma_f32_16x16x32_bf16 v[36:39], v[158:161], v[214:217], v[36:39]
	v_mfma_f32_16x16x32_bf16 v[32:35], v[166:169], v[214:217], v[32:35]
	s_setprio 0
	s_barrier
	s_add_u32 s50, s50, 0x40080
	s_addc_u32 s51, s51, 0
	s_add_i32 s6, s19, s57
	v_lshl_add_u64 v[146:147], s[50:51], 0, v[140:141]
	s_mov_b32 m0, s6
	s_nop 0
	global_load_lds_dwordx4 v[146:147], off
	v_lshl_add_u64 v[146:147], s[50:51], 0, v[132:133]
	s_add_i32 m0, s6, 0x2000
	s_nop 0
	global_load_lds_dwordx4 v[146:147], off
	v_add_u32_e32 v166, 0x10000, v154
	ds_read_b128 v[146:149], v166
	ds_read_b128 v[158:161], v166 offset:1024
	ds_read_b128 v[162:165], v166 offset:2048
	ds_read_b128 v[166:169], v166 offset:3072
	s_waitcnt vmcnt(6)
	s_barrier
	s_setprio 1
	v_mfma_f32_16x16x32_bf16 v[28:31], v[218:221], v[170:173], v[28:31]
	v_mfma_f32_16x16x32_bf16 v[24:27], v[226:229], v[170:173], v[24:27]
	v_mfma_f32_16x16x32_bf16 v[20:23], v[218:221], v[178:181], v[20:23]
	v_mfma_f32_16x16x32_bf16 v[16:19], v[226:229], v[178:181], v[16:19]
	v_mfma_f32_16x16x32_bf16 v[12:15], v[218:221], v[194:197], v[12:15]
	v_mfma_f32_16x16x32_bf16 v[8:11], v[226:229], v[194:197], v[8:11]
	v_mfma_f32_16x16x32_bf16 v[4:7], v[218:221], v[210:213], v[4:7]
	v_mfma_f32_16x16x32_bf16 v[0:3], v[226:229], v[210:213], v[0:3]
	v_mfma_f32_16x16x32_bf16 v[28:31], v[222:225], v[174:177], v[28:31]
	v_mfma_f32_16x16x32_bf16 v[24:27], v[230:233], v[174:177], v[24:27]
	v_mfma_f32_16x16x32_bf16 v[20:23], v[222:225], v[182:185], v[20:23]
	v_mfma_f32_16x16x32_bf16 v[16:19], v[230:233], v[182:185], v[16:19]
	v_mfma_f32_16x16x32_bf16 v[12:15], v[222:225], v[206:209], v[12:15]
	v_mfma_f32_16x16x32_bf16 v[8:11], v[230:233], v[206:209], v[8:11]
	v_mfma_f32_16x16x32_bf16 v[4:7], v[222:225], v[214:217], v[4:7]
	v_mfma_f32_16x16x32_bf16 v[0:3], v[230:233], v[214:217], v[0:3]
	s_setprio 0
	s_add_i32 s75, s75, 2
	s_add_u32 s48, s48, 0x100
	s_addc_u32 s49, s49, 0
	s_cmp_gt_u32 s75, 13
	s_barrier
	s_cbranch_scc0 .LBB0_295
	s_waitcnt lgkmcnt(0)
	s_add_u32 s48, s10, 0xffffff00
	v_lshl_add_u32 v166, s73, 10, v155
	s_addc_u32 s49, s11, -1
	s_ashr_i32 s29, s28, 31
	v_lshl_or_b32 v146, s72, 8, v156
	ds_read2_b32 v[158:159], v166 offset1:16
	s_lshl_b64 s[10:11], s[28:29], 8
	v_ashrrev_i32_e32 v147, 31, v146
	v_lshl_add_u64 v[148:149], s[10:11], 0, v[134:135]
	v_lshl_add_u64 v[146:147], v[146:147], 1, s[26:27]
	v_mad_u64_u32 v[150:151], s[10:11], v148, s13, v[146:147]
	v_mov_b32_e32 v146, v151
	v_mad_u64_u32 v[152:153], s[10:11], v149, s13, v[146:147]
	s_waitcnt lgkmcnt(0)
	v_pk_mul_f32 v[148:149], v[126:127], v[158:159] op_sel_hi:[1,0]
	v_pk_mul_f32 v[146:147], v[124:125], v[158:159] op_sel_hi:[1,0]
	v_pk_mul_f32 v[160:161], v[122:123], v[158:159] op_sel_hi:[1,0]
	v_pk_mul_f32 v[162:163], v[120:121], v[158:159] op_sel_hi:[1,0]
	v_mov_b32_e32 v151, v152
	v_cvt_pk_bf16_f32 v146, v146, v147
	v_cvt_pk_bf16_f32 v147, v148, v149
	v_cvt_pk_bf16_f32 v148, v162, v163
	v_cvt_pk_bf16_f32 v149, v160, v161
	global_store_dwordx4 v[150:151], v[146:149], off
	v_pk_mul_f32 v[160:161], v[90:91], v[158:159] op_sel_hi:[1,0]
	v_pk_mul_f32 v[162:163], v[88:89], v[158:159] op_sel_hi:[1,0]
	v_pk_mul_f32 v[148:149], v[94:95], v[158:159] op_sel_hi:[1,0]
	v_pk_mul_f32 v[146:147], v[92:93], v[158:159] op_sel_hi:[1,0]
	v_mov_b32_e32 v158, v159
	v_cvt_pk_bf16_f32 v146, v146, v147
	v_cvt_pk_bf16_f32 v147, v148, v149
	v_cvt_pk_bf16_f32 v148, v162, v163
	v_cvt_pk_bf16_f32 v149, v160, v161
	global_store_dwordx4 v[150:151], v[146:149], off offset:256
	v_pk_mul_f32 v[160:161], v[114:115], v[158:159] op_sel_hi:[1,0]
	s_mov_b32 s6, 0x1e000
	v_pk_mul_f32 v[148:149], v[118:119], v[158:159] op_sel_hi:[1,0]
	v_pk_mul_f32 v[146:147], v[116:117], v[158:159] op_sel_hi:[1,0]
	ds_read2_b32 v[164:165], v166 offset0:32 offset1:48
	v_pk_mul_f32 v[162:163], v[112:113], v[158:159] op_sel_hi:[1,0]
	v_cvt_pk_bf16_f32 v146, v146, v147
	v_cvt_pk_bf16_f32 v147, v148, v149
	v_cvt_pk_bf16_f32 v149, v160, v161
	v_add_co_u32_e32 v160, vcc, s6, v150
	v_cvt_pk_bf16_f32 v148, v162, v163
	s_nop 0
	v_addc_co_u32_e32 v161, vcc, 0, v152, vcc
	global_store_dwordx4 v[160:161], v[146:149], off
	v_pk_mul_f32 v[162:163], v[82:83], v[158:159] op_sel_hi:[1,0]
	s_mov_b32 s6, 0x3c000
	v_pk_mul_f32 v[148:149], v[86:87], v[158:159] op_sel_hi:[1,0]
	v_pk_mul_f32 v[146:147], v[84:85], v[158:159] op_sel_hi:[1,0]
	v_pk_mul_f32 v[158:159], v[80:81], v[158:159] op_sel_hi:[1,0]
	v_cvt_pk_bf16_f32 v146, v146, v147
	v_cvt_pk_bf16_f32 v147, v148, v149
	v_cvt_pk_bf16_f32 v148, v158, v159
	v_cvt_pk_bf16_f32 v149, v162, v163
	global_store_dwordx4 v[160:161], v[146:149], off offset:256
	s_waitcnt lgkmcnt(0)
	v_pk_mul_f32 v[158:159], v[106:107], v[164:165] op_sel_hi:[1,0]
	v_pk_mul_f32 v[160:161], v[104:105], v[164:165] op_sel_hi:[1,0]
	v_pk_mul_f32 v[148:149], v[110:111], v[164:165] op_sel_hi:[1,0]
	v_pk_mul_f32 v[146:147], v[108:109], v[164:165] op_sel_hi:[1,0]
	v_pk_mul_f32 v[162:163], v[72:73], v[164:165] op_sel_hi:[1,0]
	v_cvt_pk_bf16_f32 v146, v146, v147
	v_cvt_pk_bf16_f32 v147, v148, v149
	v_cvt_pk_bf16_f32 v149, v158, v159
	v_add_co_u32_e32 v158, vcc, s6, v150
	v_cvt_pk_bf16_f32 v148, v160, v161
	s_nop 0
	v_addc_co_u32_e32 v159, vcc, 0, v152, vcc
	global_store_dwordx4 v[158:159], v[146:149], off
	v_pk_mul_f32 v[160:161], v[74:75], v[164:165] op_sel_hi:[1,0]
	s_mov_b32 s6, 0x5a000
	v_pk_mul_f32 v[148:149], v[78:79], v[164:165] op_sel_hi:[1,0]
	v_pk_mul_f32 v[146:147], v[76:77], v[164:165] op_sel_hi:[1,0]
	s_nop 0
	v_cvt_pk_bf16_f32 v146, v146, v147
	v_cvt_pk_bf16_f32 v147, v148, v149
	v_cvt_pk_bf16_f32 v148, v162, v163
	v_cvt_pk_bf16_f32 v149, v160, v161
	global_store_dwordx4 v[158:159], v[146:149], off offset:256
	v_mov_b32_e32 v158, v165
	v_pk_mul_f32 v[160:161], v[98:99], v[158:159] op_sel_hi:[1,0]
	v_pk_mul_f32 v[148:149], v[102:103], v[158:159] op_sel_hi:[1,0]
	v_pk_mul_f32 v[146:147], v[100:101], v[158:159] op_sel_hi:[1,0]
	ds_read2_b32 v[164:165], v166 offset0:128 offset1:144
	v_pk_mul_f32 v[162:163], v[96:97], v[158:159] op_sel_hi:[1,0]
	v_cvt_pk_bf16_f32 v146, v146, v147
	v_cvt_pk_bf16_f32 v147, v148, v149
	v_cvt_pk_bf16_f32 v149, v160, v161
	v_add_co_u32_e32 v160, vcc, s6, v150
	v_cvt_pk_bf16_f32 v148, v162, v163
	s_nop 0
	v_addc_co_u32_e32 v161, vcc, 0, v152, vcc
	global_store_dwordx4 v[160:161], v[146:149], off
	v_pk_mul_f32 v[162:163], v[66:67], v[158:159] op_sel_hi:[1,0]
	s_mov_b32 s6, 0xf0000
	v_pk_mul_f32 v[148:149], v[70:71], v[158:159] op_sel_hi:[1,0]
	v_pk_mul_f32 v[146:147], v[68:69], v[158:159] op_sel_hi:[1,0]
	v_pk_mul_f32 v[158:159], v[64:65], v[158:159] op_sel_hi:[1,0]
	v_cvt_pk_bf16_f32 v146, v146, v147
	v_cvt_pk_bf16_f32 v147, v148, v149
	v_cvt_pk_bf16_f32 v148, v158, v159
	v_cvt_pk_bf16_f32 v149, v162, v163
	global_store_dwordx4 v[160:161], v[146:149], off offset:256
	s_waitcnt lgkmcnt(0)
	v_pk_mul_f32 v[158:159], v[58:59], v[164:165] op_sel_hi:[1,0]
	v_pk_mul_f32 v[160:161], v[56:57], v[164:165] op_sel_hi:[1,0]
	v_pk_mul_f32 v[148:149], v[62:63], v[164:165] op_sel_hi:[1,0]
	v_pk_mul_f32 v[146:147], v[60:61], v[164:165] op_sel_hi:[1,0]
	v_pk_mul_f32 v[162:163], v[24:25], v[164:165] op_sel_hi:[1,0]
	v_cvt_pk_bf16_f32 v146, v146, v147
	v_cvt_pk_bf16_f32 v147, v148, v149
	v_cvt_pk_bf16_f32 v149, v158, v159
	v_add_co_u32_e32 v158, vcc, s6, v150
	v_cvt_pk_bf16_f32 v148, v160, v161
	s_nop 0
	v_addc_co_u32_e32 v159, vcc, 0, v152, vcc
	global_store_dwordx4 v[158:159], v[146:149], off
	v_pk_mul_f32 v[160:161], v[26:27], v[164:165] op_sel_hi:[1,0]
	s_mov_b32 s6, 0x10e000
	v_pk_mul_f32 v[148:149], v[30:31], v[164:165] op_sel_hi:[1,0]
	v_pk_mul_f32 v[146:147], v[28:29], v[164:165] op_sel_hi:[1,0]
	s_nop 0
	v_cvt_pk_bf16_f32 v146, v146, v147
	v_cvt_pk_bf16_f32 v147, v148, v149
	v_cvt_pk_bf16_f32 v148, v162, v163
	v_cvt_pk_bf16_f32 v149, v160, v161
	global_store_dwordx4 v[158:159], v[146:149], off offset:256
	v_mov_b32_e32 v158, v165
	v_pk_mul_f32 v[160:161], v[50:51], v[158:159] op_sel_hi:[1,0]
	v_pk_mul_f32 v[148:149], v[54:55], v[158:159] op_sel_hi:[1,0]
	v_pk_mul_f32 v[146:147], v[52:53], v[158:159] op_sel_hi:[1,0]
	ds_read2_b32 v[164:165], v166 offset0:160 offset1:176
	v_pk_mul_f32 v[162:163], v[48:49], v[158:159] op_sel_hi:[1,0]
	v_cvt_pk_bf16_f32 v146, v146, v147
	v_cvt_pk_bf16_f32 v147, v148, v149
	v_cvt_pk_bf16_f32 v149, v160, v161
	v_add_co_u32_e32 v160, vcc, s6, v150
	v_cvt_pk_bf16_f32 v148, v162, v163
	s_nop 0
	v_addc_co_u32_e32 v161, vcc, 0, v152, vcc
	global_store_dwordx4 v[160:161], v[146:149], off
	v_pk_mul_f32 v[162:163], v[18:19], v[158:159] op_sel_hi:[1,0]
	s_mov_b32 s6, 0x12c000
	v_pk_mul_f32 v[148:149], v[22:23], v[158:159] op_sel_hi:[1,0]
	v_pk_mul_f32 v[146:147], v[20:21], v[158:159] op_sel_hi:[1,0]
	v_pk_mul_f32 v[158:159], v[16:17], v[158:159] op_sel_hi:[1,0]
	v_cvt_pk_bf16_f32 v146, v146, v147
	v_cvt_pk_bf16_f32 v147, v148, v149
	v_cvt_pk_bf16_f32 v148, v158, v159
	v_cvt_pk_bf16_f32 v149, v162, v163
	global_store_dwordx4 v[160:161], v[146:149], off offset:256
	s_waitcnt lgkmcnt(0)
	v_pk_mul_f32 v[158:159], v[42:43], v[164:165] op_sel_hi:[1,0]
	v_pk_mul_f32 v[160:161], v[40:41], v[164:165] op_sel_hi:[1,0]
	v_pk_mul_f32 v[148:149], v[46:47], v[164:165] op_sel_hi:[1,0]
	v_pk_mul_f32 v[146:147], v[44:45], v[164:165] op_sel_hi:[1,0]
	v_pk_mul_f32 v[162:163], v[8:9], v[164:165] op_sel_hi:[1,0]
	v_cvt_pk_bf16_f32 v146, v146, v147
	v_cvt_pk_bf16_f32 v147, v148, v149
	v_cvt_pk_bf16_f32 v149, v158, v159
	v_add_co_u32_e32 v158, vcc, s6, v150
	v_cvt_pk_bf16_f32 v148, v160, v161
	s_nop 0
	v_addc_co_u32_e32 v159, vcc, 0, v152, vcc
	global_store_dwordx4 v[158:159], v[146:149], off
	v_pk_mul_f32 v[160:161], v[10:11], v[164:165] op_sel_hi:[1,0]
	s_mov_b32 s6, 0x14a000
	v_pk_mul_f32 v[148:149], v[14:15], v[164:165] op_sel_hi:[1,0]
	v_pk_mul_f32 v[146:147], v[12:13], v[164:165] op_sel_hi:[1,0]
	v_add_co_u32_e32 v150, vcc, s6, v150
	v_cvt_pk_bf16_f32 v146, v146, v147
	v_cvt_pk_bf16_f32 v147, v148, v149
	v_cvt_pk_bf16_f32 v148, v162, v163
	v_cvt_pk_bf16_f32 v149, v160, v161
	global_store_dwordx4 v[158:159], v[146:149], off offset:256
	v_mov_b32_e32 v158, v165
	v_pk_mul_f32 v[160:161], v[34:35], v[158:159] op_sel_hi:[1,0]
	v_pk_mul_f32 v[148:149], v[38:39], v[158:159] op_sel_hi:[1,0]
	v_pk_mul_f32 v[146:147], v[36:37], v[158:159] op_sel_hi:[1,0]
	v_pk_mul_f32 v[162:163], v[32:33], v[158:159] op_sel_hi:[1,0]
	v_cvt_pk_bf16_f32 v146, v146, v147
	v_cvt_pk_bf16_f32 v147, v148, v149
	v_cvt_pk_bf16_f32 v148, v162, v163
	v_cvt_pk_bf16_f32 v149, v160, v161
	v_addc_co_u32_e32 v151, vcc, 0, v152, vcc
	global_store_dwordx4 v[150:151], v[146:149], off
	v_pk_mul_f32 v[152:153], v[2:3], v[158:159] op_sel_hi:[1,0]
	s_andn2_b64 vcc, exec, s[44:45]
	v_pk_mul_f32 v[148:149], v[6:7], v[158:159] op_sel_hi:[1,0]
	v_pk_mul_f32 v[146:147], v[4:5], v[158:159] op_sel_hi:[1,0]
	v_pk_mul_f32 v[158:159], v[0:1], v[158:159] op_sel_hi:[1,0]
	v_cvt_pk_bf16_f32 v146, v146, v147
	v_cvt_pk_bf16_f32 v147, v148, v149
	v_cvt_pk_bf16_f32 v148, v158, v159
	v_cvt_pk_bf16_f32 v149, v152, v153
	global_store_dwordx4 v[150:151], v[146:149], off offset:256
	s_cbranch_vccz .LBB0_291
	s_mov_b64 s[38:39], s[48:49]
	s_andn2_b64 vcc, exec, s[42:43]
	s_mov_b64 s[48:49], s[38:39]
	s_cbranch_vccnz .LBB0_292

.LBB0_314:
	s_add_u32 s11, s48, 0x100
	s_addc_u32 s12, s49, 0
	s_ashr_i32 s31, s30, 31
	s_lshl_b64 s[42:43], s[30:31], 19
	s_add_u32 s46, s33, s42
	s_addc_u32 s47, s41, s43
	s_and_b64 s[42:43], s[44:45], exec
	s_cselect_b32 s29, s47, s5
	s_cselect_b32 s31, s46, s4
	s_ashr_i32 s35, s34, 31
	s_lshl_b64 s[42:43], s[34:35], 19
	s_add_u32 s42, s54, s42
	s_addc_u32 s43, s55, s43
	s_and_b64 s[50:51], s[44:45], exec
	s_cselect_b32 s35, s43, s49
	s_cselect_b32 s74, s42, s48
	s_add_u32 s48, s4, 0x40080
	s_addc_u32 s49, s5, 0
	v_lshl_add_u64 v[150:151], s[48:49], 0, v[136:137]
	v_lshl_add_u64 v[152:153], s[48:49], 0, v[138:139]
	s_mov_b32 s75, -2
	s_mov_b64 s[48:49], 0
	v_add_u32_e32 v157, 0x10000, v154
	ds_read_b128 v[146:149], v157
	ds_read_b128 v[158:161], v157 offset:1024
	ds_read_b128 v[162:165], v157 offset:2048
	ds_read_b128 v[166:169], v157 offset:3072
.LBB0_315:
	s_add_u32 s6, s4, s48
	s_addc_u32 s19, s5, s49
	s_add_u32 s6, s6, 0x100
	s_addc_u32 s19, s19, 0
	s_add_u32 s23, s11, s48
	s_addc_u32 s50, s12, s49
	s_add_i32 s80, 0, 0x10000
	s_cmpk_eq_i32 s48, 0x700
	s_cselect_b32 s53, s29, s19
	s_cselect_b32 s52, s31, s6
	s_cselect_b32 s51, s35, s50
	s_cselect_b32 s50, s74, s23
	v_lshl_add_u64 v[218:219], v[150:151], 0, s[48:49]
	s_add_i32 m0, s58, 0xc000
	ds_read_b128 v[170:173], v156
	ds_read_b128 v[174:177], v156 offset:1024
	ds_read_b128 v[178:181], v156 offset:2048
	ds_read_b128 v[182:185], v156 offset:3072
	ds_read_b128 v[194:197], v156 offset:4096
	ds_read_b128 v[206:209], v156 offset:5120
	ds_read_b128 v[210:213], v156 offset:6144
	ds_read_b128 v[214:217], v156 offset:7168
	global_load_lds_dwordx4 v[218:219], off
	v_lshl_add_u64 v[218:219], v[152:153], 0, s[48:49]
	s_add_i32 m0, s58, 0xe000
	s_nop 0
	global_load_lds_dwordx4 v[218:219], off
	s_waitcnt lgkmcnt(8)
	s_barrier
	s_setprio 1
	s_waitcnt lgkmcnt(7)
	v_mfma_f32_16x16x32_bf16 v[124:127], v[146:149], v[170:173], v[124:127]
	v_mfma_f32_16x16x32_bf16 v[120:123], v[162:165], v[170:173], v[120:123]
	s_waitcnt lgkmcnt(5)
	v_mfma_f32_16x16x32_bf16 v[116:119], v[146:149], v[178:181], v[116:119]
	v_mfma_f32_16x16x32_bf16 v[112:115], v[162:165], v[178:181], v[112:115]
	s_waitcnt lgkmcnt(3)
	v_mfma_f32_16x16x32_bf16 v[108:111], v[146:149], v[194:197], v[108:111]
	v_mfma_f32_16x16x32_bf16 v[104:107], v[162:165], v[194:197], v[104:107]
	s_waitcnt lgkmcnt(1)
	v_mfma_f32_16x16x32_bf16 v[100:103], v[146:149], v[210:213], v[100:103]
	v_mfma_f32_16x16x32_bf16 v[96:99], v[162:165], v[210:213], v[96:99]
	v_mfma_f32_16x16x32_bf16 v[124:127], v[158:161], v[174:177], v[124:127]
	v_mfma_f32_16x16x32_bf16 v[120:123], v[166:169], v[174:177], v[120:123]
	v_mfma_f32_16x16x32_bf16 v[116:119], v[158:161], v[182:185], v[116:119]
	v_mfma_f32_16x16x32_bf16 v[112:115], v[166:169], v[182:185], v[112:115]
	v_mfma_f32_16x16x32_bf16 v[108:111], v[158:161], v[206:209], v[108:111]
	v_mfma_f32_16x16x32_bf16 v[104:107], v[166:169], v[206:209], v[104:107]
	s_waitcnt lgkmcnt(0)
	v_mfma_f32_16x16x32_bf16 v[100:103], v[158:161], v[214:217], v[100:103]
	v_mfma_f32_16x16x32_bf16 v[96:99], v[166:169], v[214:217], v[96:99]
	s_setprio 0
	s_barrier
	s_add_i32 s6, 0, 0x14000
	s_add_i32 s19, s80, s57
	v_add_u32_e32 v157, s6, v154
	v_lshl_add_u64 v[234:235], s[50:51], 0, v[140:141]
	s_mov_b32 m0, s19
	ds_read_b128 v[218:221], v157
	ds_read_b128 v[222:225], v157 offset:1024
	ds_read_b128 v[226:229], v157 offset:2048
	ds_read_b128 v[230:233], v157 offset:3072
	global_load_lds_dwordx4 v[234:235], off
	v_lshl_add_u64 v[236:237], s[50:51], 0, v[132:133]
	s_add_i32 m0, s19, 0x2000
	s_nop 0
	global_load_lds_dwordx4 v[236:237], off
	s_barrier
	s_setprio 1
	s_waitcnt lgkmcnt(3)
	v_mfma_f32_16x16x32_bf16 v[92:95], v[218:221], v[170:173], v[92:95]
	s_waitcnt lgkmcnt(1)
	v_mfma_f32_16x16x32_bf16 v[88:91], v[226:229], v[170:173], v[88:91]
	v_mfma_f32_16x16x32_bf16 v[84:87], v[218:221], v[178:181], v[84:87]
	v_mfma_f32_16x16x32_bf16 v[80:83], v[226:229], v[178:181], v[80:83]
	v_mfma_f32_16x16x32_bf16 v[76:79], v[218:221], v[194:197], v[76:79]
	v_mfma_f32_16x16x32_bf16 v[72:75], v[226:229], v[194:197], v[72:75]
	v_mfma_f32_16x16x32_bf16 v[68:71], v[218:221], v[210:213], v[68:71]
	v_mfma_f32_16x16x32_bf16 v[64:67], v[226:229], v[210:213], v[64:67]
	v_mfma_f32_16x16x32_bf16 v[92:95], v[222:225], v[174:177], v[92:95]
	s_waitcnt lgkmcnt(0)
	v_mfma_f32_16x16x32_bf16 v[88:91], v[230:233], v[174:177], v[88:91]
	v_mfma_f32_16x16x32_bf16 v[84:87], v[222:225], v[182:185], v[84:87]
	v_mfma_f32_16x16x32_bf16 v[80:83], v[230:233], v[182:185], v[80:83]
	v_mfma_f32_16x16x32_bf16 v[76:79], v[222:225], v[206:209], v[76:79]
	v_mfma_f32_16x16x32_bf16 v[72:75], v[230:233], v[206:209], v[72:75]
	v_mfma_f32_16x16x32_bf16 v[68:71], v[222:225], v[214:217], v[68:71]
	v_mfma_f32_16x16x32_bf16 v[64:67], v[230:233], v[214:217], v[64:67]
	s_setprio 0
	s_mov_b32 m0, s58
	v_lshl_add_u64 v[238:239], s[52:53], 0, v[128:129]
	s_barrier
	ds_read_b128 v[170:173], v156 offset:16384
	ds_read_b128 v[174:177], v156 offset:17408
	ds_read_b128 v[178:181], v156 offset:18432
	ds_read_b128 v[182:185], v156 offset:19456
	ds_read_b128 v[194:197], v156 offset:20480
	ds_read_b128 v[206:209], v156 offset:21504
	ds_read_b128 v[210:213], v156 offset:22528
	ds_read_b128 v[214:217], v156 offset:23552
	global_load_lds_dwordx4 v[238:239], off
	v_lshl_add_u64 v[240:241], s[52:53], 0, v[130:131]
	s_mov_b32 m0, s59
	s_nop 0
	global_load_lds_dwordx4 v[240:241], off
	s_waitcnt vmcnt(10)
	s_barrier
	s_setprio 1
	s_waitcnt lgkmcnt(7)
	v_mfma_f32_16x16x32_bf16 v[60:63], v[146:149], v[170:173], v[60:63]
	v_mfma_f32_16x16x32_bf16 v[56:59], v[162:165], v[170:173], v[56:59]
	s_waitcnt lgkmcnt(5)
	v_mfma_f32_16x16x32_bf16 v[52:55], v[146:149], v[178:181], v[52:55]
	v_mfma_f32_16x16x32_bf16 v[48:51], v[162:165], v[178:181], v[48:51]
	s_waitcnt lgkmcnt(3)
	v_mfma_f32_16x16x32_bf16 v[44:47], v[146:149], v[194:197], v[44:47]
	v_mfma_f32_16x16x32_bf16 v[40:43], v[162:165], v[194:197], v[40:43]
	s_waitcnt lgkmcnt(1)
	v_mfma_f32_16x16x32_bf16 v[36:39], v[146:149], v[210:213], v[36:39]
	v_mfma_f32_16x16x32_bf16 v[32:35], v[162:165], v[210:213], v[32:35]
	v_mfma_f32_16x16x32_bf16 v[60:63], v[158:161], v[174:177], v[60:63]
	v_mfma_f32_16x16x32_bf16 v[56:59], v[166:169], v[174:177], v[56:59]
	v_mfma_f32_16x16x32_bf16 v[52:55], v[158:161], v[182:185], v[52:55]
	v_mfma_f32_16x16x32_bf16 v[48:51], v[166:169], v[182:185], v[48:51]
	v_mfma_f32_16x16x32_bf16 v[44:47], v[158:161], v[206:209], v[44:47]
	v_mfma_f32_16x16x32_bf16 v[40:43], v[166:169], v[206:209], v[40:43]
	s_waitcnt lgkmcnt(0)
	v_mfma_f32_16x16x32_bf16 v[36:39], v[158:161], v[214:217], v[36:39]
	v_mfma_f32_16x16x32_bf16 v[32:35], v[166:169], v[214:217], v[32:35]
	s_setprio 0
	s_barrier
	s_add_u32 s80, s50, 0x40000
	s_addc_u32 s81, s51, 0
	s_add_i32 s6, s6, s57
	v_lshl_add_u64 v[146:147], s[80:81], 0, v[140:141]
	s_mov_b32 m0, s6
	s_nop 0
	global_load_lds_dwordx4 v[146:147], off
	v_lshl_add_u64 v[146:147], s[80:81], 0, v[132:133]
	s_add_i32 m0, s6, 0x2000
	s_nop 0
	global_load_lds_dwordx4 v[146:147], off
	v_add_u32_e32 v157, 0x18000, v154
	ds_read_b128 v[146:149], v157
	ds_read_b128 v[158:161], v157 offset:1024
	ds_read_b128 v[162:165], v157 offset:2048
	ds_read_b128 v[166:169], v157 offset:3072
	s_waitcnt vmcnt(6)
	s_barrier
	s_setprio 1
	v_mfma_f32_16x16x32_bf16 v[28:31], v[218:221], v[170:173], v[28:31]
	v_mfma_f32_16x16x32_bf16 v[24:27], v[226:229], v[170:173], v[24:27]
	v_mfma_f32_16x16x32_bf16 v[20:23], v[218:221], v[178:181], v[20:23]
	v_mfma_f32_16x16x32_bf16 v[16:19], v[226:229], v[178:181], v[16:19]
	v_mfma_f32_16x16x32_bf16 v[12:15], v[218:221], v[194:197], v[12:15]
	v_mfma_f32_16x16x32_bf16 v[8:11], v[226:229], v[194:197], v[8:11]
	v_mfma_f32_16x16x32_bf16 v[4:7], v[218:221], v[210:213], v[4:7]
	v_mfma_f32_16x16x32_bf16 v[0:3], v[226:229], v[210:213], v[0:3]
	v_mfma_f32_16x16x32_bf16 v[28:31], v[222:225], v[174:177], v[28:31]
	v_mfma_f32_16x16x32_bf16 v[24:27], v[230:233], v[174:177], v[24:27]
	v_mfma_f32_16x16x32_bf16 v[20:23], v[222:225], v[182:185], v[20:23]
	v_mfma_f32_16x16x32_bf16 v[16:19], v[230:233], v[182:185], v[16:19]
	v_mfma_f32_16x16x32_bf16 v[12:15], v[222:225], v[206:209], v[12:15]
	v_mfma_f32_16x16x32_bf16 v[8:11], v[230:233], v[206:209], v[8:11]
	v_mfma_f32_16x16x32_bf16 v[4:7], v[222:225], v[214:217], v[4:7]
	v_mfma_f32_16x16x32_bf16 v[0:3], v[230:233], v[214:217], v[0:3]
	s_setprio 0
	s_add_i32 s6, 0, 0x18000
	s_barrier
	s_add_u32 s52, s52, 0x40000
	s_addc_u32 s53, s53, 0
	s_mov_b32 m0, s68
	v_lshl_add_u64 v[218:219], s[52:53], 0, v[128:129]
	ds_read_b128 v[170:173], v156 offset:32768
	ds_read_b128 v[174:177], v156 offset:33792
	ds_read_b128 v[178:181], v156 offset:34816
	ds_read_b128 v[182:185], v156 offset:35840
	ds_read_b128 v[194:197], v156 offset:36864
	ds_read_b128 v[206:209], v156 offset:37888
	ds_read_b128 v[210:213], v156 offset:38912
	ds_read_b128 v[214:217], v156 offset:39936
	global_load_lds_dwordx4 v[218:219], off
	v_lshl_add_u64 v[218:219], s[52:53], 0, v[130:131]
	s_mov_b32 m0, s69
	s_nop 0
	global_load_lds_dwordx4 v[218:219], off
	s_waitcnt lgkmcnt(8)
	s_barrier
	s_setprio 1
	s_waitcnt lgkmcnt(7)
	v_mfma_f32_16x16x32_bf16 v[124:127], v[146:149], v[170:173], v[124:127]
	v_mfma_f32_16x16x32_bf16 v[120:123], v[162:165], v[170:173], v[120:123]
	s_waitcnt lgkmcnt(5)
	v_mfma_f32_16x16x32_bf16 v[116:119], v[146:149], v[178:181], v[116:119]
	v_mfma_f32_16x16x32_bf16 v[112:115], v[162:165], v[178:181], v[112:115]
	s_waitcnt lgkmcnt(3)
	v_mfma_f32_16x16x32_bf16 v[108:111], v[146:149], v[194:197], v[108:111]
	v_mfma_f32_16x16x32_bf16 v[104:107], v[162:165], v[194:197], v[104:107]
	s_waitcnt lgkmcnt(1)
	v_mfma_f32_16x16x32_bf16 v[100:103], v[146:149], v[210:213], v[100:103]
	v_mfma_f32_16x16x32_bf16 v[96:99], v[162:165], v[210:213], v[96:99]
	v_mfma_f32_16x16x32_bf16 v[124:127], v[158:161], v[174:177], v[124:127]
	v_mfma_f32_16x16x32_bf16 v[120:123], v[166:169], v[174:177], v[120:123]
	v_mfma_f32_16x16x32_bf16 v[116:119], v[158:161], v[182:185], v[116:119]
	v_mfma_f32_16x16x32_bf16 v[112:115], v[166:169], v[182:185], v[112:115]
	v_mfma_f32_16x16x32_bf16 v[108:111], v[158:161], v[206:209], v[108:111]
	v_mfma_f32_16x16x32_bf16 v[104:107], v[166:169], v[206:209], v[104:107]
	s_waitcnt lgkmcnt(0)
	v_mfma_f32_16x16x32_bf16 v[100:103], v[158:161], v[214:217], v[100:103]
	v_mfma_f32_16x16x32_bf16 v[96:99], v[166:169], v[214:217], v[96:99]
	s_setprio 0
	s_barrier
	s_add_i32 s19, 0, 0x1c000
	s_add_i32 s6, s6, s57
	v_add_u32_e32 v157, s19, v154
	v_lshl_add_u64 v[234:235], v[234:235], 0, s[36:37]
	s_mov_b32 m0, s6
	ds_read_b128 v[218:221], v157
	ds_read_b128 v[222:225], v157 offset:1024
	ds_read_b128 v[226:229], v157 offset:2048
	ds_read_b128 v[230:233], v157 offset:3072
	global_load_lds_dwordx4 v[234:235], off
	v_lshl_add_u64 v[234:235], v[236:237], 0, s[36:37]
	s_add_i32 m0, s6, 0x2000
	s_nop 0
	global_load_lds_dwordx4 v[234:235], off
	s_barrier
	s_setprio 1
	s_waitcnt lgkmcnt(3)
	v_mfma_f32_16x16x32_bf16 v[92:95], v[218:221], v[170:173], v[92:95]
	s_waitcnt lgkmcnt(1)
	v_mfma_f32_16x16x32_bf16 v[88:91], v[226:229], v[170:173], v[88:91]
	v_mfma_f32_16x16x32_bf16 v[84:87], v[218:221], v[178:181], v[84:87]
	v_mfma_f32_16x16x32_bf16 v[80:83], v[226:229], v[178:181], v[80:83]
	v_mfma_f32_16x16x32_bf16 v[76:79], v[218:221], v[194:197], v[76:79]
	v_mfma_f32_16x16x32_bf16 v[72:75], v[226:229], v[194:197], v[72:75]
	v_mfma_f32_16x16x32_bf16 v[68:71], v[218:221], v[210:213], v[68:71]
	v_mfma_f32_16x16x32_bf16 v[64:67], v[226:229], v[210:213], v[64:67]
	v_mfma_f32_16x16x32_bf16 v[92:95], v[222:225], v[174:177], v[92:95]
	s_waitcnt lgkmcnt(0)
	v_mfma_f32_16x16x32_bf16 v[88:91], v[230:233], v[174:177], v[88:91]
	v_mfma_f32_16x16x32_bf16 v[84:87], v[222:225], v[182:185], v[84:87]
	v_mfma_f32_16x16x32_bf16 v[80:83], v[230:233], v[182:185], v[80:83]
	v_mfma_f32_16x16x32_bf16 v[76:79], v[222:225], v[206:209], v[76:79]
	v_mfma_f32_16x16x32_bf16 v[72:75], v[230:233], v[206:209], v[72:75]
	v_mfma_f32_16x16x32_bf16 v[68:71], v[222:225], v[214:217], v[68:71]
	v_mfma_f32_16x16x32_bf16 v[64:67], v[230:233], v[214:217], v[64:67]
	s_setprio 0
	s_mov_b32 m0, s71
	v_lshl_add_u64 v[234:235], v[238:239], 0, s[36:37]
	s_barrier
	ds_read_b128 v[170:173], v156 offset:49152
	ds_read_b128 v[174:177], v156 offset:50176
	ds_read_b128 v[178:181], v156 offset:51200
	ds_read_b128 v[182:185], v156 offset:52224
	ds_read_b128 v[194:197], v156 offset:53248
	ds_read_b128 v[206:209], v156 offset:54272
	ds_read_b128 v[210:213], v156 offset:55296
	ds_read_b128 v[214:217], v156 offset:56320
	global_load_lds_dwordx4 v[234:235], off
	v_lshl_add_u64 v[234:235], v[240:241], 0, s[36:37]
	s_mov_b32 m0, s72
	s_nop 0
	global_load_lds_dwordx4 v[234:235], off
	s_waitcnt vmcnt(10)
	s_barrier
	s_setprio 1
	s_waitcnt lgkmcnt(7)
	v_mfma_f32_16x16x32_bf16 v[60:63], v[146:149], v[170:173], v[60:63]
	v_mfma_f32_16x16x32_bf16 v[56:59], v[162:165], v[170:173], v[56:59]
	s_waitcnt lgkmcnt(5)
	v_mfma_f32_16x16x32_bf16 v[52:55], v[146:149], v[178:181], v[52:55]
	v_mfma_f32_16x16x32_bf16 v[48:51], v[162:165], v[178:181], v[48:51]
	s_waitcnt lgkmcnt(3)
	v_mfma_f32_16x16x32_bf16 v[44:47], v[146:149], v[194:197], v[44:47]
	v_mfma_f32_16x16x32_bf16 v[40:43], v[162:165], v[194:197], v[40:43]
	s_waitcnt lgkmcnt(1)
	v_mfma_f32_16x16x32_bf16 v[36:39], v[146:149], v[210:213], v[36:39]
	v_mfma_f32_16x16x32_bf16 v[32:35], v[162:165], v[210:213], v[32:35]
	v_mfma_f32_16x16x32_bf16 v[60:63], v[158:161], v[174:177], v[60:63]
	v_mfma_f32_16x16x32_bf16 v[56:59], v[166:169], v[174:177], v[56:59]
	v_mfma_f32_16x16x32_bf16 v[52:55], v[158:161], v[182:185], v[52:55]
	v_mfma_f32_16x16x32_bf16 v[48:51], v[166:169], v[182:185], v[48:51]
	v_mfma_f32_16x16x32_bf16 v[44:47], v[158:161], v[206:209], v[44:47]
	v_mfma_f32_16x16x32_bf16 v[40:43], v[166:169], v[206:209], v[40:43]
	s_waitcnt lgkmcnt(0)
	v_mfma_f32_16x16x32_bf16 v[36:39], v[158:161], v[214:217], v[36:39]
	v_mfma_f32_16x16x32_bf16 v[32:35], v[166:169], v[214:217], v[32:35]
	s_setprio 0
	s_barrier
	s_add_u32 s50, s50, 0x40080
	s_addc_u32 s51, s51, 0
	s_add_i32 s6, s19, s57
	v_lshl_add_u64 v[146:147], s[50:51], 0, v[140:141]
	s_mov_b32 m0, s6
	s_nop 0
	global_load_lds_dwordx4 v[146:147], off
	v_lshl_add_u64 v[146:147], s[50:51], 0, v[132:133]
	s_add_i32 m0, s6, 0x2000
	s_nop 0
	global_load_lds_dwordx4 v[146:147], off
	v_add_u32_e32 v157, 0x10000, v154
	ds_read_b128 v[146:149], v157
	ds_read_b128 v[158:161], v157 offset:1024
	ds_read_b128 v[162:165], v157 offset:2048
	ds_read_b128 v[166:169], v157 offset:3072
	s_waitcnt vmcnt(6)
	s_barrier
	s_setprio 1
	v_mfma_f32_16x16x32_bf16 v[28:31], v[218:221], v[170:173], v[28:31]
	v_mfma_f32_16x16x32_bf16 v[24:27], v[226:229], v[170:173], v[24:27]
	v_mfma_f32_16x16x32_bf16 v[20:23], v[218:221], v[178:181], v[20:23]
	v_mfma_f32_16x16x32_bf16 v[16:19], v[226:229], v[178:181], v[16:19]
	v_mfma_f32_16x16x32_bf16 v[12:15], v[218:221], v[194:197], v[12:15]
	v_mfma_f32_16x16x32_bf16 v[8:11], v[226:229], v[194:197], v[8:11]
	v_mfma_f32_16x16x32_bf16 v[4:7], v[218:221], v[210:213], v[4:7]
	v_mfma_f32_16x16x32_bf16 v[0:3], v[226:229], v[210:213], v[0:3]
	v_mfma_f32_16x16x32_bf16 v[28:31], v[222:225], v[174:177], v[28:31]
	v_mfma_f32_16x16x32_bf16 v[24:27], v[230:233], v[174:177], v[24:27]
	v_mfma_f32_16x16x32_bf16 v[20:23], v[222:225], v[182:185], v[20:23]
	v_mfma_f32_16x16x32_bf16 v[16:19], v[230:233], v[182:185], v[16:19]
	v_mfma_f32_16x16x32_bf16 v[12:15], v[222:225], v[206:209], v[12:15]
	v_mfma_f32_16x16x32_bf16 v[8:11], v[230:233], v[206:209], v[8:11]
	v_mfma_f32_16x16x32_bf16 v[4:7], v[222:225], v[214:217], v[4:7]
	v_mfma_f32_16x16x32_bf16 v[0:3], v[230:233], v[214:217], v[0:3]
	s_setprio 0
	s_add_i32 s75, s75, 2
	s_add_u32 s48, s48, 0x100
	s_addc_u32 s49, s49, 0
	s_cmp_gt_u32 s75, 13
	s_barrier
	s_cbranch_scc0 .LBB0_315
	s_waitcnt lgkmcnt(0)
	s_add_u32 s48, s11, 0xffffff00
	v_lshl_or_b32 v146, s70, 8, v155
	s_addc_u32 s49, s12, -1
	s_ashr_i32 s29, s28, 31
	v_ashrrev_i32_e32 v147, 31, v146
	v_lshl_add_u64 v[146:147], v[146:147], 1, s[26:27]
	s_lshl_b64 s[50:51], s[28:29], 20
	v_lshl_add_u64 v[146:147], v[146:147], 0, s[50:51]
	v_lshl_add_u64 v[150:151], v[146:147], 0, v[134:135]
	v_cvt_pk_bf16_f32 v146, v124, v125
	v_cvt_pk_bf16_f32 v147, v126, v127
	v_cvt_pk_bf16_f32 v148, v120, v121
	v_cvt_pk_bf16_f32 v149, v122, v123
	global_store_dwordx4 v[150:151], v[146:149], off
	v_add_co_u32_e32 v152, vcc, s66, v150
	s_nop 0
	v_cvt_pk_bf16_f32 v146, v92, v93
	v_cvt_pk_bf16_f32 v147, v94, v95
	v_cvt_pk_bf16_f32 v148, v88, v89
	v_cvt_pk_bf16_f32 v149, v90, v91
	global_store_dwordx4 v[150:151], v[146:149], off offset:256
	v_addc_co_u32_e32 v153, vcc, 0, v151, vcc
	s_nop 0
	v_cvt_pk_bf16_f32 v146, v116, v117
	v_cvt_pk_bf16_f32 v147, v118, v119
	v_cvt_pk_bf16_f32 v148, v112, v113
	v_cvt_pk_bf16_f32 v149, v114, v115
	global_store_dwordx4 v[152:153], v[146:149], off
	s_mov_b32 s6, 0x20000
	s_nop 0
	v_cvt_pk_bf16_f32 v146, v84, v85
	v_cvt_pk_bf16_f32 v147, v86, v87
	v_cvt_pk_bf16_f32 v148, v80, v81
	v_cvt_pk_bf16_f32 v149, v82, v83
	global_store_dwordx4 v[152:153], v[146:149], off offset:256
	v_add_co_u32_e32 v152, vcc, s6, v150
	s_nop 0
	v_cvt_pk_bf16_f32 v146, v108, v109
	v_cvt_pk_bf16_f32 v147, v110, v111
	v_cvt_pk_bf16_f32 v148, v104, v105
	v_cvt_pk_bf16_f32 v149, v106, v107
	v_addc_co_u32_e32 v153, vcc, 0, v151, vcc
	global_store_dwordx4 v[152:153], v[146:149], off
	s_mov_b32 s6, 0x30000
	s_nop 0
	v_cvt_pk_bf16_f32 v146, v76, v77
	v_cvt_pk_bf16_f32 v147, v78, v79
	v_cvt_pk_bf16_f32 v148, v72, v73
	v_cvt_pk_bf16_f32 v149, v74, v75
	global_store_dwordx4 v[152:153], v[146:149], off offset:256
	v_add_co_u32_e32 v152, vcc, s6, v150
	s_nop 0
	v_cvt_pk_bf16_f32 v146, v100, v101
	v_cvt_pk_bf16_f32 v147, v102, v103
	v_cvt_pk_bf16_f32 v148, v96, v97
	v_cvt_pk_bf16_f32 v149, v98, v99
	v_addc_co_u32_e32 v153, vcc, 0, v151, vcc
	global_store_dwordx4 v[152:153], v[146:149], off
	s_mov_b32 s6, 0x80000
	s_nop 0
	v_cvt_pk_bf16_f32 v146, v68, v69
	v_cvt_pk_bf16_f32 v147, v70, v71
	v_cvt_pk_bf16_f32 v148, v64, v65
	v_cvt_pk_bf16_f32 v149, v66, v67
	global_store_dwordx4 v[152:153], v[146:149], off offset:256
	v_add_co_u32_e32 v152, vcc, s6, v150
	s_nop 0
	v_cvt_pk_bf16_f32 v146, v60, v61
	v_cvt_pk_bf16_f32 v147, v62, v63
	v_cvt_pk_bf16_f32 v148, v56, v57
	v_cvt_pk_bf16_f32 v149, v58, v59
	v_addc_co_u32_e32 v153, vcc, 0, v151, vcc
	global_store_dwordx4 v[152:153], v[146:149], off
	s_mov_b32 s6, 0x90000
	s_nop 0
	v_cvt_pk_bf16_f32 v146, v28, v29
	v_cvt_pk_bf16_f32 v147, v30, v31
	v_cvt_pk_bf16_f32 v148, v24, v25
	v_cvt_pk_bf16_f32 v149, v26, v27
	global_store_dwordx4 v[152:153], v[146:149], off offset:256
	v_add_co_u32_e32 v152, vcc, s6, v150
	s_nop 0
	v_cvt_pk_bf16_f32 v146, v52, v53
	v_cvt_pk_bf16_f32 v147, v54, v55
	v_cvt_pk_bf16_f32 v148, v48, v49
	v_cvt_pk_bf16_f32 v149, v50, v51
	v_addc_co_u32_e32 v153, vcc, 0, v151, vcc
	global_store_dwordx4 v[152:153], v[146:149], off
	s_mov_b32 s6, 0xa0000
	s_nop 0
	v_cvt_pk_bf16_f32 v146, v20, v21
	v_cvt_pk_bf16_f32 v147, v22, v23
	v_cvt_pk_bf16_f32 v148, v16, v17
	v_cvt_pk_bf16_f32 v149, v18, v19
	global_store_dwordx4 v[152:153], v[146:149], off offset:256
	v_add_co_u32_e32 v152, vcc, s6, v150
	s_nop 0
	v_cvt_pk_bf16_f32 v146, v44, v45
	v_cvt_pk_bf16_f32 v147, v46, v47
	v_cvt_pk_bf16_f32 v148, v40, v41
	v_cvt_pk_bf16_f32 v149, v42, v43
	v_addc_co_u32_e32 v153, vcc, 0, v151, vcc
	s_mov_b32 s6, 0xb0000
	global_store_dwordx4 v[152:153], v[146:149], off
	v_add_co_u32_e32 v150, vcc, s6, v150
	s_nop 0
	v_cvt_pk_bf16_f32 v146, v12, v13
	v_cvt_pk_bf16_f32 v147, v14, v15
	v_cvt_pk_bf16_f32 v148, v8, v9
	v_cvt_pk_bf16_f32 v149, v10, v11
	global_store_dwordx4 v[152:153], v[146:149], off offset:256
	v_addc_co_u32_e32 v151, vcc, 0, v151, vcc
	s_nop 0
	v_cvt_pk_bf16_f32 v146, v36, v37
	v_cvt_pk_bf16_f32 v147, v38, v39
	v_cvt_pk_bf16_f32 v148, v32, v33
	v_cvt_pk_bf16_f32 v149, v34, v35
	global_store_dwordx4 v[150:151], v[146:149], off
	s_andn2_b64 vcc, exec, s[44:45]
	s_nop 0
	v_cvt_pk_bf16_f32 v146, v4, v5
	v_cvt_pk_bf16_f32 v147, v6, v7
	v_cvt_pk_bf16_f32 v148, v0, v1
	v_cvt_pk_bf16_f32 v149, v2, v3
	global_store_dwordx4 v[150:151], v[146:149], off offset:256
	s_cbranch_vccz .LBB0_307
	s_mov_b64 s[42:43], s[48:49]
	s_andn2_b64 vcc, exec, s[38:39]
	s_mov_b64 s[48:49], s[42:43]
	s_cbranch_vccnz .LBB0_308

.LBB0_341:
	s_add_u32 s46, s50, 0x100
	s_addc_u32 s47, s51, 0
	s_add_i32 s6, 0, 0x10000
	s_cmp_eq_u32 s12, 40
	s_cselect_b32 s53, s31, s47
	s_cselect_b32 s52, s30, s46
	s_cselect_b32 s49, s35, s11
	s_cselect_b32 s48, s34, s10
	v_lshl_add_u64 v[214:215], s[50:51], 0, v[158:159]
	s_add_i32 m0, s58, 0xc000
	ds_read_b128 v[162:165], v208
	ds_read_b128 v[166:169], v208 offset:1024
	ds_read_b128 v[170:173], v208 offset:2048
	ds_read_b128 v[174:177], v208 offset:3072
	ds_read_b128 v[178:181], v208 offset:4096
	ds_read_b128 v[182:185], v208 offset:5120
	ds_read_b128 v[194:197], v208 offset:6144
	ds_read_b128 v[210:213], v208 offset:7168
	global_load_lds_dwordx4 v[214:215], off
	v_lshl_add_u64 v[214:215], s[50:51], 0, v[160:161]
	s_add_i32 m0, s58, 0xe000
	s_nop 0
	global_load_lds_dwordx4 v[214:215], off
	s_waitcnt lgkmcnt(8)
	s_barrier
	s_setprio 1
	s_waitcnt lgkmcnt(7)
	v_mfma_f32_16x16x32_bf16 v[124:127], v[128:131], v[162:165], v[124:127]
	v_mfma_f32_16x16x32_bf16 v[120:123], v[136:139], v[162:165], v[120:123]
	s_waitcnt lgkmcnt(5)
	v_mfma_f32_16x16x32_bf16 v[108:111], v[128:131], v[170:173], v[108:111]
	v_mfma_f32_16x16x32_bf16 v[104:107], v[136:139], v[170:173], v[104:107]
	s_waitcnt lgkmcnt(3)
	v_mfma_f32_16x16x32_bf16 v[96:99], v[128:131], v[178:181], v[96:99]
	v_mfma_f32_16x16x32_bf16 v[88:91], v[136:139], v[178:181], v[88:91]
	s_waitcnt lgkmcnt(1)
	v_mfma_f32_16x16x32_bf16 v[84:87], v[128:131], v[194:197], v[84:87]
	v_mfma_f32_16x16x32_bf16 v[80:83], v[136:139], v[194:197], v[80:83]
	v_mfma_f32_16x16x32_bf16 v[124:127], v[132:135], v[166:169], v[124:127]
	v_mfma_f32_16x16x32_bf16 v[120:123], v[146:149], v[166:169], v[120:123]
	v_mfma_f32_16x16x32_bf16 v[108:111], v[132:135], v[174:177], v[108:111]
	v_mfma_f32_16x16x32_bf16 v[104:107], v[146:149], v[174:177], v[104:107]
	v_mfma_f32_16x16x32_bf16 v[96:99], v[132:135], v[182:185], v[96:99]
	v_mfma_f32_16x16x32_bf16 v[88:91], v[146:149], v[182:185], v[88:91]
	s_waitcnt lgkmcnt(0)
	v_mfma_f32_16x16x32_bf16 v[84:87], v[132:135], v[210:213], v[84:87]
	v_mfma_f32_16x16x32_bf16 v[80:83], v[146:149], v[210:213], v[80:83]
	s_setprio 0
	s_barrier
	s_add_i32 s19, 0, 0x14000
	s_add_i32 s6, s6, s57
	v_add_u32_e32 v192, s19, v206
	v_lshl_add_u64 v[230:231], s[48:49], 0, v[140:141]
	s_mov_b32 m0, s6
	ds_read_b128 v[214:217], v192
	ds_read_b128 v[218:221], v192 offset:1024
	ds_read_b128 v[222:225], v192 offset:2048
	ds_read_b128 v[226:229], v192 offset:3072
	global_load_lds_dwordx4 v[230:231], off
	v_lshl_add_u64 v[232:233], s[48:49], 0, v[150:151]
	s_add_i32 m0, s6, 0x2000
	s_nop 0
	global_load_lds_dwordx4 v[232:233], off
	s_barrier
	s_setprio 1
	s_waitcnt lgkmcnt(3)
	v_mfma_f32_16x16x32_bf16 v[116:119], v[214:217], v[162:165], v[116:119]
	s_waitcnt lgkmcnt(1)
	v_mfma_f32_16x16x32_bf16 v[112:115], v[222:225], v[162:165], v[112:115]
	v_mfma_f32_16x16x32_bf16 v[100:103], v[214:217], v[170:173], v[100:103]
	v_mfma_f32_16x16x32_bf16 v[92:95], v[222:225], v[170:173], v[92:95]
	v_mfma_f32_16x16x32_bf16 v[76:79], v[214:217], v[178:181], v[76:79]
	v_mfma_f32_16x16x32_bf16 v[72:75], v[222:225], v[178:181], v[72:75]
	v_mfma_f32_16x16x32_bf16 v[68:71], v[214:217], v[194:197], v[68:71]
	v_mfma_f32_16x16x32_bf16 v[64:67], v[222:225], v[194:197], v[64:67]
	v_mfma_f32_16x16x32_bf16 v[116:119], v[218:221], v[166:169], v[116:119]
	s_waitcnt lgkmcnt(0)
	v_mfma_f32_16x16x32_bf16 v[112:115], v[226:229], v[166:169], v[112:115]
	v_mfma_f32_16x16x32_bf16 v[100:103], v[218:221], v[174:177], v[100:103]
	v_mfma_f32_16x16x32_bf16 v[92:95], v[226:229], v[174:177], v[92:95]
	v_mfma_f32_16x16x32_bf16 v[76:79], v[218:221], v[182:185], v[76:79]
	v_mfma_f32_16x16x32_bf16 v[72:75], v[226:229], v[182:185], v[72:75]
	v_mfma_f32_16x16x32_bf16 v[68:71], v[218:221], v[210:213], v[68:71]
	v_mfma_f32_16x16x32_bf16 v[64:67], v[226:229], v[210:213], v[64:67]
	s_setprio 0
	s_mov_b32 m0, s58
	v_lshl_add_u64 v[234:235], s[52:53], 0, v[154:155]
	s_barrier
	ds_read_b128 v[162:165], v208 offset:16384
	ds_read_b128 v[166:169], v208 offset:17408
	ds_read_b128 v[170:173], v208 offset:18432
	ds_read_b128 v[174:177], v208 offset:19456
	ds_read_b128 v[178:181], v208 offset:20480
	ds_read_b128 v[182:185], v208 offset:21504
	ds_read_b128 v[194:197], v208 offset:22528
	ds_read_b128 v[210:213], v208 offset:23552
	global_load_lds_dwordx4 v[234:235], off
	v_lshl_add_u64 v[236:237], s[52:53], 0, v[152:153]
	s_mov_b32 m0, s59
	s_nop 0
	global_load_lds_dwordx4 v[236:237], off
	s_waitcnt vmcnt(10)
	s_barrier
	s_setprio 1
	s_waitcnt lgkmcnt(7)
	v_mfma_f32_16x16x32_bf16 v[60:63], v[128:131], v[162:165], v[60:63]
	v_mfma_f32_16x16x32_bf16 v[56:59], v[136:139], v[162:165], v[56:59]
	s_waitcnt lgkmcnt(5)
	v_mfma_f32_16x16x32_bf16 v[48:51], v[128:131], v[170:173], v[48:51]
	v_mfma_f32_16x16x32_bf16 v[40:43], v[136:139], v[170:173], v[40:43]
	s_waitcnt lgkmcnt(3)
	v_mfma_f32_16x16x32_bf16 v[32:35], v[128:131], v[178:181], v[32:35]
	v_mfma_f32_16x16x32_bf16 v[24:27], v[136:139], v[178:181], v[24:27]
	s_waitcnt lgkmcnt(1)
	v_mfma_f32_16x16x32_bf16 v[16:19], v[128:131], v[194:197], v[16:19]
	v_mfma_f32_16x16x32_bf16 v[8:11], v[136:139], v[194:197], v[8:11]
	v_mfma_f32_16x16x32_bf16 v[60:63], v[132:135], v[166:169], v[60:63]
	v_mfma_f32_16x16x32_bf16 v[56:59], v[146:149], v[166:169], v[56:59]
	v_mfma_f32_16x16x32_bf16 v[48:51], v[132:135], v[174:177], v[48:51]
	v_mfma_f32_16x16x32_bf16 v[40:43], v[146:149], v[174:177], v[40:43]
	v_mfma_f32_16x16x32_bf16 v[32:35], v[132:135], v[182:185], v[32:35]
	v_mfma_f32_16x16x32_bf16 v[24:27], v[146:149], v[182:185], v[24:27]
	s_waitcnt lgkmcnt(0)
	v_mfma_f32_16x16x32_bf16 v[16:19], v[132:135], v[210:213], v[16:19]
	v_mfma_f32_16x16x32_bf16 v[8:11], v[146:149], v[210:213], v[8:11]
	s_setprio 0
	s_barrier
	s_add_u32 s50, s48, 0xb0000
	s_addc_u32 s51, s49, 0
	s_add_i32 s6, s19, s57
	v_lshl_add_u64 v[128:129], s[50:51], 0, v[140:141]
	s_mov_b32 m0, s6
	s_nop 0
	global_load_lds_dwordx4 v[128:129], off
	v_lshl_add_u64 v[128:129], s[50:51], 0, v[150:151]
	s_add_i32 m0, s6, 0x2000
	s_nop 0
	global_load_lds_dwordx4 v[128:129], off
	v_add_u32_e32 v146, 0x18000, v206
	ds_read_b128 v[128:131], v146
	ds_read_b128 v[132:135], v146 offset:1024
	ds_read_b128 v[136:139], v146 offset:2048
	ds_read_b128 v[146:149], v146 offset:3072
	s_waitcnt vmcnt(6)
	s_barrier
	s_setprio 1
	v_mfma_f32_16x16x32_bf16 v[52:55], v[214:217], v[162:165], v[52:55]
	v_mfma_f32_16x16x32_bf16 v[44:47], v[222:225], v[162:165], v[44:47]
	v_mfma_f32_16x16x32_bf16 v[36:39], v[214:217], v[170:173], v[36:39]
	v_mfma_f32_16x16x32_bf16 v[28:31], v[222:225], v[170:173], v[28:31]
	v_mfma_f32_16x16x32_bf16 v[20:23], v[214:217], v[178:181], v[20:23]
	v_mfma_f32_16x16x32_bf16 v[12:15], v[222:225], v[178:181], v[12:15]
	v_mfma_f32_16x16x32_bf16 v[4:7], v[214:217], v[194:197], v[4:7]
	v_mfma_f32_16x16x32_bf16 v[0:3], v[222:225], v[194:197], v[0:3]
	v_mfma_f32_16x16x32_bf16 v[52:55], v[218:221], v[166:169], v[52:55]
	v_mfma_f32_16x16x32_bf16 v[44:47], v[226:229], v[166:169], v[44:47]
	v_mfma_f32_16x16x32_bf16 v[36:39], v[218:221], v[174:177], v[36:39]
	v_mfma_f32_16x16x32_bf16 v[28:31], v[226:229], v[174:177], v[28:31]
	v_mfma_f32_16x16x32_bf16 v[20:23], v[218:221], v[182:185], v[20:23]
	v_mfma_f32_16x16x32_bf16 v[12:15], v[226:229], v[182:185], v[12:15]
	v_mfma_f32_16x16x32_bf16 v[4:7], v[218:221], v[210:213], v[4:7]
	v_mfma_f32_16x16x32_bf16 v[0:3], v[226:229], v[210:213], v[0:3]
	s_setprio 0
	s_add_i32 s6, 0, 0x18000
	s_barrier
	s_add_u32 s50, s52, 0xb0000
	s_addc_u32 s51, s53, 0
	s_mov_b32 m0, s68
	v_lshl_add_u64 v[214:215], s[50:51], 0, v[154:155]
	ds_read_b128 v[162:165], v208 offset:32768
	ds_read_b128 v[166:169], v208 offset:33792
	ds_read_b128 v[170:173], v208 offset:34816
	ds_read_b128 v[174:177], v208 offset:35840
	ds_read_b128 v[178:181], v208 offset:36864
	ds_read_b128 v[182:185], v208 offset:37888
	ds_read_b128 v[194:197], v208 offset:38912
	ds_read_b128 v[210:213], v208 offset:39936
	global_load_lds_dwordx4 v[214:215], off
	v_lshl_add_u64 v[214:215], s[50:51], 0, v[152:153]
	s_mov_b32 m0, s69
	s_nop 0
	global_load_lds_dwordx4 v[214:215], off
	s_waitcnt lgkmcnt(8)
	s_barrier
	s_setprio 1
	s_waitcnt lgkmcnt(7)
	v_mfma_f32_16x16x32_bf16 v[124:127], v[128:131], v[162:165], v[124:127]
	v_mfma_f32_16x16x32_bf16 v[120:123], v[136:139], v[162:165], v[120:123]
	s_waitcnt lgkmcnt(5)
	v_mfma_f32_16x16x32_bf16 v[108:111], v[128:131], v[170:173], v[108:111]
	v_mfma_f32_16x16x32_bf16 v[104:107], v[136:139], v[170:173], v[104:107]
	s_waitcnt lgkmcnt(3)
	v_mfma_f32_16x16x32_bf16 v[96:99], v[128:131], v[178:181], v[96:99]
	v_mfma_f32_16x16x32_bf16 v[88:91], v[136:139], v[178:181], v[88:91]
	s_waitcnt lgkmcnt(1)
	v_mfma_f32_16x16x32_bf16 v[84:87], v[128:131], v[194:197], v[84:87]
	v_mfma_f32_16x16x32_bf16 v[80:83], v[136:139], v[194:197], v[80:83]
	v_mfma_f32_16x16x32_bf16 v[124:127], v[132:135], v[166:169], v[124:127]
	v_mfma_f32_16x16x32_bf16 v[120:123], v[146:149], v[166:169], v[120:123]
	v_mfma_f32_16x16x32_bf16 v[108:111], v[132:135], v[174:177], v[108:111]
	v_mfma_f32_16x16x32_bf16 v[104:107], v[146:149], v[174:177], v[104:107]
	v_mfma_f32_16x16x32_bf16 v[96:99], v[132:135], v[182:185], v[96:99]
	v_mfma_f32_16x16x32_bf16 v[88:91], v[146:149], v[182:185], v[88:91]
	s_waitcnt lgkmcnt(0)
	v_mfma_f32_16x16x32_bf16 v[84:87], v[132:135], v[210:213], v[84:87]
	v_mfma_f32_16x16x32_bf16 v[80:83], v[146:149], v[210:213], v[80:83]
	s_setprio 0
	s_barrier
	s_add_i32 s19, 0, 0x1c000
	s_add_i32 s6, s6, s57
	v_add_u32_e32 v192, s19, v206
	v_lshl_add_u64 v[230:231], v[230:231], 0, s[36:37]
	s_mov_b32 m0, s6
	ds_read_b128 v[214:217], v192
	ds_read_b128 v[218:221], v192 offset:1024
	ds_read_b128 v[222:225], v192 offset:2048
	ds_read_b128 v[226:229], v192 offset:3072
	global_load_lds_dwordx4 v[230:231], off
	v_lshl_add_u64 v[230:231], v[232:233], 0, s[36:37]
	s_add_i32 m0, s6, 0x2000
	s_nop 0
	global_load_lds_dwordx4 v[230:231], off
	s_barrier
	s_setprio 1
	s_waitcnt lgkmcnt(3)
	v_mfma_f32_16x16x32_bf16 v[116:119], v[214:217], v[162:165], v[116:119]
	s_waitcnt lgkmcnt(1)
	v_mfma_f32_16x16x32_bf16 v[112:115], v[222:225], v[162:165], v[112:115]
	v_mfma_f32_16x16x32_bf16 v[100:103], v[214:217], v[170:173], v[100:103]
	v_mfma_f32_16x16x32_bf16 v[92:95], v[222:225], v[170:173], v[92:95]
	v_mfma_f32_16x16x32_bf16 v[76:79], v[214:217], v[178:181], v[76:79]
	v_mfma_f32_16x16x32_bf16 v[72:75], v[222:225], v[178:181], v[72:75]
	v_mfma_f32_16x16x32_bf16 v[68:71], v[214:217], v[194:197], v[68:71]
	v_mfma_f32_16x16x32_bf16 v[64:67], v[222:225], v[194:197], v[64:67]
	v_mfma_f32_16x16x32_bf16 v[116:119], v[218:221], v[166:169], v[116:119]
	s_waitcnt lgkmcnt(0)
	v_mfma_f32_16x16x32_bf16 v[112:115], v[226:229], v[166:169], v[112:115]
	v_mfma_f32_16x16x32_bf16 v[100:103], v[218:221], v[174:177], v[100:103]
	v_mfma_f32_16x16x32_bf16 v[92:95], v[226:229], v[174:177], v[92:95]
	v_mfma_f32_16x16x32_bf16 v[76:79], v[218:221], v[182:185], v[76:79]
	v_mfma_f32_16x16x32_bf16 v[72:75], v[226:229], v[182:185], v[72:75]
	v_mfma_f32_16x16x32_bf16 v[68:71], v[218:221], v[210:213], v[68:71]
	v_mfma_f32_16x16x32_bf16 v[64:67], v[226:229], v[210:213], v[64:67]
	s_setprio 0
	s_mov_b32 m0, s70
	v_lshl_add_u64 v[230:231], v[234:235], 0, s[36:37]
	s_barrier
	ds_read_b128 v[162:165], v208 offset:49152
	ds_read_b128 v[166:169], v208 offset:50176
	ds_read_b128 v[170:173], v208 offset:51200
	ds_read_b128 v[174:177], v208 offset:52224
	ds_read_b128 v[178:181], v208 offset:53248
	ds_read_b128 v[182:185], v208 offset:54272
	ds_read_b128 v[194:197], v208 offset:55296
	ds_read_b128 v[210:213], v208 offset:56320
	global_load_lds_dwordx4 v[230:231], off
	v_lshl_add_u64 v[230:231], v[236:237], 0, s[36:37]
	s_mov_b32 m0, s71
	s_nop 0
	global_load_lds_dwordx4 v[230:231], off
	s_waitcnt vmcnt(10)
	s_barrier
	s_setprio 1
	s_waitcnt lgkmcnt(7)
	v_mfma_f32_16x16x32_bf16 v[60:63], v[128:131], v[162:165], v[60:63]
	v_mfma_f32_16x16x32_bf16 v[56:59], v[136:139], v[162:165], v[56:59]
	s_waitcnt lgkmcnt(5)
	v_mfma_f32_16x16x32_bf16 v[48:51], v[128:131], v[170:173], v[48:51]
	v_mfma_f32_16x16x32_bf16 v[40:43], v[136:139], v[170:173], v[40:43]
	s_waitcnt lgkmcnt(3)
	v_mfma_f32_16x16x32_bf16 v[32:35], v[128:131], v[178:181], v[32:35]
	v_mfma_f32_16x16x32_bf16 v[24:27], v[136:139], v[178:181], v[24:27]
	s_waitcnt lgkmcnt(1)
	v_mfma_f32_16x16x32_bf16 v[16:19], v[128:131], v[194:197], v[16:19]
	v_mfma_f32_16x16x32_bf16 v[8:11], v[136:139], v[194:197], v[8:11]
	v_mfma_f32_16x16x32_bf16 v[60:63], v[132:135], v[166:169], v[60:63]
	v_mfma_f32_16x16x32_bf16 v[56:59], v[146:149], v[166:169], v[56:59]
	v_mfma_f32_16x16x32_bf16 v[48:51], v[132:135], v[174:177], v[48:51]
	v_mfma_f32_16x16x32_bf16 v[40:43], v[146:149], v[174:177], v[40:43]
	v_mfma_f32_16x16x32_bf16 v[32:35], v[132:135], v[182:185], v[32:35]
	v_mfma_f32_16x16x32_bf16 v[24:27], v[146:149], v[182:185], v[24:27]
	s_waitcnt lgkmcnt(0)
	v_mfma_f32_16x16x32_bf16 v[16:19], v[132:135], v[210:213], v[16:19]
	v_mfma_f32_16x16x32_bf16 v[8:11], v[146:149], v[210:213], v[8:11]
	s_setprio 0
	s_barrier
	s_add_u32 s48, s48, 0xb0080
	s_addc_u32 s49, s49, 0
	s_add_i32 s6, s19, s57
	v_lshl_add_u64 v[128:129], s[48:49], 0, v[140:141]
	s_mov_b32 m0, s6
	s_nop 0
	global_load_lds_dwordx4 v[128:129], off
	v_lshl_add_u64 v[128:129], s[48:49], 0, v[150:151]
	s_add_i32 m0, s6, 0x2000
	s_nop 0
	global_load_lds_dwordx4 v[128:129], off
	v_add_u32_e32 v146, 0x10000, v206
	ds_read_b128 v[128:131], v146
	ds_read_b128 v[132:135], v146 offset:1024
	ds_read_b128 v[136:139], v146 offset:2048
	ds_read_b128 v[146:149], v146 offset:3072
	s_waitcnt vmcnt(6)
	s_barrier
	s_setprio 1
	v_mfma_f32_16x16x32_bf16 v[52:55], v[214:217], v[162:165], v[52:55]
	v_mfma_f32_16x16x32_bf16 v[44:47], v[222:225], v[162:165], v[44:47]
	v_mfma_f32_16x16x32_bf16 v[36:39], v[214:217], v[170:173], v[36:39]
	v_mfma_f32_16x16x32_bf16 v[28:31], v[222:225], v[170:173], v[28:31]
	v_mfma_f32_16x16x32_bf16 v[20:23], v[214:217], v[178:181], v[20:23]
	v_mfma_f32_16x16x32_bf16 v[12:15], v[222:225], v[178:181], v[12:15]
	v_mfma_f32_16x16x32_bf16 v[4:7], v[214:217], v[194:197], v[4:7]
	v_mfma_f32_16x16x32_bf16 v[0:3], v[222:225], v[194:197], v[0:3]
	v_mfma_f32_16x16x32_bf16 v[52:55], v[218:221], v[166:169], v[52:55]
	v_mfma_f32_16x16x32_bf16 v[44:47], v[226:229], v[166:169], v[44:47]
	v_mfma_f32_16x16x32_bf16 v[36:39], v[218:221], v[174:177], v[36:39]
	v_mfma_f32_16x16x32_bf16 v[28:31], v[226:229], v[174:177], v[28:31]
	v_mfma_f32_16x16x32_bf16 v[20:23], v[218:221], v[182:185], v[20:23]
	v_mfma_f32_16x16x32_bf16 v[12:15], v[226:229], v[182:185], v[12:15]
	v_mfma_f32_16x16x32_bf16 v[4:7], v[218:221], v[210:213], v[4:7]
	v_mfma_f32_16x16x32_bf16 v[0:3], v[226:229], v[210:213], v[0:3]
	s_setprio 0
	s_add_i32 s12, s12, 2
	s_add_u32 s10, s10, 0x100
	s_addc_u32 s11, s11, 0
	s_cmp_gt_u32 s12, 41
	s_mov_b64 s[50:51], s[46:47]
	s_barrier
	s_cbranch_scc0 .LBB0_341
	s_waitcnt lgkmcnt(0)
	s_ashr_i32 s39, s38, 31
	v_lshl_or_b32 v128, s81, 8, v207
	s_lshl_b64 s[10:11], s[38:39], 8
	v_ashrrev_i32_e32 v129, 31, v128
	v_lshl_add_u64 v[168:169], s[10:11], 0, v[156:157]
	v_lshlrev_b64 v[170:171], 1, v[128:129]
	v_lshl_add_u64 v[174:175], s[26:27], 0, v[170:171]
	v_lshlrev_b64 v[172:173], 11, v[168:169]
	v_lshl_add_u64 v[128:129], v[174:175], 0, v[172:173]
	global_load_dwordx4 v[182:185], v[128:129], off
	global_load_dwordx4 v[210:213], v[128:129], off offset:256
	v_or_b32_e32 v166, 16, v168
	v_mov_b32_e32 v167, v169
	v_lshlrev_b64 v[176:177], 11, v[166:167]
	v_lshl_add_u64 v[128:129], v[174:175], 0, v[176:177]
	global_load_dwordx4 v[214:217], v[128:129], off
	global_load_dwordx4 v[218:221], v[128:129], off offset:256
	v_or_b32_e32 v164, 32, v168
	v_mov_b32_e32 v165, v169
	v_or_b32_e32 v162, 48, v168
	v_mov_b32_e32 v163, v169
	v_lshlrev_b64 v[180:181], 11, v[164:165]
	v_lshlrev_b64 v[178:179], 11, v[162:163]
	v_lshl_add_u64 v[128:129], v[174:175], 0, v[180:181]
	v_lshl_add_u64 v[130:131], v[174:175], 0, v[178:179]
	global_load_dwordx4 v[222:225], v[128:129], off
	global_load_dwordx4 v[136:139], v[128:129], off offset:256
	global_load_dwordx4 v[132:135], v[130:131], off
	s_nop 0
	global_load_dwordx4 v[128:131], v[130:131], off offset:256
	s_mov_b64 s[10:11], 0x90
	v_lshl_add_u64 v[172:173], s[28:29], 0, v[172:173]
	v_lshl_add_u64 v[172:173], v[172:173], 0, v[170:171]
	s_waitcnt vmcnt(0)
	v_lshlrev_b32_e32 v146, 16, v182
	v_and_b32_e32 v147, 0xffff0000, v182
	v_lshlrev_b32_e32 v148, 16, v184
	v_and_b32_e32 v149, 0xffff0000, v184
	v_lshlrev_b32_e32 v182, 16, v183
	v_and_b32_e32 v183, 0xffff0000, v183
	v_lshlrev_b32_e32 v194, 16, v210
	v_and_b32_e32 v195, 0xffff0000, v210
	v_lshlrev_b32_e32 v196, 16, v212
	v_and_b32_e32 v197, 0xffff0000, v212
	v_lshlrev_b32_e32 v210, 16, v211
	v_and_b32_e32 v211, 0xffff0000, v211
	v_lshlrev_b32_e32 v212, 16, v213
	v_and_b32_e32 v213, 0xffff0000, v213
	v_pk_fma_f32 v[124:125], v[124:125], 0.5, v[146:147] op_sel_hi:[1,0,1]
	v_pk_fma_f32 v[120:121], v[120:121], 0.5, v[148:149] op_sel_hi:[1,0,1]
	v_pk_fma_f32 v[126:127], v[126:127], 0.5, v[182:183] op_sel_hi:[1,0,1]
	v_pk_fma_f32 v[116:117], v[116:117], 0.5, v[194:195] op_sel_hi:[1,0,1]
	v_pk_fma_f32 v[146:147], v[112:113], 0.5, v[196:197] op_sel_hi:[1,0,1]
	v_pk_fma_f32 v[118:119], v[118:119], 0.5, v[210:211] op_sel_hi:[1,0,1]
	v_pk_fma_f32 v[148:149], v[114:115], 0.5, v[212:213] op_sel_hi:[1,0,1]
	v_pk_mul_f32 v[212:213], v[124:125], v[124:125]
	v_lshlrev_b32_e32 v182, 16, v214
	v_and_b32_e32 v183, 0xffff0000, v214
	v_lshlrev_b32_e32 v194, 16, v215
	v_and_b32_e32 v195, 0xffff0000, v215
	v_pk_mul_f32 v[214:215], v[126:127], v[126:127]
	v_cvt_pk_bf16_f32 v112, v124, v125
	v_cvt_pk_bf16_f32 v113, v126, v127
	v_pk_mul_f32 v[124:125], v[116:117], v[116:117]
	v_pk_mul_f32 v[126:127], v[118:119], v[118:119]
	v_pk_mul_f32 v[228:229], v[146:147], v[146:147]
	v_cvt_pk_bf16_f32 v116, v116, v117
	v_cvt_pk_bf16_f32 v117, v118, v119
	v_cvt_pk_bf16_f32 v118, v146, v147
	v_add_f32_e32 v146, v212, v213
	v_lshlrev_b32_e32 v184, 16, v185
	v_and_b32_e32 v185, 0xffff0000, v185
	v_add_f32_e32 v146, v214, v146
	v_pk_fma_f32 v[122:123], v[122:123], 0.5, v[184:185] op_sel_hi:[1,0,1]
	v_lshlrev_b32_e32 v184, 16, v216
	v_and_b32_e32 v185, 0xffff0000, v216
	v_lshlrev_b32_e32 v196, 16, v217
	v_and_b32_e32 v197, 0xffff0000, v217
	v_pk_mul_f32 v[216:217], v[120:121], v[120:121]
	v_add_f32_e32 v146, v215, v146
	v_add_f32_e32 v146, v216, v146
	v_pk_mul_f32 v[226:227], v[122:123], v[122:123]
	v_add_f32_e32 v146, v217, v146
	v_add_f32_e32 v146, v226, v146
	v_add_f32_e32 v146, v227, v146
	v_add_f32_e32 v124, v124, v146
	v_add_f32_e32 v124, v125, v124
	v_add_f32_e32 v124, v126, v124
	v_add_f32_e32 v124, v127, v124
	v_add_f32_e32 v124, v228, v124
	v_pk_mul_f32 v[230:231], v[148:149], v[148:149]
	v_add_f32_e32 v124, v229, v124
	v_add_f32_e32 v124, v230, v124
	v_add_f32_e32 v209, v231, v124
	v_lshlrev_b32_e32 v124, 16, v220
	v_and_b32_e32 v125, 0xffff0000, v220
	v_pk_fma_f32 v[124:125], v[92:93], 0.5, v[124:125] op_sel_hi:[1,0,1]
	v_lshlrev_b32_e32 v92, 16, v219
	v_and_b32_e32 v93, 0xffff0000, v219
	v_pk_fma_f32 v[102:103], v[102:103], 0.5, v[92:93] op_sel_hi:[1,0,1]
	v_lshlrev_b32_e32 v92, 16, v221
	v_and_b32_e32 v93, 0xffff0000, v221
	v_pk_fma_f32 v[126:127], v[94:95], 0.5, v[92:93] op_sel_hi:[1,0,1]
	v_lshlrev_b32_e32 v92, 16, v222
	v_and_b32_e32 v93, 0xffff0000, v222
	v_pk_fma_f32 v[92:93], v[96:97], 0.5, v[92:93] op_sel_hi:[1,0,1]
	v_lshlrev_b32_e32 v96, 16, v225
	v_and_b32_e32 v97, 0xffff0000, v225
	v_lshlrev_b32_e32 v94, 16, v224
	v_and_b32_e32 v95, 0xffff0000, v224
	v_pk_fma_f32 v[90:91], v[90:91], 0.5, v[96:97] op_sel_hi:[1,0,1]
	v_lshlrev_b32_e32 v96, 16, v136
	v_and_b32_e32 v97, 0xffff0000, v136
	v_pk_fma_f32 v[88:89], v[88:89], 0.5, v[94:95] op_sel_hi:[1,0,1]
	v_lshlrev_b32_e32 v94, 16, v223
	v_and_b32_e32 v95, 0xffff0000, v223
	v_pk_fma_f32 v[96:97], v[76:77], 0.5, v[96:97] op_sel_hi:[1,0,1]
	v_lshl_add_u64 v[76:77], v[168:169], 0, s[36:37]
	v_cvt_pk_bf16_f32 v114, v120, v121
	v_pk_fma_f32 v[120:121], v[108:109], 0.5, v[182:183] op_sel_hi:[1,0,1]
	v_pk_fma_f32 v[94:95], v[98:99], 0.5, v[94:95] op_sel_hi:[1,0,1]
	v_lshlrev_b64 v[182:183], 11, v[76:77]
	v_lshlrev_b32_e32 v98, 16, v138
	v_and_b32_e32 v99, 0xffff0000, v138
	v_lshl_add_u64 v[146:147], v[174:175], 0, v[182:183]
	v_pk_fma_f32 v[98:99], v[72:73], 0.5, v[98:99] op_sel_hi:[1,0,1]
	v_lshlrev_b32_e32 v72, 16, v137
	v_and_b32_e32 v73, 0xffff0000, v137
	v_lshlrev_b32_e32 v210, 16, v218
	v_and_b32_e32 v211, 0xffff0000, v218
	global_load_dwordx4 v[218:221], v[146:147], off
	global_load_dwordx4 v[226:229], v[146:147], off offset:256
	v_pk_fma_f32 v[136:137], v[78:79], 0.5, v[72:73] op_sel_hi:[1,0,1]
	v_lshlrev_b32_e32 v72, 16, v139
	v_and_b32_e32 v73, 0xffff0000, v139
	v_pk_fma_f32 v[138:139], v[74:75], 0.5, v[72:73] op_sel_hi:[1,0,1]
	v_lshlrev_b32_e32 v72, 16, v132
	v_and_b32_e32 v73, 0xffff0000, v132
	v_pk_fma_f32 v[74:75], v[84:85], 0.5, v[72:73] op_sel_hi:[1,0,1]
	v_lshlrev_b32_e32 v72, 16, v134
	v_and_b32_e32 v73, 0xffff0000, v134
	v_pk_fma_f32 v[78:79], v[80:81], 0.5, v[72:73] op_sel_hi:[1,0,1]
	v_lshlrev_b32_e32 v72, 16, v133
	v_and_b32_e32 v73, 0xffff0000, v133
	v_pk_fma_f32 v[80:81], v[86:87], 0.5, v[72:73] op_sel_hi:[1,0,1]
	v_lshlrev_b32_e32 v72, 16, v135
	v_and_b32_e32 v73, 0xffff0000, v135
	v_pk_fma_f32 v[82:83], v[82:83], 0.5, v[72:73] op_sel_hi:[1,0,1]
	v_lshl_add_u64 v[72:73], v[168:169], 0, s[10:11]
	v_lshlrev_b64 v[132:133], 11, v[72:73]
	v_lshl_add_u64 v[134:135], v[174:175], 0, v[132:133]
	global_load_dwordx4 v[234:237], v[134:135], off
	global_load_dwordx4 v[242:245], v[134:135], off offset:256
	v_lshlrev_b32_e32 v84, 16, v128
	v_and_b32_e32 v85, 0xffff0000, v128
	v_pk_fma_f32 v[84:85], v[68:69], 0.5, v[84:85] op_sel_hi:[1,0,1]
	v_lshlrev_b32_e32 v68, 16, v130
	v_and_b32_e32 v69, 0xffff0000, v130
	v_pk_fma_f32 v[86:87], v[64:65], 0.5, v[68:69] op_sel_hi:[1,0,1]
	v_lshlrev_b32_e32 v64, 16, v129
	v_and_b32_e32 v65, 0xffff0000, v129
	s_mov_b64 s[10:11], 0xa0
	v_pk_fma_f32 v[128:129], v[70:71], 0.5, v[64:65] op_sel_hi:[1,0,1]
	v_lshl_add_u64 v[70:71], v[168:169], 0, s[10:11]
	v_lshlrev_b32_e32 v64, 16, v131
	v_and_b32_e32 v65, 0xffff0000, v131
	v_lshlrev_b64 v[134:135], 11, v[70:71]
	v_pk_fma_f32 v[130:131], v[66:67], 0.5, v[64:65] op_sel_hi:[1,0,1]
	v_lshl_add_u64 v[64:65], v[174:175], 0, v[134:135]
	v_cvt_pk_bf16_f32 v115, v122, v123
	v_pk_fma_f32 v[122:123], v[110:111], 0.5, v[194:195] op_sel_hi:[1,0,1]
	v_pk_fma_f32 v[110:111], v[106:107], 0.5, v[196:197] op_sel_hi:[1,0,1]
	global_load_dwordx4 v[246:249], v[64:65], off
	global_load_dwordx4 v[194:197], v[64:65], off offset:256
	s_mov_b64 s[10:11], 0xb0
	v_lshl_add_u64 v[68:69], v[168:169], 0, s[10:11]
	v_pk_fma_f32 v[108:109], v[104:105], 0.5, v[184:185] op_sel_hi:[1,0,1]
	v_lshlrev_b64 v[184:185], 11, v[68:69]
	v_lshl_add_u64 v[64:65], v[174:175], 0, v[184:185]
	v_cvt_pk_bf16_f32 v119, v148, v149
	global_load_dwordx4 v[146:149], v[64:65], off
	s_nop 0
	global_load_dwordx4 v[64:67], v[64:65], off offset:256
	global_store_dwordx4 v[172:173], v[112:115], off
	global_store_dwordx4 v[172:173], v[116:119], off offset:256
	v_cvt_pk_bf16_f32 v104, v120, v121
	v_lshl_add_u64 v[112:113], s[28:29], 0, v[176:177]
	v_cvt_pk_bf16_f32 v105, v122, v123
	v_cvt_pk_bf16_f32 v106, v108, v109
	v_cvt_pk_bf16_f32 v107, v110, v111
	v_pk_fma_f32 v[100:101], v[100:101], 0.5, v[210:211] op_sel_hi:[1,0,1]
	v_lshl_add_u64 v[112:113], v[112:113], 0, v[170:171]
	v_cvt_pk_bf16_f32 v210, v100, v101
	v_cvt_pk_bf16_f32 v211, v102, v103
	v_cvt_pk_bf16_f32 v212, v124, v125
	v_cvt_pk_bf16_f32 v213, v126, v127
	global_store_dwordx4 v[112:113], v[104:107], off
	global_store_dwordx4 v[112:113], v[210:213], off offset:256
	v_cvt_pk_bf16_f32 v214, v92, v93
	v_lshl_add_u64 v[104:105], s[28:29], 0, v[180:181]
	v_cvt_pk_bf16_f32 v215, v94, v95
	v_cvt_pk_bf16_f32 v216, v88, v89
	v_cvt_pk_bf16_f32 v217, v90, v91
	v_lshl_add_u64 v[104:105], v[104:105], 0, v[170:171]
	v_cvt_pk_bf16_f32 v222, v96, v97
	v_cvt_pk_bf16_f32 v223, v136, v137
	v_cvt_pk_bf16_f32 v224, v98, v99
	v_cvt_pk_bf16_f32 v225, v138, v139
	global_store_dwordx4 v[104:105], v[214:217], off
	global_store_dwordx4 v[104:105], v[222:225], off offset:256
	v_lshl_add_u64 v[104:105], s[28:29], 0, v[178:179]
	v_cvt_pk_bf16_f32 v230, v74, v75
	v_cvt_pk_bf16_f32 v231, v80, v81
	v_cvt_pk_bf16_f32 v232, v78, v79
	v_cvt_pk_bf16_f32 v233, v82, v83
	v_lshl_add_u64 v[104:105], v[104:105], 0, v[170:171]
	v_cvt_pk_bf16_f32 v238, v84, v85
	v_cvt_pk_bf16_f32 v239, v128, v129
	v_cvt_pk_bf16_f32 v240, v86, v87
	v_cvt_pk_bf16_f32 v241, v130, v131
	global_store_dwordx4 v[104:105], v[230:233], off
	global_store_dwordx4 v[104:105], v[238:241], off offset:256
	s_waitcnt vmcnt(0)
	v_lshlrev_b32_e32 v104, 16, v218
	v_and_b32_e32 v105, 0xffff0000, v218
	v_pk_fma_f32 v[60:61], v[60:61], 0.5, v[104:105] op_sel_hi:[1,0,1]
	v_lshlrev_b32_e32 v104, 16, v220
	v_and_b32_e32 v105, 0xffff0000, v220
	v_pk_fma_f32 v[56:57], v[56:57], 0.5, v[104:105] op_sel_hi:[1,0,1]
	v_lshlrev_b32_e32 v104, 16, v219
	v_and_b32_e32 v105, 0xffff0000, v219
	v_pk_fma_f32 v[62:63], v[62:63], 0.5, v[104:105] op_sel_hi:[1,0,1]
	v_lshlrev_b32_e32 v104, 16, v221
	v_and_b32_e32 v105, 0xffff0000, v221
	v_pk_fma_f32 v[58:59], v[58:59], 0.5, v[104:105] op_sel_hi:[1,0,1]
	v_lshlrev_b32_e32 v104, 16, v226
	v_and_b32_e32 v105, 0xffff0000, v226
	v_pk_fma_f32 v[52:53], v[52:53], 0.5, v[104:105] op_sel_hi:[1,0,1]
	v_lshlrev_b32_e32 v104, 16, v228
	v_and_b32_e32 v105, 0xffff0000, v228
	v_pk_fma_f32 v[104:105], v[44:45], 0.5, v[104:105] op_sel_hi:[1,0,1]
	v_lshlrev_b32_e32 v44, 16, v227
	v_and_b32_e32 v45, 0xffff0000, v227
	v_pk_fma_f32 v[54:55], v[54:55], 0.5, v[44:45] op_sel_hi:[1,0,1]
	v_lshlrev_b32_e32 v44, 16, v229
	v_and_b32_e32 v45, 0xffff0000, v229
	v_pk_fma_f32 v[106:107], v[46:47], 0.5, v[44:45] op_sel_hi:[1,0,1]
	v_lshlrev_b32_e32 v44, 16, v234
	v_and_b32_e32 v45, 0xffff0000, v234
	v_pk_fma_f32 v[44:45], v[48:49], 0.5, v[44:45] op_sel_hi:[1,0,1]
	v_lshlrev_b32_e32 v48, 16, v237
	v_and_b32_e32 v49, 0xffff0000, v237
	v_pk_fma_f32 v[42:43], v[42:43], 0.5, v[48:49] op_sel_hi:[1,0,1]
	v_lshlrev_b32_e32 v48, 16, v242
	v_and_b32_e32 v49, 0xffff0000, v242
	v_pk_fma_f32 v[36:37], v[36:37], 0.5, v[48:49] op_sel_hi:[1,0,1]
	v_lshlrev_b32_e32 v48, 16, v244
	v_and_b32_e32 v49, 0xffff0000, v244
	v_lshlrev_b32_e32 v46, 16, v236
	v_and_b32_e32 v47, 0xffff0000, v236
	v_pk_fma_f32 v[48:49], v[28:29], 0.5, v[48:49] op_sel_hi:[1,0,1]
	v_lshlrev_b32_e32 v28, 16, v243
	v_and_b32_e32 v29, 0xffff0000, v243
	v_pk_fma_f32 v[40:41], v[40:41], 0.5, v[46:47] op_sel_hi:[1,0,1]
	v_lshlrev_b32_e32 v46, 16, v235
	v_and_b32_e32 v47, 0xffff0000, v235
	v_pk_fma_f32 v[38:39], v[38:39], 0.5, v[28:29] op_sel_hi:[1,0,1]
	v_lshlrev_b32_e32 v28, 16, v245
	v_and_b32_e32 v29, 0xffff0000, v245
	v_pk_fma_f32 v[46:47], v[50:51], 0.5, v[46:47] op_sel_hi:[1,0,1]
	v_pk_fma_f32 v[50:51], v[30:31], 0.5, v[28:29] op_sel_hi:[1,0,1]
	v_lshlrev_b32_e32 v28, 16, v246
	v_and_b32_e32 v29, 0xffff0000, v246
	v_pk_fma_f32 v[28:29], v[32:33], 0.5, v[28:29] op_sel_hi:[1,0,1]
	v_lshlrev_b32_e32 v32, 16, v249
	v_and_b32_e32 v33, 0xffff0000, v249
	v_pk_fma_f32 v[26:27], v[26:27], 0.5, v[32:33] op_sel_hi:[1,0,1]
	v_lshlrev_b32_e32 v32, 16, v194
	v_and_b32_e32 v33, 0xffff0000, v194
	v_pk_fma_f32 v[20:21], v[20:21], 0.5, v[32:33] op_sel_hi:[1,0,1]
	v_lshlrev_b32_e32 v32, 16, v196
	v_and_b32_e32 v33, 0xffff0000, v196
	v_lshlrev_b32_e32 v30, 16, v248
	v_and_b32_e32 v31, 0xffff0000, v248
	v_pk_fma_f32 v[32:33], v[12:13], 0.5, v[32:33] op_sel_hi:[1,0,1]
	v_lshlrev_b32_e32 v12, 16, v195
	v_and_b32_e32 v13, 0xffff0000, v195
	v_pk_fma_f32 v[24:25], v[24:25], 0.5, v[30:31] op_sel_hi:[1,0,1]
	v_lshlrev_b32_e32 v30, 16, v247
	v_and_b32_e32 v31, 0xffff0000, v247
	v_pk_fma_f32 v[22:23], v[22:23], 0.5, v[12:13] op_sel_hi:[1,0,1]
	v_lshlrev_b32_e32 v12, 16, v197
	v_and_b32_e32 v13, 0xffff0000, v197
	v_pk_fma_f32 v[30:31], v[34:35], 0.5, v[30:31] op_sel_hi:[1,0,1]
	v_pk_fma_f32 v[34:35], v[14:15], 0.5, v[12:13] op_sel_hi:[1,0,1]
	v_lshlrev_b32_e32 v14, 16, v148
	v_and_b32_e32 v15, 0xffff0000, v148
	v_lshlrev_b32_e32 v12, 16, v146
	v_and_b32_e32 v13, 0xffff0000, v146
	v_pk_fma_f32 v[8:9], v[8:9], 0.5, v[14:15] op_sel_hi:[1,0,1]
	v_lshlrev_b32_e32 v14, 16, v147
	v_and_b32_e32 v15, 0xffff0000, v147
	v_lshlrev_b32_e32 v146, 16, v64
	v_and_b32_e32 v147, 0xffff0000, v64
	v_pk_fma_f32 v[4:5], v[4:5], 0.5, v[146:147] op_sel_hi:[1,0,1]
	v_lshlrev_b32_e32 v146, 16, v66
	v_and_b32_e32 v147, 0xffff0000, v66
	v_pk_fma_f32 v[0:1], v[0:1], 0.5, v[146:147] op_sel_hi:[1,0,1]
	v_lshl_add_u64 v[146:147], s[28:29], 0, v[182:183]
	v_cvt_pk_bf16_f32 v112, v60, v61
	v_cvt_pk_bf16_f32 v113, v62, v63
	v_cvt_pk_bf16_f32 v114, v56, v57
	v_cvt_pk_bf16_f32 v115, v58, v59
	v_lshl_add_u64 v[146:147], v[146:147], 0, v[170:171]
	v_cvt_pk_bf16_f32 v116, v52, v53
	v_cvt_pk_bf16_f32 v117, v54, v55
	v_cvt_pk_bf16_f32 v118, v104, v105
	v_cvt_pk_bf16_f32 v119, v106, v107
	global_store_dwordx4 v[146:147], v[112:115], off
	global_store_dwordx4 v[146:147], v[116:119], off offset:256
	v_cvt_pk_bf16_f32 v172, v44, v45
	v_lshl_add_u64 v[112:113], s[28:29], 0, v[132:133]
	v_cvt_pk_bf16_f32 v173, v46, v47
	v_cvt_pk_bf16_f32 v174, v40, v41
	v_cvt_pk_bf16_f32 v175, v42, v43
	v_lshl_add_u64 v[112:113], v[112:113], 0, v[170:171]
	v_cvt_pk_bf16_f32 v176, v36, v37
	v_cvt_pk_bf16_f32 v177, v38, v39
	v_cvt_pk_bf16_f32 v178, v48, v49
	v_cvt_pk_bf16_f32 v179, v50, v51
	global_store_dwordx4 v[112:113], v[172:175], off
	global_store_dwordx4 v[112:113], v[176:179], off offset:256
	v_lshl_add_u64 v[112:113], s[28:29], 0, v[134:135]
	v_cvt_pk_bf16_f32 v210, v28, v29
	v_cvt_pk_bf16_f32 v211, v30, v31
	v_cvt_pk_bf16_f32 v212, v24, v25
	v_cvt_pk_bf16_f32 v213, v26, v27
	v_pk_fma_f32 v[12:13], v[16:17], 0.5, v[12:13] op_sel_hi:[1,0,1]
	v_lshlrev_b32_e32 v16, 16, v149
	v_and_b32_e32 v17, 0xffff0000, v149
	v_lshlrev_b32_e32 v64, 16, v65
	v_and_b32_e32 v65, 0xffff0000, v65
	v_lshl_add_u64 v[112:113], v[112:113], 0, v[170:171]
	v_cvt_pk_bf16_f32 v194, v20, v21
	v_cvt_pk_bf16_f32 v195, v22, v23
	v_cvt_pk_bf16_f32 v196, v32, v33
	v_cvt_pk_bf16_f32 v197, v34, v35
	v_pk_fma_f32 v[14:15], v[18:19], 0.5, v[14:15] op_sel_hi:[1,0,1]
	v_pk_fma_f32 v[10:11], v[10:11], 0.5, v[16:17] op_sel_hi:[1,0,1]
	v_pk_fma_f32 v[6:7], v[6:7], 0.5, v[64:65] op_sel_hi:[1,0,1]
	v_lshlrev_b32_e32 v64, 16, v67
	v_and_b32_e32 v65, 0xffff0000, v67
	global_store_dwordx4 v[112:113], v[210:213], off
	global_store_dwordx4 v[112:113], v[194:197], off offset:256
	v_lshl_add_u64 v[112:113], s[28:29], 0, v[184:185]
	v_cvt_pk_bf16_f32 v16, v12, v13
	v_cvt_pk_bf16_f32 v17, v14, v15
	v_cvt_pk_bf16_f32 v18, v8, v9
	v_cvt_pk_bf16_f32 v19, v10, v11
	v_pk_fma_f32 v[2:3], v[2:3], 0.5, v[64:65] op_sel_hi:[1,0,1]
	v_lshl_add_u64 v[112:113], v[112:113], 0, v[170:171]
	v_cvt_pk_bf16_f32 v64, v4, v5
	v_cvt_pk_bf16_f32 v65, v6, v7
	v_cvt_pk_bf16_f32 v66, v0, v1
	v_cvt_pk_bf16_f32 v67, v2, v3
	global_store_dwordx4 v[112:113], v[16:19], off
	global_store_dwordx4 v[112:113], v[64:67], off offset:256
	s_lshl_b32 s10, s81, 2
	v_and_b32_e32 v17, 64, v188
	v_xor_b32_e32 v16, 16, v188
	v_add_u32_e32 v17, 64, v17
	v_cmp_lt_i32_e32 vcc, v16, v17
	v_xor_b32_e32 v18, 32, v188
	s_ashr_i32 s11, s10, 31
	v_cndmask_b32_e32 v16, v188, v16, vcc
	v_lshlrev_b32_e32 v16, 2, v16
	ds_bpermute_b32 v19, v16, v209
	v_cmp_lt_i32_e32 vcc, v18, v17
	s_lshl_b64 s[10:11], s[10:11], 2
	s_add_u32 s38, s73, s10
	v_cndmask_b32_e32 v17, v188, v18, vcc
	v_lshlrev_b32_e32 v17, 2, v17
	s_waitcnt lgkmcnt(0)
	v_add_f32_e32 v18, v209, v19
	ds_bpermute_b32 v19, v17, v18
	s_addc_u32 s39, s74, s11
	s_and_saveexec_b64 s[46:47], s[42:43]
	s_cbranch_execz .LBB0_344
	s_waitcnt lgkmcnt(0)
	v_add_f32_e32 v64, v18, v19
	v_lshlrev_b64 v[18:19], 6, v[168:169]
	v_lshl_add_u64 v[18:19], s[38:39], 0, v[18:19]
	global_store_dword v[18:19], v64, off

.LBB0_385:
	s_add_u32 s10, s52, 0x100
	s_addc_u32 s11, s53, 0
	s_ashr_i32 s39, s38, 31
	s_lshl_b64 s[48:49], s[38:39], 19
	s_add_u32 s50, s33, s48
	s_addc_u32 s51, s41, s49
	s_and_b64 s[48:49], s[44:45], exec
	s_cselect_b32 s12, s51, s29
	s_cselect_b32 s35, s50, s28
	s_ashr_i32 s47, s46, 31
	s_lshl_b64 s[48:49], s[46:47], 19
	s_add_u32 s48, s26, s48
	s_addc_u32 s49, s27, s49
	s_and_b64 s[54:55], s[44:45], exec
	s_cselect_b32 s39, s49, s53
	s_cselect_b32 s47, s48, s52
	s_add_u32 s52, s28, 0x40080
	s_addc_u32 s53, s29, 0
	v_lshl_add_u64 v[150:151], s[52:53], 0, v[136:137]
	v_lshl_add_u64 v[152:153], s[52:53], 0, v[138:139]
	s_mov_b32 s81, -2
	s_mov_b64 s[52:53], 0
	v_add_u32_e32 v146, 0x10000, v154
	ds_read_b128 v[158:161], v146
	ds_read_b128 v[162:165], v146 offset:1024
	ds_read_b128 v[166:169], v146 offset:2048
	ds_read_b128 v[170:173], v146 offset:3072
.LBB0_386:
	s_add_u32 s6, s28, s52
	s_addc_u32 s19, s29, s53
	s_add_u32 s6, s6, 0x100
	s_addc_u32 s19, s19, 0
	s_add_u32 s23, s10, s52
	s_addc_u32 s54, s11, s53
	s_add_i32 s82, 0, 0x10000
	s_cmpk_eq_i32 s52, 0x700
	s_cselect_b32 s59, s12, s19
	s_cselect_b32 s58, s35, s6
	s_cselect_b32 s55, s39, s54
	s_cselect_b32 s54, s47, s23
	v_lshl_add_u64 v[146:147], v[150:151], 0, s[52:53]
	s_add_i32 m0, s68, 0xc000
	ds_read_b128 v[174:177], v157
	ds_read_b128 v[178:181], v157 offset:1024
	ds_read_b128 v[182:185], v157 offset:2048
	ds_read_b128 v[206:209], v157 offset:3072
	ds_read_b128 v[210:213], v157 offset:4096
	ds_read_b128 v[214:217], v157 offset:5120
	ds_read_b128 v[218:221], v157 offset:6144
	ds_read_b128 v[222:225], v157 offset:7168
	global_load_lds_dwordx4 v[146:147], off
	v_lshl_add_u64 v[146:147], v[152:153], 0, s[52:53]
	s_add_i32 m0, s68, 0xe000
	s_nop 0
	global_load_lds_dwordx4 v[146:147], off
	s_waitcnt lgkmcnt(8)
	s_barrier
	s_setprio 1
	s_waitcnt lgkmcnt(7)
	v_mfma_f32_16x16x32_bf16 v[124:127], v[158:161], v[174:177], v[124:127]
	v_mfma_f32_16x16x32_bf16 v[120:123], v[166:169], v[174:177], v[120:123]
	s_waitcnt lgkmcnt(5)
	v_mfma_f32_16x16x32_bf16 v[116:119], v[158:161], v[182:185], v[116:119]
	v_mfma_f32_16x16x32_bf16 v[112:115], v[166:169], v[182:185], v[112:115]
	s_waitcnt lgkmcnt(3)
	v_mfma_f32_16x16x32_bf16 v[108:111], v[158:161], v[210:213], v[108:111]
	v_mfma_f32_16x16x32_bf16 v[104:107], v[166:169], v[210:213], v[104:107]
	s_waitcnt lgkmcnt(1)
	v_mfma_f32_16x16x32_bf16 v[100:103], v[158:161], v[218:221], v[100:103]
	v_mfma_f32_16x16x32_bf16 v[96:99], v[166:169], v[218:221], v[96:99]
	v_mfma_f32_16x16x32_bf16 v[124:127], v[162:165], v[178:181], v[124:127]
	v_mfma_f32_16x16x32_bf16 v[120:123], v[170:173], v[178:181], v[120:123]
	v_mfma_f32_16x16x32_bf16 v[116:119], v[162:165], v[206:209], v[116:119]
	v_mfma_f32_16x16x32_bf16 v[112:115], v[170:173], v[206:209], v[112:115]
	v_mfma_f32_16x16x32_bf16 v[108:111], v[162:165], v[214:217], v[108:111]
	v_mfma_f32_16x16x32_bf16 v[104:107], v[170:173], v[214:217], v[104:107]
	s_waitcnt lgkmcnt(0)
	v_mfma_f32_16x16x32_bf16 v[100:103], v[162:165], v[222:225], v[100:103]
	v_mfma_f32_16x16x32_bf16 v[96:99], v[170:173], v[222:225], v[96:99]
	s_setprio 0
	s_barrier
	s_add_i32 s6, 0, 0x14000
	v_add_u32_e32 v146, s6, v154
	s_add_i32 s19, s82, s57
	ds_read_b128 v[226:229], v146
	ds_read_b128 v[230:233], v146 offset:1024
	ds_read_b128 v[234:237], v146 offset:2048
	ds_read_b128 v[238:241], v146 offset:3072
	v_lshl_add_u64 v[146:147], s[54:55], 0, v[140:141]
	s_mov_b32 m0, s19
	v_lshl_add_u64 v[148:149], s[54:55], 0, v[132:133]
	global_load_lds_dwordx4 v[146:147], off
	s_add_i32 m0, s19, 0x2000
	s_nop 0
	global_load_lds_dwordx4 v[148:149], off
	s_barrier
	s_setprio 1
	s_waitcnt lgkmcnt(3)
	v_mfma_f32_16x16x32_bf16 v[92:95], v[226:229], v[174:177], v[92:95]
	s_waitcnt lgkmcnt(1)
	v_mfma_f32_16x16x32_bf16 v[88:91], v[234:237], v[174:177], v[88:91]
	v_mfma_f32_16x16x32_bf16 v[84:87], v[226:229], v[182:185], v[84:87]
	v_mfma_f32_16x16x32_bf16 v[80:83], v[234:237], v[182:185], v[80:83]
	v_mfma_f32_16x16x32_bf16 v[76:79], v[226:229], v[210:213], v[76:79]
	v_mfma_f32_16x16x32_bf16 v[72:75], v[234:237], v[210:213], v[72:75]
	v_mfma_f32_16x16x32_bf16 v[68:71], v[226:229], v[218:221], v[68:71]
	v_mfma_f32_16x16x32_bf16 v[64:67], v[234:237], v[218:221], v[64:67]
	v_mfma_f32_16x16x32_bf16 v[92:95], v[230:233], v[178:181], v[92:95]
	s_waitcnt lgkmcnt(0)
	v_mfma_f32_16x16x32_bf16 v[88:91], v[238:241], v[178:181], v[88:91]
	v_mfma_f32_16x16x32_bf16 v[84:87], v[230:233], v[206:209], v[84:87]
	v_mfma_f32_16x16x32_bf16 v[80:83], v[238:241], v[206:209], v[80:83]
	v_mfma_f32_16x16x32_bf16 v[76:79], v[230:233], v[214:217], v[76:79]
	v_mfma_f32_16x16x32_bf16 v[72:75], v[238:241], v[214:217], v[72:75]
	v_mfma_f32_16x16x32_bf16 v[68:71], v[230:233], v[222:225], v[68:71]
	v_mfma_f32_16x16x32_bf16 v[64:67], v[238:241], v[222:225], v[64:67]
	s_setprio 0
	s_mov_b32 m0, s68
	v_lshl_add_u64 v[194:195], s[58:59], 0, v[128:129]
	s_barrier
	ds_read_b128 v[174:177], v157 offset:16384
	ds_read_b128 v[178:181], v157 offset:17408
	ds_read_b128 v[182:185], v157 offset:18432
	ds_read_b128 v[206:209], v157 offset:19456
	ds_read_b128 v[210:213], v157 offset:20480
	ds_read_b128 v[214:217], v157 offset:21504
	ds_read_b128 v[218:221], v157 offset:22528
	ds_read_b128 v[222:225], v157 offset:23552
	global_load_lds_dwordx4 v[194:195], off
	v_lshl_add_u64 v[196:197], s[58:59], 0, v[130:131]
	s_mov_b32 m0, s69
	s_nop 0
	global_load_lds_dwordx4 v[196:197], off
	s_waitcnt vmcnt(10)
	s_barrier
	s_setprio 1
	s_waitcnt lgkmcnt(7)
	v_mfma_f32_16x16x32_bf16 v[60:63], v[158:161], v[174:177], v[60:63]
	v_mfma_f32_16x16x32_bf16 v[56:59], v[166:169], v[174:177], v[56:59]
	s_waitcnt lgkmcnt(5)
	v_mfma_f32_16x16x32_bf16 v[52:55], v[158:161], v[182:185], v[52:55]
	v_mfma_f32_16x16x32_bf16 v[48:51], v[166:169], v[182:185], v[48:51]
	s_waitcnt lgkmcnt(3)
	v_mfma_f32_16x16x32_bf16 v[44:47], v[158:161], v[210:213], v[44:47]
	v_mfma_f32_16x16x32_bf16 v[40:43], v[166:169], v[210:213], v[40:43]
	s_waitcnt lgkmcnt(1)
	v_mfma_f32_16x16x32_bf16 v[36:39], v[158:161], v[218:221], v[36:39]
	v_mfma_f32_16x16x32_bf16 v[32:35], v[166:169], v[218:221], v[32:35]
	v_mfma_f32_16x16x32_bf16 v[60:63], v[162:165], v[178:181], v[60:63]
	v_mfma_f32_16x16x32_bf16 v[56:59], v[170:173], v[178:181], v[56:59]
	v_mfma_f32_16x16x32_bf16 v[52:55], v[162:165], v[206:209], v[52:55]
	v_mfma_f32_16x16x32_bf16 v[48:51], v[170:173], v[206:209], v[48:51]
	v_mfma_f32_16x16x32_bf16 v[44:47], v[162:165], v[214:217], v[44:47]
	v_mfma_f32_16x16x32_bf16 v[40:43], v[170:173], v[214:217], v[40:43]
	s_waitcnt lgkmcnt(0)
	v_mfma_f32_16x16x32_bf16 v[36:39], v[162:165], v[222:225], v[36:39]
	v_mfma_f32_16x16x32_bf16 v[32:35], v[170:173], v[222:225], v[32:35]
	s_setprio 0
	s_barrier
	s_add_u32 s82, s54, 0x40000
	s_addc_u32 s83, s55, 0
	s_add_i32 s6, s6, s57
	v_lshl_add_u64 v[158:159], s[82:83], 0, v[140:141]
	s_mov_b32 m0, s6
	s_nop 0
	global_load_lds_dwordx4 v[158:159], off
	v_lshl_add_u64 v[158:159], s[82:83], 0, v[132:133]
	s_add_i32 m0, s6, 0x2000
	s_nop 0
	global_load_lds_dwordx4 v[158:159], off
	v_add_u32_e32 v170, 0x18000, v154
	ds_read_b128 v[158:161], v170
	ds_read_b128 v[162:165], v170 offset:1024
	ds_read_b128 v[166:169], v170 offset:2048
	ds_read_b128 v[170:173], v170 offset:3072
	s_waitcnt vmcnt(6)
	s_barrier
	s_setprio 1
	v_mfma_f32_16x16x32_bf16 v[28:31], v[226:229], v[174:177], v[28:31]
	v_mfma_f32_16x16x32_bf16 v[24:27], v[234:237], v[174:177], v[24:27]
	v_mfma_f32_16x16x32_bf16 v[20:23], v[226:229], v[182:185], v[20:23]
	v_mfma_f32_16x16x32_bf16 v[16:19], v[234:237], v[182:185], v[16:19]
	v_mfma_f32_16x16x32_bf16 v[12:15], v[226:229], v[210:213], v[12:15]
	v_mfma_f32_16x16x32_bf16 v[8:11], v[234:237], v[210:213], v[8:11]
	v_mfma_f32_16x16x32_bf16 v[4:7], v[226:229], v[218:221], v[4:7]
	v_mfma_f32_16x16x32_bf16 v[0:3], v[234:237], v[218:221], v[0:3]
	v_mfma_f32_16x16x32_bf16 v[28:31], v[230:233], v[178:181], v[28:31]
	v_mfma_f32_16x16x32_bf16 v[24:27], v[238:241], v[178:181], v[24:27]
	v_mfma_f32_16x16x32_bf16 v[20:23], v[230:233], v[206:209], v[20:23]
	v_mfma_f32_16x16x32_bf16 v[16:19], v[238:241], v[206:209], v[16:19]
	v_mfma_f32_16x16x32_bf16 v[12:15], v[230:233], v[214:217], v[12:15]
	v_mfma_f32_16x16x32_bf16 v[8:11], v[238:241], v[214:217], v[8:11]
	v_mfma_f32_16x16x32_bf16 v[4:7], v[230:233], v[222:225], v[4:7]
	v_mfma_f32_16x16x32_bf16 v[0:3], v[238:241], v[222:225], v[0:3]
	s_setprio 0
	s_add_i32 s6, 0, 0x18000
	s_barrier
	s_add_u32 s58, s58, 0x40000
	s_addc_u32 s59, s59, 0
	s_mov_b32 m0, s70
	v_lshl_add_u64 v[226:227], s[58:59], 0, v[128:129]
	ds_read_b128 v[174:177], v157 offset:32768
	ds_read_b128 v[178:181], v157 offset:33792
	ds_read_b128 v[182:185], v157 offset:34816
	ds_read_b128 v[206:209], v157 offset:35840
	ds_read_b128 v[210:213], v157 offset:36864
	ds_read_b128 v[214:217], v157 offset:37888
	ds_read_b128 v[218:221], v157 offset:38912
	ds_read_b128 v[222:225], v157 offset:39936
	global_load_lds_dwordx4 v[226:227], off
	v_lshl_add_u64 v[226:227], s[58:59], 0, v[130:131]
	s_mov_b32 m0, s71
	s_nop 0
	global_load_lds_dwordx4 v[226:227], off
	s_waitcnt lgkmcnt(8)
	s_barrier
	s_setprio 1
	s_waitcnt lgkmcnt(7)
	v_mfma_f32_16x16x32_bf16 v[124:127], v[158:161], v[174:177], v[124:127]
	v_mfma_f32_16x16x32_bf16 v[120:123], v[166:169], v[174:177], v[120:123]
	s_waitcnt lgkmcnt(5)
	v_mfma_f32_16x16x32_bf16 v[116:119], v[158:161], v[182:185], v[116:119]
	v_mfma_f32_16x16x32_bf16 v[112:115], v[166:169], v[182:185], v[112:115]
	s_waitcnt lgkmcnt(3)
	v_mfma_f32_16x16x32_bf16 v[108:111], v[158:161], v[210:213], v[108:111]
	v_mfma_f32_16x16x32_bf16 v[104:107], v[166:169], v[210:213], v[104:107]
	s_waitcnt lgkmcnt(1)
	v_mfma_f32_16x16x32_bf16 v[100:103], v[158:161], v[218:221], v[100:103]
	v_mfma_f32_16x16x32_bf16 v[96:99], v[166:169], v[218:221], v[96:99]
	v_mfma_f32_16x16x32_bf16 v[124:127], v[162:165], v[178:181], v[124:127]
	v_mfma_f32_16x16x32_bf16 v[120:123], v[170:173], v[178:181], v[120:123]
	v_mfma_f32_16x16x32_bf16 v[116:119], v[162:165], v[206:209], v[116:119]
	v_mfma_f32_16x16x32_bf16 v[112:115], v[170:173], v[206:209], v[112:115]
	v_mfma_f32_16x16x32_bf16 v[108:111], v[162:165], v[214:217], v[108:111]
	v_mfma_f32_16x16x32_bf16 v[104:107], v[170:173], v[214:217], v[104:107]
	s_waitcnt lgkmcnt(0)
	v_mfma_f32_16x16x32_bf16 v[100:103], v[162:165], v[222:225], v[100:103]
	v_mfma_f32_16x16x32_bf16 v[96:99], v[170:173], v[222:225], v[96:99]
	s_setprio 0
	s_barrier
	s_add_i32 s19, 0, 0x1c000
	s_add_i32 s6, s6, s57
	v_add_u32_e32 v192, s19, v154
	v_lshl_add_u64 v[146:147], v[146:147], 0, s[36:37]
	s_mov_b32 m0, s6
	ds_read_b128 v[226:229], v192
	ds_read_b128 v[230:233], v192 offset:1024
	ds_read_b128 v[234:237], v192 offset:2048
	ds_read_b128 v[238:241], v192 offset:3072
	global_load_lds_dwordx4 v[146:147], off
	v_lshl_add_u64 v[146:147], v[148:149], 0, s[36:37]
	s_add_i32 m0, s6, 0x2000
	s_nop 0
	global_load_lds_dwordx4 v[146:147], off
	s_barrier
	s_setprio 1
	s_waitcnt lgkmcnt(3)
	v_mfma_f32_16x16x32_bf16 v[92:95], v[226:229], v[174:177], v[92:95]
	s_waitcnt lgkmcnt(1)
	v_mfma_f32_16x16x32_bf16 v[88:91], v[234:237], v[174:177], v[88:91]
	v_mfma_f32_16x16x32_bf16 v[84:87], v[226:229], v[182:185], v[84:87]
	v_mfma_f32_16x16x32_bf16 v[80:83], v[234:237], v[182:185], v[80:83]
	v_mfma_f32_16x16x32_bf16 v[76:79], v[226:229], v[210:213], v[76:79]
	v_mfma_f32_16x16x32_bf16 v[72:75], v[234:237], v[210:213], v[72:75]
	v_mfma_f32_16x16x32_bf16 v[68:71], v[226:229], v[218:221], v[68:71]
	v_mfma_f32_16x16x32_bf16 v[64:67], v[234:237], v[218:221], v[64:67]
	v_mfma_f32_16x16x32_bf16 v[92:95], v[230:233], v[178:181], v[92:95]
	s_waitcnt lgkmcnt(0)
	v_mfma_f32_16x16x32_bf16 v[88:91], v[238:241], v[178:181], v[88:91]
	v_mfma_f32_16x16x32_bf16 v[84:87], v[230:233], v[206:209], v[84:87]
	v_mfma_f32_16x16x32_bf16 v[80:83], v[238:241], v[206:209], v[80:83]
	v_mfma_f32_16x16x32_bf16 v[76:79], v[230:233], v[214:217], v[76:79]
	v_mfma_f32_16x16x32_bf16 v[72:75], v[238:241], v[214:217], v[72:75]
	v_mfma_f32_16x16x32_bf16 v[68:71], v[230:233], v[222:225], v[68:71]
	v_mfma_f32_16x16x32_bf16 v[64:67], v[238:241], v[222:225], v[64:67]
	s_setprio 0
	s_mov_b32 m0, s72
	v_lshl_add_u64 v[146:147], v[194:195], 0, s[36:37]
	s_barrier
	ds_read_b128 v[174:177], v157 offset:49152
	ds_read_b128 v[178:181], v157 offset:50176
	ds_read_b128 v[182:185], v157 offset:51200
	ds_read_b128 v[206:209], v157 offset:52224
	ds_read_b128 v[210:213], v157 offset:53248
	ds_read_b128 v[214:217], v157 offset:54272
	ds_read_b128 v[218:221], v157 offset:55296
	ds_read_b128 v[222:225], v157 offset:56320
	global_load_lds_dwordx4 v[146:147], off
	v_lshl_add_u64 v[146:147], v[196:197], 0, s[36:37]
	s_mov_b32 m0, s73
	s_nop 0
	global_load_lds_dwordx4 v[146:147], off
	s_waitcnt vmcnt(10)
	s_barrier
	s_setprio 1
	s_waitcnt lgkmcnt(7)
	v_mfma_f32_16x16x32_bf16 v[60:63], v[158:161], v[174:177], v[60:63]
	v_mfma_f32_16x16x32_bf16 v[56:59], v[166:169], v[174:177], v[56:59]
	s_waitcnt lgkmcnt(5)
	v_mfma_f32_16x16x32_bf16 v[52:55], v[158:161], v[182:185], v[52:55]
	v_mfma_f32_16x16x32_bf16 v[48:51], v[166:169], v[182:185], v[48:51]
	s_waitcnt lgkmcnt(3)
	v_mfma_f32_16x16x32_bf16 v[44:47], v[158:161], v[210:213], v[44:47]
	v_mfma_f32_16x16x32_bf16 v[40:43], v[166:169], v[210:213], v[40:43]
	s_waitcnt lgkmcnt(1)
	v_mfma_f32_16x16x32_bf16 v[36:39], v[158:161], v[218:221], v[36:39]
	v_mfma_f32_16x16x32_bf16 v[32:35], v[166:169], v[218:221], v[32:35]
	v_mfma_f32_16x16x32_bf16 v[60:63], v[162:165], v[178:181], v[60:63]
	v_mfma_f32_16x16x32_bf16 v[56:59], v[170:173], v[178:181], v[56:59]
	v_mfma_f32_16x16x32_bf16 v[52:55], v[162:165], v[206:209], v[52:55]
	v_mfma_f32_16x16x32_bf16 v[48:51], v[170:173], v[206:209], v[48:51]
	v_mfma_f32_16x16x32_bf16 v[44:47], v[162:165], v[214:217], v[44:47]
	v_mfma_f32_16x16x32_bf16 v[40:43], v[170:173], v[214:217], v[40:43]
	s_waitcnt lgkmcnt(0)
	v_mfma_f32_16x16x32_bf16 v[36:39], v[162:165], v[222:225], v[36:39]
	v_mfma_f32_16x16x32_bf16 v[32:35], v[170:173], v[222:225], v[32:35]
	s_setprio 0
	s_barrier
	s_add_u32 s54, s54, 0x40080
	s_addc_u32 s55, s55, 0
	s_add_i32 s6, s19, s57
	v_lshl_add_u64 v[146:147], s[54:55], 0, v[140:141]
	s_mov_b32 m0, s6
	s_nop 0
	global_load_lds_dwordx4 v[146:147], off
	v_lshl_add_u64 v[146:147], s[54:55], 0, v[132:133]
	s_add_i32 m0, s6, 0x2000
	s_nop 0
	global_load_lds_dwordx4 v[146:147], off
	v_add_u32_e32 v146, 0x10000, v154
	ds_read_b128 v[158:161], v146
	ds_read_b128 v[162:165], v146 offset:1024
	ds_read_b128 v[166:169], v146 offset:2048
	ds_read_b128 v[170:173], v146 offset:3072
	s_waitcnt vmcnt(6)
	s_barrier
	s_setprio 1
	v_mfma_f32_16x16x32_bf16 v[28:31], v[226:229], v[174:177], v[28:31]
	v_mfma_f32_16x16x32_bf16 v[24:27], v[234:237], v[174:177], v[24:27]
	v_mfma_f32_16x16x32_bf16 v[20:23], v[226:229], v[182:185], v[20:23]
	v_mfma_f32_16x16x32_bf16 v[16:19], v[234:237], v[182:185], v[16:19]
	v_mfma_f32_16x16x32_bf16 v[12:15], v[226:229], v[210:213], v[12:15]
	v_mfma_f32_16x16x32_bf16 v[8:11], v[234:237], v[210:213], v[8:11]
	v_mfma_f32_16x16x32_bf16 v[4:7], v[226:229], v[218:221], v[4:7]
	v_mfma_f32_16x16x32_bf16 v[0:3], v[234:237], v[218:221], v[0:3]
	v_mfma_f32_16x16x32_bf16 v[28:31], v[230:233], v[178:181], v[28:31]
	v_mfma_f32_16x16x32_bf16 v[24:27], v[238:241], v[178:181], v[24:27]
	v_mfma_f32_16x16x32_bf16 v[20:23], v[230:233], v[206:209], v[20:23]
	v_mfma_f32_16x16x32_bf16 v[16:19], v[238:241], v[206:209], v[16:19]
	v_mfma_f32_16x16x32_bf16 v[12:15], v[230:233], v[214:217], v[12:15]
	v_mfma_f32_16x16x32_bf16 v[8:11], v[238:241], v[214:217], v[8:11]
	v_mfma_f32_16x16x32_bf16 v[4:7], v[230:233], v[222:225], v[4:7]
	v_mfma_f32_16x16x32_bf16 v[0:3], v[238:241], v[222:225], v[0:3]
	s_setprio 0
	s_add_i32 s81, s81, 2
	s_add_u32 s52, s52, 0x100
	s_addc_u32 s53, s53, 0
	s_cmp_gt_u32 s81, 13
	s_barrier
	s_cbranch_scc0 .LBB0_386
	s_waitcnt lgkmcnt(0)
	v_lshl_add_u32 v158, s75, 10, v155
	ds_read2_b32 v[146:147], v158 offset1:16
	s_add_u32 s52, s10, 0xffffff00
	s_addc_u32 s53, s11, -1
	s_ashr_i32 s35, s34, 31
	s_lshl_b64 s[10:11], s[34:35], 8
	s_waitcnt lgkmcnt(0)
	v_pk_mul_f32 v[148:149], v[124:125], v[146:147] op_sel_hi:[1,0]
	v_lshl_add_u64 v[152:153], v[134:135], 0, s[10:11]
	v_mul_f32_e32 v159, 0xbfb8aa3b, v148
	v_exp_f32_e32 v159, v159
	s_movk_i32 s6, 0x1600
	v_lshl_or_b32 v150, s74, 7, v156
	v_ashrrev_i32_e32 v151, 31, v150
	v_add_f32_e32 v159, 1.0, v159
	v_rcp_f32_e32 v160, v159
	v_mul_f32_e32 v159, 0xbfb8aa3b, v149
	v_exp_f32_e32 v159, v159
	s_nop 0
	v_add_f32_e32 v159, 1.0, v159
	v_rcp_f32_e32 v161, v159
	s_nop 0
	v_pk_mul_f32 v[148:149], v[148:149], v[160:161]
	v_pk_mul_f32 v[160:161], v[92:93], v[146:147] op_sel_hi:[1,0]
	s_nop 0
	v_pk_mul_f32 v[148:149], v[160:161], v[148:149]
	v_pk_mul_f32 v[160:161], v[126:127], v[146:147] op_sel_hi:[1,0]
	s_nop 0
	v_mul_f32_e32 v159, 0xbfb8aa3b, v160
	v_exp_f32_e32 v159, v159
	s_nop 0
	v_add_f32_e32 v159, 1.0, v159
	v_rcp_f32_e32 v162, v159
	v_mul_f32_e32 v159, 0xbfb8aa3b, v161
	v_exp_f32_e32 v159, v159
	s_nop 0
	v_add_f32_e32 v159, 1.0, v159
	v_rcp_f32_e32 v163, v159
	s_nop 0
	v_pk_mul_f32 v[160:161], v[160:161], v[162:163]
	v_pk_mul_f32 v[162:163], v[94:95], v[146:147] op_sel_hi:[1,0]
	s_nop 0
	v_pk_mul_f32 v[162:163], v[162:163], v[160:161]
	v_pk_mul_f32 v[160:161], v[120:121], v[146:147] op_sel_hi:[1,0]
	s_nop 0
	v_mul_f32_e32 v159, 0xbfb8aa3b, v160
	v_exp_f32_e32 v159, v159
	s_nop 0
	v_add_f32_e32 v159, 1.0, v159
	v_rcp_f32_e32 v164, v159
	v_mul_f32_e32 v159, 0xbfb8aa3b, v161
	v_exp_f32_e32 v159, v159
	s_nop 0
	v_add_f32_e32 v159, 1.0, v159
	v_rcp_f32_e32 v165, v159
	s_nop 0
	v_pk_mul_f32 v[160:161], v[160:161], v[164:165]
	v_pk_mul_f32 v[164:165], v[88:89], v[146:147] op_sel_hi:[1,0]
	s_nop 0
	v_pk_mul_f32 v[164:165], v[164:165], v[160:161]
	v_pk_mul_f32 v[160:161], v[122:123], v[146:147] op_sel_hi:[1,0]
	s_nop 0
	v_mul_f32_e32 v159, 0xbfb8aa3b, v160
	v_exp_f32_e32 v159, v159
	s_nop 0
	v_add_f32_e32 v159, 1.0, v159
	v_rcp_f32_e32 v166, v159
	v_mul_f32_e32 v159, 0xbfb8aa3b, v161
	v_exp_f32_e32 v159, v159
	s_nop 0
	v_add_f32_e32 v159, 1.0, v159
	v_rcp_f32_e32 v167, v159
	s_nop 0
	v_pk_mul_f32 v[160:161], v[160:161], v[166:167]
	v_pk_mul_f32 v[166:167], v[90:91], v[146:147] op_sel_hi:[1,0]
	s_nop 0
	v_pk_mul_f32 v[166:167], v[166:167], v[160:161]
	v_cvt_pk_bf16_f32 v160, v148, v149
	v_mov_b64_e32 v[148:149], s[30:31]
	v_mad_u64_u32 v[148:149], s[10:11], v152, s6, v[148:149]
	v_mov_b32_e32 v146, v149
	v_mad_u64_u32 v[152:153], s[10:11], v153, s6, v[146:147]
	v_mov_b32_e32 v149, v152
	v_mov_b32_e32 v146, v147
	v_lshl_add_u64 v[150:151], v[150:151], 1, v[148:149]
	v_pk_mul_f32 v[148:149], v[116:117], v[146:147] op_sel_hi:[1,0]
	v_cvt_pk_bf16_f32 v161, v162, v163
	v_mul_f32_e32 v147, 0xbfb8aa3b, v148
	v_exp_f32_e32 v147, v147
	v_cvt_pk_bf16_f32 v162, v164, v165
	v_cvt_pk_bf16_f32 v163, v166, v167
	global_store_dwordx4 v[150:151], v[160:163], off
	v_add_f32_e32 v147, 1.0, v147
	v_rcp_f32_e32 v152, v147
	v_mul_f32_e32 v147, 0xbfb8aa3b, v149
	v_exp_f32_e32 v147, v147
	s_mov_b32 s6, 0x16000
	v_add_f32_e32 v147, 1.0, v147
	v_rcp_f32_e32 v153, v147
	s_nop 0
	v_pk_mul_f32 v[148:149], v[148:149], v[152:153]
	v_pk_mul_f32 v[152:153], v[84:85], v[146:147] op_sel_hi:[1,0]
	s_nop 0
	v_pk_mul_f32 v[148:149], v[152:153], v[148:149]
	v_pk_mul_f32 v[152:153], v[118:119], v[146:147] op_sel_hi:[1,0]
	s_nop 0
	v_mul_f32_e32 v147, 0xbfb8aa3b, v152
	v_exp_f32_e32 v147, v147
	s_nop 0
	v_add_f32_e32 v147, 1.0, v147
	v_rcp_f32_e32 v160, v147
	v_mul_f32_e32 v147, 0xbfb8aa3b, v153
	v_exp_f32_e32 v147, v147
	s_nop 0
	v_add_f32_e32 v147, 1.0, v147
	v_rcp_f32_e32 v161, v147
	s_nop 0
	v_pk_mul_f32 v[152:153], v[152:153], v[160:161]
	v_pk_mul_f32 v[160:161], v[86:87], v[146:147] op_sel_hi:[1,0]
	s_nop 0
	v_pk_mul_f32 v[152:153], v[160:161], v[152:153]
	v_pk_mul_f32 v[160:161], v[112:113], v[146:147] op_sel_hi:[1,0]
	s_nop 0
	v_mul_f32_e32 v147, 0xbfb8aa3b, v160
	v_exp_f32_e32 v147, v147
	s_nop 0
	v_add_f32_e32 v147, 1.0, v147
	v_rcp_f32_e32 v162, v147
	v_mul_f32_e32 v147, 0xbfb8aa3b, v161
	v_exp_f32_e32 v147, v147
	s_nop 0
	v_add_f32_e32 v147, 1.0, v147
	v_rcp_f32_e32 v163, v147
	s_nop 0
	v_pk_mul_f32 v[160:161], v[160:161], v[162:163]
	v_pk_mul_f32 v[162:163], v[80:81], v[146:147] op_sel_hi:[1,0]
	s_nop 0
	v_pk_mul_f32 v[162:163], v[162:163], v[160:161]
	v_pk_mul_f32 v[160:161], v[114:115], v[146:147] op_sel_hi:[1,0]
	v_cvt_pk_bf16_f32 v162, v162, v163
	v_mul_f32_e32 v147, 0xbfb8aa3b, v160
	v_exp_f32_e32 v147, v147
	s_nop 0
	v_add_f32_e32 v147, 1.0, v147
	v_rcp_f32_e32 v164, v147
	v_mul_f32_e32 v147, 0xbfb8aa3b, v161
	v_exp_f32_e32 v147, v147
	s_nop 0
	v_add_f32_e32 v147, 1.0, v147
	v_rcp_f32_e32 v165, v147
	v_pk_mul_f32 v[146:147], v[82:83], v[146:147] op_sel_hi:[1,0]
	v_pk_mul_f32 v[160:161], v[160:161], v[164:165]
	s_nop 0
	v_pk_mul_f32 v[146:147], v[146:147], v[160:161]
	v_cvt_pk_bf16_f32 v160, v148, v149
	v_cvt_pk_bf16_f32 v163, v146, v147
	v_add_co_u32_e32 v146, vcc, s6, v150
	v_cvt_pk_bf16_f32 v161, v152, v153
	s_nop 0
	v_addc_co_u32_e32 v147, vcc, 0, v151, vcc
	global_store_dwordx4 v[146:147], v[160:163], off
	ds_read2_b32 v[146:147], v158 offset0:32 offset1:48
	s_mov_b32 s6, 0x2c000
	s_waitcnt lgkmcnt(0)
	v_pk_mul_f32 v[148:149], v[108:109], v[146:147] op_sel_hi:[1,0]
	s_nop 0
	v_mul_f32_e32 v152, 0xbfb8aa3b, v148
	v_mul_f32_e32 v153, 0xbfb8aa3b, v149
	v_exp_f32_e32 v152, v152
	v_exp_f32_e32 v153, v153
	v_add_f32_e32 v152, 1.0, v152
	v_add_f32_e32 v153, 1.0, v153
	v_rcp_f32_e32 v152, v152
	v_rcp_f32_e32 v153, v153
	s_nop 0
	v_pk_mul_f32 v[148:149], v[148:149], v[152:153]
	v_pk_mul_f32 v[152:153], v[76:77], v[146:147] op_sel_hi:[1,0]
	s_nop 0
	v_pk_mul_f32 v[148:149], v[152:153], v[148:149]
	v_pk_mul_f32 v[152:153], v[110:111], v[146:147] op_sel_hi:[1,0]
	s_nop 0
	v_mul_f32_e32 v159, 0xbfb8aa3b, v152
	v_exp_f32_e32 v159, v159
	s_nop 0
	v_add_f32_e32 v159, 1.0, v159
	v_rcp_f32_e32 v160, v159
	v_mul_f32_e32 v159, 0xbfb8aa3b, v153
	v_exp_f32_e32 v159, v159
	s_nop 0
	v_add_f32_e32 v159, 1.0, v159
	v_rcp_f32_e32 v161, v159
	s_nop 0
	v_pk_mul_f32 v[152:153], v[152:153], v[160:161]
	v_pk_mul_f32 v[160:161], v[78:79], v[146:147] op_sel_hi:[1,0]
	s_nop 0
	v_pk_mul_f32 v[152:153], v[160:161], v[152:153]
	v_pk_mul_f32 v[160:161], v[104:105], v[146:147] op_sel_hi:[1,0]
	s_nop 0
	v_mul_f32_e32 v159, 0xbfb8aa3b, v160
	v_exp_f32_e32 v159, v159
	s_nop 0
	v_add_f32_e32 v159, 1.0, v159
	v_rcp_f32_e32 v162, v159
	v_mul_f32_e32 v159, 0xbfb8aa3b, v161
	v_exp_f32_e32 v159, v159
	s_nop 0
	v_add_f32_e32 v159, 1.0, v159
	v_rcp_f32_e32 v163, v159
	s_nop 0
	v_pk_mul_f32 v[160:161], v[160:161], v[162:163]
	v_pk_mul_f32 v[162:163], v[72:73], v[146:147] op_sel_hi:[1,0]
	s_nop 0
	v_pk_mul_f32 v[162:163], v[162:163], v[160:161]
	v_pk_mul_f32 v[160:161], v[106:107], v[146:147] op_sel_hi:[1,0]
	v_cvt_pk_bf16_f32 v162, v162, v163
	v_mul_f32_e32 v159, 0xbfb8aa3b, v160
	v_exp_f32_e32 v159, v159
	s_nop 0
	v_add_f32_e32 v159, 1.0, v159
	v_rcp_f32_e32 v164, v159
	v_mul_f32_e32 v159, 0xbfb8aa3b, v161
	v_exp_f32_e32 v159, v159
	s_nop 0
	v_add_f32_e32 v159, 1.0, v159
	v_rcp_f32_e32 v165, v159
	s_nop 0
	v_pk_mul_f32 v[160:161], v[160:161], v[164:165]
	v_pk_mul_f32 v[164:165], v[74:75], v[146:147] op_sel_hi:[1,0]
	v_mov_b32_e32 v146, v147
	v_pk_mul_f32 v[164:165], v[164:165], v[160:161]
	v_cvt_pk_bf16_f32 v160, v148, v149
	v_add_co_u32_e32 v148, vcc, s6, v150
	v_cvt_pk_bf16_f32 v161, v152, v153
	v_cvt_pk_bf16_f32 v163, v164, v165
	v_addc_co_u32_e32 v149, vcc, 0, v151, vcc
	global_store_dwordx4 v[148:149], v[160:163], off
	v_pk_mul_f32 v[148:149], v[100:101], v[146:147] op_sel_hi:[1,0]
	s_mov_b32 s6, 0x42000
	v_mul_f32_e32 v147, 0xbfb8aa3b, v148
	v_exp_f32_e32 v147, v147
	s_nop 0
	v_add_f32_e32 v147, 1.0, v147
	v_rcp_f32_e32 v152, v147
	v_mul_f32_e32 v147, 0xbfb8aa3b, v149
	v_exp_f32_e32 v147, v147
	s_nop 0
	v_add_f32_e32 v147, 1.0, v147
	v_rcp_f32_e32 v153, v147
	s_nop 0
	v_pk_mul_f32 v[148:149], v[148:149], v[152:153]
	v_pk_mul_f32 v[152:153], v[68:69], v[146:147] op_sel_hi:[1,0]
	s_nop 0
	v_pk_mul_f32 v[148:149], v[152:153], v[148:149]
	v_pk_mul_f32 v[152:153], v[102:103], v[146:147] op_sel_hi:[1,0]
	s_nop 0
	v_mul_f32_e32 v147, 0xbfb8aa3b, v152
	v_exp_f32_e32 v147, v147
	s_nop 0
	v_add_f32_e32 v147, 1.0, v147
	v_rcp_f32_e32 v160, v147
	v_mul_f32_e32 v147, 0xbfb8aa3b, v153
	v_exp_f32_e32 v147, v147
	s_nop 0
	v_add_f32_e32 v147, 1.0, v147
	v_rcp_f32_e32 v161, v147
	s_nop 0
	v_pk_mul_f32 v[152:153], v[152:153], v[160:161]
	v_pk_mul_f32 v[160:161], v[70:71], v[146:147] op_sel_hi:[1,0]
	s_nop 0
	v_pk_mul_f32 v[152:153], v[160:161], v[152:153]
	v_pk_mul_f32 v[160:161], v[96:97], v[146:147] op_sel_hi:[1,0]
	s_nop 0
	v_mul_f32_e32 v147, 0xbfb8aa3b, v160
	v_exp_f32_e32 v147, v147
	s_nop 0
	v_add_f32_e32 v147, 1.0, v147
	v_rcp_f32_e32 v162, v147
	v_mul_f32_e32 v147, 0xbfb8aa3b, v161
	v_exp_f32_e32 v147, v147
	s_nop 0
	v_add_f32_e32 v147, 1.0, v147
	v_rcp_f32_e32 v163, v147
	s_nop 0
	v_pk_mul_f32 v[160:161], v[160:161], v[162:163]
	v_pk_mul_f32 v[162:163], v[64:65], v[146:147] op_sel_hi:[1,0]
	s_nop 0
	v_pk_mul_f32 v[162:163], v[162:163], v[160:161]
	v_pk_mul_f32 v[160:161], v[98:99], v[146:147] op_sel_hi:[1,0]
	v_cvt_pk_bf16_f32 v162, v162, v163
	v_mul_f32_e32 v147, 0xbfb8aa3b, v160
	v_exp_f32_e32 v147, v147
	s_nop 0
	v_add_f32_e32 v147, 1.0, v147
	v_rcp_f32_e32 v164, v147
	v_mul_f32_e32 v147, 0xbfb8aa3b, v161
	v_exp_f32_e32 v147, v147
	s_nop 0
	v_add_f32_e32 v147, 1.0, v147
	v_rcp_f32_e32 v165, v147
	v_pk_mul_f32 v[146:147], v[66:67], v[146:147] op_sel_hi:[1,0]
	v_pk_mul_f32 v[160:161], v[160:161], v[164:165]
	s_nop 0
	v_pk_mul_f32 v[146:147], v[146:147], v[160:161]
	v_cvt_pk_bf16_f32 v160, v148, v149
	v_cvt_pk_bf16_f32 v163, v146, v147
	v_add_co_u32_e32 v146, vcc, s6, v150
	v_cvt_pk_bf16_f32 v161, v152, v153
	s_nop 0
	v_addc_co_u32_e32 v147, vcc, 0, v151, vcc
	global_store_dwordx4 v[146:147], v[160:163], off
	ds_read2_b32 v[146:147], v158 offset0:128 offset1:144
	s_mov_b32 s6, 0xb0000
	s_waitcnt lgkmcnt(0)
	v_pk_mul_f32 v[148:149], v[60:61], v[146:147] op_sel_hi:[1,0]
	s_nop 0
	v_mul_f32_e32 v152, 0xbfb8aa3b, v148
	v_mul_f32_e32 v153, 0xbfb8aa3b, v149
	v_exp_f32_e32 v152, v152
	v_exp_f32_e32 v153, v153
	v_add_f32_e32 v152, 1.0, v152
	v_add_f32_e32 v153, 1.0, v153
	v_rcp_f32_e32 v152, v152
	v_rcp_f32_e32 v153, v153
	s_nop 0
	v_pk_mul_f32 v[148:149], v[148:149], v[152:153]
	v_pk_mul_f32 v[152:153], v[28:29], v[146:147] op_sel_hi:[1,0]
	s_nop 0
	v_pk_mul_f32 v[148:149], v[152:153], v[148:149]
	v_pk_mul_f32 v[152:153], v[62:63], v[146:147] op_sel_hi:[1,0]
	s_nop 0
	v_mul_f32_e32 v159, 0xbfb8aa3b, v152
	v_exp_f32_e32 v159, v159
	s_nop 0
	v_add_f32_e32 v159, 1.0, v159
	v_rcp_f32_e32 v160, v159
	v_mul_f32_e32 v159, 0xbfb8aa3b, v153
	v_exp_f32_e32 v159, v159
	s_nop 0
	v_add_f32_e32 v159, 1.0, v159
	v_rcp_f32_e32 v161, v159
	s_nop 0
	v_pk_mul_f32 v[152:153], v[152:153], v[160:161]
	v_pk_mul_f32 v[160:161], v[30:31], v[146:147] op_sel_hi:[1,0]
	s_nop 0
	v_pk_mul_f32 v[152:153], v[160:161], v[152:153]
	v_pk_mul_f32 v[160:161], v[56:57], v[146:147] op_sel_hi:[1,0]
	s_nop 0
	v_mul_f32_e32 v159, 0xbfb8aa3b, v160
	v_exp_f32_e32 v159, v159
	s_nop 0
	v_add_f32_e32 v159, 1.0, v159
	v_rcp_f32_e32 v162, v159
	v_mul_f32_e32 v159, 0xbfb8aa3b, v161
	v_exp_f32_e32 v159, v159
	s_nop 0
	v_add_f32_e32 v159, 1.0, v159
	v_rcp_f32_e32 v163, v159
	s_nop 0
	v_pk_mul_f32 v[160:161], v[160:161], v[162:163]
	v_pk_mul_f32 v[162:163], v[24:25], v[146:147] op_sel_hi:[1,0]
	s_nop 0
	v_pk_mul_f32 v[162:163], v[162:163], v[160:161]
	v_pk_mul_f32 v[160:161], v[58:59], v[146:147] op_sel_hi:[1,0]
	v_cvt_pk_bf16_f32 v162, v162, v163
	v_mul_f32_e32 v159, 0xbfb8aa3b, v160
	v_exp_f32_e32 v159, v159
	s_nop 0
	v_add_f32_e32 v159, 1.0, v159
	v_rcp_f32_e32 v164, v159
	v_mul_f32_e32 v159, 0xbfb8aa3b, v161
	v_exp_f32_e32 v159, v159
	s_nop 0
	v_add_f32_e32 v159, 1.0, v159
	v_rcp_f32_e32 v165, v159
	s_nop 0
	v_pk_mul_f32 v[160:161], v[160:161], v[164:165]
	v_pk_mul_f32 v[164:165], v[26:27], v[146:147] op_sel_hi:[1,0]
	v_mov_b32_e32 v146, v147
	v_pk_mul_f32 v[164:165], v[164:165], v[160:161]
	v_cvt_pk_bf16_f32 v160, v148, v149
	v_add_co_u32_e32 v148, vcc, s6, v150
	v_cvt_pk_bf16_f32 v161, v152, v153
	v_cvt_pk_bf16_f32 v163, v164, v165
	v_addc_co_u32_e32 v149, vcc, 0, v151, vcc
	global_store_dwordx4 v[148:149], v[160:163], off
	v_pk_mul_f32 v[148:149], v[52:53], v[146:147] op_sel_hi:[1,0]
	s_mov_b32 s6, 0xc6000
	v_mul_f32_e32 v147, 0xbfb8aa3b, v148
	v_exp_f32_e32 v147, v147
	s_nop 0
	v_add_f32_e32 v147, 1.0, v147
	v_rcp_f32_e32 v152, v147
	v_mul_f32_e32 v147, 0xbfb8aa3b, v149
	v_exp_f32_e32 v147, v147
	s_nop 0
	v_add_f32_e32 v147, 1.0, v147
	v_rcp_f32_e32 v153, v147
	s_nop 0
	v_pk_mul_f32 v[148:149], v[148:149], v[152:153]
	v_pk_mul_f32 v[152:153], v[20:21], v[146:147] op_sel_hi:[1,0]
	s_nop 0
	v_pk_mul_f32 v[148:149], v[152:153], v[148:149]
	v_pk_mul_f32 v[152:153], v[54:55], v[146:147] op_sel_hi:[1,0]
	s_nop 0
	v_mul_f32_e32 v147, 0xbfb8aa3b, v152
	v_exp_f32_e32 v147, v147
	s_nop 0
	v_add_f32_e32 v147, 1.0, v147
	v_rcp_f32_e32 v160, v147
	v_mul_f32_e32 v147, 0xbfb8aa3b, v153
	v_exp_f32_e32 v147, v147
	s_nop 0
	v_add_f32_e32 v147, 1.0, v147
	v_rcp_f32_e32 v161, v147
	s_nop 0
	v_pk_mul_f32 v[152:153], v[152:153], v[160:161]
	v_pk_mul_f32 v[160:161], v[22:23], v[146:147] op_sel_hi:[1,0]
	s_nop 0
	v_pk_mul_f32 v[152:153], v[160:161], v[152:153]
	v_pk_mul_f32 v[160:161], v[48:49], v[146:147] op_sel_hi:[1,0]
	s_nop 0
	v_mul_f32_e32 v147, 0xbfb8aa3b, v160
	v_exp_f32_e32 v147, v147
	s_nop 0
	v_add_f32_e32 v147, 1.0, v147
	v_rcp_f32_e32 v162, v147
	v_mul_f32_e32 v147, 0xbfb8aa3b, v161
	v_exp_f32_e32 v147, v147
	s_nop 0
	v_add_f32_e32 v147, 1.0, v147
	v_rcp_f32_e32 v163, v147
	s_nop 0
	v_pk_mul_f32 v[160:161], v[160:161], v[162:163]
	v_pk_mul_f32 v[162:163], v[16:17], v[146:147] op_sel_hi:[1,0]
	s_nop 0
	v_pk_mul_f32 v[162:163], v[162:163], v[160:161]
	v_pk_mul_f32 v[160:161], v[50:51], v[146:147] op_sel_hi:[1,0]
	v_cvt_pk_bf16_f32 v162, v162, v163
	v_mul_f32_e32 v147, 0xbfb8aa3b, v160
	v_exp_f32_e32 v147, v147
	s_nop 0
	v_add_f32_e32 v147, 1.0, v147
	v_rcp_f32_e32 v164, v147
	v_mul_f32_e32 v147, 0xbfb8aa3b, v161
	v_exp_f32_e32 v147, v147
	s_nop 0
	v_add_f32_e32 v147, 1.0, v147
	v_rcp_f32_e32 v165, v147
	v_pk_mul_f32 v[146:147], v[18:19], v[146:147] op_sel_hi:[1,0]
	v_pk_mul_f32 v[160:161], v[160:161], v[164:165]
	s_nop 0
	v_pk_mul_f32 v[146:147], v[146:147], v[160:161]
	v_cvt_pk_bf16_f32 v160, v148, v149
	v_cvt_pk_bf16_f32 v163, v146, v147
	v_add_co_u32_e32 v146, vcc, s6, v150
	v_cvt_pk_bf16_f32 v161, v152, v153
	s_nop 0
	v_addc_co_u32_e32 v147, vcc, 0, v151, vcc
	global_store_dwordx4 v[146:147], v[160:163], off
	ds_read2_b32 v[146:147], v158 offset0:160 offset1:176
	s_mov_b32 s6, 0xdc000
	s_waitcnt lgkmcnt(0)
	v_pk_mul_f32 v[148:149], v[44:45], v[146:147] op_sel_hi:[1,0]
	s_nop 0
	v_mul_f32_e32 v152, 0xbfb8aa3b, v148
	v_mul_f32_e32 v153, 0xbfb8aa3b, v149
	v_exp_f32_e32 v152, v152
	v_exp_f32_e32 v153, v153
	v_add_f32_e32 v152, 1.0, v152
	v_add_f32_e32 v153, 1.0, v153
	v_rcp_f32_e32 v152, v152
	v_rcp_f32_e32 v153, v153
	s_nop 0
	v_pk_mul_f32 v[148:149], v[148:149], v[152:153]
	v_pk_mul_f32 v[152:153], v[12:13], v[146:147] op_sel_hi:[1,0]
	s_nop 0
	v_pk_mul_f32 v[148:149], v[152:153], v[148:149]
	v_pk_mul_f32 v[152:153], v[46:47], v[146:147] op_sel_hi:[1,0]
	s_nop 0
	v_mul_f32_e32 v158, 0xbfb8aa3b, v152
	v_mul_f32_e32 v159, 0xbfb8aa3b, v153
	v_exp_f32_e32 v158, v158
	v_exp_f32_e32 v159, v159
	v_add_f32_e32 v158, 1.0, v158
	v_add_f32_e32 v159, 1.0, v159
	v_rcp_f32_e32 v158, v158
	v_rcp_f32_e32 v159, v159
	s_nop 0
	v_pk_mul_f32 v[152:153], v[152:153], v[158:159]
	v_pk_mul_f32 v[158:159], v[14:15], v[146:147] op_sel_hi:[1,0]
	s_nop 0
	v_pk_mul_f32 v[152:153], v[158:159], v[152:153]
	v_pk_mul_f32 v[158:159], v[40:41], v[146:147] op_sel_hi:[1,0]
	s_nop 0
	v_mul_f32_e32 v160, 0xbfb8aa3b, v158
	v_mul_f32_e32 v161, 0xbfb8aa3b, v159
	v_exp_f32_e32 v160, v160
	v_exp_f32_e32 v161, v161
	v_add_f32_e32 v160, 1.0, v160
	v_add_f32_e32 v161, 1.0, v161
	v_rcp_f32_e32 v160, v160
	v_rcp_f32_e32 v161, v161
	s_nop 0
	v_pk_mul_f32 v[158:159], v[158:159], v[160:161]
	v_pk_mul_f32 v[160:161], v[8:9], v[146:147] op_sel_hi:[1,0]
	s_nop 0
	v_pk_mul_f32 v[160:161], v[160:161], v[158:159]
	v_pk_mul_f32 v[158:159], v[42:43], v[146:147] op_sel_hi:[1,0]
	v_cvt_pk_bf16_f32 v160, v160, v161
	v_mul_f32_e32 v162, 0xbfb8aa3b, v158
	v_mul_f32_e32 v163, 0xbfb8aa3b, v159
	v_exp_f32_e32 v162, v162
	v_exp_f32_e32 v163, v163
	v_add_f32_e32 v162, 1.0, v162
	v_add_f32_e32 v163, 1.0, v163
	v_rcp_f32_e32 v162, v162
	v_rcp_f32_e32 v163, v163
	s_nop 0
	v_pk_mul_f32 v[158:159], v[158:159], v[162:163]
	v_pk_mul_f32 v[162:163], v[10:11], v[146:147] op_sel_hi:[1,0]
	v_mov_b32_e32 v146, v147
	v_pk_mul_f32 v[162:163], v[162:163], v[158:159]
	v_cvt_pk_bf16_f32 v158, v148, v149
	v_add_co_u32_e32 v148, vcc, s6, v150
	v_cvt_pk_bf16_f32 v159, v152, v153
	v_cvt_pk_bf16_f32 v161, v162, v163
	v_addc_co_u32_e32 v149, vcc, 0, v151, vcc
	global_store_dwordx4 v[148:149], v[158:161], off
	v_pk_mul_f32 v[148:149], v[36:37], v[146:147] op_sel_hi:[1,0]
	s_nop 0
	v_mul_f32_e32 v147, 0xbfb8aa3b, v148
	v_exp_f32_e32 v147, v147
	s_nop 0
	v_add_f32_e32 v147, 1.0, v147
	v_rcp_f32_e32 v152, v147
	v_mul_f32_e32 v147, 0xbfb8aa3b, v149
	v_exp_f32_e32 v147, v147
	s_nop 0
	v_add_f32_e32 v147, 1.0, v147
	v_rcp_f32_e32 v153, v147
	s_nop 0
	v_pk_mul_f32 v[148:149], v[148:149], v[152:153]
	v_pk_mul_f32 v[152:153], v[4:5], v[146:147] op_sel_hi:[1,0]
	s_nop 0
	v_pk_mul_f32 v[148:149], v[152:153], v[148:149]
	v_pk_mul_f32 v[152:153], v[38:39], v[146:147] op_sel_hi:[1,0]
	s_nop 0
	v_mul_f32_e32 v147, 0xbfb8aa3b, v152
	v_exp_f32_e32 v147, v147
	s_nop 0
	v_add_f32_e32 v147, 1.0, v147
	v_rcp_f32_e32 v158, v147
	v_mul_f32_e32 v147, 0xbfb8aa3b, v153
	v_exp_f32_e32 v147, v147
	s_nop 0
	v_add_f32_e32 v147, 1.0, v147
	v_rcp_f32_e32 v159, v147
	s_nop 0
	v_pk_mul_f32 v[152:153], v[152:153], v[158:159]
	v_pk_mul_f32 v[158:159], v[6:7], v[146:147] op_sel_hi:[1,0]
	s_nop 0
	v_pk_mul_f32 v[152:153], v[158:159], v[152:153]
	v_pk_mul_f32 v[158:159], v[32:33], v[146:147] op_sel_hi:[1,0]
	s_nop 0
	v_mul_f32_e32 v147, 0xbfb8aa3b, v158
	v_exp_f32_e32 v147, v147
	s_nop 0
	v_add_f32_e32 v147, 1.0, v147
	v_rcp_f32_e32 v160, v147
	v_mul_f32_e32 v147, 0xbfb8aa3b, v159
	v_exp_f32_e32 v147, v147
	s_nop 0
	v_add_f32_e32 v147, 1.0, v147
	v_rcp_f32_e32 v161, v147
	s_nop 0
	v_pk_mul_f32 v[158:159], v[158:159], v[160:161]
	v_pk_mul_f32 v[160:161], v[0:1], v[146:147] op_sel_hi:[1,0]
	s_nop 0
	v_pk_mul_f32 v[160:161], v[160:161], v[158:159]
	v_pk_mul_f32 v[158:159], v[34:35], v[146:147] op_sel_hi:[1,0]
	v_cvt_pk_bf16_f32 v160, v160, v161
	v_mul_f32_e32 v147, 0xbfb8aa3b, v158
	v_exp_f32_e32 v147, v147
	s_nop 0
	v_add_f32_e32 v147, 1.0, v147
	v_rcp_f32_e32 v162, v147
	v_mul_f32_e32 v147, 0xbfb8aa3b, v159
	v_exp_f32_e32 v147, v147
	s_nop 0
	v_add_f32_e32 v147, 1.0, v147
	v_rcp_f32_e32 v163, v147
	v_pk_mul_f32 v[146:147], v[2:3], v[146:147] op_sel_hi:[1,0]
	v_pk_mul_f32 v[158:159], v[158:159], v[162:163]
	s_nop 0
	v_pk_mul_f32 v[146:147], v[146:147], v[158:159]
	v_cvt_pk_bf16_f32 v158, v148, v149
	v_cvt_pk_bf16_f32 v161, v146, v147
	v_add_co_u32_e32 v146, vcc, 0xf2000, v150
	v_cvt_pk_bf16_f32 v159, v152, v153
	s_nop 0
	v_addc_co_u32_e32 v147, vcc, 0, v151, vcc
	s_andn2_b64 vcc, exec, s[44:45]
	global_store_dwordx4 v[146:147], v[158:161], off
	s_cbranch_vccz .LBB0_382
	s_mov_b64 s[48:49], s[52:53]
	s_andn2_b64 vcc, exec, s[42:43]
	s_mov_b64 s[52:53], s[48:49]
	s_cbranch_vccnz .LBB0_383
